# all flat_load/flat_store (global addresses) converted to global_load/global_store so LDS waits do not see them
# baseline (speedup 1.0000x reference)
; DI unsigned xb_ld(unsigned* p)              { return __hip_atomic_load(p, __ATOMIC_RELAXED, __HIP_MEMORY_SCOPE_AGENT); }
; DI void xcd_barrier_complete(unsigned* bar, unsigned x, unsigned& nloc, unsigned& nx) {
;     ...
;     for (;;) {
;         sum = 0u; cnt = 0u; mine = 0u;
; #pragma unroll
;         for (unsigned j = 0; j < 16; ++j) { const unsigned c = xb_ld(&bar[XB_XCNT(j)]); sum += c; cnt += (c > 0u) ? 1u : 0u; mine = (j == x) ? c : mine; }
;         if (sum == G) break;
;         __builtin_amdgcn_s_sleep(1);
;         if ((++sp & 255u) == 0u) { if (xb_ld(&bar[XB_TMO])) break; if (sp > XB_SPIN_CAP) { atomicAdd(&bar[XB_TMO], 1u); break; } }
;     }
.LBB0_1758:
	global_load_dword v47, v[0:1], off sc1
	global_load_dword v32, v[2:3], off sc1
	global_load_dword v33, v[4:5], off sc1
	global_load_dword v34, v[6:7], off sc1
	global_load_dword v35, v[8:9], off sc1
	global_load_dword v36, v[10:11], off sc1
	global_load_dword v37, v[12:13], off sc1
	global_load_dword v38, v[14:15], off sc1
	global_load_dword v39, v[16:17], off sc1
	global_load_dword v40, v[18:19], off sc1
	global_load_dword v41, v[20:21], off sc1
	global_load_dword v42, v[22:23], off sc1
	global_load_dword v43, v[24:25], off sc1
	global_load_dword v44, v[26:27], off sc1
	global_load_dword v45, v[28:29], off sc1
	global_load_dword v46, v[30:31], off sc1
	s_or_b64 s[8:9], s[8:9], exec
	s_or_b64 s[6:7], s[6:7], exec
	s_waitcnt vmcnt(0) lgkmcnt(0)
	v_add_u32_e32 v48, v32, v47
	v_add_u32_e32 v48, v48, v33
	v_add_u32_e32 v48, v48, v34
	v_add_u32_e32 v48, v48, v35
	v_add_u32_e32 v48, v48, v36
	v_add_u32_e32 v48, v48, v37
	v_add_u32_e32 v48, v48, v38
	v_add_u32_e32 v48, v48, v39
	v_add_u32_e32 v48, v48, v40
	v_add_u32_e32 v48, v48, v41
	v_add_u32_e32 v48, v48, v42
	v_add_u32_e32 v48, v48, v43
	v_add_u32_e32 v48, v48, v44
	v_add_u32_e32 v48, v48, v45
	v_add_u32_e32 v48, v48, v46
	v_cmp_ne_u32_e32 vcc, s33, v48
	s_and_saveexec_b64 s[12:13], vcc
	s_cbranch_execz .LBB0_1757
	s_and_b32 s16, s22, 0xff
	s_mov_b64 s[14:15], -1
	s_cmp_eq_u32 s16, 0
	s_mov_b64 s[18:19], -1
	s_mov_b64 s[16:17], -1
	s_sleep 1
	s_cbranch_scc1 .LBB0_1761
	s_and_saveexec_b64 s[20:21], s[18:19]
	s_cbranch_execz .LBB0_1756
	s_branch .LBB0_1764
.LBB0_1761:
	v_mov_b64_e32 v[48:49], s[0:1]
	global_load_dword v48, v[48:49], off sc1
	s_mov_b64 s[18:19], 0
	s_waitcnt vmcnt(0) lgkmcnt(0)
	v_cmp_eq_u32_e32 vcc, 0, v48
	s_and_saveexec_b64 s[20:21], vcc
	s_cmp_lt_u32 s22, 0x40001
	s_cselect_b64 s[18:19], -1, 0
	s_xor_b64 s[16:17], exec, -1
	s_and_b64 s[18:19], s[18:19], exec
	s_or_b64 exec, exec, s[20:21]
	s_and_saveexec_b64 s[20:21], s[18:19]
	s_cbranch_execz .LBB0_1756

; DI unsigned xb_ld(unsigned* p)              { return __hip_atomic_load(p, __ATOMIC_RELAXED, __HIP_MEMORY_SCOPE_AGENT); }
; DI unsigned xb_add(unsigned* p, unsigned v) { return __hip_atomic_fetch_add(p, v, __ATOMIC_RELAXED, __HIP_MEMORY_SCOPE_AGENT); }
; #define XB_SPIN(cond, bar) do { unsigned _sp = 0; while (cond) { __builtin_amdgcn_s_sleep(1); \
;     if ((++_sp & 255u) == 0u) { if (xb_ld(&(bar)[XB_TMO])) break; if (_sp > XB_SPIN_CAP) { atomicAdd(&(bar)[XB_TMO], 1u); break; } } } } while (0)
; DI void xcd_barrier(int wv, unsigned* bar, volatile LAS unsigned* st) {
;     ...
;         const unsigned old = xb_add(&bar[XB_XSUB(x)], 1u);
;         const unsigned gen = old / nloc;
;         if (old + 1u == (gen + 1u) * nloc) {
;             __builtin_amdgcn_fence(__ATOMIC_RELEASE, "agent");
;             asm volatile("s_waitcnt vmcnt(0)" ::: "memory");
;             const unsigned og = xb_add(&bar[XB_TOP], 1u);
;             const unsigned tg = og / nx;
;             if (og + 1u == (tg + 1u) * nx) xb_add(&bar[XB_TOPGEN], 1u);
;             else XB_SPIN(xb_ld(&bar[XB_TOPGEN]) == tg, bar);
;             __builtin_amdgcn_fence(__ATOMIC_ACQUIRE, "agent");
;             xb_add(&bar[XB_XGEN(x)], 1u);
;             asm volatile("s_waitcnt vmcnt(0)" ::: "memory");
;         } else {
;             XB_SPIN(xb_ld(&bar[XB_XGEN(x)]) == gen, bar);
.LBB0_1768:
	s_lshl_b32 s0, s38, 8
	s_add_u32 s0, s36, s0
	s_addc_u32 s1, s37, 0
	v_mov_b32_e32 v1, s0
	v_add_co_u32_e32 v4, vcc, 0xc1000, v1
	v_mov_b32_e32 v1, s1
	s_nop 0
	v_addc_co_u32_e32 v5, vcc, 0, v1, vcc
	v_mov_b32_e32 v1, 1
	flat_atomic_add v1, v[4:5], v1 offset:1024 sc0
	v_cvt_f32_u32_e32 v3, v2
	v_sub_u32_e32 v4, 0, v2
	s_add_u32 s25, s0, 0xc0000
	s_addc_u32 s24, s1, 0
	v_rcp_iflag_f32_e32 v3, v3
	s_nop 0
	v_mul_f32_e32 v3, 0x4f7ffffe, v3
	v_cvt_u32_f32_e32 v3, v3
	v_mul_lo_u32 v4, v4, v3
	v_mul_hi_u32 v4, v3, v4
	v_add_u32_e32 v3, v3, v4
	s_waitcnt vmcnt(0) lgkmcnt(0)
	v_mul_hi_u32 v3, v1, v3
	v_mul_lo_u32 v5, v3, v2
	v_add_u32_e32 v4, 1, v1
	v_sub_u32_e32 v1, v1, v5
	v_add_u32_e32 v6, 1, v3
	v_cmp_ge_u32_e32 vcc, v1, v2
	v_sub_u32_e32 v5, v1, v2
	s_nop 0
	v_cndmask_b32_e32 v3, v3, v6, vcc
	v_cndmask_b32_e32 v1, v1, v5, vcc
	v_add_u32_e32 v5, 1, v3
	v_cmp_ge_u32_e32 vcc, v1, v2
	s_nop 1
	v_cndmask_b32_e32 v1, v3, v5, vcc
	v_mad_u64_u32 v[2:3], s[0:1], v2, v1, v[2:3]
	v_cmp_ne_u32_e32 vcc, v4, v2
	s_and_saveexec_b64 s[0:1], vcc
	s_xor_b64 s[0:1], exec, s[0:1]
	s_cbranch_execz .LBB0_1781
	v_mov_b32_e32 v0, s25
	v_add_co_u32_e32 v2, vcc, 0x2000, v0
	v_mov_b32_e32 v0, s24
	s_nop 0
	v_addc_co_u32_e32 v3, vcc, 0, v0, vcc
	global_load_dword v0, v[2:3], off offset:1024 sc1
	s_add_u32 s6, s25, 0x2400
	s_addc_u32 s7, s24, 0
	s_waitcnt vmcnt(0) lgkmcnt(0)
	v_cmp_eq_u32_e32 vcc, v0, v1
	s_and_saveexec_b64 s[2:3], vcc
	s_cbranch_execz .LBB0_1780
	s_add_u32 s4, s36, 0xc0200
	s_addc_u32 s5, s37, 0
	s_mov_b32 s26, 1
	s_mov_b64 s[8:9], 0
	s_branch .LBB0_1772

; DI unsigned xb_ld(unsigned* p)              { return __hip_atomic_load(p, __ATOMIC_RELAXED, __HIP_MEMORY_SCOPE_AGENT); }
; #define XB_SPIN(cond, bar) do { unsigned _sp = 0; while (cond) { __builtin_amdgcn_s_sleep(1); \
;     if ((++_sp & 255u) == 0u) { if (xb_ld(&(bar)[XB_TMO])) break; if (_sp > XB_SPIN_CAP) { atomicAdd(&(bar)[XB_TMO], 1u); break; } } } } while (0)
; DI void xcd_barrier(int wv, unsigned* bar, volatile LAS unsigned* st) {
;     ...
;             XB_SPIN(xb_ld(&bar[XB_XGEN(x)]) == gen, bar);
.LBB0_1772:
	s_and_b32 s18, s26, 0xff
	s_mov_b64 s[16:17], -1
	s_cmp_lg_u32 s18, 0
	s_mov_b64 s[18:19], -1
	s_sleep 1
	s_cbranch_scc1 .LBB0_1776
	v_mov_b64_e32 v[2:3], s[4:5]
	global_load_dword v0, v[2:3], off sc1
	s_mov_b64 s[18:19], 0
	s_mov_b64 s[20:21], -1
	s_waitcnt vmcnt(0) lgkmcnt(0)
	v_cmp_eq_u32_e32 vcc, 0, v0
	s_and_saveexec_b64 s[22:23], vcc
	s_cmp_lt_u32 s26, 0x40001
	s_cselect_b64 s[18:19], -1, 0
	s_xor_b64 s[20:21], exec, -1
	s_and_b64 s[18:19], s[18:19], exec
	s_or_b64 exec, exec, s[22:23]
.LBB0_1776:
	s_andn2_b64 s[14:15], s[14:15], exec
	s_and_b64 s[20:21], s[20:21], exec
	s_or_b64 s[14:15], s[14:15], s[20:21]
	s_and_saveexec_b64 s[20:21], s[18:19]
	s_cbranch_execz .LBB0_1771
	v_mov_b64_e32 v[2:3], s[6:7]
	global_load_dword v0, v[2:3], off sc1
	s_add_i32 s26, s26, 1
	s_or_b64 s[14:15], s[14:15], exec
	s_waitcnt vmcnt(0) lgkmcnt(0)
	v_cmp_ne_u32_e32 vcc, v0, v1
	s_orn2_b64 s[16:17], vcc, exec
	s_branch .LBB0_1771

; DI unsigned xb_ld(unsigned* p)              { return __hip_atomic_load(p, __ATOMIC_RELAXED, __HIP_MEMORY_SCOPE_AGENT); }
; DI unsigned xb_add(unsigned* p, unsigned v) { return __hip_atomic_fetch_add(p, v, __ATOMIC_RELAXED, __HIP_MEMORY_SCOPE_AGENT); }
; #define XB_SPIN(cond, bar) do { unsigned _sp = 0; while (cond) { __builtin_amdgcn_s_sleep(1); \
;     if ((++_sp & 255u) == 0u) { if (xb_ld(&(bar)[XB_TMO])) break; if (_sp > XB_SPIN_CAP) { atomicAdd(&(bar)[XB_TMO], 1u); break; } } } } while (0)
; DI void xcd_barrier(int wv, unsigned* bar, volatile LAS unsigned* st) {
;     ...
;         if (old + 1u == (gen + 1u) * nloc) {
;             __builtin_amdgcn_fence(__ATOMIC_RELEASE, "agent");
;             asm volatile("s_waitcnt vmcnt(0)" ::: "memory");
;             const unsigned og = xb_add(&bar[XB_TOP], 1u);
;             const unsigned tg = og / nx;
;             if (og + 1u == (tg + 1u) * nx) xb_add(&bar[XB_TOPGEN], 1u);
;             else XB_SPIN(xb_ld(&bar[XB_TOPGEN]) == tg, bar);
.LBB0_1781:
	s_andn2_saveexec_b64 s[0:1], s[0:1]
	s_cbranch_execz .LBB0_1797
	v_mov_b32_e32 v1, s36
	v_add_co_u32_e32 v2, vcc, 0xc3000, v1
	v_mov_b32_e32 v1, s37
	buffer_wbl2 sc1
	s_waitcnt vmcnt(0)
	v_addc_co_u32_e32 v3, vcc, 0, v1, vcc
	v_mov_b32_e32 v1, 1
	flat_atomic_add v1, v[2:3], v1 offset:1024 sc0
	v_cvt_f32_u32_e32 v2, v0
	v_sub_u32_e32 v3, 0, v0
	s_add_u32 s0, s36, 0xc3500
	s_addc_u32 s1, s37, 0
	v_rcp_iflag_f32_e32 v2, v2
	s_mov_b64 s[4:5], -1
	v_mul_f32_e32 v2, 0x4f7ffffe, v2
	v_cvt_u32_f32_e32 v2, v2
	v_mul_lo_u32 v3, v3, v2
	v_mul_hi_u32 v3, v2, v3
	v_add_u32_e32 v2, v2, v3
	s_waitcnt vmcnt(0) lgkmcnt(0)
	v_mul_hi_u32 v2, v1, v2
	v_mul_lo_u32 v4, v2, v0
	v_add_u32_e32 v3, 1, v1
	v_sub_u32_e32 v1, v1, v4
	v_add_u32_e32 v5, 1, v2
	v_cmp_ge_u32_e32 vcc, v1, v0
	v_sub_u32_e32 v4, v1, v0
	s_nop 0
	v_cndmask_b32_e32 v2, v2, v5, vcc
	v_cndmask_b32_e32 v1, v1, v4, vcc
	v_add_u32_e32 v4, 1, v2
	v_cmp_ge_u32_e32 vcc, v1, v0
	s_nop 1
	v_cndmask_b32_e32 v2, v2, v4, vcc
	v_mad_u64_u32 v[0:1], s[2:3], v0, v2, v[0:1]
	v_cmp_ne_u32_e32 vcc, v3, v0
	v_mov_b64_e32 v[0:1], s[0:1]
	s_and_saveexec_b64 s[2:3], vcc
	s_cbranch_execz .LBB0_1794
	v_mov_b64_e32 v[0:1], s[0:1]
	global_load_dword v0, v[0:1], off sc1
	s_mov_b64 s[8:9], 0
	s_waitcnt vmcnt(0) lgkmcnt(0)
	v_cmp_eq_u32_e32 vcc, v0, v2
	s_and_saveexec_b64 s[6:7], vcc
	s_cbranch_execz .LBB0_1793
	s_add_u32 s4, s36, 0xc0200
	s_addc_u32 s5, s37, 0
	s_mov_b32 s22, 1
	s_branch .LBB0_1786

; DI unsigned xb_ld(unsigned* p)              { return __hip_atomic_load(p, __ATOMIC_RELAXED, __HIP_MEMORY_SCOPE_AGENT); }
; DI unsigned xb_add(unsigned* p, unsigned v) { return __hip_atomic_fetch_add(p, v, __ATOMIC_RELAXED, __HIP_MEMORY_SCOPE_AGENT); }
; #define XB_SPIN(cond, bar) do { unsigned _sp = 0; while (cond) { __builtin_amdgcn_s_sleep(1); \
;     if ((++_sp & 255u) == 0u) { if (xb_ld(&(bar)[XB_TMO])) break; if (_sp > XB_SPIN_CAP) { atomicAdd(&(bar)[XB_TMO], 1u); break; } } } } while (0)
; DI void xcd_barrier(int wv, unsigned* bar, volatile LAS unsigned* st) {
;     ...
;             else XB_SPIN(xb_ld(&bar[XB_TOPGEN]) == tg, bar);
;             __builtin_amdgcn_fence(__ATOMIC_ACQUIRE, "agent");
;             xb_add(&bar[XB_XGEN(x)], 1u);
;             asm volatile("s_waitcnt vmcnt(0)" ::: "memory");
;         } else {
;             XB_SPIN(xb_ld(&bar[XB_XGEN(x)]) == gen, bar);
.LBB0_1788:
	v_mov_b64_e32 v[0:1], s[4:5]
	global_load_dword v0, v[0:1], off sc1
	s_mov_b64 s[16:17], 0
	s_mov_b64 s[14:15], -1
	s_waitcnt vmcnt(0) lgkmcnt(0)
	v_cmp_eq_u32_e32 vcc, 0, v0
	s_and_saveexec_b64 s[18:19], vcc
	s_cmp_lt_u32 s22, 0x40001
	s_cselect_b64 s[16:17], -1, 0
	s_xor_b64 s[14:15], exec, -1
	s_and_b64 s[16:17], s[16:17], exec
	s_or_b64 exec, exec, s[18:19]
	s_mov_b64 s[18:19], -1
	s_and_saveexec_b64 s[20:21], s[16:17]
	s_cbranch_execz .LBB0_1785
.LBB0_1791:
	v_mov_b64_e32 v[0:1], s[0:1]
	global_load_dword v0, v[0:1], off sc1
	s_add_i32 s22, s22, 1
	s_or_b64 s[14:15], s[14:15], exec
	s_waitcnt vmcnt(0) lgkmcnt(0)
	v_cmp_ne_u32_e32 vcc, v0, v2
	s_orn2_b64 s[18:19], vcc, exec
	s_branch .LBB0_1785

; DI int opaque_tid(int wv) { unsigned ones = ~0u; asm volatile("" : "+s"(ones)); int t = wv * 64 + (int)__builtin_amdgcn_mbcnt_hi(ones, __builtin_amdgcn_mbcnt_lo(ones, 0u)); asm volatile("" : "+v"(t)); return t; }
; template <class Epi, class Sched>
; DI void gemm_phase(int wv, LAS unsigned char* lds, const Gemm g, const Sched& S, const Epi& E) {
;     const int tid = opaque_tid(wv), wid = __builtin_amdgcn_readfirstlane(tid >> 6), lane = tid & 63, wr = wid >> 2, wc = wid & 3, fr = lane & 15, fq = lane >> 4;
;     const int K = g.K, nt = K / BK;
;     unsigned voffA[2], voffB[2];
; #pragma unroll
;     for (int i = 0; i < 2; ++i) { int R, C; stage_rc(tid * 16 + i * 8192, R, C); const int Rb = (R & ~31) + perm32(R & 31);
;         voffA[i] = (unsigned)(R * g.lda + C) * 2u; voffB[i] = (unsigned)(Rb * g.ldb + C) * 2u; }
;     const size_t kstep = (size_t)(BK * 2);
;     const size_t hstepA = (size_t)HALF * g.lda * 2, hstepB = (size_t)HALF * g.ldb * 2;
;     const size_t tstepA = 2 * hstepA, tstepB = 2 * hstepB;
;     const unsigned ldsw = (unsigned)wid * 1024u;
;     const int aoff = lds_byte(wr * 64 + fr, fq * 8), boff = lds_byte(wc * 32 + fr, fq * 8);
; template <int STRIDE, int P0, int NP4>
; DI void rstd8(const float* parts, size_t row0, float invK, int fq, float (&rs)[2][4]) {
;     f32x4 v[2][4];
; #pragma unroll
;     for (int ai = 0; ai < 2; ++ai)
; #pragma unroll
;         for (int m = 0; m < 4; ++m) {
;             const float* p = parts + (row0 + ai * 128 + m * 16) * STRIDE + P0;
;             if (NP4 == 1) v[ai][m] = *(const f32x4*)p;
;             else if (fq < NP4) v[ai][m] = *(const f32x4*)(p + 4 * fq);
;             else v[ai][m] = (f32x4){0.f, 0.f, 0.f, 0.f};
;         }
.LBB0_1807:
	s_andn2_b64 vcc, exec, s[2:3]
	s_cbranch_vccnz .LBB0_1872
	s_mov_b64 s[8:9], s[74:75]
	s_mov_b32 s0, -1
	s_nop 0
	v_mbcnt_lo_u32_b32 v0, s0, 0
	v_mbcnt_hi_u32_b32 v0, s0, v0
	v_readlane_b32 s0, v254, 35
	v_add_u32_e32 v0, s11, v0
	v_readlane_b32 s1, v254, 36
	s_andn2_b64 vcc, exec, s[0:1]
	v_readfirstlane_b32 s0, v0
	s_cbranch_vccnz .LBB0_1826
	v_bfe_i32 v4, v0, 27, 1
	s_waitcnt lgkmcnt(0)
	v_lshlrev_b32_e32 v2, 4, v0
	v_lshrrev_b32_e32 v4, 22, v4
	v_add_u32_e32 v4, v2, v4
	v_and_b32_e32 v4, 0xfffffc00, v4
	v_sub_u32_e32 v4, v2, v4
	s_lshr_b32 s1, s68, 1
	v_readlane_b32 s2, v255, 40
	v_ashrrev_i32_e32 v3, 31, v0
	v_lshrrev_b32_e32 v5, 4, v4
	s_add_i32 s1, s1, s2
	v_lshrrev_b32_e32 v3, 26, v3
	v_bitop3_b32 v5, v5, v4, 32 bitop3:0x6c
	v_ashrrev_i32_e32 v4, 31, v4
	s_add_u32 s34, s8, 0x500000
	v_add_u32_e32 v3, v0, v3
	v_lshrrev_b32_e32 v4, 26, v4
	s_addc_u32 s35, s9, 0
	v_ashrrev_i32_e32 v3, 6, v3
	v_add_u32_e32 v4, v5, v4
	s_mul_i32 s96, s1, 0x840000
	s_add_u32 s4, s8, 0x100000
	v_lshlrev_b32_e32 v6, 3, v3
	v_ashrrev_i32_e32 v4, 6, v4
	s_addc_u32 s5, s9, 0
	s_lshl_b64 s[2:3], s[96:97], 1
	v_and_b32_e32 v6, -16, v6
	s_waitcnt lgkmcnt(0)
	v_mul_i32_i24_e32 v7, 64, v4
	s_add_u32 s1, s8, s2
	v_add_u32_e32 v6, v4, v6
	v_sub_u32_e32 v5, v5, v7
	v_mov_b32_e32 v9, 1
	s_addc_u32 s2, s9, s3
	v_lshlrev_b32_e32 v3, 5, v3
	v_ashrrev_i16_sdwa v5, v9, sext(v5) dst_sel:DWORD dst_unused:UNUSED_PAD src0_sel:DWORD src1_sel:BYTE_0
	v_lshlrev_b32_e32 v7, 1, v6
	v_lshrrev_b32_e32 v8, 2, v6
	v_and_b32_e32 v4, 3, v4
	s_mov_b32 s3, 0x1fffe0
	v_and_b32_e32 v3, 32, v3
	v_bfe_i32 v5, v5, 0, 16
	v_and_b32_e32 v7, 24, v7
	v_and_b32_e32 v8, 4, v8
	v_and_or_b32 v4, v6, s3, v4
	v_or3_b32 v4, v4, v8, v7
	v_add_lshl_u32 v3, v3, v5, 1
	v_add_u32_e32 v2, 0x2000, v2
	v_lshl_add_u32 v170, v6, 11, v3
	v_lshl_add_u32 v171, v4, 11, v3
	v_ashrrev_i32_e32 v3, 31, v2
	v_lshrrev_b32_e32 v3, 22, v3
	v_add_u32_e32 v3, v2, v3
	v_ashrrev_i32_e32 v3, 10, v3
	v_mul_i32_i24_e32 v4, 0x400, v3
	v_sub_u32_e32 v2, v2, v4
	v_lshrrev_b32_e32 v4, 4, v2
	v_bitop3_b32 v2, v4, v2, 32 bitop3:0x6c
	v_ashrrev_i32_e32 v5, 31, v2
	v_lshrrev_b32_e32 v5, 26, v5
	v_lshlrev_b32_e32 v4, 3, v3
	v_add_u32_e32 v5, v2, v5
	s_add_u32 s36, s1, 0x4500000
	v_and_b32_e32 v4, -16, v4
	v_ashrrev_i32_e32 v6, 6, v5
	s_addc_u32 s37, s2, 0
	s_ashr_i32 s2, s0, 6
	v_add_u32_e32 v4, v6, v4
	v_and_b32_e32 v6, 3, v6
	s_ashr_i32 s12, s0, 8
	s_and_b32 s1, s2, 3
	v_and_b32_e32 v5, 0xc0, v5
	v_and_or_b32 v6, v4, s3, v6
	s_lshl_b32 s38, s2, 10
	s_lshl_b32 s39, s12, 6
	v_readlane_b32 s2, v254, 40
	v_sub_u32_e32 v2, v2, v5
	v_readlane_b32 s3, v254, 41
	s_add_u32 s26, s36, s2
	v_lshlrev_b32_e32 v3, 5, v3
	v_ashrrev_i16_sdwa v2, v9, sext(v2) dst_sel:DWORD dst_unused:UNUSED_PAD src0_sel:DWORD src1_sel:BYTE_0
	v_lshlrev_b32_e32 v5, 1, v4
	v_lshrrev_b32_e32 v7, 2, v4
	s_addc_u32 s27, s37, s3
	s_ashr_i32 s44, s39, 31
	v_readlane_b32 s2, v254, 44
	v_and_b32_e32 v3, 32, v3
	v_bfe_i32 v2, v2, 0, 16
	v_and_b32_e32 v5, 24, v5
	v_and_b32_e32 v7, 4, v7
	v_readlane_b32 s3, v254, 45
	s_add_u32 s2, s2, s39
	v_or3_b32 v5, v6, v7, v5
	v_add_lshl_u32 v2, v3, v2, 1
	v_and_b32_e32 v34, 15, v0
	s_addc_u32 s3, s3, s44
	v_lshl_add_u32 v172, v4, 11, v2
	v_lshl_add_u32 v173, v5, 11, v2
	v_and_b32_e32 v0, 48, v0
	v_or_b32_e32 v2, s2, v34
	v_mov_b32_e32 v3, s3
	v_lshl_add_u64 v[4:5], s[4:5], 0, v[0:1]
	v_lshlrev_b64 v[2:3], 6, v[2:3]
	v_lshl_add_u64 v[2:3], v[4:5], 0, v[2:3]
	global_load_dwordx4 v[30:33], v[2:3], off
	global_load_dwordx4 v[10:13], v[2:3], off offset:1024
	global_load_dwordx4 v[26:29], v[2:3], off offset:2048
	global_load_dwordx4 v[22:25], v[2:3], off offset:3072
	s_movk_i32 s2, 0x2000
	v_add_co_u32_e32 v2, vcc, s2, v2
	v_xor_b32_e32 v35, 16, v207
	s_nop 0
	v_addc_co_u32_e32 v3, vcc, 0, v3, vcc
	global_load_dwordx4 v[18:21], v[2:3], off
	global_load_dwordx4 v[14:17], v[2:3], off offset:1024
	global_load_dwordx4 v[6:9], v[2:3], off offset:2048
	s_nop 0
	global_load_dwordx4 v[2:5], v[2:3], off offset:3072
	v_cmp_lt_i32_e32 vcc, v35, v222
	s_mov_b32 s2, 0x358637bd
	s_add_i32 s46, s38, 0
	v_cndmask_b32_e32 v35, v207, v35, vcc
	v_lshlrev_b32_e32 v174, 2, v35
	v_cmp_lt_i32_e32 vcc, v223, v222
	s_add_i32 m0, s46, 0x10000
	s_waitcnt vmcnt(0) lgkmcnt(0)
	v_mov_b32_e32 v36, v30
	v_mov_b32_e32 v37, v10
	v_mov_b32_e32 v10, v31
	v_mov_b32_e32 v30, v32
	v_mov_b32_e32 v31, v12
	v_mov_b32_e32 v12, v33
	v_pk_add_f32 v[10:11], v[36:37], v[10:11]
	v_pk_add_f32 v[12:13], v[30:31], v[12:13]
	v_cndmask_b32_e32 v35, v207, v223, vcc
	v_pk_add_f32 v[10:11], v[10:11], v[12:13]
	ds_bpermute_b32 v12, v174, v10
	ds_bpermute_b32 v13, v174, v11
	v_lshlrev_b32_e32 v175, 2, v35
	v_mov_b64_e32 v[30:31], s[2:3]
	s_waitcnt lgkmcnt(0)
	v_pk_add_f32 v[10:11], v[10:11], v[12:13]
	ds_bpermute_b32 v12, v175, v10
	ds_bpermute_b32 v13, v175, v11
	s_waitcnt lgkmcnt(0)
; #define LAS __attribute__((address_space(3)))
; #define PG8_STAGE(bufoff, gbase, voff) do { const char* _gb = (const char*)(gbase); asm volatile("" : "+s"(_gb)); _Pragma("unroll") for (int _i = 0; _i < 2; ++_i) { \
;         unsigned _vo = (voff)[_i]; asm volatile("" : "+v"(_vo));     \
;         __builtin_amdgcn_global_load_lds((const unsigned*)(_gb + _vo), (LAS unsigned*)(lds + (bufoff) + ldsw + _i * 8192), 16, 0, 0); } } while (0)
; #define PG8_BAR __builtin_amdgcn_s_barrier()
; template <class Epi, class Sched>
; DI void gemm_phase(int wv, LAS unsigned char* lds, const Gemm g, const Sched& S, const Epi& E) {
;     ...
;     PG8_STAGE(PG8_SB(0, 0), cB, voffB); PG8_STAGE(PG8_SB(0, 1), cB + hstepB, voffB); PG8_STAGE(PG8_SA(0, 0), cA, voffA); PG8_STAGE(PG8_SA(0, 1), cA + hstepA, voffA);
;     if (wr == 1) PG8_BAR;
; template <int STRIDE, int P0, int NP4>
; DI void rstd8(const float* parts, size_t row0, float invK, int fq, float (&rs)[2][4]) {
;     ...
; #pragma unroll
;     for (int ai = 0; ai < 2; ++ai)
; #pragma unroll
;         for (int m = 0; m < 4; ++m) {
;             float t = (v[ai][m].x + v[ai][m].y) + (v[ai][m].z + v[ai][m].w);
;             if (NP4 > 1) { t += __shfl_xor(t, 16); t += __shfl_xor(t, 32); }
;             rs[ai][m] = rsqrtf(t * invK + EPS);
;         }
; }
;     DI void operator()(const AccT& acc, const Unit& u, int wr, int wc, int fr, int fq) const {
;         f32x4 t = acc[0][0][0][0];
; #pragma unroll
;         for (int ai = 0; ai < 2; ++ai)
; #pragma unroll
;             for (int bj = 0; bj < 2; ++bj)
; #pragma unroll
;                 for (int m = 0; m < 4; ++m)
; #pragma unroll
;                     for (int n = 0; n < 2; ++n) t += acc[ai][bj][m][n];
;         if (t.x == 12345.678f) sink[0] = t.y + t.z + t.w;
;     }
;     DI void pre(const Unit& u, int wr, int wc, int fr, int fq, float (&rs)[2][4]) const { rstd8<16, 0, 4>(ss, (size_t)u.pm * 256 + wr * 64 + fr, 1.f / 1024.f, fq, rs); park(rs, (wr * 4 + wc) * 64 + fq * 16 + fr); }
;     DI static LAS f32x4* slot(int t) { extern __shared__ __attribute__((aligned(16))) unsigned char lds_raw_[]; return (LAS f32x4*)((LAS unsigned char*)lds_raw_ + LDS_RS) + 2 * t; }
;     DI static void park(const float (&rs)[2][4], int t) { LAS f32x4* p = slot(t); p[0] = (f32x4){rs[0][0], rs[0][1], rs[0][2], rs[0][3]}; p[1] = (f32x4){rs[1][0], rs[1][1], rs[1][2], rs[1][3]}; }
	v_pk_add_f32 v[10:11], v[10:11], v[12:13]
	s_nop 0
	v_pk_fma_f32 v[10:11], v[10:11], s[88:89], v[30:31] op_sel_hi:[1,0,0]
	s_nop 0
	v_mul_f32_e32 v12, 0x4b800000, v10
	v_cmp_gt_f32_e64 s[2:3], s42, v10
	v_cmp_gt_f32_e32 vcc, s42, v11
	s_nop 0
	v_cndmask_b32_e64 v10, v10, v12, s[2:3]
	v_mul_f32_e32 v12, 0x4b800000, v11
	v_cndmask_b32_e32 v11, v11, v12, vcc
	v_rsq_f32_e32 v10, v10
	v_rsq_f32_e32 v11, v11
	s_nop 0
	v_pk_mul_f32 v[12:13], v[10:11], s[52:53] op_sel_hi:[1,0]
	s_nop 0
	v_cndmask_b32_e32 v11, v11, v13, vcc
	v_cndmask_b32_e64 v10, v10, v12, s[2:3]
	v_mov_b32_e32 v12, v26
	v_mov_b32_e32 v13, v22
	v_mov_b32_e32 v22, v27
	v_pk_add_f32 v[12:13], v[12:13], v[22:23]
	v_mov_b32_e32 v22, v28
	v_mov_b32_e32 v23, v24
	v_mov_b32_e32 v24, v29
	v_pk_add_f32 v[22:23], v[22:23], v[24:25]
	s_nop 0
	v_pk_add_f32 v[12:13], v[12:13], v[22:23]
	ds_bpermute_b32 v22, v174, v12
	ds_bpermute_b32 v23, v174, v13
	s_waitcnt lgkmcnt(0)
	v_pk_add_f32 v[12:13], v[12:13], v[22:23]
	ds_bpermute_b32 v22, v175, v12
	ds_bpermute_b32 v23, v175, v13
	s_waitcnt lgkmcnt(0)
	v_pk_add_f32 v[12:13], v[12:13], v[22:23]
	s_nop 0
	v_pk_fma_f32 v[12:13], v[12:13], s[88:89], v[30:31] op_sel_hi:[1,0,0]
	s_nop 0
	v_mul_f32_e32 v22, 0x4b800000, v12
	v_cmp_gt_f32_e64 s[2:3], s42, v12
	v_cmp_gt_f32_e32 vcc, s42, v13
	s_nop 0
	v_cndmask_b32_e64 v12, v12, v22, s[2:3]
	v_mul_f32_e32 v22, 0x4b800000, v13
	v_cndmask_b32_e32 v13, v13, v22, vcc
	v_rsq_f32_e32 v12, v12
	v_rsq_f32_e32 v13, v13
	s_nop 0
	v_pk_mul_f32 v[22:23], v[12:13], s[52:53] op_sel_hi:[1,0]
	s_nop 0
	v_cndmask_b32_e32 v13, v13, v23, vcc
	v_cndmask_b32_e64 v12, v12, v22, s[2:3]
	v_mov_b32_e32 v22, v18
	v_mov_b32_e32 v23, v14
	v_mov_b32_e32 v14, v19
	v_mov_b32_e32 v18, v20
	v_mov_b32_e32 v19, v16
	v_mov_b32_e32 v16, v21
	v_pk_add_f32 v[14:15], v[22:23], v[14:15]
	v_pk_add_f32 v[16:17], v[18:19], v[16:17]
	s_nop 0
	v_pk_add_f32 v[14:15], v[14:15], v[16:17]
	ds_bpermute_b32 v16, v174, v14
	ds_bpermute_b32 v17, v174, v15
	s_waitcnt lgkmcnt(0)
	v_pk_add_f32 v[14:15], v[14:15], v[16:17]
	ds_bpermute_b32 v16, v175, v14
	ds_bpermute_b32 v17, v175, v15
	s_waitcnt lgkmcnt(0)
	v_pk_add_f32 v[14:15], v[14:15], v[16:17]
	s_nop 0
	v_pk_fma_f32 v[14:15], v[14:15], s[88:89], v[30:31] op_sel_hi:[1,0,0]
	s_nop 0
	v_mul_f32_e32 v16, 0x4b800000, v14
	v_cmp_gt_f32_e64 s[2:3], s42, v14
	v_cmp_gt_f32_e32 vcc, s42, v15
	s_nop 0
	v_cndmask_b32_e64 v14, v14, v16, s[2:3]
	v_mul_f32_e32 v16, 0x4b800000, v15
	v_cndmask_b32_e32 v15, v15, v16, vcc
	v_rsq_f32_e32 v14, v14
	v_rsq_f32_e32 v15, v15
	s_nop 0
	v_pk_mul_f32 v[16:17], v[14:15], s[52:53] op_sel_hi:[1,0]
	s_nop 0
	v_cndmask_b32_e32 v15, v15, v17, vcc
	v_cndmask_b32_e64 v14, v14, v16, s[2:3]
	v_mov_b32_e32 v16, v6
	v_mov_b32_e32 v17, v2
	v_mov_b32_e32 v2, v7
	v_mov_b32_e32 v6, v8
	v_mov_b32_e32 v7, v4
	v_mov_b32_e32 v4, v9
	v_pk_add_f32 v[2:3], v[16:17], v[2:3]
	v_pk_add_f32 v[4:5], v[6:7], v[4:5]
	s_nop 0
	v_pk_add_f32 v[2:3], v[2:3], v[4:5]
	ds_bpermute_b32 v4, v174, v2
	ds_bpermute_b32 v5, v174, v3
	s_waitcnt lgkmcnt(0)
	v_pk_add_f32 v[2:3], v[2:3], v[4:5]
	ds_bpermute_b32 v4, v175, v2
	ds_bpermute_b32 v5, v175, v3
	s_waitcnt lgkmcnt(0)
	v_pk_add_f32 v[2:3], v[2:3], v[4:5]
	s_nop 0
	v_pk_fma_f32 v[2:3], v[2:3], s[88:89], v[30:31] op_sel_hi:[1,0,0]
	s_nop 0
	v_mul_f32_e32 v4, 0x4b800000, v2
	v_cmp_gt_f32_e64 s[2:3], s42, v2
	v_cmp_gt_f32_e32 vcc, s42, v3
	s_nop 0
	v_cndmask_b32_e64 v2, v2, v4, s[2:3]
	v_mul_f32_e32 v4, 0x4b800000, v3
	v_cndmask_b32_e32 v3, v3, v4, vcc
	v_rsq_f32_e32 v2, v2
	v_rsq_f32_e32 v3, v3
	s_nop 0
	v_pk_mul_f32 v[4:5], v[2:3], s[52:53] op_sel_hi:[1,0]
	s_nop 0
	v_cndmask_b32_e64 v16, v2, v4, s[2:3]
	s_and_b32 s2, s0, 0xffffff00
	s_lshl_b32 s3, s1, 6
	s_or_b32 s45, s3, s2
	v_or3_b32 v2, v0, s45, v34
	v_lshl_add_u32 v2, v2, 5, 0
	v_add_u32_e32 v2, 0x20010, v2
	v_cndmask_b32_e32 v17, v3, v5, vcc
	ds_write_b128 v2, v[10:13]
	ds_write_b128 v2, v[14:17] offset:16
	s_mov_b64 s[2:3], s[26:27]
	v_mov_b32_e32 v2, v171
	s_nop 0
	global_load_lds_dwordx4 v2, s[2:3]
	v_mov_b32_e32 v2, v173
	s_add_i32 m0, s46, 0x12000
	s_nop 0
	global_load_lds_dwordx4 v2, s[2:3]
	s_add_u32 s2, s26, 0x40000
	s_addc_u32 s3, s27, 0
	v_mov_b32_e32 v2, v171
	s_add_i32 m0, s46, 0x14000
	s_nop 0
	global_load_lds_dwordx4 v2, s[2:3]
	v_mov_b32_e32 v2, v173
	s_add_i32 m0, s46, 0x16000
	s_nop 0
	global_load_lds_dwordx4 v2, s[2:3]
	v_readlane_b32 s2, v254, 38
	v_readlane_b32 s3, v254, 39
	s_add_u32 s2, s34, s2
	s_addc_u32 s3, s35, s3
	s_mov_b64 s[6:7], s[2:3]
	v_mov_b32_e32 v2, v170
	s_mov_b32 m0, s46
	s_add_i32 s47, s46, 0x2000
	global_load_lds_dwordx4 v2, s[6:7]
	v_mov_b32_e32 v2, v172
	s_mov_b32 m0, s47
	s_nop 0
	global_load_lds_dwordx4 v2, s[6:7]
	s_add_u32 s6, s2, 0x40000
	s_addc_u32 s7, s3, 0
	s_add_i32 s48, s46, 0x4000
	v_mov_b32_e32 v2, v170
	s_mov_b32 m0, s48
	s_add_i32 s49, s46, 0x6000
	global_load_lds_dwordx4 v2, s[6:7]
	v_mov_b32_e32 v2, v172
	s_mov_b32 m0, s49
	s_cmp_eq_u32 s12, 1
	global_load_lds_dwordx4 v2, s[6:7]
	s_cselect_b64 s[6:7], -1, 0
	s_cmp_lg_u32 s12, 1
	s_cbranch_scc1 .LBB0_1811
	s_barrier

; DI u32x4 pk8(f32x4 a, f32x4 b) { u32x4 o; o.x = pk2(a.x, a.y); o.y = pk2(a.z, a.w); o.z = pk2(b.x, b.y); o.w = pk2(b.z, b.w); return o; }
; DI float fexp2(float x) { return __builtin_amdgcn_exp2f(x); }
; DI float frcp(float x) { return __builtin_amdgcn_rcpf(x); }
; #define EPI_SCHED() __builtin_amdgcn_sched_barrier(0)
;     DI void operator()(const AccT& acc, const Unit& u, const Unit& nxt, bool has_next, int wr, int wc, int fr, int fq, float (&rs_unused)[2][4]) const {
;     ...
; #pragma unroll
;         for (int ai = 0; ai < 2; ++ai)
; #pragma unroll
;             for (int m = 0; m < 4; ++m) {
;                 EPI_SCHED(); const size_t row = row0 + ai * 128 + m * 16;
;                 f32x4 o[2];
;                 const float c1 = -LOG2E * rs[ai][m], rs2 = rs[ai][m] * rs[ai][m];
; #pragma unroll
;                 for (int n = 0; n < 2; ++n) {
;                     const f32x4 gt = acc[ai][0][m][n], t = gt * acc[ai][1][m][n];
; #pragma unroll
;                     for (int e = 0; e < 4; ++e) o[n][e] = t[e] * (rs2 * frcp(1.f + fexp2(gt[e] * c1)));
;                 }
;                 *(u32x4*)(hid + row * FF + u.pn * 128 + wc * 32 + fq * 8) = pk8(o[0], o[1]);
;             }
.LBB0_1822:
	s_ashr_i32 s23, s22, 31
	s_lshl_b64 s[22:23], s[22:23], 8
	s_add_u32 s1, s22, s39
	s_addc_u32 s15, s23, s44
	s_lshl_b32 s22, s0, 7
	v_lshlrev_b32_e32 v178, 3, v178
	v_or_b32_e32 v188, s1, v179
	s_ashr_i32 s23, s22, 31
	v_ashrrev_i32_e32 v179, 31, v178
	s_waitcnt lgkmcnt(0)
	v_mul_f32_e32 v185, 0xbfb8aa3b, v150
	v_mul_f32_e32 v180, v134, v185
	v_mul_f32_e32 v181, v135, v185
	v_exp_f32_e32 v180, v180
	v_exp_f32_e32 v181, v181
	v_mul_f32_e32 v182, v136, v185
	v_mul_f32_e32 v183, v137, v185
	v_exp_f32_e32 v182, v182
	v_exp_f32_e32 v183, v183
	v_mul_f32_e32 v184, v130, v185
	v_mul_f32_e32 v186, v131, v185
	v_exp_f32_e32 v184, v184
	v_exp_f32_e32 v186, v186
	v_add_f32_e32 v180, 1.0, v180
	v_add_f32_e32 v181, 1.0, v181
	v_mul_f32_e32 v187, v132, v185
	v_mul_f32_e32 v185, v133, v185
	v_rcp_f32_e32 v180, v180
	v_rcp_f32_e32 v181, v181
	v_add_f32_e32 v182, 1.0, v182
	v_add_f32_e32 v183, 1.0, v183
	v_exp_f32_e32 v187, v187
	v_exp_f32_e32 v189, v185
	v_rcp_f32_e32 v182, v182
	v_rcp_f32_e32 v183, v183
	v_add_f32_e32 v184, 1.0, v184
	v_add_f32_e32 v186, 1.0, v186
	v_mul_f32_e32 v150, v150, v150
	v_rcp_f32_e32 v184, v184
	v_rcp_f32_e32 v185, v186
	v_add_f32_e32 v186, 1.0, v187
	v_add_f32_e32 v187, 1.0, v189
	v_pk_mul_f32 v[126:127], v[134:135], v[126:127]
	v_pk_mul_f32 v[134:135], v[150:151], v[180:181] op_sel_hi:[0,1]
	v_rcp_f32_e32 v186, v186
	v_rcp_f32_e32 v187, v187
	v_pk_mul_f32 v[128:129], v[136:137], v[128:129]
	v_pk_mul_f32 v[126:127], v[126:127], v[134:135]
	v_pk_mul_f32 v[134:135], v[150:151], v[182:183] op_sel_hi:[0,1]
	v_pk_mul_f32 v[128:129], v[128:129], v[134:135]
	v_cvt_pk_bf16_f32 v126, v126, v127
	v_cvt_pk_bf16_f32 v127, v128, v129
	v_pk_mul_f32 v[122:123], v[130:131], v[122:123]
	v_pk_mul_f32 v[128:129], v[150:151], v[184:185] op_sel_hi:[0,1]
	v_pk_mul_f32 v[122:123], v[122:123], v[128:129]
	v_pk_mul_f32 v[124:125], v[132:133], v[124:125]
	v_cvt_pk_bf16_f32 v128, v122, v123
	v_pk_mul_f32 v[122:123], v[150:151], v[186:187] op_sel_hi:[0,1]
	v_pk_mul_f32 v[122:123], v[124:125], v[122:123]
	s_movk_i32 s0, 0x1600
	v_cvt_pk_bf16_f32 v129, v122, v123
	v_mov_b64_e32 v[122:123], s[8:9]
	v_mad_u64_u32 v[122:123], s[0:1], v188, s0, v[122:123]
	v_mov_b32_e32 v124, 0x1600
	v_mad_i32_i24 v123, s15, v124, v123
	v_lshl_add_u64 v[122:123], s[22:23], 1, v[122:123]
	v_lshl_add_u64 v[122:123], v[122:123], 0, s[96:97]
	v_lshl_add_u64 v[122:123], v[178:179], 1, v[122:123]
	global_store_dwordx4 v[122:123], v[126:129], off
	v_mul_f32_e32 v125, 0xbfb8aa3b, v151
	v_mul_f32_e32 v124, v114, v125
	v_exp_f32_e32 v126, v124
	v_mul_f32_e32 v124, v115, v125
	v_exp_f32_e32 v127, v124
	v_mul_f32_e32 v128, v116, v125
	v_mul_f32_e32 v129, v117, v125
	v_exp_f32_e32 v128, v128
	v_exp_f32_e32 v129, v129
	v_mul_f32_e32 v130, v110, v125
	v_mul_f32_e32 v131, v111, v125
	v_exp_f32_e32 v130, v130
	v_exp_f32_e32 v131, v131
	v_mul_f32_e32 v132, v112, v125
	v_mul_f32_e32 v125, v113, v125
	v_add_f32_e32 v126, 1.0, v126
	v_add_f32_e32 v127, 1.0, v127
	v_exp_f32_e32 v125, v125
	v_rcp_f32_e32 v126, v126
	v_rcp_f32_e32 v127, v127
	v_add_f32_e32 v128, 1.0, v128
	v_add_f32_e32 v129, 1.0, v129
	v_exp_f32_e32 v132, v132
	v_rcp_f32_e32 v128, v128
	v_rcp_f32_e32 v129, v129
	v_add_f32_e32 v130, 1.0, v130
	v_add_f32_e32 v131, 1.0, v131
	v_mul_f32_e32 v124, v151, v151
	v_rcp_f32_e32 v130, v130
	v_rcp_f32_e32 v131, v131
	v_add_f32_e32 v125, 1.0, v125
	v_add_f32_e32 v132, 1.0, v132
	v_pk_mul_f32 v[106:107], v[114:115], v[106:107]
	v_pk_mul_f32 v[114:115], v[124:125], v[126:127] op_sel_hi:[0,1]
	v_rcp_f32_e32 v132, v132
	v_rcp_f32_e32 v133, v125
	v_pk_mul_f32 v[108:109], v[116:117], v[108:109]
	v_pk_mul_f32 v[106:107], v[106:107], v[114:115]
	v_pk_mul_f32 v[114:115], v[124:125], v[128:129] op_sel_hi:[0,1]
	v_pk_mul_f32 v[108:109], v[108:109], v[114:115]
	v_cvt_pk_bf16_f32 v106, v106, v107
	v_cvt_pk_bf16_f32 v107, v108, v109
	v_pk_mul_f32 v[102:103], v[110:111], v[102:103]
	v_pk_mul_f32 v[108:109], v[124:125], v[130:131] op_sel_hi:[0,1]
	v_pk_mul_f32 v[102:103], v[102:103], v[108:109]
	v_pk_mul_f32 v[104:105], v[112:113], v[104:105]
	v_cvt_pk_bf16_f32 v108, v102, v103
	v_pk_mul_f32 v[102:103], v[124:125], v[132:133] op_sel_hi:[0,1]
	v_pk_mul_f32 v[102:103], v[104:105], v[102:103]
	s_mov_b32 s0, 0x16000
	v_cvt_pk_bf16_f32 v109, v102, v103
	v_add_co_u32_e32 v102, vcc, s0, v122
	s_nop 1
	v_addc_co_u32_e32 v103, vcc, 0, v123, vcc
	global_store_dwordx4 v[102:103], v[106:109], off
	v_mul_f32_e32 v103, 0xbfb8aa3b, v152
	v_mul_f32_e32 v102, v94, v103
	v_exp_f32_e32 v104, v102
	v_mul_f32_e32 v102, v95, v103
	v_exp_f32_e32 v105, v102
	v_mul_f32_e32 v106, v96, v103
	v_mul_f32_e32 v107, v97, v103
	v_exp_f32_e32 v106, v106
	v_exp_f32_e32 v107, v107
	v_mul_f32_e32 v108, v90, v103
	v_mul_f32_e32 v109, v91, v103
	v_exp_f32_e32 v108, v108
	v_exp_f32_e32 v109, v109
	v_mul_f32_e32 v110, v92, v103
	v_mul_f32_e32 v103, v93, v103
	v_add_f32_e32 v104, 1.0, v104
	v_add_f32_e32 v105, 1.0, v105
	v_exp_f32_e32 v103, v103
	v_rcp_f32_e32 v104, v104
	v_rcp_f32_e32 v105, v105
	v_add_f32_e32 v106, 1.0, v106
	v_add_f32_e32 v107, 1.0, v107
	v_exp_f32_e32 v110, v110
	v_rcp_f32_e32 v106, v106
	v_rcp_f32_e32 v107, v107
	v_add_f32_e32 v108, 1.0, v108
	v_add_f32_e32 v109, 1.0, v109
	v_mul_f32_e32 v102, v152, v152
	v_rcp_f32_e32 v108, v108
	v_rcp_f32_e32 v109, v109
	v_add_f32_e32 v103, 1.0, v103
	v_add_f32_e32 v110, 1.0, v110
	v_pk_mul_f32 v[86:87], v[94:95], v[86:87]
	v_pk_mul_f32 v[94:95], v[102:103], v[104:105] op_sel_hi:[0,1]
	v_rcp_f32_e32 v110, v110
	v_rcp_f32_e32 v111, v103
	v_pk_mul_f32 v[88:89], v[96:97], v[88:89]
	v_pk_mul_f32 v[86:87], v[86:87], v[94:95]
	v_pk_mul_f32 v[94:95], v[102:103], v[106:107] op_sel_hi:[0,1]
; DI u32x4 pk8(f32x4 a, f32x4 b) { u32x4 o; o.x = pk2(a.x, a.y); o.y = pk2(a.z, a.w); o.z = pk2(b.x, b.y); o.w = pk2(b.z, b.w); return o; }
; DI float fexp2(float x) { return __builtin_amdgcn_exp2f(x); }
; DI float frcp(float x) { return __builtin_amdgcn_rcpf(x); }
; #define EPI_SCHED() __builtin_amdgcn_sched_barrier(0)
;     DI void operator()(const AccT& acc, const Unit& u, const Unit& nxt, bool has_next, int wr, int wc, int fr, int fq, float (&rs_unused)[2][4]) const {
;     ...
; #pragma unroll
;         for (int ai = 0; ai < 2; ++ai)
; #pragma unroll
;             for (int m = 0; m < 4; ++m) {
;                 EPI_SCHED(); const size_t row = row0 + ai * 128 + m * 16;
;                 f32x4 o[2];
;                 const float c1 = -LOG2E * rs[ai][m], rs2 = rs[ai][m] * rs[ai][m];
; #pragma unroll
;                 for (int n = 0; n < 2; ++n) {
;                     const f32x4 gt = acc[ai][0][m][n], t = gt * acc[ai][1][m][n];
; #pragma unroll
;                     for (int e = 0; e < 4; ++e) o[n][e] = t[e] * (rs2 * frcp(1.f + fexp2(gt[e] * c1)));
;                 }
;                 *(u32x4*)(hid + row * FF + u.pn * 128 + wc * 32 + fq * 8) = pk8(o[0], o[1]);
;             }
	v_pk_mul_f32 v[88:89], v[88:89], v[94:95]
	v_cvt_pk_bf16_f32 v86, v86, v87
	v_cvt_pk_bf16_f32 v87, v88, v89
	v_pk_mul_f32 v[82:83], v[90:91], v[82:83]
	v_pk_mul_f32 v[88:89], v[102:103], v[108:109] op_sel_hi:[0,1]
	v_pk_mul_f32 v[82:83], v[82:83], v[88:89]
	v_pk_mul_f32 v[84:85], v[92:93], v[84:85]
	v_cvt_pk_bf16_f32 v88, v82, v83
	v_pk_mul_f32 v[82:83], v[102:103], v[110:111] op_sel_hi:[0,1]
	v_pk_mul_f32 v[82:83], v[84:85], v[82:83]
	s_mov_b32 s0, 0x2c000
	v_cvt_pk_bf16_f32 v89, v82, v83
	v_add_co_u32_e32 v82, vcc, s0, v122
	s_nop 1
	v_addc_co_u32_e32 v83, vcc, 0, v123, vcc
	global_store_dwordx4 v[82:83], v[86:89], off
	v_mul_f32_e32 v83, 0xbfb8aa3b, v153
	v_mul_f32_e32 v82, v78, v83
	v_exp_f32_e32 v84, v82
	v_mul_f32_e32 v82, v79, v83
	v_exp_f32_e32 v85, v82
	v_mul_f32_e32 v86, v80, v83
	v_mul_f32_e32 v87, v81, v83
	v_exp_f32_e32 v86, v86
	v_exp_f32_e32 v87, v87
	v_mul_f32_e32 v88, v74, v83
	v_mul_f32_e32 v89, v75, v83
	v_exp_f32_e32 v88, v88
	v_exp_f32_e32 v89, v89
	v_mul_f32_e32 v90, v76, v83
	v_mul_f32_e32 v83, v77, v83
	v_add_f32_e32 v84, 1.0, v84
	v_add_f32_e32 v85, 1.0, v85
	v_exp_f32_e32 v83, v83
	v_rcp_f32_e32 v84, v84
	v_rcp_f32_e32 v85, v85
	v_add_f32_e32 v86, 1.0, v86
	v_add_f32_e32 v87, 1.0, v87
	v_exp_f32_e32 v90, v90
	v_rcp_f32_e32 v86, v86
	v_rcp_f32_e32 v87, v87
	v_add_f32_e32 v88, 1.0, v88
	v_add_f32_e32 v89, 1.0, v89
	v_mul_f32_e32 v82, v153, v153
	v_rcp_f32_e32 v88, v88
	v_rcp_f32_e32 v89, v89
	v_add_f32_e32 v83, 1.0, v83
	v_add_f32_e32 v90, 1.0, v90
	v_pk_mul_f32 v[70:71], v[78:79], v[70:71]
	v_pk_mul_f32 v[78:79], v[82:83], v[84:85] op_sel_hi:[0,1]
	v_rcp_f32_e32 v90, v90
	v_rcp_f32_e32 v91, v83
	v_pk_mul_f32 v[72:73], v[80:81], v[72:73]
	v_pk_mul_f32 v[70:71], v[70:71], v[78:79]
	v_pk_mul_f32 v[78:79], v[82:83], v[86:87] op_sel_hi:[0,1]
	v_pk_mul_f32 v[72:73], v[72:73], v[78:79]
	v_cvt_pk_bf16_f32 v70, v70, v71
	v_cvt_pk_bf16_f32 v71, v72, v73
	v_pk_mul_f32 v[66:67], v[74:75], v[66:67]
	v_pk_mul_f32 v[72:73], v[82:83], v[88:89] op_sel_hi:[0,1]
	v_pk_mul_f32 v[66:67], v[66:67], v[72:73]
	v_pk_mul_f32 v[68:69], v[76:77], v[68:69]
	v_cvt_pk_bf16_f32 v72, v66, v67
	v_pk_mul_f32 v[66:67], v[82:83], v[90:91] op_sel_hi:[0,1]
	v_pk_mul_f32 v[66:67], v[68:69], v[66:67]
	s_mov_b32 s0, 0x42000
	v_cvt_pk_bf16_f32 v73, v66, v67
	v_add_co_u32_e32 v66, vcc, s0, v122
	s_nop 1
	v_addc_co_u32_e32 v67, vcc, 0, v123, vcc
	global_store_dwordx4 v[66:67], v[70:73], off
	v_mul_f32_e32 v67, 0xbfb8aa3b, v146
	v_mul_f32_e32 v66, v62, v67
	v_exp_f32_e32 v68, v66
	v_mul_f32_e32 v66, v63, v67
	v_exp_f32_e32 v69, v66
	v_mul_f32_e32 v70, v64, v67
	v_mul_f32_e32 v71, v65, v67
	v_exp_f32_e32 v70, v70
	v_exp_f32_e32 v71, v71
	v_mul_f32_e32 v72, v58, v67
	v_mul_f32_e32 v73, v59, v67
	v_exp_f32_e32 v72, v72
	v_exp_f32_e32 v73, v73
	v_mul_f32_e32 v74, v60, v67
	v_mul_f32_e32 v67, v61, v67
	v_add_f32_e32 v68, 1.0, v68
	v_add_f32_e32 v69, 1.0, v69
	v_exp_f32_e32 v67, v67
	v_rcp_f32_e32 v68, v68
	v_rcp_f32_e32 v69, v69
	v_add_f32_e32 v70, 1.0, v70
	v_add_f32_e32 v71, 1.0, v71
	v_exp_f32_e32 v74, v74
	v_rcp_f32_e32 v70, v70
	v_rcp_f32_e32 v71, v71
	v_add_f32_e32 v72, 1.0, v72
	v_add_f32_e32 v73, 1.0, v73
	v_mul_f32_e32 v66, v146, v146
	v_rcp_f32_e32 v72, v72
	v_rcp_f32_e32 v73, v73
	v_add_f32_e32 v67, 1.0, v67
	v_add_f32_e32 v74, 1.0, v74
	v_pk_mul_f32 v[54:55], v[62:63], v[54:55]
	v_pk_mul_f32 v[62:63], v[66:67], v[68:69] op_sel_hi:[0,1]
	v_rcp_f32_e32 v74, v74
	v_rcp_f32_e32 v75, v67
	v_pk_mul_f32 v[56:57], v[64:65], v[56:57]
	v_pk_mul_f32 v[54:55], v[54:55], v[62:63]
	v_pk_mul_f32 v[62:63], v[66:67], v[70:71] op_sel_hi:[0,1]
	v_pk_mul_f32 v[56:57], v[56:57], v[62:63]
	v_cvt_pk_bf16_f32 v54, v54, v55
	v_cvt_pk_bf16_f32 v55, v56, v57
	v_pk_mul_f32 v[50:51], v[58:59], v[50:51]
	v_pk_mul_f32 v[56:57], v[66:67], v[72:73] op_sel_hi:[0,1]
	v_pk_mul_f32 v[50:51], v[50:51], v[56:57]
	v_pk_mul_f32 v[52:53], v[60:61], v[52:53]
	v_cvt_pk_bf16_f32 v56, v50, v51
	v_pk_mul_f32 v[50:51], v[66:67], v[74:75] op_sel_hi:[0,1]
	v_pk_mul_f32 v[50:51], v[52:53], v[50:51]
	s_mov_b32 s0, 0xb0000
	v_cvt_pk_bf16_f32 v57, v50, v51
	v_add_co_u32_e32 v50, vcc, s0, v122
	s_nop 1
	v_addc_co_u32_e32 v51, vcc, 0, v123, vcc
	global_store_dwordx4 v[50:51], v[54:57], off
	v_mul_f32_e32 v51, 0xbfb8aa3b, v147
	v_mul_f32_e32 v50, v46, v51
	v_exp_f32_e32 v52, v50
	v_mul_f32_e32 v50, v47, v51
	v_exp_f32_e32 v53, v50
	v_mul_f32_e32 v54, v48, v51
	v_mul_f32_e32 v55, v49, v51
	v_exp_f32_e32 v54, v54
	v_exp_f32_e32 v55, v55
	v_mul_f32_e32 v56, v42, v51
	v_mul_f32_e32 v57, v43, v51
	v_exp_f32_e32 v56, v56
	v_exp_f32_e32 v57, v57
	v_mul_f32_e32 v58, v44, v51
	v_mul_f32_e32 v51, v45, v51
	v_add_f32_e32 v52, 1.0, v52
	v_add_f32_e32 v53, 1.0, v53
	v_exp_f32_e32 v51, v51
	v_rcp_f32_e32 v52, v52
	v_rcp_f32_e32 v53, v53
	v_add_f32_e32 v54, 1.0, v54
	v_add_f32_e32 v55, 1.0, v55
	v_exp_f32_e32 v58, v58
	v_rcp_f32_e32 v54, v54
	v_rcp_f32_e32 v55, v55
	v_add_f32_e32 v56, 1.0, v56
	v_add_f32_e32 v57, 1.0, v57
	v_mul_f32_e32 v50, v147, v147
	v_rcp_f32_e32 v56, v56
	v_rcp_f32_e32 v57, v57
	v_add_f32_e32 v51, 1.0, v51
	v_add_f32_e32 v58, 1.0, v58
	v_pk_mul_f32 v[38:39], v[46:47], v[38:39]
	v_pk_mul_f32 v[46:47], v[50:51], v[52:53] op_sel_hi:[0,1]
	v_rcp_f32_e32 v58, v58
	v_rcp_f32_e32 v59, v51
	v_pk_mul_f32 v[40:41], v[48:49], v[40:41]
	v_pk_mul_f32 v[38:39], v[38:39], v[46:47]
	v_pk_mul_f32 v[46:47], v[50:51], v[54:55] op_sel_hi:[0,1]
	v_pk_mul_f32 v[40:41], v[40:41], v[46:47]
	v_cvt_pk_bf16_f32 v38, v38, v39
	v_cvt_pk_bf16_f32 v39, v40, v41
	v_pk_mul_f32 v[34:35], v[42:43], v[34:35]
	v_pk_mul_f32 v[40:41], v[50:51], v[56:57] op_sel_hi:[0,1]
	v_pk_mul_f32 v[34:35], v[34:35], v[40:41]
	v_pk_mul_f32 v[36:37], v[44:45], v[36:37]
; DI u32x4 pk8(f32x4 a, f32x4 b) { u32x4 o; o.x = pk2(a.x, a.y); o.y = pk2(a.z, a.w); o.z = pk2(b.x, b.y); o.w = pk2(b.z, b.w); return o; }
; DI float fexp2(float x) { return __builtin_amdgcn_exp2f(x); }
; DI float frcp(float x) { return __builtin_amdgcn_rcpf(x); }
; #define EPI_SCHED() __builtin_amdgcn_sched_barrier(0)
;     DI void operator()(const AccT& acc, const Unit& u, const Unit& nxt, bool has_next, int wr, int wc, int fr, int fq, float (&rs_unused)[2][4]) const {
;     ...
; #pragma unroll
;         for (int ai = 0; ai < 2; ++ai)
; #pragma unroll
;             for (int m = 0; m < 4; ++m) {
;                 EPI_SCHED(); const size_t row = row0 + ai * 128 + m * 16;
;                 f32x4 o[2];
;                 const float c1 = -LOG2E * rs[ai][m], rs2 = rs[ai][m] * rs[ai][m];
; #pragma unroll
;                 for (int n = 0; n < 2; ++n) {
;                     const f32x4 gt = acc[ai][0][m][n], t = gt * acc[ai][1][m][n];
; #pragma unroll
;                     for (int e = 0; e < 4; ++e) o[n][e] = t[e] * (rs2 * frcp(1.f + fexp2(gt[e] * c1)));
;                 }
;                 *(u32x4*)(hid + row * FF + u.pn * 128 + wc * 32 + fq * 8) = pk8(o[0], o[1]);
;             }
	v_cvt_pk_bf16_f32 v40, v34, v35
	v_pk_mul_f32 v[34:35], v[50:51], v[58:59] op_sel_hi:[0,1]
	v_pk_mul_f32 v[34:35], v[36:37], v[34:35]
	s_mov_b32 s0, 0xc6000
	v_cvt_pk_bf16_f32 v41, v34, v35
	v_add_co_u32_e32 v34, vcc, s0, v122
	s_nop 1
	v_addc_co_u32_e32 v35, vcc, 0, v123, vcc
	global_store_dwordx4 v[34:35], v[38:41], off
	v_mul_f32_e32 v35, 0xbfb8aa3b, v148
	v_mul_f32_e32 v34, v30, v35
	v_exp_f32_e32 v36, v34
	v_mul_f32_e32 v34, v31, v35
	v_exp_f32_e32 v37, v34
	v_mul_f32_e32 v38, v32, v35
	v_mul_f32_e32 v39, v33, v35
	v_exp_f32_e32 v38, v38
	v_exp_f32_e32 v39, v39
	v_mul_f32_e32 v40, v26, v35
	v_mul_f32_e32 v41, v27, v35
	v_exp_f32_e32 v40, v40
	v_exp_f32_e32 v41, v41
	v_mul_f32_e32 v42, v28, v35
	v_mul_f32_e32 v35, v29, v35
	v_add_f32_e32 v36, 1.0, v36
	v_add_f32_e32 v37, 1.0, v37
	v_exp_f32_e32 v35, v35
	v_rcp_f32_e32 v36, v36
	v_rcp_f32_e32 v37, v37
	v_add_f32_e32 v38, 1.0, v38
	v_add_f32_e32 v39, 1.0, v39
	v_exp_f32_e32 v42, v42
	v_rcp_f32_e32 v38, v38
	v_rcp_f32_e32 v39, v39
	v_add_f32_e32 v40, 1.0, v40
	v_add_f32_e32 v41, 1.0, v41
	v_mul_f32_e32 v34, v148, v148
	v_rcp_f32_e32 v40, v40
	v_rcp_f32_e32 v41, v41
	v_add_f32_e32 v35, 1.0, v35
	v_add_f32_e32 v42, 1.0, v42
	v_pk_mul_f32 v[22:23], v[30:31], v[22:23]
	v_pk_mul_f32 v[30:31], v[34:35], v[36:37] op_sel_hi:[0,1]
	v_rcp_f32_e32 v42, v42
	v_rcp_f32_e32 v43, v35
	v_pk_mul_f32 v[24:25], v[32:33], v[24:25]
	v_pk_mul_f32 v[22:23], v[22:23], v[30:31]
	v_pk_mul_f32 v[30:31], v[34:35], v[38:39] op_sel_hi:[0,1]
	v_pk_mul_f32 v[24:25], v[24:25], v[30:31]
	v_cvt_pk_bf16_f32 v22, v22, v23
	v_cvt_pk_bf16_f32 v23, v24, v25
	v_pk_mul_f32 v[18:19], v[26:27], v[18:19]
	v_pk_mul_f32 v[24:25], v[34:35], v[40:41] op_sel_hi:[0,1]
	v_pk_mul_f32 v[18:19], v[18:19], v[24:25]
	v_pk_mul_f32 v[20:21], v[28:29], v[20:21]
	v_cvt_pk_bf16_f32 v24, v18, v19
	v_pk_mul_f32 v[18:19], v[34:35], v[42:43] op_sel_hi:[0,1]
	v_pk_mul_f32 v[18:19], v[20:21], v[18:19]
	s_mov_b32 s0, 0xdc000
	v_cvt_pk_bf16_f32 v25, v18, v19
	v_add_co_u32_e32 v18, vcc, s0, v122
	s_nop 1
	v_addc_co_u32_e32 v19, vcc, 0, v123, vcc
	global_store_dwordx4 v[18:19], v[22:25], off
	v_mul_f32_e32 v19, 0xbfb8aa3b, v149
	v_mul_f32_e32 v18, v14, v19
	v_exp_f32_e32 v20, v18
	v_mul_f32_e32 v18, v15, v19
	v_exp_f32_e32 v21, v18
	v_mul_f32_e32 v22, v16, v19
	v_mul_f32_e32 v23, v17, v19
	v_exp_f32_e32 v22, v22
	v_exp_f32_e32 v23, v23
	v_mul_f32_e32 v24, v10, v19
	v_mul_f32_e32 v25, v11, v19
	v_exp_f32_e32 v24, v24
	v_exp_f32_e32 v25, v25
	v_mul_f32_e32 v26, v12, v19
	v_mul_f32_e32 v19, v13, v19
	v_add_f32_e32 v20, 1.0, v20
	v_add_f32_e32 v21, 1.0, v21
	v_exp_f32_e32 v19, v19
	v_rcp_f32_e32 v20, v20
	v_rcp_f32_e32 v21, v21
	v_add_f32_e32 v22, 1.0, v22
	v_add_f32_e32 v23, 1.0, v23
	v_exp_f32_e32 v26, v26
	v_rcp_f32_e32 v22, v22
	v_rcp_f32_e32 v23, v23
	v_add_f32_e32 v24, 1.0, v24
	v_add_f32_e32 v25, 1.0, v25
	v_mul_f32_e32 v18, v149, v149
	v_rcp_f32_e32 v24, v24
	v_rcp_f32_e32 v25, v25
	v_add_f32_e32 v19, 1.0, v19
	v_add_f32_e32 v26, 1.0, v26
	v_pk_mul_f32 v[6:7], v[14:15], v[6:7]
	v_pk_mul_f32 v[14:15], v[18:19], v[20:21] op_sel_hi:[0,1]
	v_rcp_f32_e32 v26, v26
	v_rcp_f32_e32 v27, v19
	v_pk_mul_f32 v[8:9], v[16:17], v[8:9]
	v_pk_mul_f32 v[6:7], v[6:7], v[14:15]
	v_pk_mul_f32 v[14:15], v[18:19], v[22:23] op_sel_hi:[0,1]
	v_pk_mul_f32 v[8:9], v[8:9], v[14:15]
	v_cvt_pk_bf16_f32 v6, v6, v7
	v_cvt_pk_bf16_f32 v7, v8, v9
	v_pk_mul_f32 v[2:3], v[10:11], v[2:3]
	v_pk_mul_f32 v[8:9], v[18:19], v[24:25] op_sel_hi:[0,1]
	v_pk_mul_f32 v[2:3], v[2:3], v[8:9]
	v_pk_mul_f32 v[4:5], v[12:13], v[4:5]
	v_cvt_pk_bf16_f32 v8, v2, v3
	v_pk_mul_f32 v[2:3], v[18:19], v[26:27] op_sel_hi:[0,1]
	v_pk_mul_f32 v[2:3], v[4:5], v[2:3]
	s_nop 0
	v_cvt_pk_bf16_f32 v9, v2, v3
	v_add_co_u32_e32 v2, vcc, 0xf2000, v122
	s_nop 1
	v_addc_co_u32_e32 v3, vcc, 0, v123, vcc
	s_and_b64 vcc, exec, s[2:3]
	s_mov_b64 s[2:3], -1
	global_store_dwordx4 v[2:3], v[6:9], off
	s_cbranch_vccnz .LBB0_1813
; #define PG8_BAR __builtin_amdgcn_s_barrier()
;     DI static void park(const float (&rs)[2][4], int t) { LAS f32x4* p = slot(t); p[0] = (f32x4){rs[0][0], rs[0][1], rs[0][2], rs[0][3]}; p[1] = (f32x4){rs[1][0], rs[1][1], rs[1][2], rs[1][3]}; }
; template <class Epi, class Sched>
; DI void gemm_phase(int wv, LAS unsigned char* lds, const Gemm g, const Sched& S, const Epi& E) {
;     ...
;         if (wr == 1) PG8_BAR;
;     DI void operator()(const AccT& acc, const Unit& u, const Unit& nxt, bool has_next, int wr, int wc, int fr, int fq, float (&rs_unused)[2][4]) const {
;     ...
;         if (has_next) {
; #pragma unroll
;             for (int ai = 0; ai < 2; ++ai)
; #pragma unroll
;                 for (int m = 0; m < 4; ++m) {
;                     float t = (nv[ai][m].x + nv[ai][m].y) + (nv[ai][m].z + nv[ai][m].w);
;                     t += __shfl_xor(t, 16); t += __shfl_xor(t, 32);
;                     rs[ai][m] = rsqrtf(t * (1.f / 1024.f) + EPS);
;                 }
;             park(rs, myt);
	s_waitcnt vmcnt(8)
	v_mov_b32_e32 v2, v154
	v_mov_b32_e32 v3, v155
	v_mov_b32_e32 v4, v156
	v_mov_b32_e32 v5, v157
	v_mov_b32_e32 v156, v158
	v_mov_b32_e32 v157, v98
	v_mov_b32_e32 v155, v100
	v_mov_b32_e32 v98, v159
	v_mov_b32_e32 v154, v160
	v_mov_b32_e32 v100, v161
	v_mov_b32_e32 v161, v118
	v_mov_b32_e32 v159, v120
	v_mov_b32_e32 v160, v162
	v_mov_b32_e32 v118, v163
	v_mov_b32_e32 v158, v164
	v_mov_b32_e32 v120, v165
	v_mov_b32_e32 v165, v138
	v_mov_b32_e32 v163, v140
	v_mov_b32_e32 v164, v166
	v_mov_b32_e32 v138, v167
	v_mov_b32_e32 v162, v168
	v_mov_b32_e32 v140, v169
	v_mov_b32_e32 v169, v142
	v_mov_b32_e32 v167, v144
	v_mov_b32_e32 v168, v2
	v_mov_b32_e32 v142, v3
	v_mov_b32_e32 v166, v4
	v_mov_b32_e32 v144, v5
	v_pk_add_f32 v[2:3], v[168:169], v[142:143]
	v_pk_add_f32 v[12:13], v[166:167], v[144:145]
	v_pk_add_f32 v[4:5], v[164:165], v[138:139]
	v_pk_add_f32 v[14:15], v[162:163], v[140:141]
	v_pk_add_f32 v[8:9], v[160:161], v[118:119]
	v_pk_add_f32 v[16:17], v[158:159], v[120:121]
	v_pk_add_f32 v[10:11], v[156:157], v[98:99]
	v_pk_add_f32 v[18:19], v[154:155], v[100:101]
	s_mov_b32 s0, 0x358637bd
	v_pk_add_f32 v[2:3], v[2:3], v[12:13]
	v_pk_add_f32 v[4:5], v[4:5], v[14:15]
	v_pk_add_f32 v[8:9], v[8:9], v[16:17]
	v_pk_add_f32 v[10:11], v[10:11], v[18:19]
	ds_bpermute_b32 v12, v174, v2
	ds_bpermute_b32 v13, v174, v3
	ds_bpermute_b32 v14, v174, v4
	ds_bpermute_b32 v15, v174, v5
	ds_bpermute_b32 v16, v174, v8
	ds_bpermute_b32 v17, v174, v9
	ds_bpermute_b32 v18, v174, v10
	ds_bpermute_b32 v19, v174, v11
	v_mov_b64_e32 v[6:7], s[0:1]
	s_waitcnt lgkmcnt(6)
	v_pk_add_f32 v[2:3], v[2:3], v[12:13]
	s_waitcnt lgkmcnt(4)
	v_pk_add_f32 v[4:5], v[4:5], v[14:15]
	s_waitcnt lgkmcnt(2)
	v_pk_add_f32 v[8:9], v[8:9], v[16:17]
	s_waitcnt lgkmcnt(0)
	v_pk_add_f32 v[10:11], v[10:11], v[18:19]
	ds_bpermute_b32 v12, v175, v2
	ds_bpermute_b32 v13, v175, v3
	ds_bpermute_b32 v14, v175, v4
	ds_bpermute_b32 v15, v175, v5
	ds_bpermute_b32 v16, v175, v8
	ds_bpermute_b32 v17, v175, v9
	ds_bpermute_b32 v18, v175, v10
	ds_bpermute_b32 v19, v175, v11
	s_waitcnt lgkmcnt(6)
	v_pk_add_f32 v[2:3], v[2:3], v[12:13]
	s_waitcnt lgkmcnt(4)
	v_pk_add_f32 v[4:5], v[4:5], v[14:15]
	s_waitcnt lgkmcnt(2)
	v_pk_add_f32 v[8:9], v[8:9], v[16:17]
	s_waitcnt lgkmcnt(0)
	v_pk_add_f32 v[10:11], v[10:11], v[18:19]
	v_pk_fma_f32 v[2:3], v[2:3], s[88:89], v[6:7] op_sel_hi:[1,0,0]
	v_pk_fma_f32 v[4:5], v[4:5], s[88:89], v[6:7] op_sel_hi:[1,0,0]
	v_pk_fma_f32 v[8:9], v[8:9], s[88:89], v[6:7] op_sel_hi:[1,0,0]
	v_pk_fma_f32 v[10:11], v[10:11], s[88:89], v[6:7] op_sel_hi:[1,0,0]
	v_mul_f32_e32 v12, 0x4b800000, v2
	v_cmp_gt_f32_e64 s[2:3], s42, v2
	v_cmp_gt_f32_e32 vcc, s42, v3
	s_nop 0
	v_cndmask_b32_e64 v2, v2, v12, s[2:3]
	v_mul_f32_e32 v12, 0x4b800000, v3
	v_cndmask_b32_e32 v3, v3, v12, vcc
	v_rsq_f32_e32 v2, v2
	v_rsq_f32_e32 v3, v3
	s_nop 0
	v_pk_mul_f32 v[12:13], v[2:3], s[52:53] op_sel_hi:[1,0]
	s_nop 0
	v_cndmask_b32_e32 v3, v3, v13, vcc
	v_cndmask_b32_e64 v2, v2, v12, s[2:3]
	v_mul_f32_e32 v14, 0x4b800000, v4
	v_cmp_gt_f32_e64 s[2:3], s42, v4
	v_cmp_gt_f32_e32 vcc, s42, v5
	s_nop 0
	v_cndmask_b32_e64 v4, v4, v14, s[2:3]
	v_mul_f32_e32 v14, 0x4b800000, v5
	v_cndmask_b32_e32 v5, v5, v14, vcc
	v_rsq_f32_e32 v4, v4
	v_rsq_f32_e32 v5, v5
	s_nop 0
	v_pk_mul_f32 v[14:15], v[4:5], s[52:53] op_sel_hi:[1,0]
	s_nop 0
	v_cndmask_b32_e32 v5, v5, v15, vcc
	v_cndmask_b32_e64 v4, v4, v14, s[2:3]
	v_mul_f32_e32 v16, 0x4b800000, v8
	v_cmp_gt_f32_e64 s[2:3], s42, v8
	v_cmp_gt_f32_e32 vcc, s42, v9
	s_nop 0
	v_cndmask_b32_e64 v8, v8, v16, s[2:3]
	v_mul_f32_e32 v16, 0x4b800000, v9
	v_cndmask_b32_e32 v9, v9, v16, vcc
	v_rsq_f32_e32 v8, v8
	v_rsq_f32_e32 v9, v9
	s_nop 0
	v_pk_mul_f32 v[16:17], v[8:9], s[52:53] op_sel_hi:[1,0]
	s_nop 0
	v_cndmask_b32_e32 v9, v9, v17, vcc
	v_cndmask_b32_e64 v8, v8, v16, s[2:3]
	v_mul_f32_e32 v18, 0x4b800000, v10
	v_cmp_gt_f32_e64 s[2:3], s42, v10
	v_cmp_gt_f32_e32 vcc, s42, v11
	s_nop 0
	v_cndmask_b32_e64 v10, v10, v18, s[2:3]
	v_mul_f32_e32 v18, 0x4b800000, v11
	v_cndmask_b32_e32 v11, v11, v18, vcc
	v_rsq_f32_e32 v10, v10
	v_rsq_f32_e32 v11, v11
	s_nop 0
	v_pk_mul_f32 v[18:19], v[10:11], s[52:53] op_sel_hi:[1,0]
	s_nop 0
	v_cndmask_b32_e32 v11, v11, v19, vcc
	v_cndmask_b32_e64 v10, v10, v18, s[2:3]
	s_andn2_b64 vcc, exec, s[6:7]
	ds_write_b128 v177, v[2:5]
	ds_write_b128 v177, v[8:11] offset:16
	s_cbranch_vccnz .LBB0_1812
	s_barrier
	s_branch .LBB0_1812

; DI unsigned xb_ld(unsigned* p)              { return __hip_atomic_load(p, __ATOMIC_RELAXED, __HIP_MEMORY_SCOPE_AGENT); }
; DI void xcd_barrier_complete(unsigned* bar, unsigned x, unsigned& nloc, unsigned& nx) {
;     const unsigned G = gridDim.x;
;     unsigned sum, cnt, mine, sp = 0u;
;     for (;;) {
;         sum = 0u; cnt = 0u; mine = 0u;
; #pragma unroll
;         for (unsigned j = 0; j < 16; ++j) { const unsigned c = xb_ld(&bar[XB_XCNT(j)]); sum += c; cnt += (c > 0u) ? 1u : 0u; mine = (j == x) ? c : mine; }
;         if (sum == G) break;
;         __builtin_amdgcn_s_sleep(1);
;         if ((++sp & 255u) == 0u) { if (xb_ld(&bar[XB_TMO])) break; if (sp > XB_SPIN_CAP) { atomicAdd(&bar[XB_TMO], 1u); break; } }
;     }
;     nloc = mine > 0u ? mine : 1u; nx = cnt > 0u ? cnt : 1u;
; }
.LBB0_1832:
	v_mov_b64_e32 v[2:3], s[4:5]
	s_waitcnt lgkmcnt(0)
	global_load_dword v0, v[2:3], off sc1
	v_mov_b64_e32 v[2:3], s[6:7]
	global_load_dword v2, v[2:3], off sc1
	v_mov_b64_e32 v[4:5], s[8:9]
	global_load_dword v3, v[4:5], off sc1
	v_mov_b64_e32 v[4:5], s[12:13]
	global_load_dword v4, v[4:5], off sc1
	s_or_b64 s[54:55], s[54:55], exec
	s_or_b64 s[56:57], s[56:57], exec
	s_waitcnt vmcnt(0) lgkmcnt(0)
	v_add_u32_e32 v6, v2, v0
	v_add_u32_e32 v6, v6, v3
	v_add_u32_e32 v8, v6, v4
	v_mov_b64_e32 v[6:7], s[14:15]
	global_load_dword v5, v[6:7], off sc1
	v_mov_b64_e32 v[6:7], s[16:17]
	global_load_dword v6, v[6:7], off sc1
	s_waitcnt vmcnt(0) lgkmcnt(0)
	v_add_u32_e32 v8, v8, v5
	v_add_u32_e32 v10, v8, v6
	v_mov_b64_e32 v[8:9], s[18:19]
	global_load_dword v7, v[8:9], off sc1
	v_mov_b64_e32 v[8:9], s[20:21]
	global_load_dword v8, v[8:9], off sc1
	s_waitcnt vmcnt(0) lgkmcnt(0)
	v_add_u32_e32 v10, v10, v7
	v_add_u32_e32 v12, v10, v8
	v_mov_b64_e32 v[10:11], s[22:23]
	global_load_dword v9, v[10:11], off sc1
	v_mov_b64_e32 v[10:11], s[24:25]
	global_load_dword v10, v[10:11], off sc1
	s_waitcnt vmcnt(0) lgkmcnt(0)
	v_add_u32_e32 v12, v12, v9
	v_add_u32_e32 v14, v12, v10
	v_mov_b64_e32 v[12:13], s[26:27]
	global_load_dword v11, v[12:13], off sc1
	v_mov_b64_e32 v[12:13], s[28:29]
	global_load_dword v12, v[12:13], off sc1
	s_waitcnt vmcnt(0) lgkmcnt(0)
	v_add_u32_e32 v14, v14, v11
	v_add_u32_e32 v16, v14, v12
	v_mov_b64_e32 v[14:15], s[30:31]
	global_load_dword v13, v[14:15], off sc1
	v_mov_b64_e32 v[14:15], s[34:35]
	global_load_dword v14, v[14:15], off sc1
	s_waitcnt vmcnt(0) lgkmcnt(0)
	v_add_u32_e32 v16, v16, v13
	v_add_u32_e32 v18, v16, v14
	v_mov_b64_e32 v[16:17], s[50:51]
	global_load_dword v15, v[16:17], off sc1
	v_mov_b64_e32 v[16:17], s[92:93]
	global_load_dword v16, v[16:17], off sc1
	s_waitcnt vmcnt(0) lgkmcnt(0)
	v_add_u32_e32 v18, v18, v15
	v_add_u32_e32 v17, v18, v16
	v_cmp_ne_u32_e32 vcc, s33, v17
	s_and_saveexec_b64 s[84:85], vcc
	s_cbranch_execz .LBB0_1831
	s_and_b32 s46, s1, 0xff
	s_mov_b64 s[90:91], -1
	s_cmp_eq_u32 s46, 0
	s_mov_b64 s[64:65], -1
	s_mov_b64 s[60:61], -1
	s_sleep 1
	s_cbranch_scc1 .LBB0_1835
	s_and_saveexec_b64 s[46:47], s[64:65]
	s_cbranch_execz .LBB0_1830
	s_branch .LBB0_1838
.LBB0_1835:
	v_mov_b64_e32 v[18:19], s[2:3]
	global_load_dword v17, v[18:19], off sc1
	s_mov_b64 s[64:65], 0
	s_waitcnt vmcnt(0) lgkmcnt(0)
	v_cmp_eq_u32_e32 vcc, 0, v17
	s_and_saveexec_b64 s[46:47], vcc
	s_cmp_lt_u32 s1, 0x40001
	s_cselect_b64 s[64:65], -1, 0
	s_xor_b64 s[60:61], exec, -1
	s_and_b64 s[64:65], s[64:65], exec
	s_or_b64 exec, exec, s[46:47]
	s_and_saveexec_b64 s[46:47], s[64:65]
	s_cbranch_execz .LBB0_1830

; DI unsigned xb_ld(unsigned* p)              { return __hip_atomic_load(p, __ATOMIC_RELAXED, __HIP_MEMORY_SCOPE_AGENT); }
; DI unsigned xb_add(unsigned* p, unsigned v) { return __hip_atomic_fetch_add(p, v, __ATOMIC_RELAXED, __HIP_MEMORY_SCOPE_AGENT); }
; #define XB_SPIN(cond, bar) do { unsigned _sp = 0; while (cond) { __builtin_amdgcn_s_sleep(1); \
;     if ((++_sp & 255u) == 0u) { if (xb_ld(&(bar)[XB_TMO])) break; if (_sp > XB_SPIN_CAP) { atomicAdd(&(bar)[XB_TMO], 1u); break; } } } } while (0)
; DI void xcd_barrier(int wv, unsigned* bar, volatile LAS unsigned* st) {
;     ...
;         const unsigned old = xb_add(&bar[XB_XSUB(x)], 1u);
;         const unsigned gen = old / nloc;
;         if (old + 1u == (gen + 1u) * nloc) {
;             __builtin_amdgcn_fence(__ATOMIC_RELEASE, "agent");
;             asm volatile("s_waitcnt vmcnt(0)" ::: "memory");
;             const unsigned og = xb_add(&bar[XB_TOP], 1u);
;             const unsigned tg = og / nx;
;             if (og + 1u == (tg + 1u) * nx) xb_add(&bar[XB_TOPGEN], 1u);
;             else XB_SPIN(xb_ld(&bar[XB_TOPGEN]) == tg, bar);
;             __builtin_amdgcn_fence(__ATOMIC_ACQUIRE, "agent");
;             xb_add(&bar[XB_XGEN(x)], 1u);
;             asm volatile("s_waitcnt vmcnt(0)" ::: "memory");
;         } else {
;             XB_SPIN(xb_ld(&bar[XB_XGEN(x)]) == gen, bar);
.LBB0_1842:
	s_lshl_b32 s0, s0, 8
	s_add_u32 s2, s48, s0
	s_addc_u32 s3, s49, 0
	v_mov_b32_e32 v3, s2
	v_add_co_u32_e32 v4, vcc, 0xc1000, v3
	v_mov_b32_e32 v3, s3
	s_nop 0
	v_addc_co_u32_e32 v5, vcc, 0, v3, vcc
	v_mov_b32_e32 v3, 1
	flat_atomic_add v4, v[4:5], v3 offset:1024 sc0
	v_cvt_f32_u32_e32 v3, v2
	v_sub_u32_e32 v5, 0, v2
	s_add_u32 s1, s2, 0xc0000
	s_addc_u32 s0, s3, 0
	v_rcp_iflag_f32_e32 v3, v3
	s_nop 0
	v_mul_f32_e32 v3, 0x4f7ffffe, v3
	v_cvt_u32_f32_e32 v3, v3
	v_mul_lo_u32 v5, v5, v3
	v_mul_hi_u32 v5, v3, v5
	v_add_u32_e32 v3, v3, v5
	s_waitcnt vmcnt(0) lgkmcnt(0)
	v_mul_hi_u32 v3, v4, v3
	v_mul_lo_u32 v5, v3, v2
	v_sub_u32_e32 v5, v4, v5
	v_cmp_ge_u32_e32 vcc, v5, v2
	v_add_u32_e32 v6, 1, v3
	s_nop 0
	v_cndmask_b32_e32 v3, v3, v6, vcc
	v_sub_u32_e32 v6, v5, v2
	v_cndmask_b32_e32 v5, v5, v6, vcc
	v_cmp_ge_u32_e32 vcc, v5, v2
	v_add_u32_e32 v5, 1, v3
	v_add_u32_e32 v6, 1, v4
	v_cndmask_b32_e32 v3, v3, v5, vcc
	v_mad_u64_u32 v[4:5], s[2:3], v2, v3, v[2:3]
	v_cmp_ne_u32_e32 vcc, v6, v4
	s_and_saveexec_b64 s[2:3], vcc
	s_xor_b64 s[2:3], exec, s[2:3]
	s_cbranch_execz .LBB0_1855
	v_mov_b32_e32 v0, s1
	v_add_co_u32_e32 v4, vcc, 0x2000, v0
	v_mov_b32_e32 v0, s0
	s_nop 0
	v_addc_co_u32_e32 v5, vcc, 0, v0, vcc
	global_load_dword v0, v[4:5], off offset:1024 sc1
	s_add_u32 s6, s1, 0x2400
	s_addc_u32 s7, s0, 0
	s_waitcnt vmcnt(0) lgkmcnt(0)
	v_cmp_eq_u32_e32 vcc, v0, v3
	s_and_saveexec_b64 s[4:5], vcc
	s_cbranch_execz .LBB0_1854
	s_add_u32 s8, s48, 0xc0200
	s_addc_u32 s9, s49, 0
	s_mov_b32 s26, 1
	s_mov_b64 s[12:13], 0
	s_branch .LBB0_1846

; DI unsigned xb_ld(unsigned* p)              { return __hip_atomic_load(p, __ATOMIC_RELAXED, __HIP_MEMORY_SCOPE_AGENT); }
; #define XB_SPIN(cond, bar) do { unsigned _sp = 0; while (cond) { __builtin_amdgcn_s_sleep(1); \
;     if ((++_sp & 255u) == 0u) { if (xb_ld(&(bar)[XB_TMO])) break; if (_sp > XB_SPIN_CAP) { atomicAdd(&(bar)[XB_TMO], 1u); break; } } } } while (0)
; DI void xcd_barrier(int wv, unsigned* bar, volatile LAS unsigned* st) {
;     ...
;             XB_SPIN(xb_ld(&bar[XB_XGEN(x)]) == gen, bar);
.LBB0_1846:
	s_and_b32 s20, s26, 0xff
	s_mov_b64 s[18:19], -1
	s_cmp_lg_u32 s20, 0
	s_mov_b64 s[20:21], -1
	s_sleep 1
	s_cbranch_scc1 .LBB0_1850
	v_mov_b64_e32 v[4:5], s[8:9]
	global_load_dword v0, v[4:5], off sc1
	s_mov_b64 s[20:21], 0
	s_mov_b64 s[22:23], -1
	s_waitcnt vmcnt(0) lgkmcnt(0)
	v_cmp_eq_u32_e32 vcc, 0, v0
	s_and_saveexec_b64 s[24:25], vcc
	s_cmp_lt_u32 s26, 0x40001
	s_cselect_b64 s[20:21], -1, 0
	s_xor_b64 s[22:23], exec, -1
	s_and_b64 s[20:21], s[20:21], exec
	s_or_b64 exec, exec, s[24:25]
.LBB0_1850:
	s_andn2_b64 s[16:17], s[16:17], exec
	s_and_b64 s[22:23], s[22:23], exec
	s_or_b64 s[16:17], s[16:17], s[22:23]
	s_and_saveexec_b64 s[22:23], s[20:21]
	s_cbranch_execz .LBB0_1845
	v_mov_b64_e32 v[4:5], s[6:7]
	global_load_dword v0, v[4:5], off sc1
	s_add_i32 s26, s26, 1
	s_or_b64 s[16:17], s[16:17], exec
	s_waitcnt vmcnt(0) lgkmcnt(0)
	v_cmp_ne_u32_e32 vcc, v0, v3
	s_orn2_b64 s[18:19], vcc, exec
	s_branch .LBB0_1845

; DI unsigned xb_ld(unsigned* p)              { return __hip_atomic_load(p, __ATOMIC_RELAXED, __HIP_MEMORY_SCOPE_AGENT); }
; DI unsigned xb_add(unsigned* p, unsigned v) { return __hip_atomic_fetch_add(p, v, __ATOMIC_RELAXED, __HIP_MEMORY_SCOPE_AGENT); }
; #define XB_SPIN(cond, bar) do { unsigned _sp = 0; while (cond) { __builtin_amdgcn_s_sleep(1); \
;     if ((++_sp & 255u) == 0u) { if (xb_ld(&(bar)[XB_TMO])) break; if (_sp > XB_SPIN_CAP) { atomicAdd(&(bar)[XB_TMO], 1u); break; } } } } while (0)
; DI void xcd_barrier(int wv, unsigned* bar, volatile LAS unsigned* st) {
;     ...
;         if (old + 1u == (gen + 1u) * nloc) {
;             __builtin_amdgcn_fence(__ATOMIC_RELEASE, "agent");
;             asm volatile("s_waitcnt vmcnt(0)" ::: "memory");
;             const unsigned og = xb_add(&bar[XB_TOP], 1u);
;             const unsigned tg = og / nx;
;             if (og + 1u == (tg + 1u) * nx) xb_add(&bar[XB_TOPGEN], 1u);
;             else XB_SPIN(xb_ld(&bar[XB_TOPGEN]) == tg, bar);
.LBB0_1855:
	s_andn2_saveexec_b64 s[2:3], s[2:3]
	s_cbranch_execz .LBB0_1871
	v_mov_b32_e32 v2, s48
	v_add_co_u32_e32 v2, vcc, 0xc3000, v2
	v_mov_b32_e32 v3, s49
	buffer_wbl2 sc1
	s_waitcnt vmcnt(0)
	v_addc_co_u32_e32 v3, vcc, 0, v3, vcc
	v_mov_b32_e32 v4, 1
	flat_atomic_add v2, v[2:3], v4 offset:1024 sc0
	v_cvt_f32_u32_e32 v3, v0
	v_sub_u32_e32 v4, 0, v0
	s_mov_b64 s[6:7], -1
	v_rcp_iflag_f32_e32 v3, v3
	s_nop 0
	v_mul_f32_e32 v3, 0x4f7ffffe, v3
	v_cvt_u32_f32_e32 v3, v3
	v_mul_lo_u32 v4, v4, v3
	v_mul_hi_u32 v4, v3, v4
	v_add_u32_e32 v3, v3, v4
	s_waitcnt vmcnt(0) lgkmcnt(0)
	v_mul_hi_u32 v3, v2, v3
	v_mul_lo_u32 v4, v3, v0
	v_sub_u32_e32 v4, v2, v4
	v_cmp_ge_u32_e32 vcc, v4, v0
	v_add_u32_e32 v5, 1, v3
	s_nop 0
	v_cndmask_b32_e32 v3, v3, v5, vcc
	v_sub_u32_e32 v5, v4, v0
	v_cndmask_b32_e32 v4, v4, v5, vcc
	v_cmp_ge_u32_e32 vcc, v4, v0
	v_add_u32_e32 v4, 1, v3
	v_add_u32_e32 v5, 1, v2
	v_cndmask_b32_e32 v4, v3, v4, vcc
	v_mad_u64_u32 v[2:3], s[2:3], v0, v4, v[0:1]
	s_add_u32 s2, s48, 0xc3500
	s_addc_u32 s3, s49, 0
	v_cmp_ne_u32_e32 vcc, v5, v2
	v_mov_b64_e32 v[2:3], s[2:3]
	s_and_saveexec_b64 s[4:5], vcc
	s_cbranch_execz .LBB0_1868
	v_mov_b64_e32 v[2:3], s[2:3]
	global_load_dword v0, v[2:3], off sc1
	s_mov_b64 s[12:13], 0
	s_waitcnt vmcnt(0) lgkmcnt(0)
	v_cmp_eq_u32_e32 vcc, v0, v4
	s_and_saveexec_b64 s[8:9], vcc
	s_cbranch_execz .LBB0_1867
	s_add_u32 s6, s48, 0xc0200
	s_addc_u32 s7, s49, 0
	s_mov_b32 s24, 1
	s_branch .LBB0_1860

; DI unsigned xb_ld(unsigned* p)              { return __hip_atomic_load(p, __ATOMIC_RELAXED, __HIP_MEMORY_SCOPE_AGENT); }
; #define XB_SPIN(cond, bar) do { unsigned _sp = 0; while (cond) { __builtin_amdgcn_s_sleep(1); \
;     if ((++_sp & 255u) == 0u) { if (xb_ld(&(bar)[XB_TMO])) break; if (_sp > XB_SPIN_CAP) { atomicAdd(&(bar)[XB_TMO], 1u); break; } } } } while (0)
; DI void xcd_barrier(int wv, unsigned* bar, volatile LAS unsigned* st) {
;     ...
;             else XB_SPIN(xb_ld(&bar[XB_TOPGEN]) == tg, bar);
.LBB0_1862:
	v_mov_b64_e32 v[2:3], s[6:7]
	global_load_dword v0, v[2:3], off sc1
	s_mov_b64 s[20:21], 0
	s_mov_b64 s[18:19], -1
	s_waitcnt vmcnt(0) lgkmcnt(0)
	v_cmp_eq_u32_e32 vcc, 0, v0
	s_and_saveexec_b64 s[22:23], vcc
	s_cmp_lt_u32 s24, 0x40001
	s_cselect_b64 s[20:21], -1, 0
	s_xor_b64 s[18:19], exec, -1
	s_and_b64 s[20:21], s[20:21], exec
	s_or_b64 exec, exec, s[22:23]
	s_and_saveexec_b64 s[22:23], s[20:21]
	s_cbranch_execz .LBB0_1859
.LBB0_1865:
	v_mov_b64_e32 v[2:3], s[2:3]
	global_load_dword v0, v[2:3], off sc1
	s_add_i32 s24, s24, 1
	s_or_b64 s[18:19], s[18:19], exec
	s_waitcnt vmcnt(0) lgkmcnt(0)
	v_cmp_ne_u32_e32 vcc, v0, v4
	s_orn2_b64 s[16:17], vcc, exec
	s_branch .LBB0_1859

; DI u32x4 pk8(f32x4 a, f32x4 b) { u32x4 o; o.x = pk2(a.x, a.y); o.y = pk2(a.z, a.w); o.z = pk2(b.x, b.y); o.w = pk2(b.z, b.w); return o; }
; DI float sigmoidf_(float x) { return frcp(1.f + fexp2(-x * LOG2E)); }
; #define EPI_SCHED() __builtin_amdgcn_sched_barrier(0)
; template <int STRIDE, int P0, int NP4>
; DI void rstd8(const float* parts, size_t row0, float invK, int fq, float (&rs)[2][4]) {
;     ...
;             float t = (v[ai][m].x + v[ai][m].y) + (v[ai][m].z + v[ai][m].w);
;             if (NP4 > 1) { t += __shfl_xor(t, 16); t += __shfl_xor(t, 32); }
;             rs[ai][m] = rsqrtf(t * invK + EPS);
;         }
;     DI void operator()(const AccT& acc, const Unit& u, int wr, int wc, int fr, int fq) const {
;         const size_t row0 = (size_t)u.pm * 256 + wr * 64 + fr;
;         float rs[2][4]; rstd8<16, 0, 4>(ss, row0, 1.f / 1024.f, fq, rs);
; #pragma unroll
;         for (int ai = 0; ai < 2; ++ai)
; #pragma unroll
;             for (int m = 0; m < 4; ++m) {
;                 EPI_SCHED(); const size_t row = row0 + ai * 128 + m * 16;
;                 const size_t b = row >> 11, s = row & 2047;
; #pragma unroll
;                 for (int bj = 0; bj < 2; ++bj) {
;                     const int cc = bj * 128 + wc * 32 + fq * 8;
;                     f32x4 a = acc[ai][bj][m][0] * rs[ai][m], c = acc[ai][bj][m][1] * rs[ai][m];
;                     if (u.pn < 4) *(u32x4*)(q + row * 1024 + u.pn * 256 + cc) = pk8(a, c);
;                     else if (u.pn < 8) { const int g = cc >> 6, d = cc & 63; *(u32x4*)(slab + (size_t)(u.pn - 4) * SLAB_EL + ((b * 4 + g) * 2048 + s) * 64 + d) = pk8(a, c); }
;                     else if (cc < 48) {
; #pragma unroll
;                         for (int e = 0; e < 4; ++e) { a[e] = sigmoidf_(a[e]); c[e] = sigmoidf_(c[e]); }
;                         *(f32x4*)(gates + row * 48 + cc) = a; *(f32x4*)(gates + row * 48 + cc + 4) = c;
;                     }
.LBB0_1908:
	v_xor_b32_e32 v144, 16, v207
	v_cmp_lt_i32_e32 vcc, v144, v222
	v_pk_add_f32 v[134:135], v[160:161], v[134:135]
	v_pk_add_f32 v[130:131], v[162:163], v[130:131]
	v_cndmask_b32_e32 v144, v207, v144, vcc
	v_lshlrev_b32_e32 v155, 2, v144
	v_mov_b32_e32 v144, v130
	v_mov_b32_e32 v145, v134
	v_mov_b32_e32 v134, v131
	v_pk_add_f32 v[130:131], v[144:145], v[134:135]
	ds_bpermute_b32 v135, v155, v131
	ds_bpermute_b32 v134, v155, v130
	v_cmp_lt_i32_e32 vcc, v223, v222
	s_cmp_gt_i32 s0, 3
	s_cselect_b64 s[2:3], -1, 0
	v_cndmask_b32_e32 v144, v207, v223, vcc
	v_lshlrev_b32_e32 v159, 2, v144
	s_waitcnt lgkmcnt(0)
	v_pk_add_f32 v[130:131], v[130:131], v[134:135]
	ds_bpermute_b32 v135, v159, v131
	ds_bpermute_b32 v134, v159, v130
	s_cmp_gt_u32 s0, 7
	s_cselect_b64 s[38:39], -1, 0
	s_add_i32 s96, s0, -4
	s_lshr_b64 s[4:5], s[4:5], 9
	s_waitcnt lgkmcnt(0)
	v_pk_add_f32 v[130:131], v[130:131], v[134:135]
	v_mov_b32_e32 v134, 0x358637bd
	v_pk_fma_f32 v[150:151], v[130:131], s[88:89], v[134:135] op_sel_hi:[1,0,0]
	s_lshl_b64 s[34:35], s[96:97], 24
	v_mul_f32_e32 v130, 0x4b800000, v151
	v_cmp_gt_f32_e32 vcc, s42, v151
	v_cmp_gt_f32_e64 s[6:7], s42, v150
	s_and_b32 s49, s5, 0x3fff
	v_cndmask_b32_e32 v130, v151, v130, vcc
	v_rsq_f32_e32 v144, v130
	v_pk_add_f32 v[130:131], v[132:133], v[140:141]
	v_pk_add_f32 v[132:133], v[164:165], v[136:137]
	v_mov_b32_e32 v135, v130
	v_mov_b32_e32 v134, v132
	v_mov_b32_e32 v130, v133
	v_pk_add_f32 v[130:131], v[134:135], v[130:131]
	ds_bpermute_b32 v133, v155, v131
	ds_bpermute_b32 v132, v155, v130
	v_mul_f32_e32 v134, 0x45800000, v144
	v_cndmask_b32_e32 v154, v144, v134, vcc
	v_pk_add_f32 v[136:137], v[170:171], v[148:149]
	s_and_b32 s48, s4, -4
	s_waitcnt lgkmcnt(0)
	v_pk_add_f32 v[140:141], v[130:131], v[132:133]
	v_pk_add_f32 v[130:131], v[138:139], v[146:147]
	v_pk_add_f32 v[132:133], v[166:167], v[142:143]
	v_mov_b32_e32 v135, v130
	v_mov_b32_e32 v134, v132
	v_mov_b32_e32 v130, v133
	v_pk_add_f32 v[130:131], v[134:135], v[130:131]
	v_pk_add_f32 v[134:135], v[168:169], v[152:153]
	v_mov_b32_e32 v138, v136
	v_mov_b32_e32 v139, v134
	v_mov_b32_e32 v134, v137
	v_pk_add_f32 v[134:135], v[138:139], v[134:135]
	ds_bpermute_b32 v133, v155, v131
	ds_bpermute_b32 v132, v155, v130
	ds_bpermute_b32 v143, v155, v135
	ds_bpermute_b32 v142, v155, v134
	ds_bpermute_b32 v145, v159, v141
	ds_bpermute_b32 v144, v159, v140
	s_waitcnt lgkmcnt(0)
	v_pk_add_f32 v[136:137], v[130:131], v[132:133]
	ds_bpermute_b32 v139, v159, v137
	v_pk_add_f32 v[132:133], v[134:135], v[142:143]
	ds_bpermute_b32 v138, v159, v136
	ds_bpermute_b32 v135, v159, v133
	ds_bpermute_b32 v134, v159, v132
	v_lshl_add_u32 v130, v0, 3, s66
	v_mad_u64_u32 v[142:143], s[4:5], v156, 48, 0
	v_mov_b32_e32 v0, v143
	v_mad_u64_u32 v[146:147], s[4:5], v157, 48, v[0:1]
	v_mov_b32_e32 v143, v146
	v_and_b32_e32 v148, 0x1f3c0, v158
	v_pk_mul_f32 v[128:129], v[128:129], v[154:155] op_sel_hi:[1,0]
	v_pk_mul_f32 v[126:127], v[126:127], v[154:155] op_sel_hi:[1,0]
	v_pk_mul_f32 v[124:125], v[124:125], v[154:155] op_sel_hi:[1,0]
	v_pk_mul_f32 v[146:147], v[122:123], v[154:155] op_sel_hi:[1,0]
	s_mov_b64 s[4:5], -1
	s_and_b64 vcc, exec, s[2:3]
	s_cbranch_vccz .LBB0_1916
	s_and_b64 vcc, exec, s[38:39]
	s_cbranch_vccz .LBB0_1913
	v_cmp_gt_i32_e32 vcc, 48, v130
	s_and_saveexec_b64 s[4:5], vcc
	s_cbranch_execz .LBB0_1912
	v_mul_f32_e32 v0, 0xbfb8aa3b, v126
	v_exp_f32_e32 v0, v0
	v_mul_f32_e32 v122, 0xbfb8aa3b, v146
	v_exp_f32_e32 v122, v122
	v_mul_f32_e32 v123, 0xbfb8aa3b, v147
	v_add_f32_e32 v0, 1.0, v0
	v_rcp_f32_e32 v158, v0
	v_mul_f32_e32 v0, 0xbfb8aa3b, v127
	v_exp_f32_e32 v0, v0
	v_exp_f32_e32 v123, v123
	v_add_f32_e32 v122, 1.0, v122
	v_rcp_f32_e32 v162, v122
	v_add_f32_e32 v0, 1.0, v0
	v_mul_f32_e32 v122, 0xbfb8aa3b, v128
	v_rcp_f32_e32 v159, v0
	v_add_f32_e32 v0, 1.0, v123
	v_exp_f32_e32 v122, v122
	v_mul_f32_e32 v123, 0xbfb8aa3b, v124
	v_exp_f32_e32 v123, v123
	v_rcp_f32_e32 v163, v0
	v_add_f32_e32 v0, 1.0, v122
	v_mul_f32_e32 v122, 0xbfb8aa3b, v129
	v_rcp_f32_e32 v160, v0
	v_add_f32_e32 v0, 1.0, v123
	v_exp_f32_e32 v122, v122
	v_mul_f32_e32 v123, 0xbfb8aa3b, v125
	v_exp_f32_e32 v123, v123
	v_rcp_f32_e32 v164, v0
	v_add_f32_e32 v0, 1.0, v122
	v_rcp_f32_e32 v161, v0
	v_add_f32_e32 v0, 1.0, v123
	v_rcp_f32_e32 v165, v0
	v_lshl_add_u64 v[122:123], v[142:143], 2, s[18:19]
	v_ashrrev_i32_e32 v131, 31, v130
	v_lshl_add_u64 v[122:123], v[130:131], 2, v[122:123]
	global_store_dwordx4 v[122:123], v[158:161], off
	global_store_dwordx4 v[122:123], v[162:165], off offset:16

; DI u32x4 pk8(f32x4 a, f32x4 b) { u32x4 o; o.x = pk2(a.x, a.y); o.y = pk2(a.z, a.w); o.z = pk2(b.x, b.y); o.w = pk2(b.z, b.w); return o; }
;     DI void operator()(const AccT& acc, const Unit& u, int wr, int wc, int fr, int fq) const {
;     ...
;                 for (int bj = 0; bj < 2; ++bj) {
;                     const int cc = bj * 128 + wc * 32 + fq * 8;
;                     f32x4 a = acc[ai][bj][m][0] * rs[ai][m], c = acc[ai][bj][m][1] * rs[ai][m];
;                     if (u.pn < 4) *(u32x4*)(q + row * 1024 + u.pn * 256 + cc) = pk8(a, c);
;                     else if (u.pn < 8) { const int g = cc >> 6, d = cc & 63; *(u32x4*)(slab + (size_t)(u.pn - 4) * SLAB_EL + ((b * 4 + g) * 2048 + s) * 64 + d) = pk8(a, c); }
.LBB0_1913:
	s_andn2_b64 vcc, exec, s[4:5]
	s_cbranch_vccnz .LBB0_1915
	v_ashrrev_i32_e32 v122, 6, v130
	v_ashrrev_i32_e32 v123, 31, v122
	s_add_u32 s4, s61, s34
	v_lshl_add_u64 v[122:123], s[48:49], 0, v[122:123]
	s_addc_u32 s5, s64, s35
	v_lshlrev_b64 v[122:123], 18, v[122:123]
	v_and_b32_e32 v131, 56, v130
	v_lshl_add_u64 v[122:123], s[4:5], 0, v[122:123]
	v_lshlrev_b32_e32 v0, 1, v148
	v_lshl_add_u64 v[122:123], v[122:123], 0, v[0:1]
	v_lshlrev_b32_e32 v0, 1, v131
	v_cvt_pk_bf16_f32 v158, v126, v127
	v_cvt_pk_bf16_f32 v159, v128, v129
	v_cvt_pk_bf16_f32 v160, v146, v147
	v_cvt_pk_bf16_f32 v161, v124, v125
	v_lshl_add_u64 v[122:123], v[122:123], 0, v[0:1]
	global_store_dwordx4 v[122:123], v[158:161], off

; DI u32x4 pk8(f32x4 a, f32x4 b) { u32x4 o; o.x = pk2(a.x, a.y); o.y = pk2(a.z, a.w); o.z = pk2(b.x, b.y); o.w = pk2(b.z, b.w); return o; }
; DI float sigmoidf_(float x) { return frcp(1.f + fexp2(-x * LOG2E)); }
;     DI void operator()(const AccT& acc, const Unit& u, int wr, int wc, int fr, int fq) const {
;     ...
;                 for (int bj = 0; bj < 2; ++bj) {
;                     const int cc = bj * 128 + wc * 32 + fq * 8;
;                     f32x4 a = acc[ai][bj][m][0] * rs[ai][m], c = acc[ai][bj][m][1] * rs[ai][m];
;                     if (u.pn < 4) *(u32x4*)(q + row * 1024 + u.pn * 256 + cc) = pk8(a, c);
;                     else if (u.pn < 8) { const int g = cc >> 6, d = cc & 63; *(u32x4*)(slab + (size_t)(u.pn - 4) * SLAB_EL + ((b * 4 + g) * 2048 + s) * 64 + d) = pk8(a, c); }
;                     else if (cc < 48) {
; #pragma unroll
;                         for (int e = 0; e < 4; ++e) { a[e] = sigmoidf_(a[e]); c[e] = sigmoidf_(c[e]); }
;                         *(f32x4*)(gates + row * 48 + cc) = a; *(f32x4*)(gates + row * 48 + cc + 4) = c;
;                     }
.LBB0_1916:
	s_lshl_b32 s36, s0, 8
	v_lshlrev_b64 v[122:123], 11, v[156:157]
	s_ashr_i32 s37, s36, 31
	v_lshl_add_u64 v[122:123], s[16:17], 0, v[122:123]
	s_andn2_b64 vcc, exec, s[4:5]
	v_ashrrev_i32_e32 v131, 31, v130
	v_lshl_add_u64 v[122:123], s[36:37], 1, v[122:123]
	s_cbranch_vccnz .LBB0_1918
	v_cvt_pk_bf16_f32 v126, v126, v127
	v_cvt_pk_bf16_f32 v127, v128, v129
	v_cvt_pk_bf16_f32 v128, v146, v147
	v_cvt_pk_bf16_f32 v129, v124, v125
	v_lshl_add_u64 v[124:125], v[130:131], 1, v[122:123]
	global_store_dwordx4 v[124:125], v[126:129], off
.LBB0_1918:
	v_cndmask_b32_e64 v0, 0, 1, s[2:3]
	v_mov_b32_e32 v155, v154
	v_mov_b32_e32 v126, v154
	v_mov_b32_e32 v127, v154
	v_cmp_ne_u32_e64 s[4:5], 1, v0
	v_cndmask_b32_e64 v0, 0, 1, s[38:39]
	v_add_u32_e32 v124, 0x80, v130
	v_pk_mul_f32 v[120:121], v[120:121], v[126:127]
	v_pk_mul_f32 v[118:119], v[118:119], v[154:155]
	v_pk_mul_f32 v[116:117], v[116:117], v[126:127]
	v_pk_mul_f32 v[114:115], v[114:115], v[154:155]
	s_mov_b64 s[44:45], -1
	s_andn2_b64 vcc, exec, s[2:3]
	v_cmp_ne_u32_e64 s[2:3], 1, v0
	s_cbranch_vccnz .LBB0_1926
	s_and_b64 vcc, exec, s[2:3]
	s_mov_b64 s[38:39], -1
	s_cbranch_vccnz .LBB0_1923
	s_movk_i32 s0, 0xffb0
	v_cmp_gt_i32_e32 vcc, s0, v130
	s_and_saveexec_b64 s[38:39], vcc
	s_cbranch_execz .LBB0_1922
	v_mul_f32_e32 v0, 0xbfb8aa3b, v118
	v_exp_f32_e32 v0, v0
	v_mul_f32_e32 v125, 0xbfb8aa3b, v114
	v_exp_f32_e32 v125, v125
	v_mul_f32_e32 v127, 0xbfb8aa3b, v115
	v_add_f32_e32 v0, 1.0, v0
	v_rcp_f32_e32 v126, v0
	v_mul_f32_e32 v0, 0xbfb8aa3b, v119
	v_exp_f32_e32 v0, v0
	v_exp_f32_e32 v128, v127
	v_add_f32_e32 v125, 1.0, v125
	v_rcp_f32_e32 v152, v125
	v_add_f32_e32 v0, 1.0, v0
	v_mul_f32_e32 v125, 0xbfb8aa3b, v120
	v_rcp_f32_e32 v127, v0
	v_add_f32_e32 v0, 1.0, v128
	v_exp_f32_e32 v125, v125
	v_mul_f32_e32 v128, 0xbfb8aa3b, v116
	v_exp_f32_e32 v129, v128
	v_rcp_f32_e32 v153, v0
	v_add_f32_e32 v0, 1.0, v125
	v_mul_f32_e32 v125, 0xbfb8aa3b, v121
	v_rcp_f32_e32 v128, v0
	v_add_f32_e32 v0, 1.0, v129
	v_exp_f32_e32 v125, v125
	v_mul_f32_e32 v129, 0xbfb8aa3b, v117
	v_exp_f32_e32 v146, v129
	v_rcp_f32_e32 v154, v0
	v_add_f32_e32 v0, 1.0, v125
	v_rcp_f32_e32 v129, v0
	v_add_f32_e32 v0, 1.0, v146
	v_rcp_f32_e32 v155, v0
	v_lshl_add_u64 v[146:147], v[142:143], 2, s[18:19]
	v_lshl_add_u64 v[146:147], v[130:131], 2, v[146:147]
	global_store_dwordx4 v[146:147], v[126:129], off offset:512
	global_store_dwordx4 v[146:147], v[152:155], off offset:528

; DI u32x4 pk8(f32x4 a, f32x4 b) { u32x4 o; o.x = pk2(a.x, a.y); o.y = pk2(a.z, a.w); o.z = pk2(b.x, b.y); o.w = pk2(b.z, b.w); return o; }
; #define EPI_SCHED() __builtin_amdgcn_sched_barrier(0)
;     DI void operator()(const AccT& acc, const Unit& u, int wr, int wc, int fr, int fq) const {
;     ...
;             for (int m = 0; m < 4; ++m) {
;                 EPI_SCHED(); const size_t row = row0 + ai * 128 + m * 16;
;                 const size_t b = row >> 11, s = row & 2047;
; #pragma unroll
;                 for (int bj = 0; bj < 2; ++bj) {
;                     const int cc = bj * 128 + wc * 32 + fq * 8;
;                     f32x4 a = acc[ai][bj][m][0] * rs[ai][m], c = acc[ai][bj][m][1] * rs[ai][m];
;                     if (u.pn < 4) *(u32x4*)(q + row * 1024 + u.pn * 256 + cc) = pk8(a, c);
;                     else if (u.pn < 8) { const int g = cc >> 6, d = cc & 63; *(u32x4*)(slab + (size_t)(u.pn - 4) * SLAB_EL + ((b * 4 + g) * 2048 + s) * 64 + d) = pk8(a, c); }
.LBB0_1923:
	s_andn2_b64 vcc, exec, s[38:39]
	s_cbranch_vccnz .LBB0_1925
	v_ashrrev_i32_e32 v146, 6, v124
	v_ashrrev_i32_e32 v147, 31, v146
	s_add_u32 s0, s61, s34
	v_lshl_add_u64 v[146:147], s[48:49], 0, v[146:147]
	s_addc_u32 s1, s64, s35
	v_lshlrev_b64 v[146:147], 18, v[146:147]
	v_and_b32_e32 v125, 56, v130
	v_lshl_add_u64 v[146:147], s[0:1], 0, v[146:147]
	v_lshlrev_b32_e32 v0, 1, v148
	v_lshl_add_u64 v[146:147], v[146:147], 0, v[0:1]
	v_lshlrev_b32_e32 v0, 1, v125
	v_cvt_pk_bf16_f32 v126, v118, v119
	v_cvt_pk_bf16_f32 v127, v120, v121
	v_cvt_pk_bf16_f32 v128, v114, v115
	v_cvt_pk_bf16_f32 v129, v116, v117
	v_lshl_add_u64 v[146:147], v[146:147], 0, v[0:1]
	global_store_dwordx4 v[146:147], v[126:129], off

; DI u32x4 pk8(f32x4 a, f32x4 b) { u32x4 o; o.x = pk2(a.x, a.y); o.y = pk2(a.z, a.w); o.z = pk2(b.x, b.y); o.w = pk2(b.z, b.w); return o; }
; DI float sigmoidf_(float x) { return frcp(1.f + fexp2(-x * LOG2E)); }
; #define EPI_SCHED() __builtin_amdgcn_sched_barrier(0)
;     DI void operator()(const AccT& acc, const Unit& u, int wr, int wc, int fr, int fq) const {
;     ...
;             for (int m = 0; m < 4; ++m) {
;                 EPI_SCHED(); const size_t row = row0 + ai * 128 + m * 16;
;                 const size_t b = row >> 11, s = row & 2047;
; #pragma unroll
;                 for (int bj = 0; bj < 2; ++bj) {
;                     const int cc = bj * 128 + wc * 32 + fq * 8;
;                     f32x4 a = acc[ai][bj][m][0] * rs[ai][m], c = acc[ai][bj][m][1] * rs[ai][m];
;                     if (u.pn < 4) *(u32x4*)(q + row * 1024 + u.pn * 256 + cc) = pk8(a, c);
;                     else if (u.pn < 8) { const int g = cc >> 6, d = cc & 63; *(u32x4*)(slab + (size_t)(u.pn - 4) * SLAB_EL + ((b * 4 + g) * 2048 + s) * 64 + d) = pk8(a, c); }
;                     else if (cc < 48) {
; #pragma unroll
;                         for (int e = 0; e < 4; ++e) { a[e] = sigmoidf_(a[e]); c[e] = sigmoidf_(c[e]); }
;                         *(f32x4*)(gates + row * 48 + cc) = a; *(f32x4*)(gates + row * 48 + cc + 4) = c;
;                     }
.LBB0_1926:
	s_andn2_b64 vcc, exec, s[44:45]
	s_cbranch_vccnz .LBB0_1928
	v_cvt_pk_bf16_f32 v118, v118, v119
	v_cvt_pk_bf16_f32 v119, v120, v121
	v_cvt_pk_bf16_f32 v120, v114, v115
	v_cvt_pk_bf16_f32 v121, v116, v117
	v_lshl_add_u64 v[114:115], v[130:131], 1, v[122:123]
	global_store_dwordx4 v[114:115], v[118:121], off offset:256
.LBB0_1928:
	v_mul_f32_e32 v0, 0x4b800000, v150
	v_cndmask_b32_e64 v0, v150, v0, s[6:7]
	v_rsq_f32_e32 v0, v0
	s_nop 0
	v_mul_f32_e32 v114, 0x45800000, v0
	v_cndmask_b32_e64 v116, v0, v114, s[6:7]
	v_or_b32_e32 v118, 16, v156
	s_mov_b64 s[0:1], 0x300
	v_lshlrev_b32_e32 v0, 6, v118
	v_lshl_add_u64 v[114:115], v[142:143], 0, s[0:1]
	v_and_b32_e32 v122, 0x1ffc0, v0
	v_pk_mul_f32 v[112:113], v[112:113], v[116:117] op_sel_hi:[1,0]
	v_pk_mul_f32 v[110:111], v[110:111], v[116:117] op_sel_hi:[1,0]
	v_pk_mul_f32 v[108:109], v[108:109], v[116:117] op_sel_hi:[1,0]
	v_pk_mul_f32 v[120:121], v[106:107], v[116:117] op_sel_hi:[1,0]
	s_and_b64 vcc, exec, s[4:5]
	s_mov_b64 s[6:7], -1
	s_cbranch_vccnz .LBB0_1936
	s_and_b64 vcc, exec, s[2:3]
	s_cbranch_vccnz .LBB0_1933
	v_cmp_gt_i32_e32 vcc, 48, v130
	s_and_saveexec_b64 s[6:7], vcc
	s_cbranch_execz .LBB0_1932
	v_mul_f32_e32 v0, 0xbfb8aa3b, v110
	v_exp_f32_e32 v0, v0
	v_mul_f32_e32 v106, 0xbfb8aa3b, v120
	v_exp_f32_e32 v106, v106
	v_mul_f32_e32 v107, 0xbfb8aa3b, v121
	v_add_f32_e32 v0, 1.0, v0
	v_rcp_f32_e32 v126, v0
	v_mul_f32_e32 v0, 0xbfb8aa3b, v111
	v_exp_f32_e32 v0, v0
	v_exp_f32_e32 v107, v107
	v_add_f32_e32 v106, 1.0, v106
	v_rcp_f32_e32 v146, v106
	v_add_f32_e32 v0, 1.0, v0
	v_mul_f32_e32 v106, 0xbfb8aa3b, v112
	v_rcp_f32_e32 v127, v0
	v_add_f32_e32 v0, 1.0, v107
	v_exp_f32_e32 v106, v106
	v_mul_f32_e32 v107, 0xbfb8aa3b, v108
	v_exp_f32_e32 v107, v107
	v_rcp_f32_e32 v147, v0
	v_add_f32_e32 v0, 1.0, v106
	v_mul_f32_e32 v106, 0xbfb8aa3b, v113
	v_rcp_f32_e32 v128, v0
	v_add_f32_e32 v0, 1.0, v107
	v_exp_f32_e32 v106, v106
	v_mul_f32_e32 v107, 0xbfb8aa3b, v109
	v_exp_f32_e32 v107, v107
	v_rcp_f32_e32 v148, v0
	v_add_f32_e32 v0, 1.0, v106
	v_rcp_f32_e32 v129, v0
	v_add_f32_e32 v0, 1.0, v107
	v_rcp_f32_e32 v149, v0
	v_lshl_add_u64 v[106:107], v[114:115], 2, s[18:19]
	v_lshl_add_u64 v[106:107], v[130:131], 2, v[106:107]
	global_store_dwordx4 v[106:107], v[126:129], off
	global_store_dwordx4 v[106:107], v[146:149], off offset:16

; DI u32x4 pk8(f32x4 a, f32x4 b) { u32x4 o; o.x = pk2(a.x, a.y); o.y = pk2(a.z, a.w); o.z = pk2(b.x, b.y); o.w = pk2(b.z, b.w); return o; }
; #define EPI_SCHED() __builtin_amdgcn_sched_barrier(0)
;     DI void operator()(const AccT& acc, const Unit& u, int wr, int wc, int fr, int fq) const {
;     ...
;             for (int m = 0; m < 4; ++m) {
;                 EPI_SCHED(); const size_t row = row0 + ai * 128 + m * 16;
;                 const size_t b = row >> 11, s = row & 2047;
; #pragma unroll
;                 for (int bj = 0; bj < 2; ++bj) {
;                     const int cc = bj * 128 + wc * 32 + fq * 8;
;                     f32x4 a = acc[ai][bj][m][0] * rs[ai][m], c = acc[ai][bj][m][1] * rs[ai][m];
;                     if (u.pn < 4) *(u32x4*)(q + row * 1024 + u.pn * 256 + cc) = pk8(a, c);
;                     else if (u.pn < 8) { const int g = cc >> 6, d = cc & 63; *(u32x4*)(slab + (size_t)(u.pn - 4) * SLAB_EL + ((b * 4 + g) * 2048 + s) * 64 + d) = pk8(a, c); }
.LBB0_1933:
	s_andn2_b64 vcc, exec, s[6:7]
	s_cbranch_vccnz .LBB0_1935
	v_ashrrev_i32_e32 v106, 6, v130
	v_ashrrev_i32_e32 v107, 31, v106
	s_add_u32 s0, s61, s34
	v_lshl_add_u64 v[106:107], s[48:49], 0, v[106:107]
	s_addc_u32 s1, s64, s35
	v_lshlrev_b64 v[106:107], 18, v[106:107]
	v_and_b32_e32 v117, 56, v130
	v_lshl_add_u64 v[106:107], s[0:1], 0, v[106:107]
	v_lshlrev_b32_e32 v0, 1, v122
	v_lshl_add_u64 v[106:107], v[106:107], 0, v[0:1]
	v_lshlrev_b32_e32 v0, 1, v117
	v_cvt_pk_bf16_f32 v126, v110, v111
	v_cvt_pk_bf16_f32 v127, v112, v113
	v_cvt_pk_bf16_f32 v128, v120, v121
	v_cvt_pk_bf16_f32 v129, v108, v109
	v_lshl_add_u64 v[106:107], v[106:107], 0, v[0:1]
	global_store_dwordx4 v[106:107], v[126:129], off

; DI u32x4 pk8(f32x4 a, f32x4 b) { u32x4 o; o.x = pk2(a.x, a.y); o.y = pk2(a.z, a.w); o.z = pk2(b.x, b.y); o.w = pk2(b.z, b.w); return o; }
; DI float sigmoidf_(float x) { return frcp(1.f + fexp2(-x * LOG2E)); }
; #define EPI_SCHED() __builtin_amdgcn_sched_barrier(0)
;     DI void operator()(const AccT& acc, const Unit& u, int wr, int wc, int fr, int fq) const {
;     ...
;             for (int m = 0; m < 4; ++m) {
;                 EPI_SCHED(); const size_t row = row0 + ai * 128 + m * 16;
;                 const size_t b = row >> 11, s = row & 2047;
; #pragma unroll
;                 for (int bj = 0; bj < 2; ++bj) {
;                     const int cc = bj * 128 + wc * 32 + fq * 8;
;                     f32x4 a = acc[ai][bj][m][0] * rs[ai][m], c = acc[ai][bj][m][1] * rs[ai][m];
;                     if (u.pn < 4) *(u32x4*)(q + row * 1024 + u.pn * 256 + cc) = pk8(a, c);
;                     else if (u.pn < 8) { const int g = cc >> 6, d = cc & 63; *(u32x4*)(slab + (size_t)(u.pn - 4) * SLAB_EL + ((b * 4 + g) * 2048 + s) * 64 + d) = pk8(a, c); }
;                     else if (cc < 48) {
; #pragma unroll
;                         for (int e = 0; e < 4; ++e) { a[e] = sigmoidf_(a[e]); c[e] = sigmoidf_(c[e]); }
;                         *(f32x4*)(gates + row * 48 + cc) = a; *(f32x4*)(gates + row * 48 + cc + 4) = c;
;                     }
.LBB0_1936:
	v_mov_b32_e32 v119, v157
	v_lshlrev_b64 v[106:107], 11, v[118:119]
	v_lshl_add_u64 v[106:107], s[16:17], 0, v[106:107]
	s_andn2_b64 vcc, exec, s[6:7]
	v_lshl_add_u64 v[106:107], s[36:37], 1, v[106:107]
	s_cbranch_vccnz .LBB0_1938
	v_cvt_pk_bf16_f32 v110, v110, v111
	v_cvt_pk_bf16_f32 v111, v112, v113
	v_cvt_pk_bf16_f32 v112, v120, v121
	v_cvt_pk_bf16_f32 v113, v108, v109
	v_lshl_add_u64 v[108:109], v[130:131], 1, v[106:107]
	global_store_dwordx4 v[108:109], v[110:113], off
.LBB0_1938:
	v_mov_b32_e32 v117, v116
	v_mov_b32_e32 v108, v116
	v_mov_b32_e32 v109, v116
	v_pk_mul_f32 v[104:105], v[104:105], v[108:109]
	v_pk_mul_f32 v[102:103], v[102:103], v[116:117]
	v_pk_mul_f32 v[100:101], v[100:101], v[108:109]
	v_pk_mul_f32 v[98:99], v[98:99], v[116:117]
	s_and_b64 vcc, exec, s[4:5]
	s_mov_b64 s[6:7], -1
	s_cbranch_vccnz .LBB0_1946
	s_and_b64 vcc, exec, s[2:3]
	s_cbranch_vccnz .LBB0_1943
	s_movk_i32 s0, 0xffb0
	v_cmp_gt_i32_e32 vcc, s0, v130
	s_and_saveexec_b64 s[6:7], vcc
	s_cbranch_execz .LBB0_1942
	v_mul_f32_e32 v0, 0xbfb8aa3b, v102
	v_exp_f32_e32 v0, v0
	v_mul_f32_e32 v108, 0xbfb8aa3b, v98
	v_exp_f32_e32 v108, v108
	v_mul_f32_e32 v110, 0xbfb8aa3b, v99
	v_add_f32_e32 v0, 1.0, v0
	v_exp_f32_e32 v110, v110
	v_add_f32_e32 v109, 1.0, v108
	v_rcp_f32_e32 v108, v0
	v_mul_f32_e32 v0, 0xbfb8aa3b, v103
	v_exp_f32_e32 v0, v0
	v_rcp_f32_e32 v116, v109
	v_mul_f32_e32 v111, 0xbfb8aa3b, v100
	v_exp_f32_e32 v111, v111
	v_add_f32_e32 v0, 1.0, v0
	v_rcp_f32_e32 v109, v0
	v_add_f32_e32 v0, 1.0, v110
	v_mul_f32_e32 v110, 0xbfb8aa3b, v104
	v_exp_f32_e32 v110, v110
	v_rcp_f32_e32 v117, v0
	v_mul_f32_e32 v112, 0xbfb8aa3b, v101
	v_exp_f32_e32 v112, v112
	v_add_f32_e32 v0, 1.0, v110
	v_rcp_f32_e32 v110, v0
	v_add_f32_e32 v0, 1.0, v111
	v_mul_f32_e32 v111, 0xbfb8aa3b, v105
	v_exp_f32_e32 v111, v111
	v_rcp_f32_e32 v118, v0
	v_add_f32_e32 v0, 1.0, v111
	v_rcp_f32_e32 v111, v0
	v_add_f32_e32 v0, 1.0, v112
	v_rcp_f32_e32 v119, v0
	v_lshl_add_u64 v[112:113], v[114:115], 2, s[18:19]
	v_lshl_add_u64 v[112:113], v[130:131], 2, v[112:113]
	global_store_dwordx4 v[112:113], v[108:111], off offset:512
	global_store_dwordx4 v[112:113], v[116:119], off offset:528

; DI u32x4 pk8(f32x4 a, f32x4 b) { u32x4 o; o.x = pk2(a.x, a.y); o.y = pk2(a.z, a.w); o.z = pk2(b.x, b.y); o.w = pk2(b.z, b.w); return o; }
; #define EPI_SCHED() __builtin_amdgcn_sched_barrier(0)
;     DI void operator()(const AccT& acc, const Unit& u, int wr, int wc, int fr, int fq) const {
;     ...
;             for (int m = 0; m < 4; ++m) {
;                 EPI_SCHED(); const size_t row = row0 + ai * 128 + m * 16;
;                 const size_t b = row >> 11, s = row & 2047;
; #pragma unroll
;                 for (int bj = 0; bj < 2; ++bj) {
;                     const int cc = bj * 128 + wc * 32 + fq * 8;
;                     f32x4 a = acc[ai][bj][m][0] * rs[ai][m], c = acc[ai][bj][m][1] * rs[ai][m];
;                     if (u.pn < 4) *(u32x4*)(q + row * 1024 + u.pn * 256 + cc) = pk8(a, c);
;                     else if (u.pn < 8) { const int g = cc >> 6, d = cc & 63; *(u32x4*)(slab + (size_t)(u.pn - 4) * SLAB_EL + ((b * 4 + g) * 2048 + s) * 64 + d) = pk8(a, c); }
.LBB0_1943:
	s_andn2_b64 vcc, exec, s[6:7]
	s_cbranch_vccnz .LBB0_1945
	v_ashrrev_i32_e32 v112, 6, v124
	v_ashrrev_i32_e32 v113, 31, v112
	s_add_u32 s0, s61, s34
	v_lshl_add_u64 v[112:113], s[48:49], 0, v[112:113]
	s_addc_u32 s1, s64, s35
	v_lshlrev_b64 v[112:113], 18, v[112:113]
	v_and_b32_e32 v116, 56, v130
	v_lshl_add_u64 v[112:113], s[0:1], 0, v[112:113]
	v_lshlrev_b32_e32 v0, 1, v122
	v_lshl_add_u64 v[112:113], v[112:113], 0, v[0:1]
	v_lshlrev_b32_e32 v0, 1, v116
	v_cvt_pk_bf16_f32 v108, v102, v103
	v_cvt_pk_bf16_f32 v109, v104, v105
	v_cvt_pk_bf16_f32 v110, v98, v99
	v_cvt_pk_bf16_f32 v111, v100, v101
	v_lshl_add_u64 v[112:113], v[112:113], 0, v[0:1]
	global_store_dwordx4 v[112:113], v[108:111], off

; DI u32x4 pk8(f32x4 a, f32x4 b) { u32x4 o; o.x = pk2(a.x, a.y); o.y = pk2(a.z, a.w); o.z = pk2(b.x, b.y); o.w = pk2(b.z, b.w); return o; }
; DI float sigmoidf_(float x) { return frcp(1.f + fexp2(-x * LOG2E)); }
; #define EPI_SCHED() __builtin_amdgcn_sched_barrier(0)
;     DI void operator()(const AccT& acc, const Unit& u, int wr, int wc, int fr, int fq) const {
;     ...
;             for (int m = 0; m < 4; ++m) {
;                 EPI_SCHED(); const size_t row = row0 + ai * 128 + m * 16;
;                 const size_t b = row >> 11, s = row & 2047;
; #pragma unroll
;                 for (int bj = 0; bj < 2; ++bj) {
;                     const int cc = bj * 128 + wc * 32 + fq * 8;
;                     f32x4 a = acc[ai][bj][m][0] * rs[ai][m], c = acc[ai][bj][m][1] * rs[ai][m];
;                     if (u.pn < 4) *(u32x4*)(q + row * 1024 + u.pn * 256 + cc) = pk8(a, c);
;                     else if (u.pn < 8) { const int g = cc >> 6, d = cc & 63; *(u32x4*)(slab + (size_t)(u.pn - 4) * SLAB_EL + ((b * 4 + g) * 2048 + s) * 64 + d) = pk8(a, c); }
;                     else if (cc < 48) {
; #pragma unroll
;                         for (int e = 0; e < 4; ++e) { a[e] = sigmoidf_(a[e]); c[e] = sigmoidf_(c[e]); }
;                         *(f32x4*)(gates + row * 48 + cc) = a; *(f32x4*)(gates + row * 48 + cc + 4) = c;
;                     }
.LBB0_1946:
	s_andn2_b64 vcc, exec, s[6:7]
	s_cbranch_vccnz .LBB0_1948
	v_cvt_pk_bf16_f32 v102, v102, v103
	v_cvt_pk_bf16_f32 v103, v104, v105
	v_cvt_pk_bf16_f32 v104, v98, v99
	v_cvt_pk_bf16_f32 v105, v100, v101
	v_lshl_add_u64 v[98:99], v[130:131], 1, v[106:107]
	global_store_dwordx4 v[98:99], v[102:105], off offset:256
.LBB0_1948:
	v_pk_add_f32 v[98:99], v[140:141], v[144:145]
	v_mov_b32_e32 v0, 0x358637bd
	v_pk_fma_f32 v[98:99], v[98:99], s[88:89], v[0:1] op_sel_hi:[1,0,0]
	s_nop 0
	v_mul_f32_e32 v0, 0x4b800000, v99
	v_cmp_gt_f32_e32 vcc, s42, v99
	v_cmp_gt_f32_e64 s[6:7], s42, v98
	s_nop 0
	v_cndmask_b32_e32 v0, v99, v0, vcc
	v_rsq_f32_e32 v0, v0
	s_nop 0
	v_mul_f32_e32 v99, 0x45800000, v0
	v_cndmask_b32_e32 v102, v0, v99, vcc
	v_or_b32_e32 v104, 32, v156
	s_mov_b64 s[0:1], 0x300
	v_lshlrev_b32_e32 v0, 6, v104
	v_lshl_add_u64 v[100:101], v[114:115], 0, s[0:1]
	v_and_b32_e32 v99, 0x1ffc0, v0
	v_pk_mul_f32 v[96:97], v[96:97], v[102:103] op_sel_hi:[1,0]
	v_pk_mul_f32 v[94:95], v[94:95], v[102:103] op_sel_hi:[1,0]
	v_pk_mul_f32 v[92:93], v[92:93], v[102:103] op_sel_hi:[1,0]
	v_pk_mul_f32 v[106:107], v[90:91], v[102:103] op_sel_hi:[1,0]
	s_and_b64 vcc, exec, s[4:5]
	s_mov_b64 s[38:39], -1
	s_cbranch_vccnz .LBB0_1956
	s_and_b64 vcc, exec, s[2:3]
	s_cbranch_vccnz .LBB0_1953
	v_cmp_gt_i32_e32 vcc, 48, v130
	s_and_saveexec_b64 s[38:39], vcc
	s_cbranch_execz .LBB0_1952
	v_mul_f32_e32 v0, 0xbfb8aa3b, v94
	v_exp_f32_e32 v0, v0
	v_mul_f32_e32 v90, 0xbfb8aa3b, v106
	v_exp_f32_e32 v90, v90
	v_mul_f32_e32 v91, 0xbfb8aa3b, v107
	v_add_f32_e32 v0, 1.0, v0
	v_rcp_f32_e32 v108, v0
	v_mul_f32_e32 v0, 0xbfb8aa3b, v95
	v_exp_f32_e32 v0, v0
	v_exp_f32_e32 v91, v91
	v_add_f32_e32 v90, 1.0, v90
	v_rcp_f32_e32 v112, v90
	v_add_f32_e32 v0, 1.0, v0
	v_mul_f32_e32 v90, 0xbfb8aa3b, v96
	v_rcp_f32_e32 v109, v0
	v_add_f32_e32 v0, 1.0, v91
	v_exp_f32_e32 v90, v90
	v_mul_f32_e32 v91, 0xbfb8aa3b, v92
	v_exp_f32_e32 v91, v91
	v_rcp_f32_e32 v113, v0
	v_add_f32_e32 v0, 1.0, v90
	v_mul_f32_e32 v90, 0xbfb8aa3b, v97
	v_rcp_f32_e32 v110, v0
	v_add_f32_e32 v0, 1.0, v91
	v_exp_f32_e32 v90, v90
	v_mul_f32_e32 v91, 0xbfb8aa3b, v93
	v_exp_f32_e32 v91, v91
	v_rcp_f32_e32 v114, v0
	v_add_f32_e32 v0, 1.0, v90
	v_rcp_f32_e32 v111, v0
	v_add_f32_e32 v0, 1.0, v91
	v_rcp_f32_e32 v115, v0
	v_lshl_add_u64 v[90:91], v[100:101], 2, s[18:19]
	v_lshl_add_u64 v[90:91], v[130:131], 2, v[90:91]
	global_store_dwordx4 v[90:91], v[108:111], off
	global_store_dwordx4 v[90:91], v[112:115], off offset:16

; DI u32x4 pk8(f32x4 a, f32x4 b) { u32x4 o; o.x = pk2(a.x, a.y); o.y = pk2(a.z, a.w); o.z = pk2(b.x, b.y); o.w = pk2(b.z, b.w); return o; }
; #define EPI_SCHED() __builtin_amdgcn_sched_barrier(0)
;     DI void operator()(const AccT& acc, const Unit& u, int wr, int wc, int fr, int fq) const {
;     ...
;             for (int m = 0; m < 4; ++m) {
;                 EPI_SCHED(); const size_t row = row0 + ai * 128 + m * 16;
;                 const size_t b = row >> 11, s = row & 2047;
; #pragma unroll
;                 for (int bj = 0; bj < 2; ++bj) {
;                     const int cc = bj * 128 + wc * 32 + fq * 8;
;                     f32x4 a = acc[ai][bj][m][0] * rs[ai][m], c = acc[ai][bj][m][1] * rs[ai][m];
;                     if (u.pn < 4) *(u32x4*)(q + row * 1024 + u.pn * 256 + cc) = pk8(a, c);
;                     else if (u.pn < 8) { const int g = cc >> 6, d = cc & 63; *(u32x4*)(slab + (size_t)(u.pn - 4) * SLAB_EL + ((b * 4 + g) * 2048 + s) * 64 + d) = pk8(a, c); }
.LBB0_1953:
	s_andn2_b64 vcc, exec, s[38:39]
	s_cbranch_vccnz .LBB0_1955
	v_ashrrev_i32_e32 v90, 6, v130
	v_ashrrev_i32_e32 v91, 31, v90
	s_add_u32 s0, s61, s34
	v_lshl_add_u64 v[90:91], s[48:49], 0, v[90:91]
	s_addc_u32 s1, s64, s35
	v_lshlrev_b64 v[90:91], 18, v[90:91]
	v_and_b32_e32 v103, 56, v130
	v_lshl_add_u64 v[90:91], s[0:1], 0, v[90:91]
	v_lshlrev_b32_e32 v0, 1, v99
	v_lshl_add_u64 v[90:91], v[90:91], 0, v[0:1]
	v_lshlrev_b32_e32 v0, 1, v103
	v_cvt_pk_bf16_f32 v108, v94, v95
	v_cvt_pk_bf16_f32 v109, v96, v97
	v_cvt_pk_bf16_f32 v110, v106, v107
	v_cvt_pk_bf16_f32 v111, v92, v93
	v_lshl_add_u64 v[90:91], v[90:91], 0, v[0:1]
	global_store_dwordx4 v[90:91], v[108:111], off

; DI u32x4 pk8(f32x4 a, f32x4 b) { u32x4 o; o.x = pk2(a.x, a.y); o.y = pk2(a.z, a.w); o.z = pk2(b.x, b.y); o.w = pk2(b.z, b.w); return o; }
; DI float sigmoidf_(float x) { return frcp(1.f + fexp2(-x * LOG2E)); }
; #define EPI_SCHED() __builtin_amdgcn_sched_barrier(0)
;     DI void operator()(const AccT& acc, const Unit& u, int wr, int wc, int fr, int fq) const {
;     ...
;             for (int m = 0; m < 4; ++m) {
;                 EPI_SCHED(); const size_t row = row0 + ai * 128 + m * 16;
;                 const size_t b = row >> 11, s = row & 2047;
; #pragma unroll
;                 for (int bj = 0; bj < 2; ++bj) {
;                     const int cc = bj * 128 + wc * 32 + fq * 8;
;                     f32x4 a = acc[ai][bj][m][0] * rs[ai][m], c = acc[ai][bj][m][1] * rs[ai][m];
;                     if (u.pn < 4) *(u32x4*)(q + row * 1024 + u.pn * 256 + cc) = pk8(a, c);
;                     else if (u.pn < 8) { const int g = cc >> 6, d = cc & 63; *(u32x4*)(slab + (size_t)(u.pn - 4) * SLAB_EL + ((b * 4 + g) * 2048 + s) * 64 + d) = pk8(a, c); }
;                     else if (cc < 48) {
; #pragma unroll
;                         for (int e = 0; e < 4; ++e) { a[e] = sigmoidf_(a[e]); c[e] = sigmoidf_(c[e]); }
;                         *(f32x4*)(gates + row * 48 + cc) = a; *(f32x4*)(gates + row * 48 + cc + 4) = c;
;                     }
.LBB0_1956:
	v_mov_b32_e32 v105, v157
	v_lshlrev_b64 v[90:91], 11, v[104:105]
	v_lshl_add_u64 v[90:91], s[16:17], 0, v[90:91]
	s_andn2_b64 vcc, exec, s[38:39]
	v_lshl_add_u64 v[90:91], s[36:37], 1, v[90:91]
	s_cbranch_vccnz .LBB0_1958
	v_cvt_pk_bf16_f32 v94, v94, v95
	v_cvt_pk_bf16_f32 v95, v96, v97
	v_cvt_pk_bf16_f32 v96, v106, v107
	v_cvt_pk_bf16_f32 v97, v92, v93
	v_lshl_add_u64 v[92:93], v[130:131], 1, v[90:91]
	global_store_dwordx4 v[92:93], v[94:97], off
.LBB0_1958:
	v_mov_b32_e32 v103, v102
	v_mov_b32_e32 v92, v102
	v_mov_b32_e32 v93, v102
	v_pk_mul_f32 v[88:89], v[88:89], v[92:93]
	v_pk_mul_f32 v[86:87], v[86:87], v[102:103]
	v_pk_mul_f32 v[84:85], v[84:85], v[92:93]
	v_pk_mul_f32 v[82:83], v[82:83], v[102:103]
	s_and_b64 vcc, exec, s[4:5]
	s_mov_b64 s[38:39], -1
	s_cbranch_vccnz .LBB0_1966
	s_and_b64 vcc, exec, s[2:3]
	s_cbranch_vccnz .LBB0_1963
	s_movk_i32 s0, 0xffb0
	v_cmp_gt_i32_e32 vcc, s0, v130
	s_and_saveexec_b64 s[38:39], vcc
	s_cbranch_execz .LBB0_1962
	v_mul_f32_e32 v0, 0xbfb8aa3b, v86
	v_exp_f32_e32 v0, v0
	v_mul_f32_e32 v92, 0xbfb8aa3b, v82
	v_exp_f32_e32 v92, v92
	v_mul_f32_e32 v94, 0xbfb8aa3b, v83
	v_add_f32_e32 v0, 1.0, v0
	v_exp_f32_e32 v94, v94
	v_add_f32_e32 v93, 1.0, v92
	v_rcp_f32_e32 v92, v0
	v_mul_f32_e32 v0, 0xbfb8aa3b, v87
	v_exp_f32_e32 v0, v0
	v_rcp_f32_e32 v102, v93
	v_mul_f32_e32 v95, 0xbfb8aa3b, v84
	v_exp_f32_e32 v95, v95
	v_add_f32_e32 v0, 1.0, v0
	v_rcp_f32_e32 v93, v0
	v_add_f32_e32 v0, 1.0, v94
	v_mul_f32_e32 v94, 0xbfb8aa3b, v88
	v_exp_f32_e32 v94, v94
	v_rcp_f32_e32 v103, v0
	v_mul_f32_e32 v96, 0xbfb8aa3b, v85
	v_exp_f32_e32 v96, v96
	v_add_f32_e32 v0, 1.0, v94
	v_rcp_f32_e32 v94, v0
	v_add_f32_e32 v0, 1.0, v95
	v_mul_f32_e32 v95, 0xbfb8aa3b, v89
	v_exp_f32_e32 v95, v95
	v_rcp_f32_e32 v104, v0
	v_add_f32_e32 v0, 1.0, v95
	v_rcp_f32_e32 v95, v0
	v_add_f32_e32 v0, 1.0, v96
	v_rcp_f32_e32 v105, v0
	v_lshl_add_u64 v[96:97], v[100:101], 2, s[18:19]
	v_lshl_add_u64 v[96:97], v[130:131], 2, v[96:97]
	global_store_dwordx4 v[96:97], v[92:95], off offset:512
	global_store_dwordx4 v[96:97], v[102:105], off offset:528

; DI u32x4 pk8(f32x4 a, f32x4 b) { u32x4 o; o.x = pk2(a.x, a.y); o.y = pk2(a.z, a.w); o.z = pk2(b.x, b.y); o.w = pk2(b.z, b.w); return o; }
; #define EPI_SCHED() __builtin_amdgcn_sched_barrier(0)
;     DI void operator()(const AccT& acc, const Unit& u, int wr, int wc, int fr, int fq) const {
;     ...
;             for (int m = 0; m < 4; ++m) {
;                 EPI_SCHED(); const size_t row = row0 + ai * 128 + m * 16;
;                 const size_t b = row >> 11, s = row & 2047;
; #pragma unroll
;                 for (int bj = 0; bj < 2; ++bj) {
;                     const int cc = bj * 128 + wc * 32 + fq * 8;
;                     f32x4 a = acc[ai][bj][m][0] * rs[ai][m], c = acc[ai][bj][m][1] * rs[ai][m];
;                     if (u.pn < 4) *(u32x4*)(q + row * 1024 + u.pn * 256 + cc) = pk8(a, c);
;                     else if (u.pn < 8) { const int g = cc >> 6, d = cc & 63; *(u32x4*)(slab + (size_t)(u.pn - 4) * SLAB_EL + ((b * 4 + g) * 2048 + s) * 64 + d) = pk8(a, c); }
.LBB0_1963:
	s_andn2_b64 vcc, exec, s[38:39]
	s_cbranch_vccnz .LBB0_1965
	v_ashrrev_i32_e32 v96, 6, v124
	v_ashrrev_i32_e32 v97, 31, v96
	s_add_u32 s0, s61, s34
	v_lshl_add_u64 v[96:97], s[48:49], 0, v[96:97]
	s_addc_u32 s1, s64, s35
	v_lshlrev_b64 v[96:97], 18, v[96:97]
	v_and_b32_e32 v102, 56, v130
	v_lshl_add_u64 v[96:97], s[0:1], 0, v[96:97]
	v_lshlrev_b32_e32 v0, 1, v99
	v_lshl_add_u64 v[96:97], v[96:97], 0, v[0:1]
	v_lshlrev_b32_e32 v0, 1, v102
	v_cvt_pk_bf16_f32 v92, v86, v87
	v_cvt_pk_bf16_f32 v93, v88, v89
	v_cvt_pk_bf16_f32 v94, v82, v83
	v_cvt_pk_bf16_f32 v95, v84, v85
	v_lshl_add_u64 v[96:97], v[96:97], 0, v[0:1]
	global_store_dwordx4 v[96:97], v[92:95], off

; DI u32x4 pk8(f32x4 a, f32x4 b) { u32x4 o; o.x = pk2(a.x, a.y); o.y = pk2(a.z, a.w); o.z = pk2(b.x, b.y); o.w = pk2(b.z, b.w); return o; }
; DI float sigmoidf_(float x) { return frcp(1.f + fexp2(-x * LOG2E)); }
; #define EPI_SCHED() __builtin_amdgcn_sched_barrier(0)
;     DI void operator()(const AccT& acc, const Unit& u, int wr, int wc, int fr, int fq) const {
;     ...
;             for (int m = 0; m < 4; ++m) {
;                 EPI_SCHED(); const size_t row = row0 + ai * 128 + m * 16;
;                 const size_t b = row >> 11, s = row & 2047;
; #pragma unroll
;                 for (int bj = 0; bj < 2; ++bj) {
;                     const int cc = bj * 128 + wc * 32 + fq * 8;
;                     f32x4 a = acc[ai][bj][m][0] * rs[ai][m], c = acc[ai][bj][m][1] * rs[ai][m];
;                     if (u.pn < 4) *(u32x4*)(q + row * 1024 + u.pn * 256 + cc) = pk8(a, c);
;                     else if (u.pn < 8) { const int g = cc >> 6, d = cc & 63; *(u32x4*)(slab + (size_t)(u.pn - 4) * SLAB_EL + ((b * 4 + g) * 2048 + s) * 64 + d) = pk8(a, c); }
;                     else if (cc < 48) {
; #pragma unroll
;                         for (int e = 0; e < 4; ++e) { a[e] = sigmoidf_(a[e]); c[e] = sigmoidf_(c[e]); }
;                         *(f32x4*)(gates + row * 48 + cc) = a; *(f32x4*)(gates + row * 48 + cc + 4) = c;
;                     }
.LBB0_1966:
	s_andn2_b64 vcc, exec, s[38:39]
	s_cbranch_vccnz .LBB0_1968
	v_cvt_pk_bf16_f32 v86, v86, v87
	v_cvt_pk_bf16_f32 v87, v88, v89
	v_cvt_pk_bf16_f32 v88, v82, v83
	v_cvt_pk_bf16_f32 v89, v84, v85
	v_lshl_add_u64 v[82:83], v[130:131], 1, v[90:91]
	global_store_dwordx4 v[82:83], v[86:89], off offset:256
.LBB0_1968:
	v_mul_f32_e32 v0, 0x4b800000, v98
	v_cndmask_b32_e64 v0, v98, v0, s[6:7]
	v_rsq_f32_e32 v0, v0
	s_nop 0
	v_mul_f32_e32 v82, 0x45800000, v0
	v_cndmask_b32_e64 v84, v0, v82, s[6:7]
	v_or_b32_e32 v86, 48, v156
	s_mov_b64 s[0:1], 0x300
	v_lshlrev_b32_e32 v0, 6, v86
	v_lshl_add_u64 v[82:83], v[100:101], 0, s[0:1]
	v_and_b32_e32 v90, 0x1ffc0, v0
	v_pk_mul_f32 v[80:81], v[80:81], v[84:85] op_sel_hi:[1,0]
	v_pk_mul_f32 v[78:79], v[78:79], v[84:85] op_sel_hi:[1,0]
	v_pk_mul_f32 v[76:77], v[76:77], v[84:85] op_sel_hi:[1,0]
	v_pk_mul_f32 v[88:89], v[74:75], v[84:85] op_sel_hi:[1,0]
	s_and_b64 vcc, exec, s[4:5]
	s_mov_b64 s[6:7], -1
	s_cbranch_vccnz .LBB0_1976
	s_and_b64 vcc, exec, s[2:3]
	s_cbranch_vccnz .LBB0_1973
	v_cmp_gt_i32_e32 vcc, 48, v130
	s_and_saveexec_b64 s[6:7], vcc
	s_cbranch_execz .LBB0_1972
	v_mul_f32_e32 v0, 0xbfb8aa3b, v78
	v_exp_f32_e32 v0, v0
	v_mul_f32_e32 v74, 0xbfb8aa3b, v88
	v_exp_f32_e32 v74, v74
	v_mul_f32_e32 v75, 0xbfb8aa3b, v89
	v_add_f32_e32 v0, 1.0, v0
	v_rcp_f32_e32 v92, v0
	v_mul_f32_e32 v0, 0xbfb8aa3b, v79
	v_exp_f32_e32 v0, v0
	v_exp_f32_e32 v75, v75
	v_add_f32_e32 v74, 1.0, v74
	v_rcp_f32_e32 v96, v74
	v_add_f32_e32 v0, 1.0, v0
	v_mul_f32_e32 v74, 0xbfb8aa3b, v80
	v_rcp_f32_e32 v93, v0
	v_add_f32_e32 v0, 1.0, v75
	v_exp_f32_e32 v74, v74
	v_mul_f32_e32 v75, 0xbfb8aa3b, v76
	v_exp_f32_e32 v75, v75
	v_rcp_f32_e32 v97, v0
	v_add_f32_e32 v0, 1.0, v74
	v_mul_f32_e32 v74, 0xbfb8aa3b, v81
	v_rcp_f32_e32 v94, v0
	v_add_f32_e32 v0, 1.0, v75
	v_exp_f32_e32 v74, v74
	v_mul_f32_e32 v75, 0xbfb8aa3b, v77
	v_exp_f32_e32 v75, v75
	v_rcp_f32_e32 v98, v0
	v_add_f32_e32 v0, 1.0, v74
	v_rcp_f32_e32 v95, v0
	v_add_f32_e32 v0, 1.0, v75
	v_rcp_f32_e32 v99, v0
	v_lshl_add_u64 v[74:75], v[82:83], 2, s[18:19]
	v_lshl_add_u64 v[74:75], v[130:131], 2, v[74:75]
	global_store_dwordx4 v[74:75], v[92:95], off
	global_store_dwordx4 v[74:75], v[96:99], off offset:16

; DI u32x4 pk8(f32x4 a, f32x4 b) { u32x4 o; o.x = pk2(a.x, a.y); o.y = pk2(a.z, a.w); o.z = pk2(b.x, b.y); o.w = pk2(b.z, b.w); return o; }
; #define EPI_SCHED() __builtin_amdgcn_sched_barrier(0)
;     DI void operator()(const AccT& acc, const Unit& u, int wr, int wc, int fr, int fq) const {
;     ...
;             for (int m = 0; m < 4; ++m) {
;                 EPI_SCHED(); const size_t row = row0 + ai * 128 + m * 16;
;                 const size_t b = row >> 11, s = row & 2047;
; #pragma unroll
;                 for (int bj = 0; bj < 2; ++bj) {
;                     const int cc = bj * 128 + wc * 32 + fq * 8;
;                     f32x4 a = acc[ai][bj][m][0] * rs[ai][m], c = acc[ai][bj][m][1] * rs[ai][m];
;                     if (u.pn < 4) *(u32x4*)(q + row * 1024 + u.pn * 256 + cc) = pk8(a, c);
;                     else if (u.pn < 8) { const int g = cc >> 6, d = cc & 63; *(u32x4*)(slab + (size_t)(u.pn - 4) * SLAB_EL + ((b * 4 + g) * 2048 + s) * 64 + d) = pk8(a, c); }
.LBB0_1973:
	s_andn2_b64 vcc, exec, s[6:7]
	s_cbranch_vccnz .LBB0_1975
	v_ashrrev_i32_e32 v74, 6, v130
	v_ashrrev_i32_e32 v75, 31, v74
	s_add_u32 s0, s61, s34
	v_lshl_add_u64 v[74:75], s[48:49], 0, v[74:75]
	s_addc_u32 s1, s64, s35
	v_lshlrev_b64 v[74:75], 18, v[74:75]
	v_and_b32_e32 v85, 56, v130
	v_lshl_add_u64 v[74:75], s[0:1], 0, v[74:75]
	v_lshlrev_b32_e32 v0, 1, v90
	v_lshl_add_u64 v[74:75], v[74:75], 0, v[0:1]
	v_lshlrev_b32_e32 v0, 1, v85
	v_cvt_pk_bf16_f32 v92, v78, v79
	v_cvt_pk_bf16_f32 v93, v80, v81
	v_cvt_pk_bf16_f32 v94, v88, v89
	v_cvt_pk_bf16_f32 v95, v76, v77
	v_lshl_add_u64 v[74:75], v[74:75], 0, v[0:1]
	global_store_dwordx4 v[74:75], v[92:95], off

; DI u32x4 pk8(f32x4 a, f32x4 b) { u32x4 o; o.x = pk2(a.x, a.y); o.y = pk2(a.z, a.w); o.z = pk2(b.x, b.y); o.w = pk2(b.z, b.w); return o; }
; DI float sigmoidf_(float x) { return frcp(1.f + fexp2(-x * LOG2E)); }
; #define EPI_SCHED() __builtin_amdgcn_sched_barrier(0)
;     DI void operator()(const AccT& acc, const Unit& u, int wr, int wc, int fr, int fq) const {
;     ...
;             for (int m = 0; m < 4; ++m) {
;                 EPI_SCHED(); const size_t row = row0 + ai * 128 + m * 16;
;                 const size_t b = row >> 11, s = row & 2047;
; #pragma unroll
;                 for (int bj = 0; bj < 2; ++bj) {
;                     const int cc = bj * 128 + wc * 32 + fq * 8;
;                     f32x4 a = acc[ai][bj][m][0] * rs[ai][m], c = acc[ai][bj][m][1] * rs[ai][m];
;                     if (u.pn < 4) *(u32x4*)(q + row * 1024 + u.pn * 256 + cc) = pk8(a, c);
;                     else if (u.pn < 8) { const int g = cc >> 6, d = cc & 63; *(u32x4*)(slab + (size_t)(u.pn - 4) * SLAB_EL + ((b * 4 + g) * 2048 + s) * 64 + d) = pk8(a, c); }
;                     else if (cc < 48) {
; #pragma unroll
;                         for (int e = 0; e < 4; ++e) { a[e] = sigmoidf_(a[e]); c[e] = sigmoidf_(c[e]); }
;                         *(f32x4*)(gates + row * 48 + cc) = a; *(f32x4*)(gates + row * 48 + cc + 4) = c;
;                     }
.LBB0_1976:
	v_mov_b32_e32 v87, v157
	v_lshlrev_b64 v[74:75], 11, v[86:87]
	v_lshl_add_u64 v[74:75], s[16:17], 0, v[74:75]
	s_andn2_b64 vcc, exec, s[6:7]
	v_lshl_add_u64 v[74:75], s[36:37], 1, v[74:75]
	s_cbranch_vccnz .LBB0_1978
	v_cvt_pk_bf16_f32 v78, v78, v79
	v_cvt_pk_bf16_f32 v79, v80, v81
	v_cvt_pk_bf16_f32 v80, v88, v89
	v_cvt_pk_bf16_f32 v81, v76, v77
	v_lshl_add_u64 v[76:77], v[130:131], 1, v[74:75]
	global_store_dwordx4 v[76:77], v[78:81], off
.LBB0_1978:
	v_mov_b32_e32 v85, v84
	v_mov_b32_e32 v76, v84
	v_mov_b32_e32 v77, v84
	v_pk_mul_f32 v[72:73], v[72:73], v[76:77]
	v_pk_mul_f32 v[70:71], v[70:71], v[84:85]
	v_pk_mul_f32 v[68:69], v[68:69], v[76:77]
	v_pk_mul_f32 v[66:67], v[66:67], v[84:85]
	s_and_b64 vcc, exec, s[4:5]
	s_mov_b64 s[6:7], -1
	s_cbranch_vccnz .LBB0_1986
	s_and_b64 vcc, exec, s[2:3]
	s_cbranch_vccnz .LBB0_1983
	s_movk_i32 s0, 0xffb0
	v_cmp_gt_i32_e32 vcc, s0, v130
	s_and_saveexec_b64 s[6:7], vcc
	s_cbranch_execz .LBB0_1982
	v_mul_f32_e32 v0, 0xbfb8aa3b, v70
	v_exp_f32_e32 v0, v0
	v_mul_f32_e32 v76, 0xbfb8aa3b, v66
	v_exp_f32_e32 v76, v76
	v_mul_f32_e32 v78, 0xbfb8aa3b, v67
	v_add_f32_e32 v0, 1.0, v0
	v_exp_f32_e32 v78, v78
	v_add_f32_e32 v77, 1.0, v76
	v_rcp_f32_e32 v76, v0
	v_mul_f32_e32 v0, 0xbfb8aa3b, v71
	v_exp_f32_e32 v0, v0
	v_rcp_f32_e32 v84, v77
	v_mul_f32_e32 v79, 0xbfb8aa3b, v68
	v_exp_f32_e32 v79, v79
	v_add_f32_e32 v0, 1.0, v0
	v_rcp_f32_e32 v77, v0
	v_add_f32_e32 v0, 1.0, v78
	v_mul_f32_e32 v78, 0xbfb8aa3b, v72
	v_exp_f32_e32 v78, v78
	v_rcp_f32_e32 v85, v0
	v_mul_f32_e32 v80, 0xbfb8aa3b, v69
	v_exp_f32_e32 v80, v80
	v_add_f32_e32 v0, 1.0, v78
	v_rcp_f32_e32 v78, v0
	v_add_f32_e32 v0, 1.0, v79
	v_mul_f32_e32 v79, 0xbfb8aa3b, v73
	v_exp_f32_e32 v79, v79
	v_rcp_f32_e32 v86, v0
	v_add_f32_e32 v0, 1.0, v79
	v_rcp_f32_e32 v79, v0
	v_add_f32_e32 v0, 1.0, v80
	v_rcp_f32_e32 v87, v0
	v_lshl_add_u64 v[80:81], v[82:83], 2, s[18:19]
	v_lshl_add_u64 v[80:81], v[130:131], 2, v[80:81]
	global_store_dwordx4 v[80:81], v[76:79], off offset:512
	global_store_dwordx4 v[80:81], v[84:87], off offset:528

; DI u32x4 pk8(f32x4 a, f32x4 b) { u32x4 o; o.x = pk2(a.x, a.y); o.y = pk2(a.z, a.w); o.z = pk2(b.x, b.y); o.w = pk2(b.z, b.w); return o; }
; #define EPI_SCHED() __builtin_amdgcn_sched_barrier(0)
;     DI void operator()(const AccT& acc, const Unit& u, int wr, int wc, int fr, int fq) const {
;     ...
;             for (int m = 0; m < 4; ++m) {
;                 EPI_SCHED(); const size_t row = row0 + ai * 128 + m * 16;
;                 const size_t b = row >> 11, s = row & 2047;
; #pragma unroll
;                 for (int bj = 0; bj < 2; ++bj) {
;                     const int cc = bj * 128 + wc * 32 + fq * 8;
;                     f32x4 a = acc[ai][bj][m][0] * rs[ai][m], c = acc[ai][bj][m][1] * rs[ai][m];
;                     if (u.pn < 4) *(u32x4*)(q + row * 1024 + u.pn * 256 + cc) = pk8(a, c);
;                     else if (u.pn < 8) { const int g = cc >> 6, d = cc & 63; *(u32x4*)(slab + (size_t)(u.pn - 4) * SLAB_EL + ((b * 4 + g) * 2048 + s) * 64 + d) = pk8(a, c); }
.LBB0_1983:
	s_andn2_b64 vcc, exec, s[6:7]
	s_cbranch_vccnz .LBB0_1985
	v_ashrrev_i32_e32 v80, 6, v124
	v_ashrrev_i32_e32 v81, 31, v80
	s_add_u32 s0, s61, s34
	v_lshl_add_u64 v[80:81], s[48:49], 0, v[80:81]
	s_addc_u32 s1, s64, s35
	v_lshlrev_b64 v[80:81], 18, v[80:81]
	v_and_b32_e32 v84, 56, v130
	v_lshl_add_u64 v[80:81], s[0:1], 0, v[80:81]
	v_lshlrev_b32_e32 v0, 1, v90
	v_lshl_add_u64 v[80:81], v[80:81], 0, v[0:1]
	v_lshlrev_b32_e32 v0, 1, v84
	v_cvt_pk_bf16_f32 v76, v70, v71
	v_cvt_pk_bf16_f32 v77, v72, v73
	v_cvt_pk_bf16_f32 v78, v66, v67
	v_cvt_pk_bf16_f32 v79, v68, v69
	v_lshl_add_u64 v[80:81], v[80:81], 0, v[0:1]
	global_store_dwordx4 v[80:81], v[76:79], off

; DI u32x4 pk8(f32x4 a, f32x4 b) { u32x4 o; o.x = pk2(a.x, a.y); o.y = pk2(a.z, a.w); o.z = pk2(b.x, b.y); o.w = pk2(b.z, b.w); return o; }
; DI float sigmoidf_(float x) { return frcp(1.f + fexp2(-x * LOG2E)); }
; #define EPI_SCHED() __builtin_amdgcn_sched_barrier(0)
;     DI void operator()(const AccT& acc, const Unit& u, int wr, int wc, int fr, int fq) const {
;     ...
;             for (int m = 0; m < 4; ++m) {
;                 EPI_SCHED(); const size_t row = row0 + ai * 128 + m * 16;
;                 const size_t b = row >> 11, s = row & 2047;
; #pragma unroll
;                 for (int bj = 0; bj < 2; ++bj) {
;                     const int cc = bj * 128 + wc * 32 + fq * 8;
;                     f32x4 a = acc[ai][bj][m][0] * rs[ai][m], c = acc[ai][bj][m][1] * rs[ai][m];
;                     if (u.pn < 4) *(u32x4*)(q + row * 1024 + u.pn * 256 + cc) = pk8(a, c);
;                     else if (u.pn < 8) { const int g = cc >> 6, d = cc & 63; *(u32x4*)(slab + (size_t)(u.pn - 4) * SLAB_EL + ((b * 4 + g) * 2048 + s) * 64 + d) = pk8(a, c); }
;                     else if (cc < 48) {
; #pragma unroll
;                         for (int e = 0; e < 4; ++e) { a[e] = sigmoidf_(a[e]); c[e] = sigmoidf_(c[e]); }
;                         *(f32x4*)(gates + row * 48 + cc) = a; *(f32x4*)(gates + row * 48 + cc + 4) = c;
;                     }
.LBB0_1986:
	s_andn2_b64 vcc, exec, s[6:7]
	s_cbranch_vccnz .LBB0_1988
	v_cvt_pk_bf16_f32 v70, v70, v71
	v_cvt_pk_bf16_f32 v71, v72, v73
	v_cvt_pk_bf16_f32 v72, v66, v67
	v_cvt_pk_bf16_f32 v73, v68, v69
	v_lshl_add_u64 v[66:67], v[130:131], 1, v[74:75]
	global_store_dwordx4 v[66:67], v[70:73], off offset:256
.LBB0_1988:
	s_waitcnt lgkmcnt(0)
	v_pk_add_f32 v[66:67], v[136:137], v[138:139]
	v_mov_b32_e32 v0, 0x358637bd
	v_pk_fma_f32 v[70:71], v[66:67], s[88:89], v[0:1] op_sel_hi:[1,0,0]
	v_lshl_add_u64 v[68:69], v[156:157], 0, s[58:59]
	v_mul_f32_e32 v0, 0x4b800000, v71
	v_cmp_gt_f32_e32 vcc, s42, v71
	v_cmp_gt_f32_e64 s[6:7], s42, v70
	s_nop 0
	v_cndmask_b32_e32 v0, v71, v0, vcc
	v_rsq_f32_e32 v0, v0
	s_nop 0
	v_mul_f32_e32 v66, 0x45800000, v0
	v_cndmask_b32_e32 v74, v0, v66, vcc
	v_lshrrev_b64 v[66:67], 9, v[68:69]
	v_and_b32_e32 v67, 0x3fff, v67
	v_and_b32_e32 v66, -4, v66
	s_mov_b64 s[0:1], 0xf00
	v_lshlrev_b32_e32 v0, 6, v68
	v_lshl_add_u64 v[72:73], v[82:83], 0, s[0:1]
	v_and_b32_e32 v71, 0x1ffc0, v0
	v_pk_mul_f32 v[64:65], v[64:65], v[74:75] op_sel_hi:[1,0]
	v_pk_mul_f32 v[62:63], v[62:63], v[74:75] op_sel_hi:[1,0]
	v_pk_mul_f32 v[60:61], v[60:61], v[74:75] op_sel_hi:[1,0]
	v_pk_mul_f32 v[76:77], v[58:59], v[74:75] op_sel_hi:[1,0]
	s_and_b64 vcc, exec, s[4:5]
	s_mov_b64 s[38:39], -1
	s_cbranch_vccnz .LBB0_1996
	s_and_b64 vcc, exec, s[2:3]
	s_cbranch_vccnz .LBB0_1993
	v_cmp_gt_i32_e32 vcc, 48, v130
	s_and_saveexec_b64 s[38:39], vcc
	s_cbranch_execz .LBB0_1992
	v_mul_f32_e32 v0, 0xbfb8aa3b, v62
	v_exp_f32_e32 v0, v0
	v_mul_f32_e32 v58, 0xbfb8aa3b, v76
	v_exp_f32_e32 v58, v58
	v_mul_f32_e32 v59, 0xbfb8aa3b, v77
	v_add_f32_e32 v0, 1.0, v0
	v_rcp_f32_e32 v78, v0
	v_mul_f32_e32 v0, 0xbfb8aa3b, v63
	v_exp_f32_e32 v0, v0
	v_exp_f32_e32 v59, v59
	v_add_f32_e32 v58, 1.0, v58
	v_rcp_f32_e32 v82, v58
	v_add_f32_e32 v0, 1.0, v0
	v_mul_f32_e32 v58, 0xbfb8aa3b, v64
	v_rcp_f32_e32 v79, v0
	v_add_f32_e32 v0, 1.0, v59
	v_exp_f32_e32 v58, v58
	v_mul_f32_e32 v59, 0xbfb8aa3b, v60
	v_exp_f32_e32 v59, v59
	v_rcp_f32_e32 v83, v0
	v_add_f32_e32 v0, 1.0, v58
	v_mul_f32_e32 v58, 0xbfb8aa3b, v65
	v_rcp_f32_e32 v80, v0
	v_add_f32_e32 v0, 1.0, v59
	v_exp_f32_e32 v58, v58
	v_mul_f32_e32 v59, 0xbfb8aa3b, v61
	v_exp_f32_e32 v59, v59
	v_rcp_f32_e32 v84, v0
	v_add_f32_e32 v0, 1.0, v58
	v_rcp_f32_e32 v81, v0
	v_add_f32_e32 v0, 1.0, v59
	v_rcp_f32_e32 v85, v0
	v_lshl_add_u64 v[58:59], v[72:73], 2, s[18:19]
	v_lshl_add_u64 v[58:59], v[130:131], 2, v[58:59]
	global_store_dwordx4 v[58:59], v[78:81], off
	global_store_dwordx4 v[58:59], v[82:85], off offset:16

; DI u32x4 pk8(f32x4 a, f32x4 b) { u32x4 o; o.x = pk2(a.x, a.y); o.y = pk2(a.z, a.w); o.z = pk2(b.x, b.y); o.w = pk2(b.z, b.w); return o; }
; #define EPI_SCHED() __builtin_amdgcn_sched_barrier(0)
;     DI void operator()(const AccT& acc, const Unit& u, int wr, int wc, int fr, int fq) const {
;     ...
;             for (int m = 0; m < 4; ++m) {
;                 EPI_SCHED(); const size_t row = row0 + ai * 128 + m * 16;
;                 const size_t b = row >> 11, s = row & 2047;
; #pragma unroll
;                 for (int bj = 0; bj < 2; ++bj) {
;                     const int cc = bj * 128 + wc * 32 + fq * 8;
;                     f32x4 a = acc[ai][bj][m][0] * rs[ai][m], c = acc[ai][bj][m][1] * rs[ai][m];
;                     if (u.pn < 4) *(u32x4*)(q + row * 1024 + u.pn * 256 + cc) = pk8(a, c);
;                     else if (u.pn < 8) { const int g = cc >> 6, d = cc & 63; *(u32x4*)(slab + (size_t)(u.pn - 4) * SLAB_EL + ((b * 4 + g) * 2048 + s) * 64 + d) = pk8(a, c); }
.LBB0_1993:
	s_andn2_b64 vcc, exec, s[38:39]
	s_cbranch_vccnz .LBB0_1995
	v_ashrrev_i32_e32 v58, 6, v130
	v_ashrrev_i32_e32 v59, 31, v58
	s_add_u32 s0, s61, s34
	v_lshl_add_u64 v[58:59], v[66:67], 0, v[58:59]
	s_addc_u32 s1, s64, s35
	v_lshlrev_b64 v[58:59], 18, v[58:59]
	v_and_b32_e32 v75, 56, v130
	v_lshl_add_u64 v[58:59], s[0:1], 0, v[58:59]
	v_lshlrev_b32_e32 v0, 1, v71
	v_lshl_add_u64 v[58:59], v[58:59], 0, v[0:1]
	v_lshlrev_b32_e32 v0, 1, v75
	v_cvt_pk_bf16_f32 v78, v62, v63
	v_cvt_pk_bf16_f32 v79, v64, v65
	v_cvt_pk_bf16_f32 v80, v76, v77
	v_cvt_pk_bf16_f32 v81, v60, v61
	v_lshl_add_u64 v[58:59], v[58:59], 0, v[0:1]
	global_store_dwordx4 v[58:59], v[78:81], off

; DI u32x4 pk8(f32x4 a, f32x4 b) { u32x4 o; o.x = pk2(a.x, a.y); o.y = pk2(a.z, a.w); o.z = pk2(b.x, b.y); o.w = pk2(b.z, b.w); return o; }
; DI float sigmoidf_(float x) { return frcp(1.f + fexp2(-x * LOG2E)); }
; #define EPI_SCHED() __builtin_amdgcn_sched_barrier(0)
;     DI void operator()(const AccT& acc, const Unit& u, int wr, int wc, int fr, int fq) const {
;     ...
;             for (int m = 0; m < 4; ++m) {
;                 EPI_SCHED(); const size_t row = row0 + ai * 128 + m * 16;
;                 const size_t b = row >> 11, s = row & 2047;
; #pragma unroll
;                 for (int bj = 0; bj < 2; ++bj) {
;                     const int cc = bj * 128 + wc * 32 + fq * 8;
;                     f32x4 a = acc[ai][bj][m][0] * rs[ai][m], c = acc[ai][bj][m][1] * rs[ai][m];
;                     if (u.pn < 4) *(u32x4*)(q + row * 1024 + u.pn * 256 + cc) = pk8(a, c);
;                     else if (u.pn < 8) { const int g = cc >> 6, d = cc & 63; *(u32x4*)(slab + (size_t)(u.pn - 4) * SLAB_EL + ((b * 4 + g) * 2048 + s) * 64 + d) = pk8(a, c); }
;                     else if (cc < 48) {
; #pragma unroll
;                         for (int e = 0; e < 4; ++e) { a[e] = sigmoidf_(a[e]); c[e] = sigmoidf_(c[e]); }
;                         *(f32x4*)(gates + row * 48 + cc) = a; *(f32x4*)(gates + row * 48 + cc + 4) = c;
;                     }
.LBB0_1996:
	v_lshlrev_b64 v[58:59], 11, v[68:69]
	v_lshl_add_u64 v[58:59], s[16:17], 0, v[58:59]
	s_andn2_b64 vcc, exec, s[38:39]
	v_lshl_add_u64 v[58:59], s[36:37], 1, v[58:59]
	s_cbranch_vccnz .LBB0_1998
	v_cvt_pk_bf16_f32 v62, v62, v63
	v_cvt_pk_bf16_f32 v63, v64, v65
	v_cvt_pk_bf16_f32 v64, v76, v77
	v_cvt_pk_bf16_f32 v65, v60, v61
	v_lshl_add_u64 v[60:61], v[130:131], 1, v[58:59]
	global_store_dwordx4 v[60:61], v[62:65], off
.LBB0_1998:
	v_mov_b32_e32 v75, v74
	v_mov_b32_e32 v60, v74
	v_mov_b32_e32 v61, v74
	v_pk_mul_f32 v[56:57], v[56:57], v[60:61]
	v_pk_mul_f32 v[54:55], v[54:55], v[74:75]
	v_pk_mul_f32 v[52:53], v[52:53], v[60:61]
	v_pk_mul_f32 v[50:51], v[50:51], v[74:75]
	s_and_b64 vcc, exec, s[4:5]
	s_mov_b64 s[38:39], -1
	s_cbranch_vccnz .LBB0_2006
	s_and_b64 vcc, exec, s[2:3]
	s_cbranch_vccnz .LBB0_2003
	s_movk_i32 s0, 0xffb0
	v_cmp_gt_i32_e32 vcc, s0, v130
	s_and_saveexec_b64 s[38:39], vcc
	s_cbranch_execz .LBB0_2002
	v_mul_f32_e32 v0, 0xbfb8aa3b, v54
	v_exp_f32_e32 v0, v0
	v_mul_f32_e32 v60, 0xbfb8aa3b, v50
	v_exp_f32_e32 v60, v60
	v_mul_f32_e32 v62, 0xbfb8aa3b, v51
	v_add_f32_e32 v0, 1.0, v0
	v_exp_f32_e32 v62, v62
	v_add_f32_e32 v61, 1.0, v60
	v_rcp_f32_e32 v60, v0
	v_mul_f32_e32 v0, 0xbfb8aa3b, v55
	v_exp_f32_e32 v0, v0
	v_rcp_f32_e32 v74, v61
	v_mul_f32_e32 v63, 0xbfb8aa3b, v52
	v_exp_f32_e32 v63, v63
	v_add_f32_e32 v0, 1.0, v0
	v_rcp_f32_e32 v61, v0
	v_add_f32_e32 v0, 1.0, v62
	v_mul_f32_e32 v62, 0xbfb8aa3b, v56
	v_exp_f32_e32 v62, v62
	v_rcp_f32_e32 v75, v0
	v_mul_f32_e32 v64, 0xbfb8aa3b, v53
	v_exp_f32_e32 v64, v64
	v_add_f32_e32 v0, 1.0, v62
	v_rcp_f32_e32 v62, v0
	v_add_f32_e32 v0, 1.0, v63
	v_mul_f32_e32 v63, 0xbfb8aa3b, v57
	v_exp_f32_e32 v63, v63
	v_rcp_f32_e32 v76, v0
	v_add_f32_e32 v0, 1.0, v63
	v_rcp_f32_e32 v63, v0
	v_add_f32_e32 v0, 1.0, v64
	v_rcp_f32_e32 v77, v0
	v_lshl_add_u64 v[64:65], v[72:73], 2, s[18:19]
	v_lshl_add_u64 v[64:65], v[130:131], 2, v[64:65]
	global_store_dwordx4 v[64:65], v[60:63], off offset:512
	global_store_dwordx4 v[64:65], v[74:77], off offset:528

; DI u32x4 pk8(f32x4 a, f32x4 b) { u32x4 o; o.x = pk2(a.x, a.y); o.y = pk2(a.z, a.w); o.z = pk2(b.x, b.y); o.w = pk2(b.z, b.w); return o; }
; #define EPI_SCHED() __builtin_amdgcn_sched_barrier(0)
;     DI void operator()(const AccT& acc, const Unit& u, int wr, int wc, int fr, int fq) const {
;     ...
;             for (int m = 0; m < 4; ++m) {
;                 EPI_SCHED(); const size_t row = row0 + ai * 128 + m * 16;
;                 const size_t b = row >> 11, s = row & 2047;
; #pragma unroll
;                 for (int bj = 0; bj < 2; ++bj) {
;                     const int cc = bj * 128 + wc * 32 + fq * 8;
;                     f32x4 a = acc[ai][bj][m][0] * rs[ai][m], c = acc[ai][bj][m][1] * rs[ai][m];
;                     if (u.pn < 4) *(u32x4*)(q + row * 1024 + u.pn * 256 + cc) = pk8(a, c);
;                     else if (u.pn < 8) { const int g = cc >> 6, d = cc & 63; *(u32x4*)(slab + (size_t)(u.pn - 4) * SLAB_EL + ((b * 4 + g) * 2048 + s) * 64 + d) = pk8(a, c); }
.LBB0_2003:
	s_andn2_b64 vcc, exec, s[38:39]
	s_cbranch_vccnz .LBB0_2005
	v_ashrrev_i32_e32 v64, 6, v124
	v_ashrrev_i32_e32 v65, 31, v64
	s_add_u32 s0, s61, s34
	v_lshl_add_u64 v[64:65], v[66:67], 0, v[64:65]
	s_addc_u32 s1, s64, s35
	v_lshlrev_b64 v[64:65], 18, v[64:65]
	v_and_b32_e32 v72, 56, v130
	v_lshl_add_u64 v[64:65], s[0:1], 0, v[64:65]
	v_lshlrev_b32_e32 v0, 1, v71
	v_lshl_add_u64 v[64:65], v[64:65], 0, v[0:1]
	v_lshlrev_b32_e32 v0, 1, v72
	v_cvt_pk_bf16_f32 v60, v54, v55
	v_cvt_pk_bf16_f32 v61, v56, v57
	v_cvt_pk_bf16_f32 v62, v50, v51
	v_cvt_pk_bf16_f32 v63, v52, v53
	v_lshl_add_u64 v[64:65], v[64:65], 0, v[0:1]
	global_store_dwordx4 v[64:65], v[60:63], off

; DI u32x4 pk8(f32x4 a, f32x4 b) { u32x4 o; o.x = pk2(a.x, a.y); o.y = pk2(a.z, a.w); o.z = pk2(b.x, b.y); o.w = pk2(b.z, b.w); return o; }
; DI float sigmoidf_(float x) { return frcp(1.f + fexp2(-x * LOG2E)); }
; #define EPI_SCHED() __builtin_amdgcn_sched_barrier(0)
;     DI void operator()(const AccT& acc, const Unit& u, int wr, int wc, int fr, int fq) const {
;     ...
;             for (int m = 0; m < 4; ++m) {
;                 EPI_SCHED(); const size_t row = row0 + ai * 128 + m * 16;
;                 const size_t b = row >> 11, s = row & 2047;
; #pragma unroll
;                 for (int bj = 0; bj < 2; ++bj) {
;                     const int cc = bj * 128 + wc * 32 + fq * 8;
;                     f32x4 a = acc[ai][bj][m][0] * rs[ai][m], c = acc[ai][bj][m][1] * rs[ai][m];
;                     if (u.pn < 4) *(u32x4*)(q + row * 1024 + u.pn * 256 + cc) = pk8(a, c);
;                     else if (u.pn < 8) { const int g = cc >> 6, d = cc & 63; *(u32x4*)(slab + (size_t)(u.pn - 4) * SLAB_EL + ((b * 4 + g) * 2048 + s) * 64 + d) = pk8(a, c); }
;                     else if (cc < 48) {
; #pragma unroll
;                         for (int e = 0; e < 4; ++e) { a[e] = sigmoidf_(a[e]); c[e] = sigmoidf_(c[e]); }
;                         *(f32x4*)(gates + row * 48 + cc) = a; *(f32x4*)(gates + row * 48 + cc + 4) = c;
;                     }
.LBB0_2006:
	s_andn2_b64 vcc, exec, s[38:39]
	s_cbranch_vccnz .LBB0_2008
	v_cvt_pk_bf16_f32 v54, v54, v55
	v_cvt_pk_bf16_f32 v55, v56, v57
	v_cvt_pk_bf16_f32 v56, v50, v51
	v_cvt_pk_bf16_f32 v57, v52, v53
	v_lshl_add_u64 v[50:51], v[130:131], 1, v[58:59]
	global_store_dwordx4 v[50:51], v[54:57], off offset:256
.LBB0_2008:
	v_mul_f32_e32 v0, 0x4b800000, v70
	v_cndmask_b32_e64 v0, v70, v0, s[6:7]
	v_rsq_f32_e32 v0, v0
	s_nop 0
	v_mul_f32_e32 v50, 0x45800000, v0
	v_cndmask_b32_e64 v52, v0, v50, s[6:7]
	v_or_b32_e32 v54, 16, v68
	v_mad_u64_u32 v[50:51], s[0:1], v54, 48, 0
	v_mov_b32_e32 v0, v51
	v_mad_u64_u32 v[56:57], s[0:1], v69, 48, v[0:1]
	v_lshlrev_b32_e32 v0, 6, v54
	v_mov_b32_e32 v51, v56
	v_and_b32_e32 v58, 0x1ffc0, v0
	v_pk_mul_f32 v[48:49], v[48:49], v[52:53] op_sel_hi:[1,0]
	v_pk_mul_f32 v[46:47], v[46:47], v[52:53] op_sel_hi:[1,0]
	v_pk_mul_f32 v[44:45], v[44:45], v[52:53] op_sel_hi:[1,0]
	v_pk_mul_f32 v[56:57], v[42:43], v[52:53] op_sel_hi:[1,0]
	s_and_b64 vcc, exec, s[4:5]
	s_mov_b64 s[6:7], -1
	s_cbranch_vccnz .LBB0_2016
	s_and_b64 vcc, exec, s[2:3]
	s_cbranch_vccnz .LBB0_2013
	v_cmp_gt_i32_e32 vcc, 48, v130
	s_and_saveexec_b64 s[6:7], vcc
	s_cbranch_execz .LBB0_2012
	v_mul_f32_e32 v0, 0xbfb8aa3b, v46
	v_exp_f32_e32 v0, v0
	v_mul_f32_e32 v42, 0xbfb8aa3b, v56
	v_exp_f32_e32 v42, v42
	v_mul_f32_e32 v43, 0xbfb8aa3b, v57
	v_add_f32_e32 v0, 1.0, v0
	v_rcp_f32_e32 v60, v0
	v_mul_f32_e32 v0, 0xbfb8aa3b, v47
	v_exp_f32_e32 v0, v0
	v_exp_f32_e32 v43, v43
	v_add_f32_e32 v42, 1.0, v42
	v_rcp_f32_e32 v70, v42
	v_add_f32_e32 v0, 1.0, v0
	v_mul_f32_e32 v42, 0xbfb8aa3b, v48
	v_rcp_f32_e32 v61, v0
	v_add_f32_e32 v0, 1.0, v43
	v_exp_f32_e32 v42, v42
	v_mul_f32_e32 v43, 0xbfb8aa3b, v44
	v_exp_f32_e32 v43, v43
	v_rcp_f32_e32 v71, v0
	v_add_f32_e32 v0, 1.0, v42
	v_mul_f32_e32 v42, 0xbfb8aa3b, v49
	v_rcp_f32_e32 v62, v0
	v_add_f32_e32 v0, 1.0, v43
	v_exp_f32_e32 v42, v42
	v_mul_f32_e32 v43, 0xbfb8aa3b, v45
	v_exp_f32_e32 v43, v43
	v_rcp_f32_e32 v72, v0
	v_add_f32_e32 v0, 1.0, v42
	v_rcp_f32_e32 v63, v0
	v_add_f32_e32 v0, 1.0, v43
	v_rcp_f32_e32 v73, v0
	v_lshl_add_u64 v[42:43], v[50:51], 2, s[18:19]
	v_lshl_add_u64 v[42:43], v[130:131], 2, v[42:43]
	global_store_dwordx4 v[42:43], v[60:63], off
	global_store_dwordx4 v[42:43], v[70:73], off offset:16

; DI u32x4 pk8(f32x4 a, f32x4 b) { u32x4 o; o.x = pk2(a.x, a.y); o.y = pk2(a.z, a.w); o.z = pk2(b.x, b.y); o.w = pk2(b.z, b.w); return o; }
; #define EPI_SCHED() __builtin_amdgcn_sched_barrier(0)
;     DI void operator()(const AccT& acc, const Unit& u, int wr, int wc, int fr, int fq) const {
;     ...
;             for (int m = 0; m < 4; ++m) {
;                 EPI_SCHED(); const size_t row = row0 + ai * 128 + m * 16;
;                 const size_t b = row >> 11, s = row & 2047;
; #pragma unroll
;                 for (int bj = 0; bj < 2; ++bj) {
;                     const int cc = bj * 128 + wc * 32 + fq * 8;
;                     f32x4 a = acc[ai][bj][m][0] * rs[ai][m], c = acc[ai][bj][m][1] * rs[ai][m];
;                     if (u.pn < 4) *(u32x4*)(q + row * 1024 + u.pn * 256 + cc) = pk8(a, c);
;                     else if (u.pn < 8) { const int g = cc >> 6, d = cc & 63; *(u32x4*)(slab + (size_t)(u.pn - 4) * SLAB_EL + ((b * 4 + g) * 2048 + s) * 64 + d) = pk8(a, c); }
.LBB0_2013:
	s_andn2_b64 vcc, exec, s[6:7]
	s_cbranch_vccnz .LBB0_2015
	v_ashrrev_i32_e32 v42, 6, v130
	v_ashrrev_i32_e32 v43, 31, v42
	s_add_u32 s0, s61, s34
	v_lshl_add_u64 v[42:43], v[66:67], 0, v[42:43]
	s_addc_u32 s1, s64, s35
	v_lshlrev_b64 v[42:43], 18, v[42:43]
	v_and_b32_e32 v53, 56, v130
	v_lshl_add_u64 v[42:43], s[0:1], 0, v[42:43]
	v_lshlrev_b32_e32 v0, 1, v58
	v_lshl_add_u64 v[42:43], v[42:43], 0, v[0:1]
	v_lshlrev_b32_e32 v0, 1, v53
	v_cvt_pk_bf16_f32 v60, v46, v47
	v_cvt_pk_bf16_f32 v61, v48, v49
	v_cvt_pk_bf16_f32 v62, v56, v57
	v_cvt_pk_bf16_f32 v63, v44, v45
	v_lshl_add_u64 v[42:43], v[42:43], 0, v[0:1]
	global_store_dwordx4 v[42:43], v[60:63], off

; DI u32x4 pk8(f32x4 a, f32x4 b) { u32x4 o; o.x = pk2(a.x, a.y); o.y = pk2(a.z, a.w); o.z = pk2(b.x, b.y); o.w = pk2(b.z, b.w); return o; }
; DI float sigmoidf_(float x) { return frcp(1.f + fexp2(-x * LOG2E)); }
; #define EPI_SCHED() __builtin_amdgcn_sched_barrier(0)
;     DI void operator()(const AccT& acc, const Unit& u, int wr, int wc, int fr, int fq) const {
;     ...
;             for (int m = 0; m < 4; ++m) {
;                 EPI_SCHED(); const size_t row = row0 + ai * 128 + m * 16;
;                 const size_t b = row >> 11, s = row & 2047;
; #pragma unroll
;                 for (int bj = 0; bj < 2; ++bj) {
;                     const int cc = bj * 128 + wc * 32 + fq * 8;
;                     f32x4 a = acc[ai][bj][m][0] * rs[ai][m], c = acc[ai][bj][m][1] * rs[ai][m];
;                     if (u.pn < 4) *(u32x4*)(q + row * 1024 + u.pn * 256 + cc) = pk8(a, c);
;                     else if (u.pn < 8) { const int g = cc >> 6, d = cc & 63; *(u32x4*)(slab + (size_t)(u.pn - 4) * SLAB_EL + ((b * 4 + g) * 2048 + s) * 64 + d) = pk8(a, c); }
;                     else if (cc < 48) {
; #pragma unroll
;                         for (int e = 0; e < 4; ++e) { a[e] = sigmoidf_(a[e]); c[e] = sigmoidf_(c[e]); }
;                         *(f32x4*)(gates + row * 48 + cc) = a; *(f32x4*)(gates + row * 48 + cc + 4) = c;
;                     }
.LBB0_2016:
	v_mov_b32_e32 v55, v69
	v_lshlrev_b64 v[42:43], 11, v[54:55]
	v_lshl_add_u64 v[42:43], s[16:17], 0, v[42:43]
	s_andn2_b64 vcc, exec, s[6:7]
	v_lshl_add_u64 v[42:43], s[36:37], 1, v[42:43]
	s_cbranch_vccnz .LBB0_2018
	v_cvt_pk_bf16_f32 v46, v46, v47
	v_cvt_pk_bf16_f32 v47, v48, v49
	v_cvt_pk_bf16_f32 v48, v56, v57
	v_cvt_pk_bf16_f32 v49, v44, v45
	v_lshl_add_u64 v[44:45], v[130:131], 1, v[42:43]
	global_store_dwordx4 v[44:45], v[46:49], off
.LBB0_2018:
	v_mov_b32_e32 v53, v52
	v_mov_b32_e32 v44, v52
	v_mov_b32_e32 v45, v52
	v_pk_mul_f32 v[40:41], v[40:41], v[44:45]
	v_pk_mul_f32 v[38:39], v[38:39], v[52:53]
	v_pk_mul_f32 v[36:37], v[36:37], v[44:45]
	v_pk_mul_f32 v[34:35], v[34:35], v[52:53]
	s_and_b64 vcc, exec, s[4:5]
	s_mov_b64 s[6:7], -1
	s_cbranch_vccnz .LBB0_2026
	s_and_b64 vcc, exec, s[2:3]
	s_cbranch_vccnz .LBB0_2023
	s_movk_i32 s0, 0xffb0
	v_cmp_gt_i32_e32 vcc, s0, v130
	s_and_saveexec_b64 s[6:7], vcc
	s_cbranch_execz .LBB0_2022
	v_mul_f32_e32 v0, 0xbfb8aa3b, v38
	v_exp_f32_e32 v0, v0
	v_mul_f32_e32 v44, 0xbfb8aa3b, v34
	v_exp_f32_e32 v44, v44
	v_mul_f32_e32 v46, 0xbfb8aa3b, v35
	v_add_f32_e32 v0, 1.0, v0
	v_exp_f32_e32 v46, v46
	v_add_f32_e32 v45, 1.0, v44
	v_rcp_f32_e32 v44, v0
	v_mul_f32_e32 v0, 0xbfb8aa3b, v39
	v_exp_f32_e32 v0, v0
	v_rcp_f32_e32 v52, v45
	v_mul_f32_e32 v47, 0xbfb8aa3b, v36
	v_exp_f32_e32 v47, v47
	v_add_f32_e32 v0, 1.0, v0
	v_rcp_f32_e32 v45, v0
	v_add_f32_e32 v0, 1.0, v46
	v_mul_f32_e32 v46, 0xbfb8aa3b, v40
	v_exp_f32_e32 v46, v46
	v_rcp_f32_e32 v53, v0
	v_mul_f32_e32 v48, 0xbfb8aa3b, v37
	v_exp_f32_e32 v48, v48
	v_add_f32_e32 v0, 1.0, v46
	v_rcp_f32_e32 v46, v0
	v_add_f32_e32 v0, 1.0, v47
	v_mul_f32_e32 v47, 0xbfb8aa3b, v41
	v_exp_f32_e32 v47, v47
	v_rcp_f32_e32 v54, v0
	v_add_f32_e32 v0, 1.0, v47
	v_rcp_f32_e32 v47, v0
	v_add_f32_e32 v0, 1.0, v48
	v_rcp_f32_e32 v55, v0
	v_lshl_add_u64 v[48:49], v[50:51], 2, s[18:19]
	v_lshl_add_u64 v[48:49], v[130:131], 2, v[48:49]
	global_store_dwordx4 v[48:49], v[44:47], off offset:512
	global_store_dwordx4 v[48:49], v[52:55], off offset:528

; DI u32x4 pk8(f32x4 a, f32x4 b) { u32x4 o; o.x = pk2(a.x, a.y); o.y = pk2(a.z, a.w); o.z = pk2(b.x, b.y); o.w = pk2(b.z, b.w); return o; }
; #define EPI_SCHED() __builtin_amdgcn_sched_barrier(0)
;     DI void operator()(const AccT& acc, const Unit& u, int wr, int wc, int fr, int fq) const {
;     ...
;             for (int m = 0; m < 4; ++m) {
;                 EPI_SCHED(); const size_t row = row0 + ai * 128 + m * 16;
;                 const size_t b = row >> 11, s = row & 2047;
; #pragma unroll
;                 for (int bj = 0; bj < 2; ++bj) {
;                     const int cc = bj * 128 + wc * 32 + fq * 8;
;                     f32x4 a = acc[ai][bj][m][0] * rs[ai][m], c = acc[ai][bj][m][1] * rs[ai][m];
;                     if (u.pn < 4) *(u32x4*)(q + row * 1024 + u.pn * 256 + cc) = pk8(a, c);
;                     else if (u.pn < 8) { const int g = cc >> 6, d = cc & 63; *(u32x4*)(slab + (size_t)(u.pn - 4) * SLAB_EL + ((b * 4 + g) * 2048 + s) * 64 + d) = pk8(a, c); }
.LBB0_2023:
	s_andn2_b64 vcc, exec, s[6:7]
	s_cbranch_vccnz .LBB0_2025
	v_ashrrev_i32_e32 v48, 6, v124
	v_ashrrev_i32_e32 v49, 31, v48
	s_add_u32 s0, s61, s34
	v_lshl_add_u64 v[48:49], v[66:67], 0, v[48:49]
	s_addc_u32 s1, s64, s35
	v_lshlrev_b64 v[48:49], 18, v[48:49]
	v_and_b32_e32 v52, 56, v130
	v_lshl_add_u64 v[48:49], s[0:1], 0, v[48:49]
	v_lshlrev_b32_e32 v0, 1, v58
	v_lshl_add_u64 v[48:49], v[48:49], 0, v[0:1]
	v_lshlrev_b32_e32 v0, 1, v52
	v_cvt_pk_bf16_f32 v44, v38, v39
	v_cvt_pk_bf16_f32 v45, v40, v41
	v_cvt_pk_bf16_f32 v46, v34, v35
	v_cvt_pk_bf16_f32 v47, v36, v37
	v_lshl_add_u64 v[48:49], v[48:49], 0, v[0:1]
	global_store_dwordx4 v[48:49], v[44:47], off

; DI u32x4 pk8(f32x4 a, f32x4 b) { u32x4 o; o.x = pk2(a.x, a.y); o.y = pk2(a.z, a.w); o.z = pk2(b.x, b.y); o.w = pk2(b.z, b.w); return o; }
; DI float sigmoidf_(float x) { return frcp(1.f + fexp2(-x * LOG2E)); }
; #define EPI_SCHED() __builtin_amdgcn_sched_barrier(0)
;     DI void operator()(const AccT& acc, const Unit& u, int wr, int wc, int fr, int fq) const {
;     ...
;             for (int m = 0; m < 4; ++m) {
;                 EPI_SCHED(); const size_t row = row0 + ai * 128 + m * 16;
;                 const size_t b = row >> 11, s = row & 2047;
; #pragma unroll
;                 for (int bj = 0; bj < 2; ++bj) {
;                     const int cc = bj * 128 + wc * 32 + fq * 8;
;                     f32x4 a = acc[ai][bj][m][0] * rs[ai][m], c = acc[ai][bj][m][1] * rs[ai][m];
;                     if (u.pn < 4) *(u32x4*)(q + row * 1024 + u.pn * 256 + cc) = pk8(a, c);
;                     else if (u.pn < 8) { const int g = cc >> 6, d = cc & 63; *(u32x4*)(slab + (size_t)(u.pn - 4) * SLAB_EL + ((b * 4 + g) * 2048 + s) * 64 + d) = pk8(a, c); }
;                     else if (cc < 48) {
; #pragma unroll
;                         for (int e = 0; e < 4; ++e) { a[e] = sigmoidf_(a[e]); c[e] = sigmoidf_(c[e]); }
;                         *(f32x4*)(gates + row * 48 + cc) = a; *(f32x4*)(gates + row * 48 + cc + 4) = c;
;                     }
.LBB0_2026:
	s_andn2_b64 vcc, exec, s[6:7]
	s_cbranch_vccnz .LBB0_2028
	v_cvt_pk_bf16_f32 v38, v38, v39
	v_cvt_pk_bf16_f32 v39, v40, v41
	v_cvt_pk_bf16_f32 v40, v34, v35
	v_cvt_pk_bf16_f32 v41, v36, v37
	v_lshl_add_u64 v[34:35], v[130:131], 1, v[42:43]
	global_store_dwordx4 v[34:35], v[38:41], off offset:256
.LBB0_2028:
	v_pk_add_f32 v[34:35], v[132:133], v[134:135]
	v_mov_b32_e32 v0, 0x358637bd
	v_pk_fma_f32 v[34:35], v[34:35], s[88:89], v[0:1] op_sel_hi:[1,0,0]
	s_nop 0
	v_mul_f32_e32 v0, 0x4b800000, v35
	v_cmp_gt_f32_e32 vcc, s42, v35
	v_cmp_gt_f32_e64 s[6:7], s42, v34
	s_nop 0
	v_cndmask_b32_e32 v0, v35, v0, vcc
	v_rsq_f32_e32 v0, v0
	s_nop 0
	v_mul_f32_e32 v35, 0x45800000, v0
	v_cndmask_b32_e32 v38, v0, v35, vcc
	v_or_b32_e32 v40, 32, v68
	s_mov_b64 s[0:1], 0x300
	v_lshlrev_b32_e32 v0, 6, v40
	v_lshl_add_u64 v[36:37], v[50:51], 0, s[0:1]
	v_and_b32_e32 v35, 0x1ffc0, v0
	v_pk_mul_f32 v[32:33], v[32:33], v[38:39] op_sel_hi:[1,0]
	v_pk_mul_f32 v[30:31], v[30:31], v[38:39] op_sel_hi:[1,0]
	v_pk_mul_f32 v[28:29], v[28:29], v[38:39] op_sel_hi:[1,0]
	v_pk_mul_f32 v[42:43], v[26:27], v[38:39] op_sel_hi:[1,0]
	s_and_b64 vcc, exec, s[4:5]
	s_mov_b64 s[38:39], -1
	s_cbranch_vccnz .LBB0_2036
	s_and_b64 vcc, exec, s[2:3]
	s_cbranch_vccnz .LBB0_2033
	v_cmp_gt_i32_e32 vcc, 48, v130
	s_and_saveexec_b64 s[38:39], vcc
	s_cbranch_execz .LBB0_2032
	v_mul_f32_e32 v0, 0xbfb8aa3b, v30
	v_exp_f32_e32 v0, v0
	v_mul_f32_e32 v26, 0xbfb8aa3b, v42
	v_exp_f32_e32 v26, v26
	v_mul_f32_e32 v27, 0xbfb8aa3b, v43
	v_add_f32_e32 v0, 1.0, v0
	v_rcp_f32_e32 v44, v0
	v_mul_f32_e32 v0, 0xbfb8aa3b, v31
	v_exp_f32_e32 v0, v0
	v_exp_f32_e32 v27, v27
	v_add_f32_e32 v26, 1.0, v26
	v_rcp_f32_e32 v48, v26
	v_add_f32_e32 v0, 1.0, v0
	v_mul_f32_e32 v26, 0xbfb8aa3b, v32
	v_rcp_f32_e32 v45, v0
	v_add_f32_e32 v0, 1.0, v27
	v_exp_f32_e32 v26, v26
	v_mul_f32_e32 v27, 0xbfb8aa3b, v28
	v_exp_f32_e32 v27, v27
	v_rcp_f32_e32 v49, v0
	v_add_f32_e32 v0, 1.0, v26
	v_mul_f32_e32 v26, 0xbfb8aa3b, v33
	v_rcp_f32_e32 v46, v0
	v_add_f32_e32 v0, 1.0, v27
	v_exp_f32_e32 v26, v26
	v_mul_f32_e32 v27, 0xbfb8aa3b, v29
	v_exp_f32_e32 v27, v27
	v_rcp_f32_e32 v50, v0
	v_add_f32_e32 v0, 1.0, v26
	v_rcp_f32_e32 v47, v0
	v_add_f32_e32 v0, 1.0, v27
	v_rcp_f32_e32 v51, v0
	v_lshl_add_u64 v[26:27], v[36:37], 2, s[18:19]
	v_lshl_add_u64 v[26:27], v[130:131], 2, v[26:27]
	global_store_dwordx4 v[26:27], v[44:47], off
	global_store_dwordx4 v[26:27], v[48:51], off offset:16

; DI u32x4 pk8(f32x4 a, f32x4 b) { u32x4 o; o.x = pk2(a.x, a.y); o.y = pk2(a.z, a.w); o.z = pk2(b.x, b.y); o.w = pk2(b.z, b.w); return o; }
; #define EPI_SCHED() __builtin_amdgcn_sched_barrier(0)
;     DI void operator()(const AccT& acc, const Unit& u, int wr, int wc, int fr, int fq) const {
;     ...
;             for (int m = 0; m < 4; ++m) {
;                 EPI_SCHED(); const size_t row = row0 + ai * 128 + m * 16;
;                 const size_t b = row >> 11, s = row & 2047;
; #pragma unroll
;                 for (int bj = 0; bj < 2; ++bj) {
;                     const int cc = bj * 128 + wc * 32 + fq * 8;
;                     f32x4 a = acc[ai][bj][m][0] * rs[ai][m], c = acc[ai][bj][m][1] * rs[ai][m];
;                     if (u.pn < 4) *(u32x4*)(q + row * 1024 + u.pn * 256 + cc) = pk8(a, c);
;                     else if (u.pn < 8) { const int g = cc >> 6, d = cc & 63; *(u32x4*)(slab + (size_t)(u.pn - 4) * SLAB_EL + ((b * 4 + g) * 2048 + s) * 64 + d) = pk8(a, c); }
.LBB0_2033:
	s_andn2_b64 vcc, exec, s[38:39]
	s_cbranch_vccnz .LBB0_2035
	v_ashrrev_i32_e32 v26, 6, v130
	v_ashrrev_i32_e32 v27, 31, v26
	s_add_u32 s0, s61, s34
	v_lshl_add_u64 v[26:27], v[66:67], 0, v[26:27]
	s_addc_u32 s1, s64, s35
	v_lshlrev_b64 v[26:27], 18, v[26:27]
	v_and_b32_e32 v39, 56, v130
	v_lshl_add_u64 v[26:27], s[0:1], 0, v[26:27]
	v_lshlrev_b32_e32 v0, 1, v35
	v_lshl_add_u64 v[26:27], v[26:27], 0, v[0:1]
	v_lshlrev_b32_e32 v0, 1, v39
	v_cvt_pk_bf16_f32 v44, v30, v31
	v_cvt_pk_bf16_f32 v45, v32, v33
	v_cvt_pk_bf16_f32 v46, v42, v43
	v_cvt_pk_bf16_f32 v47, v28, v29
	v_lshl_add_u64 v[26:27], v[26:27], 0, v[0:1]
	global_store_dwordx4 v[26:27], v[44:47], off

; DI u32x4 pk8(f32x4 a, f32x4 b) { u32x4 o; o.x = pk2(a.x, a.y); o.y = pk2(a.z, a.w); o.z = pk2(b.x, b.y); o.w = pk2(b.z, b.w); return o; }
; DI float sigmoidf_(float x) { return frcp(1.f + fexp2(-x * LOG2E)); }
; #define EPI_SCHED() __builtin_amdgcn_sched_barrier(0)
;     DI void operator()(const AccT& acc, const Unit& u, int wr, int wc, int fr, int fq) const {
;     ...
;             for (int m = 0; m < 4; ++m) {
;                 EPI_SCHED(); const size_t row = row0 + ai * 128 + m * 16;
;                 const size_t b = row >> 11, s = row & 2047;
; #pragma unroll
;                 for (int bj = 0; bj < 2; ++bj) {
;                     const int cc = bj * 128 + wc * 32 + fq * 8;
;                     f32x4 a = acc[ai][bj][m][0] * rs[ai][m], c = acc[ai][bj][m][1] * rs[ai][m];
;                     if (u.pn < 4) *(u32x4*)(q + row * 1024 + u.pn * 256 + cc) = pk8(a, c);
;                     else if (u.pn < 8) { const int g = cc >> 6, d = cc & 63; *(u32x4*)(slab + (size_t)(u.pn - 4) * SLAB_EL + ((b * 4 + g) * 2048 + s) * 64 + d) = pk8(a, c); }
;                     else if (cc < 48) {
; #pragma unroll
;                         for (int e = 0; e < 4; ++e) { a[e] = sigmoidf_(a[e]); c[e] = sigmoidf_(c[e]); }
;                         *(f32x4*)(gates + row * 48 + cc) = a; *(f32x4*)(gates + row * 48 + cc + 4) = c;
;                     }
.LBB0_2036:
	v_mov_b32_e32 v41, v69
	v_lshlrev_b64 v[26:27], 11, v[40:41]
	v_lshl_add_u64 v[26:27], s[16:17], 0, v[26:27]
	s_andn2_b64 vcc, exec, s[38:39]
	v_lshl_add_u64 v[26:27], s[36:37], 1, v[26:27]
	s_cbranch_vccnz .LBB0_2038
	v_cvt_pk_bf16_f32 v30, v30, v31
	v_cvt_pk_bf16_f32 v31, v32, v33
	v_cvt_pk_bf16_f32 v32, v42, v43
	v_cvt_pk_bf16_f32 v33, v28, v29
	v_lshl_add_u64 v[28:29], v[130:131], 1, v[26:27]
	global_store_dwordx4 v[28:29], v[30:33], off
.LBB0_2038:
	v_mov_b32_e32 v39, v38
	v_mov_b32_e32 v28, v38
	v_mov_b32_e32 v29, v38
	v_pk_mul_f32 v[24:25], v[24:25], v[28:29]
	v_pk_mul_f32 v[22:23], v[22:23], v[38:39]
	v_pk_mul_f32 v[20:21], v[20:21], v[28:29]
	v_pk_mul_f32 v[18:19], v[18:19], v[38:39]
	s_and_b64 vcc, exec, s[4:5]
	s_mov_b64 s[38:39], -1
	s_cbranch_vccnz .LBB0_2046
	s_and_b64 vcc, exec, s[2:3]
	s_cbranch_vccnz .LBB0_2043
	s_movk_i32 s0, 0xffb0
	v_cmp_gt_i32_e32 vcc, s0, v130
	s_and_saveexec_b64 s[38:39], vcc
	s_cbranch_execz .LBB0_2042
	v_mul_f32_e32 v0, 0xbfb8aa3b, v22
	v_exp_f32_e32 v0, v0
	v_mul_f32_e32 v28, 0xbfb8aa3b, v18
	v_exp_f32_e32 v28, v28
	v_mul_f32_e32 v30, 0xbfb8aa3b, v19
	v_add_f32_e32 v0, 1.0, v0
	v_exp_f32_e32 v30, v30
	v_add_f32_e32 v29, 1.0, v28
	v_rcp_f32_e32 v28, v0
	v_mul_f32_e32 v0, 0xbfb8aa3b, v23
	v_exp_f32_e32 v0, v0
	v_rcp_f32_e32 v38, v29
	v_mul_f32_e32 v31, 0xbfb8aa3b, v20
	v_exp_f32_e32 v31, v31
	v_add_f32_e32 v0, 1.0, v0
	v_rcp_f32_e32 v29, v0
	v_add_f32_e32 v0, 1.0, v30
	v_mul_f32_e32 v30, 0xbfb8aa3b, v24
	v_exp_f32_e32 v30, v30
	v_rcp_f32_e32 v39, v0
	v_mul_f32_e32 v32, 0xbfb8aa3b, v21
	v_exp_f32_e32 v32, v32
	v_add_f32_e32 v0, 1.0, v30
	v_rcp_f32_e32 v30, v0
	v_add_f32_e32 v0, 1.0, v31
	v_mul_f32_e32 v31, 0xbfb8aa3b, v25
	v_exp_f32_e32 v31, v31
	v_rcp_f32_e32 v40, v0
	v_add_f32_e32 v0, 1.0, v31
	v_rcp_f32_e32 v31, v0
	v_add_f32_e32 v0, 1.0, v32
	v_rcp_f32_e32 v41, v0
	v_lshl_add_u64 v[32:33], v[36:37], 2, s[18:19]
	v_lshl_add_u64 v[32:33], v[130:131], 2, v[32:33]
	global_store_dwordx4 v[32:33], v[28:31], off offset:512
	global_store_dwordx4 v[32:33], v[38:41], off offset:528

; DI u32x4 pk8(f32x4 a, f32x4 b) { u32x4 o; o.x = pk2(a.x, a.y); o.y = pk2(a.z, a.w); o.z = pk2(b.x, b.y); o.w = pk2(b.z, b.w); return o; }
; #define EPI_SCHED() __builtin_amdgcn_sched_barrier(0)
;     DI void operator()(const AccT& acc, const Unit& u, int wr, int wc, int fr, int fq) const {
;     ...
;             for (int m = 0; m < 4; ++m) {
;                 EPI_SCHED(); const size_t row = row0 + ai * 128 + m * 16;
;                 const size_t b = row >> 11, s = row & 2047;
; #pragma unroll
;                 for (int bj = 0; bj < 2; ++bj) {
;                     const int cc = bj * 128 + wc * 32 + fq * 8;
;                     f32x4 a = acc[ai][bj][m][0] * rs[ai][m], c = acc[ai][bj][m][1] * rs[ai][m];
;                     if (u.pn < 4) *(u32x4*)(q + row * 1024 + u.pn * 256 + cc) = pk8(a, c);
;                     else if (u.pn < 8) { const int g = cc >> 6, d = cc & 63; *(u32x4*)(slab + (size_t)(u.pn - 4) * SLAB_EL + ((b * 4 + g) * 2048 + s) * 64 + d) = pk8(a, c); }
.LBB0_2043:
	s_andn2_b64 vcc, exec, s[38:39]
	s_cbranch_vccnz .LBB0_2045
	v_ashrrev_i32_e32 v32, 6, v124
	v_ashrrev_i32_e32 v33, 31, v32
	s_add_u32 s0, s61, s34
	v_lshl_add_u64 v[32:33], v[66:67], 0, v[32:33]
	s_addc_u32 s1, s64, s35
	v_lshlrev_b64 v[32:33], 18, v[32:33]
	v_and_b32_e32 v38, 56, v130
	v_lshl_add_u64 v[32:33], s[0:1], 0, v[32:33]
	v_lshlrev_b32_e32 v0, 1, v35
	v_lshl_add_u64 v[32:33], v[32:33], 0, v[0:1]
	v_lshlrev_b32_e32 v0, 1, v38
	v_cvt_pk_bf16_f32 v28, v22, v23
	v_cvt_pk_bf16_f32 v29, v24, v25
	v_cvt_pk_bf16_f32 v30, v18, v19
	v_cvt_pk_bf16_f32 v31, v20, v21
	v_lshl_add_u64 v[32:33], v[32:33], 0, v[0:1]
	global_store_dwordx4 v[32:33], v[28:31], off

; DI u32x4 pk8(f32x4 a, f32x4 b) { u32x4 o; o.x = pk2(a.x, a.y); o.y = pk2(a.z, a.w); o.z = pk2(b.x, b.y); o.w = pk2(b.z, b.w); return o; }
; DI float sigmoidf_(float x) { return frcp(1.f + fexp2(-x * LOG2E)); }
; #define EPI_SCHED() __builtin_amdgcn_sched_barrier(0)
;     DI void operator()(const AccT& acc, const Unit& u, int wr, int wc, int fr, int fq) const {
;     ...
;             for (int m = 0; m < 4; ++m) {
;                 EPI_SCHED(); const size_t row = row0 + ai * 128 + m * 16;
;                 const size_t b = row >> 11, s = row & 2047;
; #pragma unroll
;                 for (int bj = 0; bj < 2; ++bj) {
;                     const int cc = bj * 128 + wc * 32 + fq * 8;
;                     f32x4 a = acc[ai][bj][m][0] * rs[ai][m], c = acc[ai][bj][m][1] * rs[ai][m];
;                     if (u.pn < 4) *(u32x4*)(q + row * 1024 + u.pn * 256 + cc) = pk8(a, c);
;                     else if (u.pn < 8) { const int g = cc >> 6, d = cc & 63; *(u32x4*)(slab + (size_t)(u.pn - 4) * SLAB_EL + ((b * 4 + g) * 2048 + s) * 64 + d) = pk8(a, c); }
;                     else if (cc < 48) {
; #pragma unroll
;                         for (int e = 0; e < 4; ++e) { a[e] = sigmoidf_(a[e]); c[e] = sigmoidf_(c[e]); }
;                         *(f32x4*)(gates + row * 48 + cc) = a; *(f32x4*)(gates + row * 48 + cc + 4) = c;
;                     }
.LBB0_2046:
	s_andn2_b64 vcc, exec, s[38:39]
	s_cbranch_vccnz .LBB0_2048
	v_cvt_pk_bf16_f32 v22, v22, v23
	v_cvt_pk_bf16_f32 v23, v24, v25
	v_cvt_pk_bf16_f32 v24, v18, v19
	v_cvt_pk_bf16_f32 v25, v20, v21
	v_lshl_add_u64 v[18:19], v[130:131], 1, v[26:27]
	global_store_dwordx4 v[18:19], v[22:25], off offset:256
.LBB0_2048:
	v_mul_f32_e32 v0, 0x4b800000, v34
	v_cndmask_b32_e64 v0, v34, v0, s[6:7]
	v_rsq_f32_e32 v0, v0
	s_nop 0
	v_mul_f32_e32 v18, 0x45800000, v0
	v_cndmask_b32_e64 v20, v0, v18, s[6:7]
	v_or_b32_e32 v68, 48, v68
	s_mov_b64 s[0:1], 0x300
	v_lshlrev_b32_e32 v0, 6, v68
	v_lshl_add_u64 v[18:19], v[36:37], 0, s[0:1]
	v_and_b32_e32 v24, 0x1ffc0, v0
	v_pk_mul_f32 v[16:17], v[16:17], v[20:21] op_sel_hi:[1,0]
	v_pk_mul_f32 v[14:15], v[14:15], v[20:21] op_sel_hi:[1,0]
	v_pk_mul_f32 v[12:13], v[12:13], v[20:21] op_sel_hi:[1,0]
	v_pk_mul_f32 v[22:23], v[10:11], v[20:21] op_sel_hi:[1,0]
	s_and_b64 vcc, exec, s[4:5]
	s_mov_b64 s[6:7], -1
	s_cbranch_vccnz .LBB0_2056
	s_and_b64 vcc, exec, s[2:3]
	s_cbranch_vccnz .LBB0_2053
	v_cmp_gt_i32_e32 vcc, 48, v130
	s_and_saveexec_b64 s[6:7], vcc
	s_cbranch_execz .LBB0_2052
	v_mul_f32_e32 v0, 0xbfb8aa3b, v14
	v_exp_f32_e32 v0, v0
	v_mul_f32_e32 v10, 0xbfb8aa3b, v22
	v_exp_f32_e32 v10, v10
	v_mul_f32_e32 v11, 0xbfb8aa3b, v23
	v_add_f32_e32 v0, 1.0, v0
	v_rcp_f32_e32 v26, v0
	v_mul_f32_e32 v0, 0xbfb8aa3b, v15
	v_exp_f32_e32 v0, v0
	v_exp_f32_e32 v11, v11
	v_add_f32_e32 v10, 1.0, v10
	v_rcp_f32_e32 v30, v10
	v_add_f32_e32 v0, 1.0, v0
	v_mul_f32_e32 v10, 0xbfb8aa3b, v16
	v_rcp_f32_e32 v27, v0
	v_add_f32_e32 v0, 1.0, v11
	v_exp_f32_e32 v10, v10
	v_mul_f32_e32 v11, 0xbfb8aa3b, v12
	v_exp_f32_e32 v11, v11
	v_rcp_f32_e32 v31, v0
	v_add_f32_e32 v0, 1.0, v10
	v_mul_f32_e32 v10, 0xbfb8aa3b, v17
	v_rcp_f32_e32 v28, v0
	v_add_f32_e32 v0, 1.0, v11
	v_exp_f32_e32 v10, v10
	v_mul_f32_e32 v11, 0xbfb8aa3b, v13
	v_exp_f32_e32 v11, v11
	v_rcp_f32_e32 v32, v0
	v_add_f32_e32 v0, 1.0, v10
	v_rcp_f32_e32 v29, v0
	v_add_f32_e32 v0, 1.0, v11
	v_rcp_f32_e32 v33, v0
	v_lshl_add_u64 v[10:11], v[18:19], 2, s[18:19]
	v_lshl_add_u64 v[10:11], v[130:131], 2, v[10:11]
	global_store_dwordx4 v[10:11], v[26:29], off
	global_store_dwordx4 v[10:11], v[30:33], off offset:16

; DI u32x4 pk8(f32x4 a, f32x4 b) { u32x4 o; o.x = pk2(a.x, a.y); o.y = pk2(a.z, a.w); o.z = pk2(b.x, b.y); o.w = pk2(b.z, b.w); return o; }
; #define EPI_SCHED() __builtin_amdgcn_sched_barrier(0)
;     DI void operator()(const AccT& acc, const Unit& u, int wr, int wc, int fr, int fq) const {
;     ...
;             for (int m = 0; m < 4; ++m) {
;                 EPI_SCHED(); const size_t row = row0 + ai * 128 + m * 16;
;                 const size_t b = row >> 11, s = row & 2047;
; #pragma unroll
;                 for (int bj = 0; bj < 2; ++bj) {
;                     const int cc = bj * 128 + wc * 32 + fq * 8;
;                     f32x4 a = acc[ai][bj][m][0] * rs[ai][m], c = acc[ai][bj][m][1] * rs[ai][m];
;                     if (u.pn < 4) *(u32x4*)(q + row * 1024 + u.pn * 256 + cc) = pk8(a, c);
;                     else if (u.pn < 8) { const int g = cc >> 6, d = cc & 63; *(u32x4*)(slab + (size_t)(u.pn - 4) * SLAB_EL + ((b * 4 + g) * 2048 + s) * 64 + d) = pk8(a, c); }
.LBB0_2053:
	s_andn2_b64 vcc, exec, s[6:7]
	s_cbranch_vccnz .LBB0_2055
	v_ashrrev_i32_e32 v10, 6, v130
	v_ashrrev_i32_e32 v11, 31, v10
	s_add_u32 s0, s61, s34
	v_lshl_add_u64 v[10:11], v[66:67], 0, v[10:11]
	s_addc_u32 s1, s64, s35
	v_lshlrev_b64 v[10:11], 18, v[10:11]
	v_and_b32_e32 v21, 56, v130
	v_lshl_add_u64 v[10:11], s[0:1], 0, v[10:11]
	v_lshlrev_b32_e32 v0, 1, v24
	v_lshl_add_u64 v[10:11], v[10:11], 0, v[0:1]
	v_lshlrev_b32_e32 v0, 1, v21
	v_cvt_pk_bf16_f32 v26, v14, v15
	v_cvt_pk_bf16_f32 v27, v16, v17
	v_cvt_pk_bf16_f32 v28, v22, v23
	v_cvt_pk_bf16_f32 v29, v12, v13
	v_lshl_add_u64 v[10:11], v[10:11], 0, v[0:1]
	global_store_dwordx4 v[10:11], v[26:29], off

; DI u32x4 pk8(f32x4 a, f32x4 b) { u32x4 o; o.x = pk2(a.x, a.y); o.y = pk2(a.z, a.w); o.z = pk2(b.x, b.y); o.w = pk2(b.z, b.w); return o; }
; DI float sigmoidf_(float x) { return frcp(1.f + fexp2(-x * LOG2E)); }
; #define EPI_SCHED() __builtin_amdgcn_sched_barrier(0)
;     DI void operator()(const AccT& acc, const Unit& u, int wr, int wc, int fr, int fq) const {
;     ...
;             for (int m = 0; m < 4; ++m) {
;                 EPI_SCHED(); const size_t row = row0 + ai * 128 + m * 16;
;                 const size_t b = row >> 11, s = row & 2047;
; #pragma unroll
;                 for (int bj = 0; bj < 2; ++bj) {
;                     const int cc = bj * 128 + wc * 32 + fq * 8;
;                     f32x4 a = acc[ai][bj][m][0] * rs[ai][m], c = acc[ai][bj][m][1] * rs[ai][m];
;                     if (u.pn < 4) *(u32x4*)(q + row * 1024 + u.pn * 256 + cc) = pk8(a, c);
;                     else if (u.pn < 8) { const int g = cc >> 6, d = cc & 63; *(u32x4*)(slab + (size_t)(u.pn - 4) * SLAB_EL + ((b * 4 + g) * 2048 + s) * 64 + d) = pk8(a, c); }
;                     else if (cc < 48) {
; #pragma unroll
;                         for (int e = 0; e < 4; ++e) { a[e] = sigmoidf_(a[e]); c[e] = sigmoidf_(c[e]); }
;                         *(f32x4*)(gates + row * 48 + cc) = a; *(f32x4*)(gates + row * 48 + cc + 4) = c;
;                     }
.LBB0_2056:
	v_lshlrev_b64 v[10:11], 11, v[68:69]
	v_lshl_add_u64 v[10:11], s[16:17], 0, v[10:11]
	s_andn2_b64 vcc, exec, s[6:7]
	v_lshl_add_u64 v[10:11], s[36:37], 1, v[10:11]
	s_cbranch_vccnz .LBB0_2058
	v_cvt_pk_bf16_f32 v14, v14, v15
	v_cvt_pk_bf16_f32 v15, v16, v17
	v_cvt_pk_bf16_f32 v16, v22, v23
	v_cvt_pk_bf16_f32 v17, v12, v13
	v_lshl_add_u64 v[12:13], v[130:131], 1, v[10:11]
	global_store_dwordx4 v[12:13], v[14:17], off
.LBB0_2058:
	v_mov_b32_e32 v21, v20
	v_mov_b32_e32 v12, v20
	v_mov_b32_e32 v13, v20
	v_pk_mul_f32 v[8:9], v[8:9], v[12:13]
	v_pk_mul_f32 v[6:7], v[6:7], v[20:21]
	v_pk_mul_f32 v[4:5], v[4:5], v[12:13]
	v_pk_mul_f32 v[2:3], v[2:3], v[20:21]
	s_and_b64 vcc, exec, s[4:5]
	s_mov_b64 s[4:5], -1
	s_cbranch_vccnz .LBB0_2067
	s_and_b64 vcc, exec, s[2:3]
	s_mov_b64 s[2:3], -1
	s_cbranch_vccnz .LBB0_2063
	s_movk_i32 s0, 0xffb0
	v_cmp_gt_i32_e32 vcc, s0, v130
	s_and_saveexec_b64 s[2:3], vcc
	s_cbranch_execz .LBB0_2062
	v_mul_f32_e32 v0, 0xbfb8aa3b, v6
	v_exp_f32_e32 v0, v0
	v_mul_f32_e32 v12, 0xbfb8aa3b, v2
	v_exp_f32_e32 v12, v12
	v_mul_f32_e32 v14, 0xbfb8aa3b, v3
	v_add_f32_e32 v0, 1.0, v0
	v_exp_f32_e32 v14, v14
	v_add_f32_e32 v13, 1.0, v12
	v_rcp_f32_e32 v12, v0
	v_mul_f32_e32 v0, 0xbfb8aa3b, v7
	v_exp_f32_e32 v0, v0
	v_rcp_f32_e32 v20, v13
	v_mul_f32_e32 v15, 0xbfb8aa3b, v4
	v_exp_f32_e32 v15, v15
	v_add_f32_e32 v0, 1.0, v0
	v_rcp_f32_e32 v13, v0
	v_add_f32_e32 v0, 1.0, v14
	v_mul_f32_e32 v14, 0xbfb8aa3b, v8
	v_exp_f32_e32 v14, v14
	v_rcp_f32_e32 v21, v0
	v_mul_f32_e32 v16, 0xbfb8aa3b, v5
	v_exp_f32_e32 v16, v16
	v_add_f32_e32 v0, 1.0, v14
	v_rcp_f32_e32 v14, v0
	v_add_f32_e32 v0, 1.0, v15
	v_mul_f32_e32 v15, 0xbfb8aa3b, v9
	v_exp_f32_e32 v15, v15
	v_rcp_f32_e32 v22, v0
	v_add_f32_e32 v0, 1.0, v15
	v_rcp_f32_e32 v15, v0
	v_add_f32_e32 v0, 1.0, v16
	v_rcp_f32_e32 v23, v0
	v_lshl_add_u64 v[16:17], v[18:19], 2, s[18:19]
	v_lshl_add_u64 v[16:17], v[130:131], 2, v[16:17]
	global_store_dwordx4 v[16:17], v[12:15], off offset:512
	global_store_dwordx4 v[16:17], v[20:23], off offset:528

; DI u32x4 pk8(f32x4 a, f32x4 b) { u32x4 o; o.x = pk2(a.x, a.y); o.y = pk2(a.z, a.w); o.z = pk2(b.x, b.y); o.w = pk2(b.z, b.w); return o; }
; #define EPI_SCHED() __builtin_amdgcn_sched_barrier(0)
;     DI void operator()(const AccT& acc, const Unit& u, int wr, int wc, int fr, int fq) const {
;     ...
;             for (int m = 0; m < 4; ++m) {
;                 EPI_SCHED(); const size_t row = row0 + ai * 128 + m * 16;
;                 const size_t b = row >> 11, s = row & 2047;
; #pragma unroll
;                 for (int bj = 0; bj < 2; ++bj) {
;                     const int cc = bj * 128 + wc * 32 + fq * 8;
;                     f32x4 a = acc[ai][bj][m][0] * rs[ai][m], c = acc[ai][bj][m][1] * rs[ai][m];
;                     if (u.pn < 4) *(u32x4*)(q + row * 1024 + u.pn * 256 + cc) = pk8(a, c);
;                     else if (u.pn < 8) { const int g = cc >> 6, d = cc & 63; *(u32x4*)(slab + (size_t)(u.pn - 4) * SLAB_EL + ((b * 4 + g) * 2048 + s) * 64 + d) = pk8(a, c); }
.LBB0_2063:
	s_andn2_b64 vcc, exec, s[2:3]
	s_cbranch_vccnz .LBB0_2065
	v_ashrrev_i32_e32 v16, 6, v124
	v_ashrrev_i32_e32 v17, 31, v16
	s_add_u32 s0, s61, s34
	v_lshl_add_u64 v[16:17], v[66:67], 0, v[16:17]
	s_addc_u32 s1, s64, s35
	v_lshlrev_b64 v[16:17], 18, v[16:17]
	v_and_b32_e32 v18, 56, v130
	v_lshl_add_u64 v[16:17], s[0:1], 0, v[16:17]
	v_lshlrev_b32_e32 v0, 1, v24
	v_lshl_add_u64 v[16:17], v[16:17], 0, v[0:1]
	v_lshlrev_b32_e32 v0, 1, v18
	v_cvt_pk_bf16_f32 v12, v6, v7
	v_cvt_pk_bf16_f32 v13, v8, v9
	v_cvt_pk_bf16_f32 v14, v2, v3
	v_cvt_pk_bf16_f32 v15, v4, v5
	v_lshl_add_u64 v[16:17], v[16:17], 0, v[0:1]
	global_store_dwordx4 v[16:17], v[12:15], off

; DI u32x4 pk8(f32x4 a, f32x4 b) { u32x4 o; o.x = pk2(a.x, a.y); o.y = pk2(a.z, a.w); o.z = pk2(b.x, b.y); o.w = pk2(b.z, b.w); return o; }
;     DI void operator()(const AccT& acc, const Unit& u, int wr, int wc, int fr, int fq) const {
;     ...
;                 for (int bj = 0; bj < 2; ++bj) {
;                     const int cc = bj * 128 + wc * 32 + fq * 8;
;                     f32x4 a = acc[ai][bj][m][0] * rs[ai][m], c = acc[ai][bj][m][1] * rs[ai][m];
;                     if (u.pn < 4) *(u32x4*)(q + row * 1024 + u.pn * 256 + cc) = pk8(a, c);
.LBB0_2068:
	v_cvt_pk_bf16_f32 v6, v6, v7
	v_cvt_pk_bf16_f32 v7, v8, v9
	v_cvt_pk_bf16_f32 v8, v2, v3
	v_cvt_pk_bf16_f32 v9, v4, v5
	v_lshl_add_u64 v[2:3], v[130:131], 1, v[10:11]
	global_store_dwordx4 v[2:3], v[6:9], off offset:256
	s_andn2_b64 vcc, exec, s[26:27]
	s_mov_b64 s[2:3], -1
	s_cbranch_vccnz .LBB0_1883

; #define EPI_SCHED() __builtin_amdgcn_sched_barrier(0)
;     DI void operator()(const AccT& acc, const Unit& u, int wr, int wc, int fr, int fq) const {
;     ...
;                 for (int hb2 = 0; hb2 < 2; ++hb2) {
;                     f32x4 v[4][NP4];
; #pragma unroll
;                     for (int e = 0; e < 4; ++e)
; #pragma unroll
;                         for (int i = 0; i < NP4; ++i) v[e][i] = *(const f32x4*)(parts + (col + 4 * hb2 + e) * STRIDE + P0 + 4 * i);
; #pragma unroll
;                     for (int e = 0; e < 4; ++e) { float t = 0.f;
; #pragma unroll
;                         for (int i = 0; i < NP4; ++i) t += (v[e][i].x + v[e][i].y) + (v[e][i].z + v[e][i].w);
;                         const float r = rsqrtf(t * invK + EPS); if (hb2 == 0) c0[e] = r; else c1[e] = r; }
;                     EPI_SCHED();
;                 }
.LBB0_2088:
	s_mov_b32 s0, -1
	s_ashr_i32 s25, s24, 31
	v_mbcnt_lo_u32_b32 v0, s0, 0
	v_mbcnt_hi_u32_b32 v0, s0, v0
	s_lshl_b64 s[0:1], s[24:25], 8
	v_ashrrev_i32_e32 v130, 1, v0
	v_and_b32_e32 v130, -8, v130
	v_ashrrev_i32_e32 v131, 31, v130
	s_or_b64 s[0:1], s[0:1], s[96:97]
	s_ashr_i32 s3, s2, 31
	v_lshl_add_u64 v[168:169], s[0:1], 0, v[130:131]
	s_lshl_b64 s[0:1], s[2:3], 8
	s_add_u32 s0, s0, s49
	s_addc_u32 s1, s1, s54
	v_and_or_b32 v162, v0, 15, s0
	v_mov_b32_e32 v163, s1
	v_lshlrev_b64 v[130:131], 6, v[168:169]
	v_lshl_add_u64 v[166:167], s[8:9], 0, v[130:131]
	global_load_dwordx4 v[178:181], v[166:167], off
	global_load_dwordx4 v[182:185], v[166:167], off offset:16
	global_load_dwordx4 v[186:189], v[166:167], off offset:32
	global_load_dwordx4 v[190:193], v[166:167], off offset:48
	global_load_dwordx4 v[194:197], v[166:167], off offset:64
	global_load_dwordx4 v[198:201], v[166:167], off offset:80
	global_load_dwordx4 v[202:205], v[166:167], off offset:96
	global_load_dwordx4 v[210:213], v[166:167], off offset:112
	global_load_dwordx4 v[154:157], v[166:167], off offset:128
	global_load_dwordx4 v[146:149], v[166:167], off offset:144
	global_load_dwordx4 v[134:137], v[166:167], off offset:160
	global_load_dwordx4 v[130:133], v[166:167], off offset:176
	global_load_dwordx4 v[158:161], v[166:167], off offset:192
	global_load_dwordx4 v[150:153], v[166:167], off offset:208
	global_load_dwordx4 v[142:145], v[166:167], off offset:224
	global_load_dwordx4 v[138:141], v[166:167], off offset:240
	s_mov_b32 s0, 0x358637bd
	s_waitcnt vmcnt(0) lgkmcnt(0)
	v_mov_b32_e32 v164, v178
	v_mov_b32_e32 v170, v180
	v_mov_b32_e32 v178, v184
	v_mov_b32_e32 v165, v194
	v_mov_b32_e32 v194, v179
	v_mov_b32_e32 v171, v196
	v_mov_b32_e32 v196, v181
	v_pk_add_f32 v[164:165], v[164:165], v[194:195]
	v_pk_add_f32 v[170:171], v[170:171], v[196:197]
	v_mov_b32_e32 v179, v200
	v_pk_add_f32 v[164:165], v[164:165], v[170:171]
	v_mov_b32_e32 v170, v182
	v_mov_b32_e32 v171, v198
	v_mov_b32_e32 v198, v183
	v_mov_b32_e32 v200, v185
	v_pk_add_f32 v[170:171], v[170:171], v[198:199]
	v_pk_add_f32 v[178:179], v[178:179], v[200:201]
	v_pk_add_f32 v[164:165], v[164:165], 0 op_sel_hi:[1,0]
	v_pk_add_f32 v[170:171], v[170:171], v[178:179]
	v_mov_b32_e32 v178, v188
	v_pk_add_f32 v[164:165], v[164:165], v[170:171]
	v_mov_b32_e32 v170, v186
	v_mov_b32_e32 v171, v202
	v_mov_b32_e32 v202, v187
	v_mov_b32_e32 v179, v204
	v_mov_b32_e32 v204, v189
	v_pk_add_f32 v[170:171], v[170:171], v[202:203]
	v_pk_add_f32 v[178:179], v[178:179], v[204:205]
	s_nop 0
	v_pk_add_f32 v[170:171], v[170:171], v[178:179]
	v_mov_b32_e32 v178, v192
	v_pk_add_f32 v[164:165], v[164:165], v[170:171]
	v_mov_b32_e32 v170, v190
	v_mov_b32_e32 v171, v210
	v_mov_b32_e32 v210, v191
	v_mov_b32_e32 v179, v212
	v_mov_b32_e32 v212, v193
	v_pk_add_f32 v[170:171], v[170:171], v[210:211]
	v_pk_add_f32 v[178:179], v[178:179], v[212:213]
	s_nop 0
	v_pk_add_f32 v[170:171], v[170:171], v[178:179]
	s_nop 0
	v_pk_add_f32 v[170:171], v[164:165], v[170:171]
	v_mov_b64_e32 v[164:165], s[0:1]
	v_pk_fma_f32 v[170:171], v[170:171], s[88:89], v[164:165] op_sel_hi:[1,0,0]
	s_nop 0
	v_mul_f32_e32 v0, 0x4b800000, v170
	v_cmp_gt_f32_e64 s[2:3], s42, v170
	v_cmp_gt_f32_e32 vcc, s42, v171
	s_nop 0
	v_cndmask_b32_e64 v0, v170, v0, s[2:3]
	v_rsq_f32_e32 v170, v0
	v_mul_f32_e32 v0, 0x4b800000, v171
	v_cndmask_b32_e32 v0, v171, v0, vcc
	v_rsq_f32_e32 v171, v0
	s_nop 0
	v_pk_mul_f32 v[178:179], v[170:171], s[52:53] op_sel_hi:[1,0]
	s_nop 0
	v_cndmask_b32_e32 v171, v171, v179, vcc
	v_cndmask_b32_e64 v170, v170, v178, s[2:3]
	v_mov_b32_e32 v178, v154
	v_mov_b32_e32 v179, v158
	v_mov_b32_e32 v158, v155
	v_pk_add_f32 v[154:155], v[178:179], v[158:159]
	v_mov_b32_e32 v158, v156
	v_mov_b32_e32 v159, v160
	v_mov_b32_e32 v160, v157
	v_pk_add_f32 v[156:157], v[158:159], v[160:161]
	s_nop 0
	v_pk_add_f32 v[154:155], v[154:155], v[156:157]
	v_mov_b32_e32 v156, v146
	v_mov_b32_e32 v157, v150
	v_mov_b32_e32 v150, v147
	v_pk_add_f32 v[146:147], v[156:157], v[150:151]
	v_mov_b32_e32 v150, v148
	v_mov_b32_e32 v151, v152
	v_mov_b32_e32 v152, v149
	v_pk_add_f32 v[148:149], v[150:151], v[152:153]
	v_pk_add_f32 v[154:155], v[154:155], 0 op_sel_hi:[1,0]
	v_pk_add_f32 v[146:147], v[146:147], v[148:149]
	v_mov_b32_e32 v148, v134
	v_mov_b32_e32 v149, v142
	v_mov_b32_e32 v142, v135
	v_pk_add_f32 v[134:135], v[148:149], v[142:143]
	v_mov_b32_e32 v142, v136
	v_mov_b32_e32 v143, v144
	v_mov_b32_e32 v144, v137
	v_pk_add_f32 v[136:137], v[142:143], v[144:145]
	v_pk_add_f32 v[146:147], v[154:155], v[146:147]
	v_pk_add_f32 v[134:135], v[134:135], v[136:137]
	v_mov_b32_e32 v136, v130
	v_mov_b32_e32 v137, v138
	v_mov_b32_e32 v138, v131
	v_pk_add_f32 v[130:131], v[136:137], v[138:139]
	v_mov_b32_e32 v136, v132
	v_mov_b32_e32 v137, v140
	v_mov_b32_e32 v140, v133
	v_pk_add_f32 v[132:133], v[136:137], v[140:141]
	v_pk_add_f32 v[134:135], v[146:147], v[134:135]
	v_pk_add_f32 v[130:131], v[130:131], v[132:133]
	s_nop 0
	v_pk_add_f32 v[130:131], v[134:135], v[130:131]
	s_nop 0
	v_pk_fma_f32 v[130:131], v[130:131], s[88:89], v[164:165] op_sel_hi:[1,0,0]
	s_nop 0
	v_mul_f32_e32 v0, 0x4b800000, v130
	v_cmp_gt_f32_e64 s[2:3], s42, v130
	v_cmp_gt_f32_e32 vcc, s42, v131
	s_nop 0
	v_cndmask_b32_e64 v0, v130, v0, s[2:3]
	v_rsq_f32_e32 v130, v0
	v_mul_f32_e32 v0, 0x4b800000, v131
	v_cndmask_b32_e32 v0, v131, v0, vcc
	v_rsq_f32_e32 v131, v0
	s_nop 0
	v_pk_mul_f32 v[132:133], v[130:131], s[52:53] op_sel_hi:[1,0]
	s_nop 0
	v_cndmask_b32_e32 v151, v131, v133, vcc
	v_cndmask_b32_e64 v150, v130, v132, s[2:3]
	global_load_dwordx4 v[152:155], v[166:167], off offset:256
	global_load_dwordx4 v[156:159], v[166:167], off offset:272
	global_load_dwordx4 v[178:181], v[166:167], off offset:288
	global_load_dwordx4 v[182:185], v[166:167], off offset:304
	global_load_dwordx4 v[186:189], v[166:167], off offset:320
	global_load_dwordx4 v[190:193], v[166:167], off offset:336
	global_load_dwordx4 v[194:197], v[166:167], off offset:352
	global_load_dwordx4 v[198:201], v[166:167], off offset:368
	global_load_dwordx4 v[202:205], v[166:167], off offset:384
	global_load_dwordx4 v[146:149], v[166:167], off offset:400
	global_load_dwordx4 v[134:137], v[166:167], off offset:416
	global_load_dwordx4 v[130:133], v[166:167], off offset:432
	global_load_dwordx4 v[210:213], v[166:167], off offset:448
	global_load_dwordx4 v[214:217], v[166:167], off offset:464
	global_load_dwordx4 v[142:145], v[166:167], off offset:480
	global_load_dwordx4 v[138:141], v[166:167], off offset:496
	s_waitcnt vmcnt(0) lgkmcnt(0)
; DI u32x4 pk8(f32x4 a, f32x4 b) { u32x4 o; o.x = pk2(a.x, a.y); o.y = pk2(a.z, a.w); o.z = pk2(b.x, b.y); o.w = pk2(b.z, b.w); return o; }
; #define EPI_SCHED() __builtin_amdgcn_sched_barrier(0)
;     DI void operator()(const AccT& acc, const Unit& u, int wr, int wc, int fr, int fq) const {
;     ...
;                         for (int i = 0; i < NP4; ++i) v[e][i] = *(const f32x4*)(parts + (col + 4 * hb2 + e) * STRIDE + P0 + 4 * i);
; #pragma unroll
;                     for (int e = 0; e < 4; ++e) { float t = 0.f;
; #pragma unroll
;                         for (int i = 0; i < NP4; ++i) t += (v[e][i].x + v[e][i].y) + (v[e][i].z + v[e][i].w);
;                         const float r = rsqrtf(t * invK + EPS); if (hb2 == 0) c0[e] = r; else c1[e] = r; }
;                     EPI_SCHED();
;                 }
;             }
; #pragma unroll
;             for (int ai = 0; ai < 2; ++ai)
; #pragma unroll
;                 for (int m = 0; m < 4; ++m) {
;                     const size_t row = (size_t)u.pm * 256 + ai * 128 + wr * 64 + m * 16 + fr;
;                     *(u32x4*)(out + ((col >> 11) * nrows + row) * VPITCH + (col & 2047)) = pk8(acc[ai][bj][m][0] * c0, acc[ai][bj][m][1] * c1);
;                 }
	v_mov_b32_e32 v160, v152
	v_mov_b32_e32 v161, v186
	v_mov_b32_e32 v186, v153
	v_pk_add_f32 v[152:153], v[160:161], v[186:187]
	v_mov_b32_e32 v160, v154
	v_mov_b32_e32 v161, v188
	v_mov_b32_e32 v188, v155
	v_pk_add_f32 v[154:155], v[160:161], v[188:189]
	s_nop 0
	v_pk_add_f32 v[152:153], v[152:153], v[154:155]
	v_mov_b32_e32 v154, v156
	v_mov_b32_e32 v155, v190
	v_mov_b32_e32 v190, v157
	v_mov_b32_e32 v156, v158
	v_mov_b32_e32 v157, v192
	v_mov_b32_e32 v192, v159
	v_pk_add_f32 v[154:155], v[154:155], v[190:191]
	v_pk_add_f32 v[156:157], v[156:157], v[192:193]
	v_pk_add_f32 v[152:153], v[152:153], 0 op_sel_hi:[1,0]
	v_pk_add_f32 v[154:155], v[154:155], v[156:157]
	v_mov_b32_e32 v156, v180
	v_pk_add_f32 v[152:153], v[152:153], v[154:155]
	v_mov_b32_e32 v154, v178
	v_mov_b32_e32 v155, v194
	v_mov_b32_e32 v194, v179
	v_mov_b32_e32 v157, v196
	v_mov_b32_e32 v196, v181
	v_pk_add_f32 v[154:155], v[154:155], v[194:195]
	v_pk_add_f32 v[156:157], v[156:157], v[196:197]
	s_nop 0
	v_pk_add_f32 v[154:155], v[154:155], v[156:157]
	v_mov_b32_e32 v156, v184
	v_pk_add_f32 v[152:153], v[152:153], v[154:155]
	v_mov_b32_e32 v154, v182
	v_mov_b32_e32 v155, v198
	v_mov_b32_e32 v198, v183
	v_mov_b32_e32 v157, v200
	v_mov_b32_e32 v200, v185
	v_pk_add_f32 v[154:155], v[154:155], v[198:199]
	v_pk_add_f32 v[156:157], v[156:157], v[200:201]
	s_nop 0
	v_pk_add_f32 v[154:155], v[154:155], v[156:157]
	v_mov_b32_e32 v156, v204
	v_pk_add_f32 v[152:153], v[152:153], v[154:155]
	v_mov_b32_e32 v157, v212
	v_pk_fma_f32 v[152:153], v[152:153], s[88:89], v[164:165] op_sel_hi:[1,0,0]
	v_mov_b32_e32 v212, v205
	v_mul_f32_e32 v0, 0x4b800000, v152
	v_cmp_gt_f32_e64 s[2:3], s42, v152
	v_cmp_gt_f32_e32 vcc, s42, v153
	v_pk_add_f32 v[156:157], v[156:157], v[212:213]
	v_cndmask_b32_e64 v0, v152, v0, s[2:3]
	v_rsq_f32_e32 v152, v0
	v_mul_f32_e32 v0, 0x4b800000, v153
	v_cndmask_b32_e32 v0, v153, v0, vcc
	v_rsq_f32_e32 v153, v0
	s_nop 0
	v_pk_mul_f32 v[154:155], v[152:153], s[52:53] op_sel_hi:[1,0]
	s_nop 0
	v_cndmask_b32_e32 v153, v153, v155, vcc
	v_cndmask_b32_e64 v152, v152, v154, s[2:3]
	v_mov_b32_e32 v154, v202
	v_mov_b32_e32 v155, v210
	v_mov_b32_e32 v210, v203
	v_pk_add_f32 v[154:155], v[154:155], v[210:211]
	s_nop 0
	v_pk_add_f32 v[154:155], v[154:155], v[156:157]
	v_mov_b32_e32 v156, v146
	v_mov_b32_e32 v157, v214
	v_mov_b32_e32 v214, v147
	v_pk_add_f32 v[146:147], v[156:157], v[214:215]
	v_mov_b32_e32 v156, v148
	v_mov_b32_e32 v157, v216
	v_mov_b32_e32 v216, v149
	v_pk_add_f32 v[148:149], v[156:157], v[216:217]
	v_pk_add_f32 v[154:155], v[154:155], 0 op_sel_hi:[1,0]
	v_pk_add_f32 v[146:147], v[146:147], v[148:149]
	v_mov_b32_e32 v148, v134
	v_mov_b32_e32 v149, v142
	v_mov_b32_e32 v142, v135
	v_pk_add_f32 v[134:135], v[148:149], v[142:143]
	v_mov_b32_e32 v142, v136
	v_mov_b32_e32 v143, v144
	v_mov_b32_e32 v144, v137
	v_pk_add_f32 v[136:137], v[142:143], v[144:145]
	v_pk_add_f32 v[146:147], v[154:155], v[146:147]
	v_pk_add_f32 v[134:135], v[134:135], v[136:137]
	v_mov_b32_e32 v136, v130
	v_mov_b32_e32 v137, v138
	v_mov_b32_e32 v138, v131
	v_pk_add_f32 v[130:131], v[136:137], v[138:139]
	v_mov_b32_e32 v136, v132
	v_mov_b32_e32 v137, v140
	v_mov_b32_e32 v140, v133
	v_pk_add_f32 v[132:133], v[136:137], v[140:141]
	v_pk_add_f32 v[134:135], v[146:147], v[134:135]
	v_pk_add_f32 v[130:131], v[130:131], v[132:133]
	s_nop 0
	v_pk_add_f32 v[130:131], v[134:135], v[130:131]
	s_nop 0
	v_pk_fma_f32 v[130:131], v[130:131], s[88:89], v[164:165] op_sel_hi:[1,0,0]
	s_nop 0
	v_mul_f32_e32 v0, 0x4b800000, v130
	v_cmp_gt_f32_e64 s[2:3], s42, v130
	v_cmp_gt_f32_e32 vcc, s42, v131
	s_nop 0
	v_cndmask_b32_e64 v0, v130, v0, s[2:3]
	v_rsq_f32_e32 v130, v0
	v_mul_f32_e32 v0, 0x4b800000, v131
	v_cndmask_b32_e32 v0, v131, v0, vcc
	v_rsq_f32_e32 v131, v0
	s_nop 0
	v_pk_mul_f32 v[132:133], v[130:131], s[52:53] op_sel_hi:[1,0]
	s_nop 0
	v_cndmask_b32_e32 v131, v131, v133, vcc
	v_cndmask_b32_e64 v130, v130, v132, s[2:3]
	v_pk_mul_f32 v[126:127], v[126:127], v[170:171]
	v_pk_mul_f32 v[122:123], v[122:123], v[152:153]
	v_pk_mul_f32 v[128:129], v[128:129], v[150:151]
	v_pk_mul_f32 v[132:133], v[124:125], v[130:131]
	v_cvt_pk_bf16_f32 v124, v126, v127
	v_cvt_pk_bf16_f32 v126, v122, v123
	v_lshrrev_b64 v[122:123], 2, v[168:169]
	v_cvt_pk_bf16_f32 v125, v128, v129
	v_and_b32_e32 v129, 0x3fffffff, v123
	v_and_b32_e32 v128, 0xfffffe00, v122
	v_cvt_pk_bf16_f32 v127, v132, v133
	v_lshl_add_u64 v[132:133], v[128:129], 0, v[162:163]
	v_mov_b64_e32 v[122:123], s[6:7]
	v_mad_u64_u32 v[134:135], s[0:1], v132, s43, v[122:123]
	v_mov_b32_e32 v0, v135
	v_and_b32_e32 v136, 0x7f8, v168
	v_mad_u64_u32 v[132:133], s[0:1], v133, s43, v[0:1]
	v_mov_b32_e32 v135, v132
	v_lshlrev_b32_e32 v0, 1, v136
	v_lshl_add_u64 v[132:133], v[134:135], 0, v[0:1]
	v_pk_mul_f32 v[118:119], v[118:119], v[170:171]
	v_pk_mul_f32 v[114:115], v[114:115], v[152:153]
	global_store_dwordx4 v[132:133], v[124:127], off
	v_pk_mul_f32 v[120:121], v[120:121], v[150:151]
	v_pk_mul_f32 v[110:111], v[110:111], v[170:171]
	v_pk_mul_f32 v[124:125], v[116:117], v[130:131]
	v_cvt_pk_bf16_f32 v116, v118, v119
	v_cvt_pk_bf16_f32 v118, v114, v115
	v_or_b32_e32 v114, 16, v162
	v_mov_b32_e32 v115, v163
	v_cvt_pk_bf16_f32 v117, v120, v121
	v_lshl_add_u64 v[120:121], v[128:129], 0, v[114:115]
	v_cvt_pk_bf16_f32 v119, v124, v125
	v_mad_u64_u32 v[124:125], s[0:1], v120, s43, v[122:123]
	v_mov_b32_e32 v120, v125
	v_mad_u64_u32 v[120:121], s[0:1], v121, s43, v[120:121]
	v_mov_b32_e32 v125, v120
	v_lshl_add_u64 v[120:121], v[124:125], 0, v[0:1]
	v_pk_mul_f32 v[106:107], v[106:107], v[152:153]
	global_store_dwordx4 v[120:121], v[116:119], off
	v_pk_mul_f32 v[112:113], v[112:113], v[150:151]
; DI u32x4 pk8(f32x4 a, f32x4 b) { u32x4 o; o.x = pk2(a.x, a.y); o.y = pk2(a.z, a.w); o.z = pk2(b.x, b.y); o.w = pk2(b.z, b.w); return o; }
;     DI void operator()(const AccT& acc, const Unit& u, int wr, int wc, int fr, int fq) const {
;     ...
;                 for (int hb2 = 0; hb2 < 2; ++hb2) {
;                     f32x4 v[4][NP4];
; #pragma unroll
;                     for (int e = 0; e < 4; ++e)
; #pragma unroll
;                         for (int i = 0; i < NP4; ++i) v[e][i] = *(const f32x4*)(parts + (col + 4 * hb2 + e) * STRIDE + P0 + 4 * i);
;     ...
; #pragma unroll
;             for (int ai = 0; ai < 2; ++ai)
; #pragma unroll
;                 for (int m = 0; m < 4; ++m) {
;                     const size_t row = (size_t)u.pm * 256 + ai * 128 + wr * 64 + m * 16 + fr;
;                     *(u32x4*)(out + ((col >> 11) * nrows + row) * VPITCH + (col & 2047)) = pk8(acc[ai][bj][m][0] * c0, acc[ai][bj][m][1] * c1);
;                 }
	v_pk_mul_f32 v[104:105], v[104:105], v[150:151]
	v_pk_mul_f32 v[116:117], v[108:109], v[130:131]
	v_cvt_pk_bf16_f32 v108, v110, v111
	v_cvt_pk_bf16_f32 v110, v106, v107
	v_or_b32_e32 v106, 32, v162
	v_mov_b32_e32 v107, v163
	v_cvt_pk_bf16_f32 v109, v112, v113
	v_lshl_add_u64 v[112:113], v[128:129], 0, v[106:107]
	v_cvt_pk_bf16_f32 v111, v116, v117
	v_mad_u64_u32 v[116:117], s[0:1], v112, s43, v[122:123]
	v_mov_b32_e32 v112, v117
	v_mad_u64_u32 v[112:113], s[0:1], v113, s43, v[112:113]
	v_mov_b32_e32 v117, v112
	v_lshl_add_u64 v[112:113], v[116:117], 0, v[0:1]
	global_store_dwordx4 v[112:113], v[108:111], off
	v_pk_mul_f32 v[102:103], v[102:103], v[170:171]
	v_pk_mul_f32 v[94:95], v[94:95], v[170:171]
	v_pk_mul_f32 v[108:109], v[100:101], v[130:131]
	v_pk_mul_f32 v[100:101], v[98:99], v[152:153]
	v_cvt_pk_bf16_f32 v99, v104, v105
	v_or_b32_e32 v104, 48, v162
	v_mov_b32_e32 v105, v163
	v_cvt_pk_bf16_f32 v98, v102, v103
	v_lshl_add_u64 v[102:103], v[128:129], 0, v[104:105]
	v_cvt_pk_bf16_f32 v100, v100, v101
	v_cvt_pk_bf16_f32 v101, v108, v109
	v_mad_u64_u32 v[108:109], s[0:1], v102, s43, v[122:123]
	v_mov_b32_e32 v102, v109
	v_mad_u64_u32 v[102:103], s[0:1], v103, s43, v[102:103]
	v_mov_b32_e32 v109, v102
	v_lshl_add_u64 v[102:103], v[108:109], 0, v[0:1]
	global_store_dwordx4 v[102:103], v[98:101], off
	v_lshl_add_u64 v[102:103], v[162:163], 0, s[58:59]
	v_pk_mul_f32 v[96:97], v[96:97], v[150:151]
	v_pk_mul_f32 v[98:99], v[92:93], v[130:131]
	v_pk_mul_f32 v[92:93], v[90:91], v[152:153]
	v_cvt_pk_bf16_f32 v90, v94, v95
	v_lshl_add_u64 v[94:95], v[128:129], 0, v[102:103]
	v_cvt_pk_bf16_f32 v91, v96, v97
	v_mad_u64_u32 v[96:97], s[0:1], v94, s43, v[122:123]
	v_mov_b32_e32 v94, v97
	v_mad_u64_u32 v[94:95], s[0:1], v95, s43, v[94:95]
	v_mov_b32_e32 v97, v94
	s_mov_b64 s[0:1], 0x90
	v_cvt_pk_bf16_f32 v92, v92, v93
	v_cvt_pk_bf16_f32 v93, v98, v99
	v_lshl_add_u64 v[94:95], v[96:97], 0, v[0:1]
	v_pk_mul_f32 v[86:87], v[86:87], v[170:171]
	v_lshl_add_u64 v[108:109], v[162:163], 0, s[0:1]
	global_store_dwordx4 v[94:95], v[90:93], off
	v_pk_mul_f32 v[88:89], v[88:89], v[150:151]
	v_pk_mul_f32 v[78:79], v[78:79], v[170:171]
	v_pk_mul_f32 v[90:91], v[84:85], v[130:131]
	v_pk_mul_f32 v[84:85], v[82:83], v[152:153]
	v_cvt_pk_bf16_f32 v82, v86, v87
	v_lshl_add_u64 v[86:87], v[128:129], 0, v[108:109]
	v_cvt_pk_bf16_f32 v83, v88, v89
	v_mad_u64_u32 v[88:89], s[0:1], v86, s43, v[122:123]
	v_mov_b32_e32 v86, v89
	v_mad_u64_u32 v[86:87], s[0:1], v87, s43, v[86:87]
	v_mov_b32_e32 v89, v86
	s_mov_b64 s[0:1], 0xa0
	v_cvt_pk_bf16_f32 v84, v84, v85
	v_cvt_pk_bf16_f32 v85, v90, v91
	v_lshl_add_u64 v[86:87], v[88:89], 0, v[0:1]
	v_lshl_add_u64 v[110:111], v[162:163], 0, s[0:1]
	global_store_dwordx4 v[86:87], v[82:85], off
	v_pk_mul_f32 v[80:81], v[80:81], v[150:151]
	v_pk_mul_f32 v[70:71], v[70:71], v[170:171]
	v_pk_mul_f32 v[82:83], v[76:77], v[130:131]
	v_pk_mul_f32 v[76:77], v[74:75], v[152:153]
	v_cvt_pk_bf16_f32 v74, v78, v79
	v_lshl_add_u64 v[78:79], v[128:129], 0, v[110:111]
	v_cvt_pk_bf16_f32 v75, v80, v81
	v_mad_u64_u32 v[80:81], s[0:1], v78, s43, v[122:123]
	v_mov_b32_e32 v78, v81
	v_mad_u64_u32 v[78:79], s[0:1], v79, s43, v[78:79]
	v_mov_b32_e32 v81, v78
	s_mov_b64 s[0:1], 0xb0
	v_cvt_pk_bf16_f32 v76, v76, v77
	v_cvt_pk_bf16_f32 v77, v82, v83
	v_lshl_add_u64 v[78:79], v[80:81], 0, v[0:1]
	v_lshl_add_u64 v[112:113], v[162:163], 0, s[0:1]
	global_store_dwordx4 v[78:79], v[74:77], off
	v_pk_mul_f32 v[72:73], v[72:73], v[150:151]
	s_nop 0
	v_pk_mul_f32 v[74:75], v[68:69], v[130:131]
	v_pk_mul_f32 v[68:69], v[66:67], v[152:153]
	v_cvt_pk_bf16_f32 v66, v70, v71
	v_lshl_add_u64 v[70:71], v[128:129], 0, v[112:113]
	v_cvt_pk_bf16_f32 v67, v72, v73
	v_mad_u64_u32 v[72:73], s[0:1], v70, s43, v[122:123]
	v_mov_b32_e32 v70, v73
	v_mad_u64_u32 v[70:71], s[0:1], v71, s43, v[70:71]
	v_mov_b32_e32 v73, v70
	v_cvt_pk_bf16_f32 v68, v68, v69
	v_cvt_pk_bf16_f32 v69, v74, v75
	v_lshl_add_u64 v[70:71], v[72:73], 0, v[0:1]
	global_store_dwordx4 v[70:71], v[66:69], off
	v_lshl_add_u64 v[116:117], v[168:169], 0, s[58:59]
	s_nop 0
	v_lshlrev_b64 v[66:67], 6, v[116:117]
	v_lshl_add_u64 v[66:67], s[8:9], 0, v[66:67]
	global_load_dwordx4 v[124:127], v[66:67], off
	global_load_dwordx4 v[128:131], v[66:67], off offset:16
	global_load_dwordx4 v[132:135], v[66:67], off offset:32
	global_load_dwordx4 v[98:101], v[66:67], off offset:48
	s_movk_i32 s0, 0x2000
	v_add_co_u32_e32 v118, vcc, s0, v166
	s_waitcnt vmcnt(0) lgkmcnt(0)
	v_mov_b32_e32 v120, v124
	v_addc_co_u32_e32 v119, vcc, 0, v167, vcc
	global_load_dwordx4 v[136:139], v[118:119], off offset:64
	global_load_dwordx4 v[140:143], v[118:119], off offset:80
	global_load_dwordx4 v[144:147], v[118:119], off offset:96
	global_load_dwordx4 v[148:151], v[118:119], off offset:112
	global_load_dwordx4 v[90:93], v[118:119], off offset:128
	global_load_dwordx4 v[82:85], v[118:119], off offset:144
	global_load_dwordx4 v[70:73], v[118:119], off offset:160
	global_load_dwordx4 v[66:69], v[118:119], off offset:176
	global_load_dwordx4 v[94:97], v[118:119], off offset:192
	global_load_dwordx4 v[86:89], v[118:119], off offset:208
	global_load_dwordx4 v[74:77], v[118:119], off offset:224
	global_load_dwordx4 v[78:81], v[118:119], off offset:240
	v_mov_b32_e32 v124, v126
	v_mov_b32_e32 v126, v130
	s_waitcnt vmcnt(0) lgkmcnt(0)
; #define EPI_SCHED() __builtin_amdgcn_sched_barrier(0)
;     DI void operator()(const AccT& acc, const Unit& u, int wr, int wc, int fr, int fq) const {
;     ...
;                 for (int hb2 = 0; hb2 < 2; ++hb2) {
;                     f32x4 v[4][NP4];
; #pragma unroll
;                     for (int e = 0; e < 4; ++e)
; #pragma unroll
;                         for (int i = 0; i < NP4; ++i) v[e][i] = *(const f32x4*)(parts + (col + 4 * hb2 + e) * STRIDE + P0 + 4 * i);
; #pragma unroll
;                     for (int e = 0; e < 4; ++e) { float t = 0.f;
; #pragma unroll
;                         for (int i = 0; i < NP4; ++i) t += (v[e][i].x + v[e][i].y) + (v[e][i].z + v[e][i].w);
;                         const float r = rsqrtf(t * invK + EPS); if (hb2 == 0) c0[e] = r; else c1[e] = r; }
;                     EPI_SCHED();
;                 }
	v_mov_b32_e32 v121, v136
	v_mov_b32_e32 v136, v125
	v_mov_b32_e32 v125, v138
	v_mov_b32_e32 v138, v127
	v_pk_add_f32 v[120:121], v[120:121], v[136:137]
	v_pk_add_f32 v[124:125], v[124:125], v[138:139]
	v_mov_b32_e32 v127, v142
	v_pk_add_f32 v[120:121], v[120:121], v[124:125]
	v_mov_b32_e32 v124, v128
	v_mov_b32_e32 v125, v140
	v_mov_b32_e32 v140, v129
	v_mov_b32_e32 v142, v131
	v_pk_add_f32 v[124:125], v[124:125], v[140:141]
	v_pk_add_f32 v[126:127], v[126:127], v[142:143]
	v_pk_add_f32 v[120:121], v[120:121], 0 op_sel_hi:[1,0]
	v_pk_add_f32 v[124:125], v[124:125], v[126:127]
	v_mov_b32_e32 v126, v134
	v_pk_add_f32 v[120:121], v[120:121], v[124:125]
	v_mov_b32_e32 v124, v132
	v_mov_b32_e32 v125, v144
	v_mov_b32_e32 v144, v133
	v_mov_b32_e32 v127, v146
	v_mov_b32_e32 v146, v135
	v_pk_add_f32 v[124:125], v[124:125], v[144:145]
	v_pk_add_f32 v[126:127], v[126:127], v[146:147]
	s_nop 0
	v_pk_add_f32 v[124:125], v[124:125], v[126:127]
	s_nop 0
	v_pk_add_f32 v[120:121], v[120:121], v[124:125]
	v_mov_b32_e32 v124, v98
	v_mov_b32_e32 v125, v148
	v_mov_b32_e32 v148, v99
	v_pk_add_f32 v[98:99], v[124:125], v[148:149]
	v_mov_b32_e32 v124, v100
	v_mov_b32_e32 v125, v150
	v_mov_b32_e32 v150, v101
	v_pk_add_f32 v[100:101], v[124:125], v[150:151]
	s_nop 0
	v_pk_add_f32 v[98:99], v[98:99], v[100:101]
	s_nop 0
	v_pk_add_f32 v[98:99], v[120:121], v[98:99]
	s_nop 0
	v_pk_fma_f32 v[98:99], v[98:99], s[88:89], v[164:165] op_sel_hi:[1,0,0]
	s_nop 0
	v_mul_f32_e32 v0, 0x4b800000, v98
	v_cmp_gt_f32_e64 s[2:3], s42, v98
	v_cmp_gt_f32_e32 vcc, s42, v99
	s_nop 0
	v_cndmask_b32_e64 v0, v98, v0, s[2:3]
	v_rsq_f32_e32 v98, v0
	v_mul_f32_e32 v0, 0x4b800000, v99
	v_cndmask_b32_e32 v0, v99, v0, vcc
	v_rsq_f32_e32 v99, v0
	s_nop 0
	v_pk_mul_f32 v[100:101], v[98:99], s[52:53] op_sel_hi:[1,0]
	s_nop 0
	v_cndmask_b32_e32 v99, v99, v101, vcc
	v_cndmask_b32_e64 v98, v98, v100, s[2:3]
	v_mov_b32_e32 v100, v90
	v_mov_b32_e32 v101, v94
	v_mov_b32_e32 v94, v91
	v_pk_add_f32 v[90:91], v[100:101], v[94:95]
	v_mov_b32_e32 v94, v92
	v_mov_b32_e32 v95, v96
	v_mov_b32_e32 v96, v93
	v_pk_add_f32 v[92:93], v[94:95], v[96:97]
	s_nop 0
	v_pk_add_f32 v[90:91], v[90:91], v[92:93]
	v_mov_b32_e32 v92, v82
	v_mov_b32_e32 v93, v86
	v_mov_b32_e32 v86, v83
	v_pk_add_f32 v[82:83], v[92:93], v[86:87]
	v_mov_b32_e32 v86, v84
	v_mov_b32_e32 v87, v88
	v_mov_b32_e32 v88, v85
	v_pk_add_f32 v[84:85], v[86:87], v[88:89]
	v_pk_add_f32 v[90:91], v[90:91], 0 op_sel_hi:[1,0]
	v_pk_add_f32 v[82:83], v[82:83], v[84:85]
	v_mov_b32_e32 v84, v70
	v_mov_b32_e32 v85, v74
	v_mov_b32_e32 v74, v71
	v_pk_add_f32 v[70:71], v[84:85], v[74:75]
	v_mov_b32_e32 v74, v72
	v_mov_b32_e32 v75, v76
	v_mov_b32_e32 v76, v73
	v_pk_add_f32 v[72:73], v[74:75], v[76:77]
	v_pk_add_f32 v[82:83], v[90:91], v[82:83]
	v_pk_add_f32 v[70:71], v[70:71], v[72:73]
	v_mov_b32_e32 v72, v66
	v_mov_b32_e32 v73, v78
	v_mov_b32_e32 v78, v67
	v_pk_add_f32 v[66:67], v[72:73], v[78:79]
	v_mov_b32_e32 v72, v68
	v_mov_b32_e32 v73, v80
	v_mov_b32_e32 v80, v69
	v_pk_add_f32 v[68:69], v[72:73], v[80:81]
	v_pk_add_f32 v[70:71], v[82:83], v[70:71]
	v_pk_add_f32 v[66:67], v[66:67], v[68:69]
	s_nop 0
	v_pk_add_f32 v[66:67], v[70:71], v[66:67]
	s_nop 0
	v_pk_fma_f32 v[66:67], v[66:67], s[88:89], v[164:165] op_sel_hi:[1,0,0]
	s_nop 0
	v_mul_f32_e32 v0, 0x4b800000, v66
	v_cmp_gt_f32_e64 s[2:3], s42, v66
	v_cmp_gt_f32_e32 vcc, s42, v67
	s_nop 0
	v_cndmask_b32_e64 v0, v66, v0, s[2:3]
	v_rsq_f32_e32 v66, v0
	v_mul_f32_e32 v0, 0x4b800000, v67
	v_cndmask_b32_e32 v0, v67, v0, vcc
	v_rsq_f32_e32 v67, v0
	s_nop 0
	v_pk_mul_f32 v[68:69], v[66:67], s[52:53] op_sel_hi:[1,0]
	s_nop 0
	v_cndmask_b32_e32 v87, v67, v69, vcc
	v_cndmask_b32_e64 v86, v66, v68, s[2:3]
	global_load_dwordx4 v[88:91], v[118:119], off offset:256
	global_load_dwordx4 v[92:95], v[118:119], off offset:272
	global_load_dwordx4 v[124:127], v[118:119], off offset:288
	global_load_dwordx4 v[128:131], v[118:119], off offset:304
	global_load_dwordx4 v[132:135], v[118:119], off offset:320
	global_load_dwordx4 v[136:139], v[118:119], off offset:336
	global_load_dwordx4 v[140:143], v[118:119], off offset:352
	global_load_dwordx4 v[144:147], v[118:119], off offset:368
	global_load_dwordx4 v[148:151], v[118:119], off offset:384
	global_load_dwordx4 v[82:85], v[118:119], off offset:400
	global_load_dwordx4 v[70:73], v[118:119], off offset:416
	global_load_dwordx4 v[66:69], v[118:119], off offset:432
	global_load_dwordx4 v[152:155], v[118:119], off offset:448
	global_load_dwordx4 v[156:159], v[118:119], off offset:464
	global_load_dwordx4 v[78:81], v[118:119], off offset:480
	global_load_dwordx4 v[74:77], v[118:119], off offset:496
	s_waitcnt vmcnt(0) lgkmcnt(0)
; DI u32x4 pk8(f32x4 a, f32x4 b) { u32x4 o; o.x = pk2(a.x, a.y); o.y = pk2(a.z, a.w); o.z = pk2(b.x, b.y); o.w = pk2(b.z, b.w); return o; }
; #define EPI_SCHED() __builtin_amdgcn_sched_barrier(0)
;     DI void operator()(const AccT& acc, const Unit& u, int wr, int wc, int fr, int fq) const {
;     ...
;                     for (int e = 0; e < 4; ++e) { float t = 0.f;
; #pragma unroll
;                         for (int i = 0; i < NP4; ++i) t += (v[e][i].x + v[e][i].y) + (v[e][i].z + v[e][i].w);
;                         const float r = rsqrtf(t * invK + EPS); if (hb2 == 0) c0[e] = r; else c1[e] = r; }
;                     EPI_SCHED();
;                 }
;             }
; #pragma unroll
;             for (int ai = 0; ai < 2; ++ai)
; #pragma unroll
;                 for (int m = 0; m < 4; ++m) {
;                     const size_t row = (size_t)u.pm * 256 + ai * 128 + wr * 64 + m * 16 + fr;
;                     *(u32x4*)(out + ((col >> 11) * nrows + row) * VPITCH + (col & 2047)) = pk8(acc[ai][bj][m][0] * c0, acc[ai][bj][m][1] * c1);
;                 }
	v_mov_b32_e32 v96, v88
	v_mov_b32_e32 v97, v132
	v_mov_b32_e32 v132, v89
	v_pk_add_f32 v[88:89], v[96:97], v[132:133]
	v_mov_b32_e32 v96, v90
	v_mov_b32_e32 v97, v134
	v_mov_b32_e32 v134, v91
	v_pk_add_f32 v[90:91], v[96:97], v[134:135]
	s_nop 0
	v_pk_add_f32 v[88:89], v[88:89], v[90:91]
	v_mov_b32_e32 v90, v92
	v_mov_b32_e32 v91, v136
	v_mov_b32_e32 v136, v93
	v_mov_b32_e32 v92, v94
	v_mov_b32_e32 v93, v138
	v_mov_b32_e32 v138, v95
	v_pk_add_f32 v[90:91], v[90:91], v[136:137]
	v_pk_add_f32 v[92:93], v[92:93], v[138:139]
	v_pk_add_f32 v[88:89], v[88:89], 0 op_sel_hi:[1,0]
	v_pk_add_f32 v[90:91], v[90:91], v[92:93]
	v_mov_b32_e32 v92, v126
	v_pk_add_f32 v[88:89], v[88:89], v[90:91]
	v_mov_b32_e32 v90, v124
	v_mov_b32_e32 v91, v140
	v_mov_b32_e32 v140, v125
	v_mov_b32_e32 v93, v142
	v_mov_b32_e32 v142, v127
	v_pk_add_f32 v[90:91], v[90:91], v[140:141]
	v_pk_add_f32 v[92:93], v[92:93], v[142:143]
	s_nop 0
	v_pk_add_f32 v[90:91], v[90:91], v[92:93]
	v_mov_b32_e32 v92, v130
	v_pk_add_f32 v[88:89], v[88:89], v[90:91]
	v_mov_b32_e32 v90, v128
	v_mov_b32_e32 v91, v144
	v_mov_b32_e32 v144, v129
	v_mov_b32_e32 v93, v146
	v_mov_b32_e32 v146, v131
	v_pk_add_f32 v[90:91], v[90:91], v[144:145]
	v_pk_add_f32 v[92:93], v[92:93], v[146:147]
	s_nop 0
	v_pk_add_f32 v[90:91], v[90:91], v[92:93]
	v_mov_b32_e32 v92, v150
	v_pk_add_f32 v[88:89], v[88:89], v[90:91]
	v_mov_b32_e32 v93, v154
	v_pk_fma_f32 v[88:89], v[88:89], s[88:89], v[164:165] op_sel_hi:[1,0,0]
	v_mov_b32_e32 v154, v151
	v_mul_f32_e32 v0, 0x4b800000, v88
	v_cmp_gt_f32_e64 s[2:3], s42, v88
	v_cmp_gt_f32_e32 vcc, s42, v89
	v_pk_add_f32 v[92:93], v[92:93], v[154:155]
	v_cndmask_b32_e64 v0, v88, v0, s[2:3]
	v_rsq_f32_e32 v88, v0
	v_mul_f32_e32 v0, 0x4b800000, v89
	v_cndmask_b32_e32 v0, v89, v0, vcc
	v_rsq_f32_e32 v89, v0
	s_nop 0
	v_pk_mul_f32 v[90:91], v[88:89], s[52:53] op_sel_hi:[1,0]
	s_nop 0
	v_cndmask_b32_e32 v89, v89, v91, vcc
	v_cndmask_b32_e64 v88, v88, v90, s[2:3]
	v_mov_b32_e32 v90, v148
	v_mov_b32_e32 v91, v152
	v_mov_b32_e32 v152, v149
	v_pk_add_f32 v[90:91], v[90:91], v[152:153]
	s_nop 0
	v_pk_add_f32 v[90:91], v[90:91], v[92:93]
	v_mov_b32_e32 v92, v82
	v_mov_b32_e32 v93, v156
	v_mov_b32_e32 v156, v83
	v_pk_add_f32 v[82:83], v[92:93], v[156:157]
	v_mov_b32_e32 v92, v84
	v_mov_b32_e32 v93, v158
	v_mov_b32_e32 v158, v85
	v_pk_add_f32 v[84:85], v[92:93], v[158:159]
	v_pk_add_f32 v[90:91], v[90:91], 0 op_sel_hi:[1,0]
	v_pk_add_f32 v[82:83], v[82:83], v[84:85]
	v_mov_b32_e32 v84, v70
	v_mov_b32_e32 v85, v78
	v_mov_b32_e32 v78, v71
	v_pk_add_f32 v[70:71], v[84:85], v[78:79]
	v_mov_b32_e32 v78, v72
	v_mov_b32_e32 v79, v80
	v_mov_b32_e32 v80, v73
	v_pk_add_f32 v[72:73], v[78:79], v[80:81]
	v_pk_add_f32 v[82:83], v[90:91], v[82:83]
	v_pk_add_f32 v[70:71], v[70:71], v[72:73]
	v_mov_b32_e32 v72, v66
	v_mov_b32_e32 v73, v74
	v_mov_b32_e32 v74, v67
	v_pk_add_f32 v[66:67], v[72:73], v[74:75]
	v_mov_b32_e32 v72, v68
	v_mov_b32_e32 v73, v76
	v_mov_b32_e32 v76, v69
	v_pk_add_f32 v[68:69], v[72:73], v[76:77]
	v_pk_add_f32 v[70:71], v[82:83], v[70:71]
	v_pk_add_f32 v[66:67], v[66:67], v[68:69]
	s_nop 0
	v_pk_add_f32 v[66:67], v[70:71], v[66:67]
	s_nop 0
	v_pk_fma_f32 v[66:67], v[66:67], s[88:89], v[164:165] op_sel_hi:[1,0,0]
	s_nop 0
	v_mul_f32_e32 v0, 0x4b800000, v66
	v_cmp_gt_f32_e64 s[2:3], s42, v66
	v_cmp_gt_f32_e32 vcc, s42, v67
	s_nop 0
	v_cndmask_b32_e64 v0, v66, v0, s[2:3]
	v_rsq_f32_e32 v66, v0
	v_mul_f32_e32 v0, 0x4b800000, v67
	v_cndmask_b32_e32 v0, v67, v0, vcc
	v_rsq_f32_e32 v67, v0
	s_nop 0
	v_pk_mul_f32 v[68:69], v[66:67], s[52:53] op_sel_hi:[1,0]
	s_nop 0
	v_cndmask_b32_e32 v67, v67, v69, vcc
	v_cndmask_b32_e64 v66, v66, v68, s[2:3]
	v_pk_mul_f32 v[62:63], v[62:63], v[98:99]
	v_pk_mul_f32 v[68:69], v[60:61], v[66:67]
	v_pk_mul_f32 v[60:61], v[58:59], v[88:89]
	v_cvt_pk_bf16_f32 v58, v62, v63
	v_lshrrev_b64 v[62:63], 2, v[116:117]
	v_pk_mul_f32 v[64:65], v[64:65], v[86:87]
	v_and_b32_e32 v63, 0x3fffffff, v63
	v_and_b32_e32 v62, 0xfffffe00, v62
	v_cvt_pk_bf16_f32 v59, v64, v65
	v_lshl_add_u64 v[64:65], v[62:63], 0, v[162:163]
	v_cvt_pk_bf16_f32 v60, v60, v61
	v_cvt_pk_bf16_f32 v61, v68, v69
	v_mad_u64_u32 v[68:69], s[0:1], v64, s43, v[122:123]
	v_mov_b32_e32 v0, v69
	v_and_b32_e32 v70, 0x7f8, v116
	v_mad_u64_u32 v[64:65], s[0:1], v65, s43, v[0:1]
	v_mov_b32_e32 v69, v64
	v_lshlrev_b32_e32 v0, 1, v70
	v_lshl_add_u64 v[64:65], v[68:69], 0, v[0:1]
; DI u32x4 pk8(f32x4 a, f32x4 b) { u32x4 o; o.x = pk2(a.x, a.y); o.y = pk2(a.z, a.w); o.z = pk2(b.x, b.y); o.w = pk2(b.z, b.w); return o; }
; #define PG8_BAR __builtin_amdgcn_s_barrier()
; template <class Epi, class Sched>
; DI void gemm_phase(int wv, LAS unsigned char* lds, const Gemm g, const Sched& S, const Epi& E) {
;     ...
;         if (!has_next) break;
; #pragma unroll
;         for (int a = 0; a < 2; ++a)
; #pragma unroll
;             for (int b = 0; b < 2; ++b)
; #pragma unroll
;                 for (int m = 0; m < 4; ++m)
; #pragma unroll
;                     for (int n = 0; n < 2; ++n) acc[a][b][m][n] = (f32x4){0.f, 0.f, 0.f, 0.f};
;         cur = nxt; cA = nA; cB = nB; ++ui;
;         if (wr == 1) PG8_BAR;
;     DI void operator()(const AccT& acc, const Unit& u, int wr, int wc, int fr, int fq) const {
;     ...
;             for (int ai = 0; ai < 2; ++ai)
; #pragma unroll
;                 for (int m = 0; m < 4; ++m) {
;                     const size_t row = (size_t)u.pm * 256 + ai * 128 + wr * 64 + m * 16 + fr;
;                     *(u32x4*)(out + ((col >> 11) * nrows + row) * VPITCH + (col & 2047)) = pk8(acc[ai][bj][m][0] * c0, acc[ai][bj][m][1] * c1);
	v_pk_mul_f32 v[54:55], v[54:55], v[98:99]
	global_store_dwordx4 v[64:65], v[58:61], off
	v_pk_mul_f32 v[56:57], v[56:57], v[86:87]
	v_pk_mul_f32 v[46:47], v[46:47], v[98:99]
	v_pk_mul_f32 v[58:59], v[52:53], v[66:67]
	v_pk_mul_f32 v[52:53], v[50:51], v[88:89]
	v_cvt_pk_bf16_f32 v50, v54, v55
	v_lshl_add_u64 v[54:55], v[62:63], 0, v[114:115]
	v_cvt_pk_bf16_f32 v51, v56, v57
	v_mad_u64_u32 v[56:57], s[0:1], v54, s43, v[122:123]
	v_mov_b32_e32 v54, v57
	v_mad_u64_u32 v[54:55], s[0:1], v55, s43, v[54:55]
	v_mov_b32_e32 v57, v54
	v_cvt_pk_bf16_f32 v52, v52, v53
	v_cvt_pk_bf16_f32 v53, v58, v59
	v_lshl_add_u64 v[54:55], v[56:57], 0, v[0:1]
	global_store_dwordx4 v[54:55], v[50:53], off
	v_pk_mul_f32 v[48:49], v[48:49], v[86:87]
	v_pk_mul_f32 v[38:39], v[38:39], v[98:99]
	v_pk_mul_f32 v[50:51], v[44:45], v[66:67]
	v_pk_mul_f32 v[44:45], v[42:43], v[88:89]
	v_cvt_pk_bf16_f32 v42, v46, v47
	v_lshl_add_u64 v[46:47], v[62:63], 0, v[106:107]
	v_cvt_pk_bf16_f32 v43, v48, v49
	v_mad_u64_u32 v[48:49], s[0:1], v46, s43, v[122:123]
	v_mov_b32_e32 v46, v49
	v_mad_u64_u32 v[46:47], s[0:1], v47, s43, v[46:47]
	v_mov_b32_e32 v49, v46
	v_cvt_pk_bf16_f32 v44, v44, v45
	v_cvt_pk_bf16_f32 v45, v50, v51
	v_lshl_add_u64 v[46:47], v[48:49], 0, v[0:1]
	global_store_dwordx4 v[46:47], v[42:45], off
	v_pk_mul_f32 v[40:41], v[40:41], v[86:87]
	v_pk_mul_f32 v[30:31], v[30:31], v[98:99]
	v_pk_mul_f32 v[42:43], v[36:37], v[66:67]
	v_pk_mul_f32 v[36:37], v[34:35], v[88:89]
	v_cvt_pk_bf16_f32 v34, v38, v39
	v_lshl_add_u64 v[38:39], v[62:63], 0, v[104:105]
	v_cvt_pk_bf16_f32 v35, v40, v41
	v_mad_u64_u32 v[40:41], s[0:1], v38, s43, v[122:123]
	v_mov_b32_e32 v38, v41
	v_mad_u64_u32 v[38:39], s[0:1], v39, s43, v[38:39]
	v_mov_b32_e32 v41, v38
	v_cvt_pk_bf16_f32 v36, v36, v37
	v_cvt_pk_bf16_f32 v37, v42, v43
	v_lshl_add_u64 v[38:39], v[40:41], 0, v[0:1]
	global_store_dwordx4 v[38:39], v[34:37], off
	v_pk_mul_f32 v[32:33], v[32:33], v[86:87]
	v_pk_mul_f32 v[22:23], v[22:23], v[98:99]
	v_pk_mul_f32 v[34:35], v[28:29], v[66:67]
	v_pk_mul_f32 v[28:29], v[26:27], v[88:89]
	v_cvt_pk_bf16_f32 v26, v30, v31
	v_lshl_add_u64 v[30:31], v[62:63], 0, v[102:103]
	v_cvt_pk_bf16_f32 v27, v32, v33
	v_mad_u64_u32 v[32:33], s[0:1], v30, s43, v[122:123]
	v_mov_b32_e32 v30, v33
	v_mad_u64_u32 v[30:31], s[0:1], v31, s43, v[30:31]
	v_mov_b32_e32 v33, v30
	v_cvt_pk_bf16_f32 v28, v28, v29
	v_cvt_pk_bf16_f32 v29, v34, v35
	v_lshl_add_u64 v[30:31], v[32:33], 0, v[0:1]
	global_store_dwordx4 v[30:31], v[26:29], off
	v_pk_mul_f32 v[24:25], v[24:25], v[86:87]
	v_pk_mul_f32 v[14:15], v[14:15], v[98:99]
	v_pk_mul_f32 v[26:27], v[20:21], v[66:67]
	v_pk_mul_f32 v[20:21], v[18:19], v[88:89]
	v_cvt_pk_bf16_f32 v18, v22, v23
	v_lshl_add_u64 v[22:23], v[62:63], 0, v[108:109]
	v_cvt_pk_bf16_f32 v19, v24, v25
	v_mad_u64_u32 v[24:25], s[0:1], v22, s43, v[122:123]
	v_mov_b32_e32 v22, v25
	v_mad_u64_u32 v[22:23], s[0:1], v23, s43, v[22:23]
	v_mov_b32_e32 v25, v22
	v_cvt_pk_bf16_f32 v20, v20, v21
	v_cvt_pk_bf16_f32 v21, v26, v27
	v_lshl_add_u64 v[22:23], v[24:25], 0, v[0:1]
	global_store_dwordx4 v[22:23], v[18:21], off
	v_pk_mul_f32 v[16:17], v[16:17], v[86:87]
	v_pk_mul_f32 v[6:7], v[6:7], v[98:99]
	v_pk_mul_f32 v[18:19], v[12:13], v[66:67]
	v_pk_mul_f32 v[12:13], v[10:11], v[88:89]
	v_cvt_pk_bf16_f32 v10, v14, v15
	v_lshl_add_u64 v[14:15], v[62:63], 0, v[110:111]
	v_cvt_pk_bf16_f32 v11, v16, v17
	v_mad_u64_u32 v[16:17], s[0:1], v14, s43, v[122:123]
	v_mov_b32_e32 v14, v17
	v_mad_u64_u32 v[14:15], s[0:1], v15, s43, v[14:15]
	v_mov_b32_e32 v17, v14
	v_cvt_pk_bf16_f32 v12, v12, v13
	v_cvt_pk_bf16_f32 v13, v18, v19
	v_lshl_add_u64 v[14:15], v[16:17], 0, v[0:1]
	global_store_dwordx4 v[14:15], v[10:13], off
	v_pk_mul_f32 v[8:9], v[8:9], v[86:87]
	s_andn2_b64 vcc, exec, s[14:15]
	v_pk_mul_f32 v[10:11], v[4:5], v[66:67]
	v_pk_mul_f32 v[4:5], v[2:3], v[88:89]
	v_cvt_pk_bf16_f32 v2, v6, v7
	v_lshl_add_u64 v[6:7], v[62:63], 0, v[112:113]
	v_cvt_pk_bf16_f32 v3, v8, v9
	v_mad_u64_u32 v[8:9], s[0:1], v6, s43, v[122:123]
	v_mov_b32_e32 v6, v9
	v_mad_u64_u32 v[6:7], s[0:1], v7, s43, v[6:7]
	v_mov_b32_e32 v9, v6
	v_cvt_pk_bf16_f32 v4, v4, v5
	v_cvt_pk_bf16_f32 v5, v10, v11
	v_lshl_add_u64 v[6:7], v[8:9], 0, v[0:1]
	s_mov_b64 s[2:3], -1
	global_store_dwordx4 v[6:7], v[2:5], off
	s_cbranch_vccnz .LBB0_2077
	s_andn2_b64 vcc, exec, s[4:5]
	s_cbranch_vccnz .LBB0_2076
	s_barrier
	s_branch .LBB0_2076

; DI unsigned xb_ld(unsigned* p)              { return __hip_atomic_load(p, __ATOMIC_RELAXED, __HIP_MEMORY_SCOPE_AGENT); }
; DI void xcd_barrier_complete(unsigned* bar, unsigned x, unsigned& nloc, unsigned& nx) {
;     ...
;     for (;;) {
;         sum = 0u; cnt = 0u; mine = 0u;
; #pragma unroll
;         for (unsigned j = 0; j < 16; ++j) { const unsigned c = xb_ld(&bar[XB_XCNT(j)]); sum += c; cnt += (c > 0u) ? 1u : 0u; mine = (j == x) ? c : mine; }
;         if (sum == G) break;
;         __builtin_amdgcn_s_sleep(1);
;         if ((++sp & 255u) == 0u) { if (xb_ld(&bar[XB_TMO])) break; if (sp > XB_SPIN_CAP) { atomicAdd(&bar[XB_TMO], 1u); break; } }
;     }
.LBB0_2098:
	v_mov_b64_e32 v[2:3], s[4:5]
	s_waitcnt lgkmcnt(0)
	global_load_dword v0, v[2:3], off sc1
	v_mov_b64_e32 v[2:3], s[6:7]
	global_load_dword v2, v[2:3], off sc1
	v_mov_b64_e32 v[4:5], s[8:9]
	global_load_dword v3, v[4:5], off sc1
	v_mov_b64_e32 v[4:5], s[12:13]
	global_load_dword v4, v[4:5], off sc1
	s_or_b64 s[54:55], s[54:55], exec
	s_or_b64 s[56:57], s[56:57], exec
	s_waitcnt vmcnt(0) lgkmcnt(0)
	v_add_u32_e32 v6, v2, v0
	v_add_u32_e32 v6, v6, v3
	v_add_u32_e32 v8, v6, v4
	v_mov_b64_e32 v[6:7], s[14:15]
	global_load_dword v5, v[6:7], off sc1
	v_mov_b64_e32 v[6:7], s[16:17]
	global_load_dword v6, v[6:7], off sc1
	s_waitcnt vmcnt(0) lgkmcnt(0)
	v_add_u32_e32 v8, v8, v5
	v_add_u32_e32 v10, v8, v6
	v_mov_b64_e32 v[8:9], s[18:19]
	global_load_dword v7, v[8:9], off sc1
	v_mov_b64_e32 v[8:9], s[20:21]
	global_load_dword v8, v[8:9], off sc1
	s_waitcnt vmcnt(0) lgkmcnt(0)
	v_add_u32_e32 v10, v10, v7
	v_add_u32_e32 v12, v10, v8
	v_mov_b64_e32 v[10:11], s[22:23]
	global_load_dword v9, v[10:11], off sc1
	v_mov_b64_e32 v[10:11], s[24:25]
	global_load_dword v10, v[10:11], off sc1
	s_waitcnt vmcnt(0) lgkmcnt(0)
	v_add_u32_e32 v12, v12, v9
	v_add_u32_e32 v14, v12, v10
	v_mov_b64_e32 v[12:13], s[26:27]
	global_load_dword v11, v[12:13], off sc1
	v_mov_b64_e32 v[12:13], s[28:29]
	global_load_dword v12, v[12:13], off sc1
	s_waitcnt vmcnt(0) lgkmcnt(0)
	v_add_u32_e32 v14, v14, v11
	v_add_u32_e32 v16, v14, v12
	v_mov_b64_e32 v[14:15], s[30:31]
	global_load_dword v13, v[14:15], off sc1
	v_mov_b64_e32 v[14:15], s[34:35]
	global_load_dword v14, v[14:15], off sc1
	s_waitcnt vmcnt(0) lgkmcnt(0)
	v_add_u32_e32 v16, v16, v13
	v_add_u32_e32 v18, v16, v14
	v_mov_b64_e32 v[16:17], s[50:51]
	global_load_dword v15, v[16:17], off sc1
	v_mov_b64_e32 v[16:17], s[92:93]
	global_load_dword v16, v[16:17], off sc1
	s_waitcnt vmcnt(0) lgkmcnt(0)
	v_add_u32_e32 v18, v18, v15
	v_add_u32_e32 v17, v18, v16
	v_cmp_ne_u32_e32 vcc, s33, v17
	s_and_saveexec_b64 s[84:85], vcc
	s_cbranch_execz .LBB0_2097
	s_and_b32 s46, s66, 0xff
	s_mov_b64 s[90:91], -1
	s_cmp_eq_u32 s46, 0
	s_mov_b64 s[64:65], -1
	s_mov_b64 s[60:61], -1
	s_sleep 1
	s_cbranch_scc1 .LBB0_2101
	s_and_saveexec_b64 s[46:47], s[64:65]
	s_cbranch_execz .LBB0_2096
	s_branch .LBB0_2104
.LBB0_2101:
	v_mov_b64_e32 v[18:19], s[2:3]
	global_load_dword v17, v[18:19], off sc1
	s_mov_b64 s[64:65], 0
	s_waitcnt vmcnt(0) lgkmcnt(0)
	v_cmp_eq_u32_e32 vcc, 0, v17
	s_and_saveexec_b64 s[46:47], vcc
	s_cmp_lt_u32 s66, 0x40001
	s_cselect_b64 s[64:65], -1, 0
	s_xor_b64 s[60:61], exec, -1
	s_and_b64 s[64:65], s[64:65], exec
	s_or_b64 exec, exec, s[46:47]
	s_and_saveexec_b64 s[46:47], s[64:65]
	s_cbranch_execz .LBB0_2096

; DI unsigned xb_ld(unsigned* p)              { return __hip_atomic_load(p, __ATOMIC_RELAXED, __HIP_MEMORY_SCOPE_AGENT); }
; DI unsigned xb_add(unsigned* p, unsigned v) { return __hip_atomic_fetch_add(p, v, __ATOMIC_RELAXED, __HIP_MEMORY_SCOPE_AGENT); }
; #define XB_SPIN(cond, bar) do { unsigned _sp = 0; while (cond) { __builtin_amdgcn_s_sleep(1); \
;     if ((++_sp & 255u) == 0u) { if (xb_ld(&(bar)[XB_TMO])) break; if (_sp > XB_SPIN_CAP) { atomicAdd(&(bar)[XB_TMO], 1u); break; } } } } while (0)
; DI void xcd_barrier(int wv, unsigned* bar, volatile LAS unsigned* st) {
;     ...
;         const unsigned old = xb_add(&bar[XB_XSUB(x)], 1u);
;         const unsigned gen = old / nloc;
;         if (old + 1u == (gen + 1u) * nloc) {
;             __builtin_amdgcn_fence(__ATOMIC_RELEASE, "agent");
;             asm volatile("s_waitcnt vmcnt(0)" ::: "memory");
;             const unsigned og = xb_add(&bar[XB_TOP], 1u);
;             const unsigned tg = og / nx;
;             if (og + 1u == (tg + 1u) * nx) xb_add(&bar[XB_TOPGEN], 1u);
;             else XB_SPIN(xb_ld(&bar[XB_TOPGEN]) == tg, bar);
;             __builtin_amdgcn_fence(__ATOMIC_ACQUIRE, "agent");
;             xb_add(&bar[XB_XGEN(x)], 1u);
;             asm volatile("s_waitcnt vmcnt(0)" ::: "memory");
;         } else {
;             XB_SPIN(xb_ld(&bar[XB_XGEN(x)]) == gen, bar);
.LBB0_2108:
	s_lshl_b32 s1, s1, 8
	s_add_u32 s2, s48, s1
	s_addc_u32 s3, s49, 0
	v_mov_b32_e32 v3, s2
	v_add_co_u32_e32 v4, vcc, 0xc1000, v3
	v_mov_b32_e32 v3, s3
	s_nop 0
	v_addc_co_u32_e32 v5, vcc, 0, v3, vcc
	v_mov_b32_e32 v3, 1
	flat_atomic_add v4, v[4:5], v3 offset:1024 sc0
	v_cvt_f32_u32_e32 v3, v2
	v_sub_u32_e32 v5, 0, v2
	s_add_u32 s26, s2, 0xc0000
	s_addc_u32 s1, s3, 0
	v_rcp_iflag_f32_e32 v3, v3
	s_nop 0
	v_mul_f32_e32 v3, 0x4f7ffffe, v3
	v_cvt_u32_f32_e32 v3, v3
	v_mul_lo_u32 v5, v5, v3
	v_mul_hi_u32 v5, v3, v5
	v_add_u32_e32 v3, v3, v5
	s_waitcnt vmcnt(0) lgkmcnt(0)
	v_mul_hi_u32 v3, v4, v3
	v_mul_lo_u32 v5, v3, v2
	v_sub_u32_e32 v5, v4, v5
	v_cmp_ge_u32_e32 vcc, v5, v2
	v_add_u32_e32 v6, 1, v3
	s_nop 0
	v_cndmask_b32_e32 v3, v3, v6, vcc
	v_sub_u32_e32 v6, v5, v2
	v_cndmask_b32_e32 v5, v5, v6, vcc
	v_cmp_ge_u32_e32 vcc, v5, v2
	v_add_u32_e32 v5, 1, v3
	v_add_u32_e32 v6, 1, v4
	v_cndmask_b32_e32 v3, v3, v5, vcc
	v_mad_u64_u32 v[4:5], s[2:3], v2, v3, v[2:3]
	v_cmp_ne_u32_e32 vcc, v6, v4
	s_and_saveexec_b64 s[2:3], vcc
	s_xor_b64 s[2:3], exec, s[2:3]
	s_cbranch_execz .LBB0_2121
	v_mov_b32_e32 v0, s26
	v_add_co_u32_e32 v4, vcc, 0x2000, v0
	v_mov_b32_e32 v0, s1
	s_nop 0
	v_addc_co_u32_e32 v5, vcc, 0, v0, vcc
	global_load_dword v0, v[4:5], off offset:1024 sc1
	s_add_u32 s6, s26, 0x2400
	s_addc_u32 s7, s1, 0
	s_waitcnt vmcnt(0) lgkmcnt(0)
	v_cmp_eq_u32_e32 vcc, v0, v3
	s_and_saveexec_b64 s[4:5], vcc
	s_cbranch_execz .LBB0_2120
	s_add_u32 s8, s48, 0xc0200
	s_addc_u32 s9, s49, 0
	s_mov_b32 s27, 1
	s_mov_b64 s[12:13], 0
	s_branch .LBB0_2112

; DI unsigned xb_ld(unsigned* p)              { return __hip_atomic_load(p, __ATOMIC_RELAXED, __HIP_MEMORY_SCOPE_AGENT); }
; #define XB_SPIN(cond, bar) do { unsigned _sp = 0; while (cond) { __builtin_amdgcn_s_sleep(1); \
;     if ((++_sp & 255u) == 0u) { if (xb_ld(&(bar)[XB_TMO])) break; if (_sp > XB_SPIN_CAP) { atomicAdd(&(bar)[XB_TMO], 1u); break; } } } } while (0)
; DI void xcd_barrier(int wv, unsigned* bar, volatile LAS unsigned* st) {
;     ...
;             XB_SPIN(xb_ld(&bar[XB_XGEN(x)]) == gen, bar);
.LBB0_2112:
	s_and_b32 s20, s27, 0xff
	s_mov_b64 s[18:19], -1
	s_cmp_lg_u32 s20, 0
	s_mov_b64 s[20:21], -1
	s_sleep 1
	s_cbranch_scc1 .LBB0_2116
	v_mov_b64_e32 v[4:5], s[8:9]
	global_load_dword v0, v[4:5], off sc1
	s_mov_b64 s[20:21], 0
	s_mov_b64 s[22:23], -1
	s_waitcnt vmcnt(0) lgkmcnt(0)
	v_cmp_eq_u32_e32 vcc, 0, v0
	s_and_saveexec_b64 s[24:25], vcc
	s_cmp_lt_u32 s27, 0x40001
	s_cselect_b64 s[20:21], -1, 0
	s_xor_b64 s[22:23], exec, -1
	s_and_b64 s[20:21], s[20:21], exec
	s_or_b64 exec, exec, s[24:25]
.LBB0_2116:
	s_andn2_b64 s[16:17], s[16:17], exec
	s_and_b64 s[22:23], s[22:23], exec
	s_or_b64 s[16:17], s[16:17], s[22:23]
	s_and_saveexec_b64 s[22:23], s[20:21]
	s_cbranch_execz .LBB0_2111
	v_mov_b64_e32 v[4:5], s[6:7]
	global_load_dword v0, v[4:5], off sc1
	s_add_i32 s27, s27, 1
	s_or_b64 s[16:17], s[16:17], exec
	s_waitcnt vmcnt(0) lgkmcnt(0)
	v_cmp_ne_u32_e32 vcc, v0, v3
	s_orn2_b64 s[18:19], vcc, exec
	s_branch .LBB0_2111

; DI void nsa_compress_phase(int wv, LAS unsigned char* lds, const bf16_t* slab  , const bf16_t* wn  , const float* c1  , bf16_t* KCMP, bf16_t* VCMPT) {
;     ...
;             if (kv == 0) {
;                 bf16_t* dst = KCMP + ((size_t)(b * 4 + g) * 128 + 64 * nh + 32 * rh2 + r) * 64 + 32 * dq;
; #pragma unroll
;                 for (int gq = 0; gq < 4; ++gq) { u32x2 wv; wv.x = pk2(acc[4 * gq], acc[4 * gq + 1]); wv.y = pk2(acc[4 * gq + 2], acc[4 * gq + 3]); *(u32x2*)(dst + 8 * gq + 4 * hh) = wv; }
;             } else {
;                 bf16_t* dst = VCMPT + ((size_t)(b * 4 + g) * 64 + 32 * dq + r) * 128 + 64 * nh + 32 * rh2;
; #pragma unroll
;                 for (int gq = 0; gq < 4; ++gq) { u32x2 wv; wv.x = pk2(acc[4 * gq], acc[4 * gq + 1]); wv.y = pk2(acc[4 * gq + 2], acc[4 * gq + 3]); *(u32x2*)(dst + 8 * gq + 4 * hh) = wv; }
.LBB0_2143:
	v_cvt_pk_bf16_f32 v2, v6, v7
	v_cvt_pk_bf16_f32 v3, v8, v9
	v_cvt_pk_bf16_f32 v6, v10, v11
	v_cvt_pk_bf16_f32 v7, v12, v13
	v_cvt_pk_bf16_f32 v8, v14, v15
	v_cvt_pk_bf16_f32 v9, v16, v17
	global_store_dwordx2 v[4:5], v[2:3], off offset:16
	global_store_dwordx2 v[4:5], v[6:7], off offset:32
	global_store_dwordx2 v[4:5], v[8:9], off offset:48

; DI f32x16 mfma32(bf16x8 a, bf16x8 b, f32x16 c) { return __builtin_amdgcn_mfma_f32_32x32x16_bf16(a, b, c, 0, 0, 0); }
; DI void nsa_compress_phase(int wv, LAS unsigned char* lds, const bf16_t* slab  , const bf16_t* wn  , const float* c1  , bf16_t* KCMP, bf16_t* VCMPT) {
;     ...
; #pragma unroll 8
;             for (int ks = 0; ks < 128; ++ks) {
;                 const bf16x8 xa = *(const bf16x8*)(ap + 16 * ks), wb = *(const bf16x8*)(bp + 16 * ks);
;                 acc = mfma32(wb, xa, acc);
;             }
.Lcmp_kloop:
	v_add_co_u32_e32 v30, vcc, 0x100, v30
	s_nop 1
	v_addc_co_u32_e32 v31, vcc, 0, v31, vcc
	v_add_co_u32_e32 v32, vcc, 0x100, v32
	s_nop 1
	v_addc_co_u32_e32 v33, vcc, 0, v33, vcc
	s_waitcnt vmcnt(14)
	v_mfma_f32_32x32x16_bf16 v[2:17], v[84:87], v[80:83], v[2:17]
	global_load_dwordx4 v[80:83], v[30:31], off
	global_load_dwordx4 v[84:87], v[32:33], off
	s_waitcnt vmcnt(14)
	v_mfma_f32_32x32x16_bf16 v[2:17], v[92:95], v[88:91], v[2:17]
	global_load_dwordx4 v[88:91], v[30:31], off offset:32
	global_load_dwordx4 v[92:95], v[32:33], off offset:32
	s_waitcnt vmcnt(14)
	v_mfma_f32_32x32x16_bf16 v[2:17], v[100:103], v[96:99], v[2:17]
	global_load_dwordx4 v[96:99], v[30:31], off offset:64
	global_load_dwordx4 v[100:103], v[32:33], off offset:64
	s_waitcnt vmcnt(14)
	v_mfma_f32_32x32x16_bf16 v[2:17], v[108:111], v[104:107], v[2:17]
	global_load_dwordx4 v[104:107], v[30:31], off offset:96
	global_load_dwordx4 v[108:111], v[32:33], off offset:96
	s_waitcnt vmcnt(14)
	v_mfma_f32_32x32x16_bf16 v[2:17], v[116:119], v[112:115], v[2:17]
	global_load_dwordx4 v[112:115], v[30:31], off offset:128
	global_load_dwordx4 v[116:119], v[32:33], off offset:128
	s_waitcnt vmcnt(14)
	v_mfma_f32_32x32x16_bf16 v[2:17], v[124:127], v[120:123], v[2:17]
	global_load_dwordx4 v[120:123], v[30:31], off offset:160
	global_load_dwordx4 v[124:127], v[32:33], off offset:160
	s_waitcnt vmcnt(14)
	v_mfma_f32_32x32x16_bf16 v[2:17], v[132:135], v[128:131], v[2:17]
	global_load_dwordx4 v[128:131], v[30:31], off offset:192
	global_load_dwordx4 v[132:135], v[32:33], off offset:192
	s_waitcnt vmcnt(14)
	v_mfma_f32_32x32x16_bf16 v[2:17], v[140:143], v[136:139], v[2:17]
	global_load_dwordx4 v[136:139], v[30:31], off offset:224
	global_load_dwordx4 v[140:143], v[32:33], off offset:224
	s_add_i32 s14, s14, 1
	s_cmp_eq_u32 s14, 15
	s_cbranch_scc0 .Lcmp_kloop
; #define LAS __attribute__((address_space(3)))
; DI float sigmoidf_(float x) { return frcp(1.f + fexp2(-x * LOG2E)); }
; DI f32x16 mfma32(bf16x8 a, bf16x8 b, f32x16 c) { return __builtin_amdgcn_mfma_f32_32x32x16_bf16(a, b, c, 0, 0, 0); }
; DI f32x16 zero16() { f32x16 z; for (int i = 0; i < 16; ++i) z[i] = 0.f; return z; }
; DI void nsa_compress_phase(int wv, LAS unsigned char* lds, const bf16_t* slab  , const bf16_t* wn  , const float* c1  , bf16_t* KCMP, bf16_t* VCMPT) {
;     ...
; #pragma unroll 8
;             for (int ks = 0; ks < 128; ++ks) {
;                 const bf16x8 xa = *(const bf16x8*)(ap + 16 * ks), wb = *(const bf16x8*)(bp + 16 * ks);
;                 acc = mfma32(wb, xa, acc);
;             }
;             const float* cb = c1 + kv * 128;
; #pragma unroll
;             for (int gq = 0; gq < 4; ++gq) {
;                 float v[4];
; #pragma unroll
;                 for (int e = 0; e < 4; ++e) { const int j = 32 * cq + 8 * gq + 4 * hh + e; const float x = acc[4 * gq + e] + cb[j];
;                     const float u2 = 2.f * 0.7978845608028654f * (x + 0.044715f * x * x * x); v[e] = x * sigmoidf_(u2); }
;                 u32x2 wv; wv.x = pk2(v[0], v[1]); wv.y = pk2(v[2], v[3]);
;                 *(LAS u32x2*)(lds + (32 * rh + r) * HS + (32 * cq + 8 * gq + 4 * hh) * 2) = wv;
;             }
;         }
;         __syncthreads();
;         if (w < 4) {
;             const int rh2 = w >> 1, dq = w & 1;
;             f32x16 acc = zero16();
; #pragma unroll
;             for (int ks = 0; ks < 8; ++ks) {
;                 const bf16x8 hf = *(const LAS bf16x8*)(lds + (32 * rh2 + r) * HS + (16 * ks + 8 * hh) * 2);
;                 const bf16x8 wf = *(const bf16x8*)(w2t + (size_t)(32 * dq + r) * 128 + 16 * ks + 8 * hh);
;                 if (kv == 0) acc = mfma32(wf, hf, acc);
;                 else acc = mfma32(hf, wf, acc);
;             }
	s_waitcnt vmcnt(14)
	v_mfma_f32_32x32x16_bf16 v[2:17], v[84:87], v[80:83], v[2:17]
	s_waitcnt vmcnt(12)
	v_mfma_f32_32x32x16_bf16 v[2:17], v[92:95], v[88:91], v[2:17]
	s_waitcnt vmcnt(10)
	v_mfma_f32_32x32x16_bf16 v[2:17], v[100:103], v[96:99], v[2:17]
	s_waitcnt vmcnt(8)
	v_mfma_f32_32x32x16_bf16 v[2:17], v[108:111], v[104:107], v[2:17]
	s_waitcnt vmcnt(6)
	v_mfma_f32_32x32x16_bf16 v[2:17], v[116:119], v[112:115], v[2:17]
	s_waitcnt vmcnt(4)
	v_mfma_f32_32x32x16_bf16 v[2:17], v[124:127], v[120:123], v[2:17]
	s_waitcnt vmcnt(2)
	v_mfma_f32_32x32x16_bf16 v[2:17], v[132:135], v[128:131], v[2:17]
	s_waitcnt vmcnt(0)
	v_mfma_f32_32x32x16_bf16 v[2:17], v[140:143], v[136:139], v[2:17]
	s_nop 1
	s_lshl_b32 s96, s18, 9
	v_lshl_add_u64 v[22:23], v[58:59], 0, s[96:97]
	global_load_dwordx4 v[18:21], v[22:23], off
	s_and_b64 vcc, exec, s[6:7]
	s_waitcnt vmcnt(0) lgkmcnt(0)
	s_nop 5
	v_pk_add_f32 v[2:3], v[2:3], v[18:19]
	v_pk_add_f32 v[4:5], v[4:5], v[20:21]
	v_mul_f32_e32 v18, 0x3d372713, v2
	v_mul_f32_e32 v19, 0x3d372713, v3
	v_mul_f32_e32 v20, 0x3d372713, v4
	v_mul_f32_e32 v21, 0x3d372713, v5
	v_mul_f32_e32 v18, v2, v18
	v_mul_f32_e32 v19, v3, v19
	v_mul_f32_e32 v20, v4, v20
	v_mul_f32_e32 v21, v5, v21
	v_fma_f32 v18, v2, v18, v2
	v_fma_f32 v19, v3, v19, v3
	v_fma_f32 v20, v4, v20, v4
	v_fma_f32 v21, v5, v21, v5
	v_mul_f32_e32 v18, 0x3fcc422a, v18
	v_mul_f32_e32 v19, 0x3fcc422a, v19
	v_mul_f32_e32 v20, 0x3fcc422a, v20
	v_mul_f32_e32 v21, 0x3fcc422a, v21
	v_mul_f32_e32 v18, 0xbfb8aa3b, v18
	v_mul_f32_e32 v19, 0xbfb8aa3b, v19
	v_mul_f32_e32 v20, 0xbfb8aa3b, v20
	v_mul_f32_e32 v21, 0xbfb8aa3b, v21
	v_exp_f32_e32 v18, v18
	v_exp_f32_e32 v19, v19
	v_exp_f32_e32 v20, v20
	v_exp_f32_e32 v21, v21
	v_add_f32_e32 v18, 1.0, v18
	v_add_f32_e32 v19, 1.0, v19
	v_add_f32_e32 v20, 1.0, v20
	v_add_f32_e32 v21, 1.0, v21
	v_rcp_f32_e32 v18, v18
	v_rcp_f32_e32 v19, v19
	v_rcp_f32_e32 v20, v20
	v_rcp_f32_e32 v21, v21
	v_pk_mul_f32 v[2:3], v[2:3], v[18:19]
	s_nop 0
	v_cvt_pk_bf16_f32 v2, v2, v3
	v_pk_mul_f32 v[4:5], v[4:5], v[20:21]
	s_nop 0
	v_cvt_pk_bf16_f32 v3, v4, v5
	ds_write_b64 v67, v[2:3]
	global_load_dwordx4 v[2:5], v[22:23], off offset:32
	s_waitcnt vmcnt(0) lgkmcnt(0)
	v_pk_add_f32 v[2:3], v[6:7], v[2:3]
	v_pk_add_f32 v[4:5], v[8:9], v[4:5]
	v_mul_f32_e32 v6, 0x3d372713, v2
	v_mul_f32_e32 v7, 0x3d372713, v3
	v_mul_f32_e32 v8, 0x3d372713, v4
	v_mul_f32_e32 v9, 0x3d372713, v5
	v_mul_f32_e32 v6, v2, v6
	v_mul_f32_e32 v7, v3, v7
	v_mul_f32_e32 v8, v4, v8
	v_mul_f32_e32 v9, v5, v9
	v_fma_f32 v6, v2, v6, v2
	v_fma_f32 v7, v3, v7, v3
	v_fma_f32 v8, v4, v8, v4
	v_fma_f32 v9, v5, v9, v5
	v_mul_f32_e32 v6, 0x3fcc422a, v6
	v_mul_f32_e32 v7, 0x3fcc422a, v7
	v_mul_f32_e32 v8, 0x3fcc422a, v8
	v_mul_f32_e32 v9, 0x3fcc422a, v9
	v_mul_f32_e32 v6, 0xbfb8aa3b, v6
	v_mul_f32_e32 v7, 0xbfb8aa3b, v7
	v_mul_f32_e32 v8, 0xbfb8aa3b, v8
	v_mul_f32_e32 v9, 0xbfb8aa3b, v9
	v_exp_f32_e32 v6, v6
	v_exp_f32_e32 v7, v7
	v_exp_f32_e32 v8, v8
	v_exp_f32_e32 v9, v9
	v_add_f32_e32 v6, 1.0, v6
	v_add_f32_e32 v7, 1.0, v7
	v_add_f32_e32 v8, 1.0, v8
	v_add_f32_e32 v9, 1.0, v9
	v_rcp_f32_e32 v6, v6
	v_rcp_f32_e32 v7, v7
	v_rcp_f32_e32 v8, v8
	v_rcp_f32_e32 v9, v9
	v_pk_mul_f32 v[2:3], v[2:3], v[6:7]
	s_nop 0
	v_cvt_pk_bf16_f32 v2, v2, v3
	v_pk_mul_f32 v[4:5], v[4:5], v[8:9]
	s_nop 0
	v_cvt_pk_bf16_f32 v3, v4, v5
	ds_write_b64 v67, v[2:3] offset:16
	global_load_dwordx4 v[2:5], v[22:23], off offset:64
	s_waitcnt vmcnt(0) lgkmcnt(0)
	v_pk_add_f32 v[2:3], v[10:11], v[2:3]
	v_pk_add_f32 v[4:5], v[12:13], v[4:5]
	v_mul_f32_e32 v6, 0x3d372713, v2
	v_mul_f32_e32 v7, 0x3d372713, v3
	v_mul_f32_e32 v8, 0x3d372713, v4
	v_mul_f32_e32 v9, 0x3d372713, v5
	v_mul_f32_e32 v6, v2, v6
	v_mul_f32_e32 v7, v3, v7
	v_mul_f32_e32 v8, v4, v8
	v_mul_f32_e32 v9, v5, v9
	v_fma_f32 v6, v2, v6, v2
	v_fma_f32 v7, v3, v7, v3
	v_fma_f32 v8, v4, v8, v4
	v_fma_f32 v9, v5, v9, v5
	v_mul_f32_e32 v6, 0x3fcc422a, v6
	v_mul_f32_e32 v7, 0x3fcc422a, v7
	v_mul_f32_e32 v8, 0x3fcc422a, v8
	v_mul_f32_e32 v9, 0x3fcc422a, v9
	v_mul_f32_e32 v6, 0xbfb8aa3b, v6
	v_mul_f32_e32 v7, 0xbfb8aa3b, v7
	v_mul_f32_e32 v8, 0xbfb8aa3b, v8
	v_mul_f32_e32 v9, 0xbfb8aa3b, v9
	v_exp_f32_e32 v6, v6
	v_exp_f32_e32 v7, v7
	v_exp_f32_e32 v8, v8
	v_exp_f32_e32 v9, v9
	v_add_f32_e32 v6, 1.0, v6
	v_add_f32_e32 v7, 1.0, v7
	v_add_f32_e32 v8, 1.0, v8
	v_add_f32_e32 v9, 1.0, v9
	v_rcp_f32_e32 v6, v6
	v_rcp_f32_e32 v7, v7
	v_rcp_f32_e32 v8, v8
	v_rcp_f32_e32 v9, v9
	v_pk_mul_f32 v[2:3], v[2:3], v[6:7]
	s_nop 0
	v_cvt_pk_bf16_f32 v2, v2, v3
	v_pk_mul_f32 v[4:5], v[4:5], v[8:9]
	s_nop 0
	v_cvt_pk_bf16_f32 v3, v4, v5
	ds_write_b64 v67, v[2:3] offset:32
	global_load_dwordx4 v[2:5], v[22:23], off offset:96
	s_waitcnt vmcnt(0) lgkmcnt(0)
	v_pk_add_f32 v[2:3], v[14:15], v[2:3]
	v_pk_add_f32 v[4:5], v[16:17], v[4:5]
	v_mul_f32_e32 v6, 0x3d372713, v2
	v_mul_f32_e32 v7, 0x3d372713, v3
	v_mul_f32_e32 v8, 0x3d372713, v4
	v_mul_f32_e32 v9, 0x3d372713, v5
	v_mul_f32_e32 v6, v2, v6
	v_mul_f32_e32 v7, v3, v7
	v_mul_f32_e32 v8, v4, v8
	v_mul_f32_e32 v9, v5, v9
	v_fma_f32 v6, v2, v6, v2
	v_fma_f32 v7, v3, v7, v3
	v_fma_f32 v8, v4, v8, v4
	v_fma_f32 v9, v5, v9, v5
	v_mul_f32_e32 v6, 0x3fcc422a, v6
	v_mul_f32_e32 v7, 0x3fcc422a, v7
	v_mul_f32_e32 v8, 0x3fcc422a, v8
	v_mul_f32_e32 v9, 0x3fcc422a, v9
	v_mul_f32_e32 v6, 0xbfb8aa3b, v6
	v_mul_f32_e32 v7, 0xbfb8aa3b, v7
	v_mul_f32_e32 v8, 0xbfb8aa3b, v8
	v_mul_f32_e32 v9, 0xbfb8aa3b, v9
	v_exp_f32_e32 v6, v6
	v_exp_f32_e32 v7, v7
	v_exp_f32_e32 v8, v8
	v_exp_f32_e32 v9, v9
	v_add_f32_e32 v6, 1.0, v6
	v_add_f32_e32 v7, 1.0, v7
	v_add_f32_e32 v8, 1.0, v8
	v_add_f32_e32 v9, 1.0, v9
	v_rcp_f32_e32 v6, v6
	v_rcp_f32_e32 v7, v7
	v_rcp_f32_e32 v8, v8
	v_rcp_f32_e32 v9, v9
	v_pk_mul_f32 v[2:3], v[2:3], v[6:7]
	s_nop 0
	v_cvt_pk_bf16_f32 v2, v2, v3
	v_pk_mul_f32 v[4:5], v[4:5], v[8:9]
	s_nop 0
	v_cvt_pk_bf16_f32 v3, v4, v5
	ds_write_b64 v67, v[2:3] offset:48
	s_waitcnt lgkmcnt(0)
	s_barrier
	s_cbranch_vccz .LBB0_2144
	s_and_b64 s[4:5], s[4:5], exec
	s_mov_b32 s4, 0x680000
	s_cselect_b32 s96, s4, 0x684000
	v_lshl_add_u64 v[64:65], v[50:51], 0, s[96:97]
	global_load_dwordx4 v[18:21], v[64:65], off
	ds_read_b128 v[22:25], v68
	s_mov_b64 s[4:5], -1
	s_and_b64 vcc, exec, s[12:13]
	s_cbranch_vccz .LBB0_2150
	s_mov_b64 s[4:5], 0
	s_waitcnt vmcnt(0) lgkmcnt(0)
	v_mfma_f32_32x32x16_bf16 v[2:17], v[22:25], v[18:21], 0

; #define LAS __attribute__((address_space(3)))
; DI f32x16 mfma32(bf16x8 a, bf16x8 b, f32x16 c) { return __builtin_amdgcn_mfma_f32_32x32x16_bf16(a, b, c, 0, 0, 0); }
; DI void nsa_compress_phase(int wv, LAS unsigned char* lds, const bf16_t* slab  , const bf16_t* wn  , const float* c1  , bf16_t* KCMP, bf16_t* VCMPT) {
;     ...
;             for (int ks = 0; ks < 8; ++ks) {
;                 const bf16x8 hf = *(const LAS bf16x8*)(lds + (32 * rh2 + r) * HS + (16 * ks + 8 * hh) * 2);
;                 const bf16x8 wf = *(const bf16x8*)(w2t + (size_t)(32 * dq + r) * 128 + 16 * ks + 8 * hh);
;                 if (kv == 0) acc = mfma32(wf, hf, acc);
;                 else acc = mfma32(hf, wf, acc);
.LBB0_2152:
	global_load_dwordx4 v[34:37], v[64:65], off offset:32
	ds_read_b128 v[38:41], v68 offset:32
	s_waitcnt vmcnt(0) lgkmcnt(0)
	v_cndmask_b32_e64 v18, 0, 1, s[12:13]
	v_cmp_ne_u32_e64 s[4:5], 1, v18
	s_andn2_b64 vcc, exec, s[12:13]
	s_mov_b64 s[14:15], -1
	s_cbranch_vccnz .LBB0_2154
	v_mfma_f32_32x32x16_bf16 v[18:33], v[38:41], v[34:37], v[2:17]
	s_mov_b64 s[14:15], 0

; #define LAS __attribute__((address_space(3)))
; DI f32x16 mfma32(bf16x8 a, bf16x8 b, f32x16 c) { return __builtin_amdgcn_mfma_f32_32x32x16_bf16(a, b, c, 0, 0, 0); }
; DI void nsa_compress_phase(int wv, LAS unsigned char* lds, const bf16_t* slab  , const bf16_t* wn  , const float* c1  , bf16_t* KCMP, bf16_t* VCMPT) {
;     ...
;             for (int ks = 0; ks < 8; ++ks) {
;                 const bf16x8 hf = *(const LAS bf16x8*)(lds + (32 * rh2 + r) * HS + (16 * ks + 8 * hh) * 2);
;                 const bf16x8 wf = *(const bf16x8*)(w2t + (size_t)(32 * dq + r) * 128 + 16 * ks + 8 * hh);
;                 if (kv == 0) acc = mfma32(wf, hf, acc);
;                 else acc = mfma32(hf, wf, acc);
.LBB0_2156:
	global_load_dwordx4 v[34:37], v[64:65], off offset:64
	ds_read_b128 v[38:41], v68 offset:64
	s_and_b64 vcc, exec, s[4:5]
	s_mov_b64 s[14:15], -1
	s_cbranch_vccnz .LBB0_2158
	s_waitcnt vmcnt(0) lgkmcnt(0)
	v_mfma_f32_32x32x16_bf16 v[2:17], v[38:41], v[34:37], v[18:33]
	s_mov_b64 s[14:15], 0

; #define LAS __attribute__((address_space(3)))
; DI f32x16 mfma32(bf16x8 a, bf16x8 b, f32x16 c) { return __builtin_amdgcn_mfma_f32_32x32x16_bf16(a, b, c, 0, 0, 0); }
; DI void nsa_compress_phase(int wv, LAS unsigned char* lds, const bf16_t* slab  , const bf16_t* wn  , const float* c1  , bf16_t* KCMP, bf16_t* VCMPT) {
;     ...
;             for (int ks = 0; ks < 8; ++ks) {
;                 const bf16x8 hf = *(const LAS bf16x8*)(lds + (32 * rh2 + r) * HS + (16 * ks + 8 * hh) * 2);
;                 const bf16x8 wf = *(const bf16x8*)(w2t + (size_t)(32 * dq + r) * 128 + 16 * ks + 8 * hh);
;                 if (kv == 0) acc = mfma32(wf, hf, acc);
;                 else acc = mfma32(hf, wf, acc);
.LBB0_2160:
	s_waitcnt vmcnt(0) lgkmcnt(0)
	global_load_dwordx4 v[34:37], v[64:65], off offset:96
	ds_read_b128 v[38:41], v68 offset:96
	s_and_b64 vcc, exec, s[4:5]
	s_mov_b64 s[14:15], -1
	s_cbranch_vccnz .LBB0_2162
	s_waitcnt vmcnt(0) lgkmcnt(0)
	v_mfma_f32_32x32x16_bf16 v[18:33], v[38:41], v[34:37], v[2:17]
	s_mov_b64 s[14:15], 0

; #define LAS __attribute__((address_space(3)))
; DI f32x16 mfma32(bf16x8 a, bf16x8 b, f32x16 c) { return __builtin_amdgcn_mfma_f32_32x32x16_bf16(a, b, c, 0, 0, 0); }
; DI void nsa_compress_phase(int wv, LAS unsigned char* lds, const bf16_t* slab  , const bf16_t* wn  , const float* c1  , bf16_t* KCMP, bf16_t* VCMPT) {
;     ...
;             for (int ks = 0; ks < 8; ++ks) {
;                 const bf16x8 hf = *(const LAS bf16x8*)(lds + (32 * rh2 + r) * HS + (16 * ks + 8 * hh) * 2);
;                 const bf16x8 wf = *(const bf16x8*)(w2t + (size_t)(32 * dq + r) * 128 + 16 * ks + 8 * hh);
;                 if (kv == 0) acc = mfma32(wf, hf, acc);
;                 else acc = mfma32(hf, wf, acc);
.LBB0_2164:
	s_waitcnt vmcnt(0) lgkmcnt(0)
	global_load_dwordx4 v[34:37], v[64:65], off offset:128
	ds_read_b128 v[38:41], v68 offset:128
	s_and_b64 vcc, exec, s[4:5]
	s_mov_b64 s[14:15], -1
	s_cbranch_vccnz .LBB0_2166
	s_waitcnt vmcnt(0) lgkmcnt(0)
	v_mfma_f32_32x32x16_bf16 v[2:17], v[38:41], v[34:37], v[18:33]
	s_mov_b64 s[14:15], 0

; #define LAS __attribute__((address_space(3)))
; DI f32x16 mfma32(bf16x8 a, bf16x8 b, f32x16 c) { return __builtin_amdgcn_mfma_f32_32x32x16_bf16(a, b, c, 0, 0, 0); }
; DI void nsa_compress_phase(int wv, LAS unsigned char* lds, const bf16_t* slab  , const bf16_t* wn  , const float* c1  , bf16_t* KCMP, bf16_t* VCMPT) {
;     ...
;             for (int ks = 0; ks < 8; ++ks) {
;                 const bf16x8 hf = *(const LAS bf16x8*)(lds + (32 * rh2 + r) * HS + (16 * ks + 8 * hh) * 2);
;                 const bf16x8 wf = *(const bf16x8*)(w2t + (size_t)(32 * dq + r) * 128 + 16 * ks + 8 * hh);
;                 if (kv == 0) acc = mfma32(wf, hf, acc);
;                 else acc = mfma32(hf, wf, acc);
.LBB0_2168:
	s_waitcnt vmcnt(0) lgkmcnt(0)
	global_load_dwordx4 v[34:37], v[64:65], off offset:160
	ds_read_b128 v[38:41], v68 offset:160
	s_and_b64 vcc, exec, s[4:5]
	s_mov_b64 s[14:15], -1
	s_cbranch_vccnz .LBB0_2170
	s_waitcnt vmcnt(0) lgkmcnt(0)
	v_mfma_f32_32x32x16_bf16 v[18:33], v[38:41], v[34:37], v[2:17]
	s_mov_b64 s[14:15], 0

; #define LAS __attribute__((address_space(3)))
; DI f32x16 mfma32(bf16x8 a, bf16x8 b, f32x16 c) { return __builtin_amdgcn_mfma_f32_32x32x16_bf16(a, b, c, 0, 0, 0); }
; DI void nsa_compress_phase(int wv, LAS unsigned char* lds, const bf16_t* slab  , const bf16_t* wn  , const float* c1  , bf16_t* KCMP, bf16_t* VCMPT) {
;     ...
;             for (int ks = 0; ks < 8; ++ks) {
;                 const bf16x8 hf = *(const LAS bf16x8*)(lds + (32 * rh2 + r) * HS + (16 * ks + 8 * hh) * 2);
;                 const bf16x8 wf = *(const bf16x8*)(w2t + (size_t)(32 * dq + r) * 128 + 16 * ks + 8 * hh);
;                 if (kv == 0) acc = mfma32(wf, hf, acc);
;                 else acc = mfma32(hf, wf, acc);
.LBB0_2172:
	s_nop 3
	global_load_dwordx4 v[2:5], v[64:65], off offset:192
	ds_read_b128 v[6:9], v68 offset:192
	s_and_b64 vcc, exec, s[4:5]
	s_mov_b64 s[14:15], -1
	s_cbranch_vccnz .LBB0_2174
	s_waitcnt vmcnt(0) lgkmcnt(0)
	v_mfma_f32_32x32x16_bf16 v[34:49], v[6:9], v[2:5], v[18:33]
	s_mov_b64 s[14:15], 0

; #define LAS __attribute__((address_space(3)))
; DI f32x16 mfma32(bf16x8 a, bf16x8 b, f32x16 c) { return __builtin_amdgcn_mfma_f32_32x32x16_bf16(a, b, c, 0, 0, 0); }
; DI void nsa_compress_phase(int wv, LAS unsigned char* lds, const bf16_t* slab  , const bf16_t* wn  , const float* c1  , bf16_t* KCMP, bf16_t* VCMPT) {
;     ...
;             for (int ks = 0; ks < 8; ++ks) {
;                 const bf16x8 hf = *(const LAS bf16x8*)(lds + (32 * rh2 + r) * HS + (16 * ks + 8 * hh) * 2);
;                 const bf16x8 wf = *(const bf16x8*)(w2t + (size_t)(32 * dq + r) * 128 + 16 * ks + 8 * hh);
;                 if (kv == 0) acc = mfma32(wf, hf, acc);
;                 else acc = mfma32(hf, wf, acc);
.LBB0_2176:
	s_nop 3
	global_load_dwordx4 v[18:21], v[64:65], off offset:224
	ds_read_b128 v[22:25], v68 offset:224
	s_and_b64 vcc, exec, s[4:5]
	s_mov_b64 s[4:5], -1
	s_cbranch_vccnz .LBB0_2178
	s_waitcnt vmcnt(0) lgkmcnt(0)
	v_mfma_f32_32x32x16_bf16 v[2:17], v[22:25], v[18:21], v[34:49]
	s_mov_b64 s[4:5], 0

; DI void nsa_compress_phase(int wv, LAS unsigned char* lds, const bf16_t* slab  , const bf16_t* wn  , const float* c1  , bf16_t* KCMP, bf16_t* VCMPT) {
;     ...
;             if (kv == 0) {
;                 bf16_t* dst = KCMP + ((size_t)(b * 4 + g) * 128 + 64 * nh + 32 * rh2 + r) * 64 + 32 * dq;
; #pragma unroll
;                 for (int gq = 0; gq < 4; ++gq) { u32x2 wv; wv.x = pk2(acc[4 * gq], acc[4 * gq + 1]); wv.y = pk2(acc[4 * gq + 2], acc[4 * gq + 3]); *(u32x2*)(dst + 8 * gq + 4 * hh) = wv; }
;             } else {
;                 bf16_t* dst = VCMPT + ((size_t)(b * 4 + g) * 64 + 32 * dq + r) * 128 + 64 * nh + 32 * rh2;
; #pragma unroll
;                 for (int gq = 0; gq < 4; ++gq) { u32x2 wv; wv.x = pk2(acc[4 * gq], acc[4 * gq + 1]); wv.y = pk2(acc[4 * gq + 2], acc[4 * gq + 3]); *(u32x2*)(dst + 8 * gq + 4 * hh) = wv; }
.LBB0_2180:
	s_and_b32 s4, s16, 3
	s_or_b32 s4, s17, s4
	s_lshl_b32 s14, s1, 6
	s_ashr_i32 s5, s4, 31
	s_and_b32 s96, s14, 64
	s_waitcnt vmcnt(0) lgkmcnt(0)
	s_nop 2
	v_cvt_pk_bf16_f32 v2, v2, v3
	v_cvt_pk_bf16_f32 v3, v4, v5
	s_mov_b64 s[14:15], -1
	s_and_b64 vcc, exec, s[12:13]
	s_cbranch_vccz .LBB0_2182
	s_lshl_b64 s[12:13], s[4:5], 14
	v_lshl_add_u64 v[4:5], v[56:57], 0, s[12:13]
	s_lshl_b32 s12, s96, 1
	s_mov_b32 s13, s97
	v_lshl_add_u64 v[4:5], v[4:5], 0, s[12:13]
	v_lshl_add_u64 v[4:5], s[8:9], 1, v[4:5]
	v_lshl_add_u64 v[4:5], v[4:5], 0, v[0:1]
	global_store_dwordx2 v[4:5], v[2:3], off
	s_mov_b64 s[14:15], 0
.LBB0_2182:
	s_andn2_b64 vcc, exec, s[14:15]
	s_cbranch_vccnz .LBB0_2143
	v_lshl_add_u64 v[4:5], v[52:53], 0, s[96:97]
	s_lshl_b64 s[4:5], s[4:5], 14
	v_lshlrev_b64 v[4:5], 7, v[4:5]
	v_lshl_add_u64 v[18:19], v[54:55], 0, s[4:5]
	v_lshl_add_u64 v[4:5], v[18:19], 0, v[4:5]
	global_store_dwordx2 v[4:5], v[2:3], off
	s_branch .LBB0_2143

; DI unsigned xb_ld(unsigned* p)              { return __hip_atomic_load(p, __ATOMIC_RELAXED, __HIP_MEMORY_SCOPE_AGENT); }
; DI void xcd_barrier_complete(unsigned* bar, unsigned x, unsigned& nloc, unsigned& nx) {
;     ...
;     for (;;) {
;         sum = 0u; cnt = 0u; mine = 0u;
; #pragma unroll
;         for (unsigned j = 0; j < 16; ++j) { const unsigned c = xb_ld(&bar[XB_XCNT(j)]); sum += c; cnt += (c > 0u) ? 1u : 0u; mine = (j == x) ? c : mine; }
;         if (sum == G) break;
;         __builtin_amdgcn_s_sleep(1);
;         if ((++sp & 255u) == 0u) { if (xb_ld(&bar[XB_TMO])) break; if (sp > XB_SPIN_CAP) { atomicAdd(&bar[XB_TMO], 1u); break; } }
;     }
.LBB0_2190:
	v_mov_b64_e32 v[2:3], s[6:7]
	s_waitcnt lgkmcnt(0)
	global_load_dword v0, v[2:3], off sc1
	v_mov_b64_e32 v[2:3], s[8:9]
	global_load_dword v2, v[2:3], off sc1
	v_mov_b64_e32 v[4:5], s[12:13]
	global_load_dword v3, v[4:5], off sc1
	v_mov_b64_e32 v[4:5], s[14:15]
	global_load_dword v4, v[4:5], off sc1
	s_or_b64 s[84:85], s[84:85], exec
	s_or_b64 s[54:55], s[54:55], exec
	s_waitcnt vmcnt(0) lgkmcnt(0)
	v_add_u32_e32 v6, v2, v0
	v_add_u32_e32 v6, v6, v3
	v_add_u32_e32 v8, v6, v4
	v_mov_b64_e32 v[6:7], s[16:17]
	global_load_dword v5, v[6:7], off sc1
	v_mov_b64_e32 v[6:7], s[18:19]
	global_load_dword v6, v[6:7], off sc1
	s_waitcnt vmcnt(0) lgkmcnt(0)
	v_add_u32_e32 v8, v8, v5
	v_add_u32_e32 v10, v8, v6
	v_mov_b64_e32 v[8:9], s[20:21]
	global_load_dword v7, v[8:9], off sc1
	v_mov_b64_e32 v[8:9], s[22:23]
	global_load_dword v8, v[8:9], off sc1
	s_waitcnt vmcnt(0) lgkmcnt(0)
	v_add_u32_e32 v10, v10, v7
	v_add_u32_e32 v12, v10, v8
	v_mov_b64_e32 v[10:11], s[24:25]
	global_load_dword v9, v[10:11], off sc1
	v_mov_b64_e32 v[10:11], s[26:27]
	global_load_dword v10, v[10:11], off sc1
	s_waitcnt vmcnt(0) lgkmcnt(0)
	v_add_u32_e32 v12, v12, v9
	v_add_u32_e32 v14, v12, v10
	v_mov_b64_e32 v[12:13], s[28:29]
	global_load_dword v11, v[12:13], off sc1
	v_mov_b64_e32 v[12:13], s[30:31]
	global_load_dword v12, v[12:13], off sc1
	s_waitcnt vmcnt(0) lgkmcnt(0)
	v_add_u32_e32 v14, v14, v11
	v_add_u32_e32 v16, v14, v12
	v_mov_b64_e32 v[14:15], s[34:35]
	global_load_dword v13, v[14:15], off sc1
	v_mov_b64_e32 v[14:15], s[36:37]
	global_load_dword v14, v[14:15], off sc1
	s_waitcnt vmcnt(0) lgkmcnt(0)
	v_add_u32_e32 v16, v16, v13
	v_add_u32_e32 v18, v16, v14
	v_mov_b64_e32 v[16:17], s[92:93]
	global_load_dword v15, v[16:17], off sc1
	v_mov_b64_e32 v[16:17], s[44:45]
	global_load_dword v16, v[16:17], off sc1
	s_waitcnt vmcnt(0) lgkmcnt(0)
	v_add_u32_e32 v18, v18, v15
	v_add_u32_e32 v17, v18, v16
	v_cmp_ne_u32_e32 vcc, s33, v17
	s_and_saveexec_b64 s[90:91], vcc
	s_cbranch_execz .LBB0_2189
	s_and_b32 s46, s69, 0xff
	s_mov_b64 s[60:61], -1
	s_cmp_eq_u32 s46, 0
	s_mov_b64 s[46:47], -1
	s_mov_b64 s[64:65], -1
	s_sleep 1
	s_cbranch_scc1 .LBB0_2193
	s_and_saveexec_b64 s[66:67], s[46:47]
	s_cbranch_execz .LBB0_2188
	s_branch .LBB0_2196
.LBB0_2193:
	v_mov_b64_e32 v[18:19], s[4:5]
	global_load_dword v17, v[18:19], off sc1
	s_mov_b64 s[46:47], 0
	s_waitcnt vmcnt(0) lgkmcnt(0)
	v_cmp_eq_u32_e32 vcc, 0, v17
	s_and_saveexec_b64 s[66:67], vcc
	s_cmp_lt_u32 s69, 0x40001
	s_cselect_b64 s[46:47], -1, 0
	s_xor_b64 s[64:65], exec, -1
	s_and_b64 s[46:47], s[46:47], exec
	s_or_b64 exec, exec, s[66:67]
	s_and_saveexec_b64 s[66:67], s[46:47]
	s_cbranch_execz .LBB0_2188

; DI unsigned xb_ld(unsigned* p)              { return __hip_atomic_load(p, __ATOMIC_RELAXED, __HIP_MEMORY_SCOPE_AGENT); }
; DI unsigned xb_add(unsigned* p, unsigned v) { return __hip_atomic_fetch_add(p, v, __ATOMIC_RELAXED, __HIP_MEMORY_SCOPE_AGENT); }
; #define XB_SPIN(cond, bar) do { unsigned _sp = 0; while (cond) { __builtin_amdgcn_s_sleep(1); \
;     if ((++_sp & 255u) == 0u) { if (xb_ld(&(bar)[XB_TMO])) break; if (_sp > XB_SPIN_CAP) { atomicAdd(&(bar)[XB_TMO], 1u); break; } } } } while (0)
; DI void xcd_barrier(int wv, unsigned* bar, volatile LAS unsigned* st) {
;     ...
;         const unsigned old = xb_add(&bar[XB_XSUB(x)], 1u);
;         const unsigned gen = old / nloc;
;         if (old + 1u == (gen + 1u) * nloc) {
;             __builtin_amdgcn_fence(__ATOMIC_RELEASE, "agent");
;             asm volatile("s_waitcnt vmcnt(0)" ::: "memory");
;             const unsigned og = xb_add(&bar[XB_TOP], 1u);
;             const unsigned tg = og / nx;
;             if (og + 1u == (tg + 1u) * nx) xb_add(&bar[XB_TOPGEN], 1u);
;             else XB_SPIN(xb_ld(&bar[XB_TOPGEN]) == tg, bar);
;             __builtin_amdgcn_fence(__ATOMIC_ACQUIRE, "agent");
;             xb_add(&bar[XB_XGEN(x)], 1u);
;             asm volatile("s_waitcnt vmcnt(0)" ::: "memory");
;         } else {
;             XB_SPIN(xb_ld(&bar[XB_XGEN(x)]) == gen, bar);
.LBB0_2200:
	s_lshl_b32 s1, s1, 8
	s_add_u32 s4, s50, s1
	s_addc_u32 s5, s51, 0
	v_mov_b32_e32 v3, s4
	v_add_co_u32_e32 v4, vcc, 0xc1000, v3
	v_mov_b32_e32 v3, s5
	s_nop 0
	v_addc_co_u32_e32 v5, vcc, 0, v3, vcc
	v_mov_b32_e32 v3, 1
	flat_atomic_add v4, v[4:5], v3 offset:1024 sc0
	v_cvt_f32_u32_e32 v3, v2
	v_sub_u32_e32 v5, 0, v2
	s_add_u32 s28, s4, 0xc0000
	s_addc_u32 s1, s5, 0
	v_rcp_iflag_f32_e32 v3, v3
	s_nop 0
	v_mul_f32_e32 v3, 0x4f7ffffe, v3
	v_cvt_u32_f32_e32 v3, v3
	v_mul_lo_u32 v5, v5, v3
	v_mul_hi_u32 v5, v3, v5
	v_add_u32_e32 v3, v3, v5
	s_waitcnt vmcnt(0) lgkmcnt(0)
	v_mul_hi_u32 v3, v4, v3
	v_mul_lo_u32 v5, v3, v2
	v_sub_u32_e32 v5, v4, v5
	v_cmp_ge_u32_e32 vcc, v5, v2
	v_add_u32_e32 v6, 1, v3
	s_nop 0
	v_cndmask_b32_e32 v3, v3, v6, vcc
	v_sub_u32_e32 v6, v5, v2
	v_cndmask_b32_e32 v5, v5, v6, vcc
	v_cmp_ge_u32_e32 vcc, v5, v2
	v_add_u32_e32 v5, 1, v3
	v_add_u32_e32 v6, 1, v4
	v_cndmask_b32_e32 v3, v3, v5, vcc
	v_mad_u64_u32 v[4:5], s[4:5], v2, v3, v[2:3]
	v_cmp_ne_u32_e32 vcc, v6, v4
	s_and_saveexec_b64 s[4:5], vcc
	s_xor_b64 s[4:5], exec, s[4:5]
	s_cbranch_execz .LBB0_2213
	v_mov_b32_e32 v0, s28
	v_add_co_u32_e32 v4, vcc, 0x2000, v0
	v_mov_b32_e32 v0, s1
	s_nop 0
	v_addc_co_u32_e32 v5, vcc, 0, v0, vcc
	global_load_dword v0, v[4:5], off offset:1024 sc1
	s_add_u32 s8, s28, 0x2400
	s_addc_u32 s9, s1, 0
	s_waitcnt vmcnt(0) lgkmcnt(0)
	v_cmp_eq_u32_e32 vcc, v0, v3
	s_and_saveexec_b64 s[6:7], vcc
	s_cbranch_execz .LBB0_2212
	s_add_u32 s12, s50, 0xc0200
	s_addc_u32 s13, s51, 0
	s_mov_b32 s29, 1
	s_mov_b64 s[14:15], 0
	s_branch .LBB0_2204

; DI unsigned xb_ld(unsigned* p)              { return __hip_atomic_load(p, __ATOMIC_RELAXED, __HIP_MEMORY_SCOPE_AGENT); }
; #define XB_SPIN(cond, bar) do { unsigned _sp = 0; while (cond) { __builtin_amdgcn_s_sleep(1); \
;     if ((++_sp & 255u) == 0u) { if (xb_ld(&(bar)[XB_TMO])) break; if (_sp > XB_SPIN_CAP) { atomicAdd(&(bar)[XB_TMO], 1u); break; } } } } while (0)
; DI void xcd_barrier(int wv, unsigned* bar, volatile LAS unsigned* st) {
;     ...
;             XB_SPIN(xb_ld(&bar[XB_XGEN(x)]) == gen, bar);
.LBB0_2204:
	s_and_b32 s22, s29, 0xff
	s_mov_b64 s[20:21], -1
	s_cmp_lg_u32 s22, 0
	s_mov_b64 s[22:23], -1
	s_sleep 1
	s_cbranch_scc1 .LBB0_2208
	v_mov_b64_e32 v[4:5], s[12:13]
	global_load_dword v0, v[4:5], off sc1
	s_mov_b64 s[22:23], 0
	s_mov_b64 s[24:25], -1
	s_waitcnt vmcnt(0) lgkmcnt(0)
	v_cmp_eq_u32_e32 vcc, 0, v0
	s_and_saveexec_b64 s[26:27], vcc
	s_cmp_lt_u32 s29, 0x40001
	s_cselect_b64 s[22:23], -1, 0
	s_xor_b64 s[24:25], exec, -1
	s_and_b64 s[22:23], s[22:23], exec
	s_or_b64 exec, exec, s[26:27]
.LBB0_2208:
	s_andn2_b64 s[18:19], s[18:19], exec
	s_and_b64 s[24:25], s[24:25], exec
	s_or_b64 s[18:19], s[18:19], s[24:25]
	s_and_saveexec_b64 s[24:25], s[22:23]
	s_cbranch_execz .LBB0_2203
	v_mov_b64_e32 v[4:5], s[8:9]
	global_load_dword v0, v[4:5], off sc1
	s_add_i32 s29, s29, 1
	s_or_b64 s[18:19], s[18:19], exec
	s_waitcnt vmcnt(0) lgkmcnt(0)
	v_cmp_ne_u32_e32 vcc, v0, v3
	s_orn2_b64 s[20:21], vcc, exec
	s_branch .LBB0_2203

; DI unsigned xb_ld(unsigned* p)              { return __hip_atomic_load(p, __ATOMIC_RELAXED, __HIP_MEMORY_SCOPE_AGENT); }
; DI unsigned xb_add(unsigned* p, unsigned v) { return __hip_atomic_fetch_add(p, v, __ATOMIC_RELAXED, __HIP_MEMORY_SCOPE_AGENT); }
; #define XB_SPIN(cond, bar) do { unsigned _sp = 0; while (cond) { __builtin_amdgcn_s_sleep(1); \
;     if ((++_sp & 255u) == 0u) { if (xb_ld(&(bar)[XB_TMO])) break; if (_sp > XB_SPIN_CAP) { atomicAdd(&(bar)[XB_TMO], 1u); break; } } } } while (0)
; DI void xcd_barrier(int wv, unsigned* bar, volatile LAS unsigned* st) {
;     ...
;         if (old + 1u == (gen + 1u) * nloc) {
;             __builtin_amdgcn_fence(__ATOMIC_RELEASE, "agent");
;             asm volatile("s_waitcnt vmcnt(0)" ::: "memory");
;             const unsigned og = xb_add(&bar[XB_TOP], 1u);
;             const unsigned tg = og / nx;
;             if (og + 1u == (tg + 1u) * nx) xb_add(&bar[XB_TOPGEN], 1u);
;             else XB_SPIN(xb_ld(&bar[XB_TOPGEN]) == tg, bar);
.LBB0_2213:
	s_andn2_saveexec_b64 s[4:5], s[4:5]
	s_cbranch_execz .LBB0_2229
	v_mov_b32_e32 v2, s50
	v_add_co_u32_e32 v2, vcc, 0xc3000, v2
	v_mov_b32_e32 v3, s51
	buffer_wbl2 sc1
	s_waitcnt vmcnt(0)
	v_addc_co_u32_e32 v3, vcc, 0, v3, vcc
	v_mov_b32_e32 v4, 1
	flat_atomic_add v2, v[2:3], v4 offset:1024 sc0
	v_cvt_f32_u32_e32 v3, v0
	v_sub_u32_e32 v4, 0, v0
	s_mov_b64 s[8:9], -1
	v_rcp_iflag_f32_e32 v3, v3
	s_nop 0
	v_mul_f32_e32 v3, 0x4f7ffffe, v3
	v_cvt_u32_f32_e32 v3, v3
	v_mul_lo_u32 v4, v4, v3
	v_mul_hi_u32 v4, v3, v4
	v_add_u32_e32 v3, v3, v4
	s_waitcnt vmcnt(0) lgkmcnt(0)
	v_mul_hi_u32 v3, v2, v3
	v_mul_lo_u32 v4, v3, v0
	v_sub_u32_e32 v4, v2, v4
	v_cmp_ge_u32_e32 vcc, v4, v0
	v_add_u32_e32 v5, 1, v3
	s_nop 0
	v_cndmask_b32_e32 v3, v3, v5, vcc
	v_sub_u32_e32 v5, v4, v0
	v_cndmask_b32_e32 v4, v4, v5, vcc
	v_cmp_ge_u32_e32 vcc, v4, v0
	v_add_u32_e32 v4, 1, v3
	v_add_u32_e32 v5, 1, v2
	v_cndmask_b32_e32 v4, v3, v4, vcc
	v_mad_u64_u32 v[2:3], s[4:5], v0, v4, v[0:1]
	s_add_u32 s4, s50, 0xc3500
	s_addc_u32 s5, s51, 0
	v_cmp_ne_u32_e32 vcc, v5, v2
	v_mov_b64_e32 v[2:3], s[4:5]
	s_and_saveexec_b64 s[6:7], vcc
	s_cbranch_execz .LBB0_2226
	v_mov_b64_e32 v[2:3], s[4:5]
	global_load_dword v0, v[2:3], off sc1
	s_mov_b64 s[14:15], 0
	s_waitcnt vmcnt(0) lgkmcnt(0)
	v_cmp_eq_u32_e32 vcc, v0, v4
	s_and_saveexec_b64 s[12:13], vcc
	s_cbranch_execz .LBB0_2225
	s_add_u32 s8, s50, 0xc0200
	s_addc_u32 s9, s51, 0
	s_mov_b32 s26, 1
	s_branch .LBB0_2218

; DI unsigned xb_ld(unsigned* p)              { return __hip_atomic_load(p, __ATOMIC_RELAXED, __HIP_MEMORY_SCOPE_AGENT); }
; #define XB_SPIN(cond, bar) do { unsigned _sp = 0; while (cond) { __builtin_amdgcn_s_sleep(1); \
;     if ((++_sp & 255u) == 0u) { if (xb_ld(&(bar)[XB_TMO])) break; if (_sp > XB_SPIN_CAP) { atomicAdd(&(bar)[XB_TMO], 1u); break; } } } } while (0)
; DI void xcd_barrier(int wv, unsigned* bar, volatile LAS unsigned* st) {
;     ...
;             else XB_SPIN(xb_ld(&bar[XB_TOPGEN]) == tg, bar);
.LBB0_2220:
	v_mov_b64_e32 v[2:3], s[8:9]
	global_load_dword v0, v[2:3], off sc1
	s_mov_b64 s[22:23], 0
	s_mov_b64 s[20:21], -1
	s_waitcnt vmcnt(0) lgkmcnt(0)
	v_cmp_eq_u32_e32 vcc, 0, v0
	s_and_saveexec_b64 s[24:25], vcc
	s_cmp_lt_u32 s26, 0x40001
	s_cselect_b64 s[22:23], -1, 0
	s_xor_b64 s[20:21], exec, -1
	s_and_b64 s[22:23], s[22:23], exec
	s_or_b64 exec, exec, s[24:25]
	s_and_saveexec_b64 s[24:25], s[22:23]
	s_cbranch_execz .LBB0_2217
.LBB0_2223:
	v_mov_b64_e32 v[2:3], s[4:5]
	global_load_dword v0, v[2:3], off sc1
	s_add_i32 s26, s26, 1
	s_or_b64 s[20:21], s[20:21], exec
	s_waitcnt vmcnt(0) lgkmcnt(0)
	v_cmp_ne_u32_e32 vcc, v0, v4
	s_orn2_b64 s[18:19], vcc, exec
	s_branch .LBB0_2217

; #define LAS __attribute__((address_space(3)))
; DI int opaque_tid(int wv) { unsigned ones = ~0u; asm volatile("" : "+s"(ones)); int t = wv * 64 + (int)__builtin_amdgcn_mbcnt_hi(ones, __builtin_amdgcn_mbcnt_lo(ones, 0u)); asm volatile("" : "+v"(t)); return t; }
; DI void nsa_attn_phase(int wv, LAS unsigned char* lds, const bf16_t* Q, const bf16_t* slab, const bf16_t* VT2, const float* gates, const bf16_t* KCMP, const bf16_t* VCMPT,
;                        const float* rel_bias, bf16_t* O) {
;     ...
;     for (int item0 = blockIdx.x; item0 < 256; item0 += gridDim.x) {
;         const int item = (gridDim.x == 256) ? (item0 & 7) * 32 + (item0 >> 3) : item0;
;         const int b = item >> 4, g = (item >> 2) & 3, qtr = item & 3;
;         const int head = g * 4 + rhead;
;         const size_t bg = (size_t)(b * 4 + g);
;         int tid = opaque_tid(wv), lane = tid & 63;
;         __syncthreads();
; #pragma unroll
;         for (int e = 0; e < 2; ++e) { const int pc = tid + 512 * e;
;             const u32x4 v = *(const u32x4*)(KCMP + bg * 128 * 64 + (size_t)pc * 8); *(LAS u32x4*)(lds + OFF_KC + (pc >> 3) * KCS + (pc & 7) * 16) = v;
;             const u32x4 v2 = *(const u32x4*)(VCMPT + bg * 64 * 128 + (size_t)pc * 8); lds_store16_as2x8(lds + OFF_VC + (pc >> 4) * VCS + (pc & 15) * 16, v2); }
;         lut[tid] = rel_bias[t5_bucket(tid & 127) * 16 + g * 4 + (tid >> 7)] * LOG2E;
.LBB0_2236:
	s_lshl_b32 s0, s65, 5
	s_and_b32 s0, s0, 0xe0
	s_ashr_i32 s1, s65, 3
	s_add_i32 s2, s0, s1
	v_readlane_b32 s0, v254, 19
	v_readlane_b32 s1, v254, 20
	s_and_b64 s[0:1], s[0:1], exec
	s_cselect_b32 s1, s2, s65
	s_ashr_i32 s2, s1, 4
	s_bfe_u32 s0, s1, 0x20002
	s_lshl_b32 s3, s2, 2
	s_or_b32 s4, s3, s0
	s_mov_b32 s3, -1
	s_ashr_i32 s5, s4, 31
	v_mbcnt_lo_u32_b32 v0, s3, 0
	v_mbcnt_hi_u32_b32 v0, s3, v0
	s_waitcnt lgkmcnt(0)
	v_add_u32_e32 v2, s11, v0
	s_lshl_b64 s[6:7], s[4:5], 14
	s_add_u32 s8, s50, s6
	v_ashrrev_i32_e32 v3, 31, v2
	s_addc_u32 s9, s51, s7
	v_lshlrev_b64 v[8:9], 4, v[2:3]
	v_lshl_add_u64 v[4:5], s[8:9], 0, v[8:9]
	s_waitcnt vmcnt(0) lgkmcnt(0)
	s_barrier
	global_load_dwordx4 v[4:7], v[4:5], off
	v_lshlrev_b32_e32 v3, 4, v2
	v_and_b32_e32 v0, 0x70, v3
	v_lshrrev_b32_e32 v10, 3, v2
	v_add_u32_e32 v0, 0, v0
	s_add_u32 s6, s54, s6
	v_mad_u64_u32 v[10:11], s[12:13], v10, s87, v[0:1]
	s_addc_u32 s7, s55, s7
	v_lshl_add_u64 v[8:9], s[6:7], 0, v[8:9]
	v_and_b32_e32 v3, 0xf0, v3
	s_movk_i32 s3, 0x108
	v_add_u32_e32 v3, 0, v3
	s_movk_i32 s12, 0x4800
	s_waitcnt vmcnt(0) lgkmcnt(0)
	ds_write_b128 v10, v[4:7]
	global_load_dwordx4 v[4:7], v[8:9], off
	v_ashrrev_i32_e32 v9, 4, v2
	v_add_u32_e32 v8, 0x200, v2
	v_mul_lo_u32 v12, v9, s3
	v_ashrrev_i32_e32 v9, 31, v8
	v_lshlrev_b64 v[10:11], 4, v[8:9]
	v_add3_u32 v9, v3, v12, s12
	v_lshl_add_u64 v[12:13], s[8:9], 0, v[10:11]
	v_lshl_add_u64 v[10:11], s[6:7], 0, v[10:11]
	s_waitcnt vmcnt(0) lgkmcnt(0)
	ds_write2_b64 v9, v[4:5], v[6:7] offset1:1
	global_load_dwordx4 v[4:7], v[12:13], off
	v_lshrrev_b32_e32 v9, 3, v8
	v_mad_u64_u32 v[12:13], s[8:9], v9, s87, v[0:1]
	v_ashrrev_i32_e32 v8, 4, v8
	v_and_b32_e32 v0, 0x7f, v2
	v_mul_lo_u32 v8, v8, s3
	v_add3_u32 v3, v3, v8, s12
	v_cmp_lt_u32_e32 vcc, 15, v0
	s_waitcnt vmcnt(0) lgkmcnt(0)
	ds_write_b128 v12, v[4:7]
	global_load_dwordx4 v[4:7], v[10:11], off
	s_waitcnt vmcnt(0) lgkmcnt(0)
	ds_write2_b64 v3, v[4:5], v[6:7] offset1:1
	s_and_saveexec_b64 s[6:7], vcc
	s_cbranch_execz .LBB0_2238
	v_cvt_f32_ubyte0_e32 v0, v0
	v_mul_f32_e32 v0, 0x3d800000, v0
	v_cmp_gt_f32_e32 vcc, s42, v0
	s_mov_b32 s3, 0x3f317217
	s_nop 0
	v_cndmask_b32_e64 v3, 0, 32, vcc
	v_ldexp_f32 v0, v0, v3
	v_log_f32_e32 v0, v0
	v_mov_b32_e32 v3, 0x41b17218
	v_cndmask_b32_e32 v3, 0, v3, vcc
	v_mul_f32_e32 v4, 0x3f317217, v0
	v_fma_f32 v4, v0, s3, -v4
	v_fmac_f32_e32 v4, 0x3377d1cf, v0
	s_mov_b32 s3, 0x7f800000
	v_fmac_f32_e32 v4, 0x3f317217, v0
	v_cmp_lt_f32_e64 vcc, |v0|, s3
	s_mov_b32 s3, 0x40051592
	s_nop 0
	v_cndmask_b32_e32 v0, v0, v4, vcc
	v_sub_f32_e32 v0, v0, v3
	v_div_scale_f32 v3, s[8:9], s3, s3, v0
	v_rcp_f32_e32 v4, v3
	v_div_scale_f32 v5, vcc, v0, s3, v0
	v_fma_f32 v6, -v3, v4, 1.0
	v_fmac_f32_e32 v4, v6, v4
	v_mul_f32_e32 v6, v5, v4
	v_fma_f32 v7, -v3, v6, v5
	v_fmac_f32_e32 v6, v7, v4
	v_fma_f32 v3, -v3, v6, v5
	v_div_fmas_f32 v3, v3, v4, v6
	v_div_fixup_f32 v0, v3, s3, v0
	v_mul_f32_e32 v0, 0x41800000, v0
	v_cvt_i32_f32_e32 v0, v0
	v_min_i32_e32 v0, 15, v0
	v_add_u32_e32 v0, 16, v0

; DI void nsa_attn_phase(int wv, LAS unsigned char* lds, const bf16_t* Q, const bf16_t* slab, const bf16_t* VT2, const float* gates, const bf16_t* KCMP, const bf16_t* VCMPT,
;                        const float* rel_bias, bf16_t* O) {
;     ...
;         for (int qi = 0; qi < 8; ++qi) {
;             tid = opaque_tid(wv); lane = tid & 63; const int r = lane & 31, hh = lane >> 5;
;             const int qblk = 4 * qi + ((qi & 1) ? 3 - qtr : qtr), T0 = 64 * qblk, TW = T0 + 32 * half;
;             const int tq = TW + r; const size_t token = (size_t)b * SEQ + tq;
;             const float c31 = mylut[127];
;             bf16x8 qf[4];
; #pragma unroll
;             for (int ks = 0; ks < 4; ++ks) qf[ks] = *(const bf16x8*)(Q + token * 1024 + head * 64 + 16 * ks + 8 * hh);
;             const float g0 = gates[token * 48 + head * 3], g1 = gates[token * 48 + head * 3 + 1], g2 = gates[token * 48 + head * 3 + 2];
;             f32x16 out[2] = {zero16(), zero16()};
;             const bool need_rank = qblk >= 16;
;             {
;                 const int nsub = (TW >> 9) + 1;
;                 f32x16 s4[4];
;                 float mx = NEGF;
; #pragma unroll
;                 for (int t = 0; t < 4; ++t) {
;                     if (t < nsub) {
;                         const bool farc = TW - (16 * (32 * t + 31) + 31) >= 127;
;                         s4[t] = splat16(farc ? c31 : 0.f);
;                         bf16x8 kfc[4];
; #pragma unroll
;                         for (int ks = 0; ks < 4; ++ks) kfc[ks] = *(const LAS bf16x8*)(lds + OFF_KC + (32 * t + r) * KCS + 32 * ks + 16 * hh);
; #pragma unroll
;                         for (int ks = 0; ks < 4; ++ks) s4[t] = mfma32(kfc[ks], qf[ks], s4[t]);
;                         if (!farc) {
;                             const int d0 = tq - 31 - 16 * (32 * t + 4 * hh);
; #pragma unroll
;                             for (int i = 0; i < 16; ++i) {
;                                 const int dist = d0 - 16 * ((i & 3) + 8 * (i >> 2));
;                                 const float bias = mylut[dist < 0 ? 0 : (dist > 127 ? 127 : dist)];
;                                 s4[t][i] = dist >= 0 ? s4[t][i] + bias : NEGF;
;     ...
;             {
;                 const int l2 = opaque_tid(wv) & 63, tq2 = TW + (l2 & 31);
;                 store_ot(out, 1.f, O + ((size_t)b * SEQ + tq2) * 1024 + head * 64, l2 >> 5);
;             }
.LBB0_2239:
	s_mov_b32 s0, -1
	v_cvt_pk_bf16_f32 v4, v96, v97
	v_mbcnt_lo_u32_b32 v0, s0, 0
	v_mbcnt_hi_u32_b32 v0, s0, v0
	v_add_u32_e32 v0, s11, v0
	v_cvt_pk_bf16_f32 v5, v98, v99
	v_and_or_b32 v2, v0, 31, s90
	v_ashrrev_i32_e32 v3, 31, v2
	v_lshl_add_u64 v[2:3], s[16:17], 0, v[2:3]
	v_lshlrev_b64 v[2:3], 11, v[2:3]
	v_lshrrev_b32_e32 v0, 2, v0
	v_lshl_add_u64 v[2:3], s[24:25], 0, v[2:3]
	v_and_b32_e32 v0, 8, v0
	v_lshl_add_u64 v[2:3], v[2:3], 0, v[0:1]
	global_store_dwordx2 v[2:3], v[4:5], off
	v_cvt_pk_bf16_f32 v4, v100, v101
	v_cvt_pk_bf16_f32 v5, v102, v103
	global_store_dwordx2 v[2:3], v[4:5], off offset:16
	v_cvt_pk_bf16_f32 v4, v104, v105
	v_cvt_pk_bf16_f32 v5, v106, v107
	global_store_dwordx2 v[2:3], v[4:5], off offset:32
	v_cvt_pk_bf16_f32 v4, v108, v109
	v_cvt_pk_bf16_f32 v5, v110, v111
	global_store_dwordx2 v[2:3], v[4:5], off offset:48
	v_cvt_pk_bf16_f32 v4, v80, v81
	v_cvt_pk_bf16_f32 v5, v82, v83
	global_store_dwordx2 v[2:3], v[4:5], off offset:64
	v_cvt_pk_bf16_f32 v4, v84, v85
	v_cvt_pk_bf16_f32 v5, v86, v87
	global_store_dwordx2 v[2:3], v[4:5], off offset:80
	v_cvt_pk_bf16_f32 v4, v88, v89
	v_cvt_pk_bf16_f32 v5, v90, v91
	s_add_i32 s85, s85, 1
	global_store_dwordx2 v[2:3], v[4:5], off offset:96
	v_cvt_pk_bf16_f32 v4, v92, v93
	v_cvt_pk_bf16_f32 v5, v94, v95
	s_cmp_eq_u32 s85, 8
	global_store_dwordx2 v[2:3], v[4:5], off offset:112
	s_cbranch_scc1 .LBB0_2235
.LBB0_2240:
	s_mov_b32 s0, -1
	v_mov_b32_e32 v213, v1
	v_mbcnt_lo_u32_b32 v0, s0, 0
	v_mbcnt_hi_u32_b32 v0, s0, v0
	s_lshl_b32 s0, s85, 2
	s_bitcmp0_b32 s85, 0
	s_cselect_b32 s1, s66, s67
	s_or_b32 s26, s1, s0
	v_add_u32_e32 v114, s11, v0
	s_lshl_b32 s90, s26, 6
	s_add_i32 s90, s90, s60
	v_and_b32_e32 v112, 31, v114
	v_or_b32_e32 v210, s90, v112
	v_ashrrev_i32_e32 v211, 31, v210
	v_lshl_add_u64 v[2:3], s[16:17], 0, v[210:211]
	v_bfe_u32 v97, v114, 5, 1
	v_lshlrev_b64 v[4:5], 11, v[2:3]
	v_lshl_add_u64 v[4:5], s[18:19], 0, v[4:5]
	v_lshlrev_b32_e32 v212, 4, v97
	v_lshl_add_u64 v[4:5], v[4:5], 0, v[212:213]
	global_load_dwordx4 v[176:179], v[4:5], off
	global_load_dwordx4 v[180:183], v[4:5], off offset:32
	global_load_dwordx4 v[184:187], v[4:5], off offset:64
	global_load_dwordx4 v[188:191], v[4:5], off offset:96
	v_mov_b64_e32 v[4:5], s[20:21]
	v_mad_u64_u32 v[4:5], s[0:1], v2, s41, v[4:5]
	v_mad_i32_i24 v5, v3, s41, v5
	global_load_dwordx3 v[204:206], v[4:5], off
	v_mov_b32_e32 v0, s57
	ds_read_b32 v113, v0 offset:508
	s_ashr_i32 s0, s90, 9
	v_add_u32_e32 v96, 0, v212
	s_cmp_gt_i32 s0, -1
	v_mul_i32_i24_e32 v0, 0xffffffc0, v97
	v_mov_b32_e32 v98, 0xf149f2ca
	s_cselect_b64 s[4:5], -1, 0
	s_cmp_lt_i32 s0, 0
	v_mad_u32_u24 v2, v112, s87, v96
	s_cbranch_scc1 .LBB0_2276
	ds_read_b128 v[4:7], v2
	s_cmpk_gt_u32 s90, 0x28d
	s_cselect_b64 vcc, -1, 0
	s_waitcnt lgkmcnt(0)
	v_cndmask_b32_e32 v64, 0, v113, vcc
	v_mov_b32_e32 v65, v64
	v_mov_b32_e32 v66, v64
	v_mov_b32_e32 v67, v64
	v_mov_b32_e32 v68, v64
	v_mov_b32_e32 v69, v64
	v_mov_b32_e32 v70, v64
	v_mov_b32_e32 v71, v64
	v_mov_b32_e32 v72, v64
	v_mov_b32_e32 v73, v64
	v_mov_b32_e32 v74, v64
	v_mov_b32_e32 v75, v64
	v_mov_b32_e32 v76, v64
	v_mov_b32_e32 v77, v64
	v_mov_b32_e32 v78, v64
	v_mov_b32_e32 v79, v64
	s_and_b64 vcc, exec, vcc
	s_waitcnt vmcnt(0)
	v_mfma_f32_32x32x16_bf16 v[64:79], v[4:7], v[176:179], v[64:79]
	ds_read_b128 v[4:7], v2 offset:32
	s_waitcnt lgkmcnt(0)
	v_mfma_f32_32x32x16_bf16 v[64:79], v[4:7], v[180:183], v[64:79]
	ds_read_b128 v[4:7], v2 offset:64
	s_waitcnt lgkmcnt(0)
	v_mfma_f32_32x32x16_bf16 v[64:79], v[4:7], v[184:187], v[64:79]
	ds_read_b128 v[4:7], v2 offset:96
	s_waitcnt lgkmcnt(0)
	v_mfma_f32_32x32x16_bf16 v[64:79], v[4:7], v[188:191], v[64:79]
	s_cbranch_vccnz .LBB0_2275
	s_movk_i32 s1, 0xffe1
	v_add3_u32 v3, v210, v0, s1
	v_cmp_lt_i32_e32 vcc, -1, v3
	v_mov_b32_e32 v81, 0xf149f2ca
	v_mov_b32_e32 v80, 0xf149f2ca
	s_and_saveexec_b64 s[2:3], vcc
	s_cbranch_execz .LBB0_2244
	v_min_u32_e32 v4, 0x7f, v3
	v_lshl_add_u32 v4, v4, 2, s57
	ds_read_b32 v4, v4
	s_waitcnt lgkmcnt(0)
	v_add_f32_e32 v80, v64, v4

; #define LAS __attribute__((address_space(3)))
; DI void nsa_attn_phase(int wv, LAS unsigned char* lds, const bf16_t* Q, const bf16_t* slab, const bf16_t* VT2, const float* gates, const bf16_t* KCMP, const bf16_t* VCMPT,
;                        const float* rel_bias, bf16_t* O) {
;     ...
;                 const bf16_t* Ksrc = slab + (size_t)(br ? 3 : 2) * SLAB_EL + bg * 2048 * 64;
;                 const bf16_t* Vsrc = VT2 + ((size_t)b * 512 + (br ? 256 : 0) + g * 64) * VPITCH;
;                 unsigned tiles;
;                 if (br == 0) tiles = uni; else { const int jlo = qblk - 8 < 0 ? 0 : qblk - 8; tiles = causal & ~((1u << jlo) - 1u); }
;                 float m = 0.f, l = 0.f; f32x16 o[2] = {zero16(), zero16()};
;                 u32x4 rk, rv;
;                 auto gload = [&](int j) {
;                     rk = *(const u32x4*)(Ksrc + (size_t)j * 64 * 64 + (size_t)tid * 8);
;                     rv = *(const u32x4*)(Vsrc + (size_t)(tid >> 3) * VPITCH + 64 * j + (tid & 7) * 8);
;                 };
;                 auto lstore = [&](int buf) {
;                     LAS unsigned char* kb = lds + OFF_BUF + buf * TILE;
;                     *(LAS u32x4*)(kb + (tid >> 3) * KS + (tid & 7) * 16) = rk;
;                     lds_store16_as2x8(kb + VOFF + (tid >> 3) * VS + (tid & 7) * 16, rv);
;                 };
;                 auto process = [&](const LAS unsigned char* kb, int j) {
;                     const int k0 = 64 * j;
;                     const bool selbit = (br == 0) ? (((mysel >> j) & 1u) != 0u) : true;
;                     if (br == 0 && __ballot(selbit) == 0ull) return;
;                     const bool far = (TW - (k0 + 63) >= 127) && (br == 0 || (TW + 31 - k0 < 512));
;                     f32x16 s[2];
;                     qk_tile<4>(kb, KS, qf, s, r, hh, ref_frag(-m, far ? (selbit ? c31 : NEGF) : 0.f, hh));
;                     if (!far) {
;                         const int d0 = tq - k0 - 4 * hh;
; #pragma unroll
;                         for (int t = 0; t < 2; ++t)
; #pragma unroll
;                             for (int i = 0; i < 16; ++i) {
;                                 const int dist = d0 - (32 * t + (i & 3) + 8 * (i >> 2));
;                                 const float bias = mylut[dist < 0 ? 0 : (dist > 127 ? 127 : dist)];
;                                 const bool valid = selbit && dist >= 0 && (br == 0 || dist < 512);
.LBB0_2416:
	s_and_b64 s[0:1], s[8:9], exec
	s_brev_b32 s0, 64
	s_cselect_b32 s0, s0, 0x3000000
	v_mov_b32_e32 v0, s91
	s_add_u32 s4, s69, s0
	v_cndmask_b32_e64 v0, v0, v234, s[8:9]
	s_addc_u32 s5, s84, 0
	v_ffbl_b32_e32 v144, v0
	v_add_u32_e32 v2, -1, v0
	s_and_b64 s[0:1], s[8:9], exec
	v_and_b32_e32 v4, v2, v0
	v_lshlrev_b32_e32 v0, 13, v144
	s_cselect_b32 s0, 0, 0x100
	v_lshl_add_u64 v[2:3], s[4:5], 0, v[0:1]
	s_or_b32 s0, s0, s22
	v_lshl_add_u64 v[2:3], v[2:3], 0, v[214:215]
	v_mov_b32_e32 v0, 0x1080
	s_waitcnt vmcnt(0)
	global_load_dwordx4 v[196:199], v[2:3], off
	v_mad_u64_u32 v[2:3], s[0:1], s0, v0, v[216:217]
	s_mul_i32 s0, s23, 0x1080
	s_nop 0
	v_add_u32_e32 v3, s0, v3
	v_lshlrev_b32_e32 v0, 7, v144
	v_lshl_add_u64 v[6:7], v[2:3], 0, v[0:1]
	v_lshlrev_b32_e32 v0, 1, v204
	v_lshl_add_u64 v[6:7], v[6:7], 0, v[0:1]
	global_load_dwordx4 v[200:203], v[6:7], off
	v_mov_b32_e32 v244, -1
	v_add_u32_e32 v5, v237, v238
	v_cmp_ne_u32_e32 vcc, 0, v4
	v_mov_b32_e32 v245, 0
	v_mov_b32_e32 v145, 0
	s_waitcnt vmcnt(0) lgkmcnt(0)
	ds_write_b128 v5, v[196:199] offset:35328
	ds_write2_b64 v243, v[200:201], v[202:203] offset1:1
	s_and_saveexec_b64 s[6:7], vcc
	s_cbranch_execz .LBB0_2418
	v_ffbl_b32_e32 v244, v4
	v_lshlrev_b32_e32 v6, 13, v244
	v_mov_b32_e32 v7, v1
	v_lshl_add_u64 v[6:7], s[4:5], 0, v[6:7]
	v_lshlrev_b32_e32 v8, 7, v244
	v_mov_b32_e32 v9, v1
	v_lshl_add_u64 v[6:7], v[6:7], 0, v[214:215]
	v_lshl_add_u64 v[8:9], v[2:3], 0, v[8:9]
	v_lshl_add_u64 v[8:9], v[8:9], 0, v[0:1]
	global_load_dwordx4 v[196:199], v[6:7], off
	global_load_dwordx4 v[200:203], v[8:9], off
	v_add_u32_e32 v5, -1, v4
	v_and_b32_e32 v145, v5, v4

; DI void nsa_attn_phase(int wv, LAS unsigned char* lds, const bf16_t* Q, const bf16_t* slab, const bf16_t* VT2, const float* gates, const bf16_t* KCMP, const bf16_t* VCMPT,
;                        const float* rel_bias, bf16_t* O) {
;     ...
;                 for (;;) {
;                     const int bn = bi == 2 ? 0 : bi + 1;
;                     if (jn >= 0) lstore(bn);
;                     int jnn = -1; if (tiles) { jnn = __builtin_ctz(tiles); tiles &= tiles - 1; gload(jnn); }
;                     process(lds + OFF_BUF + bi * TILE, j);
;                     __syncthreads();
;                     if (jn < 0) break;
;                     j = jn; jn = jnn; bi = bn;
.LBB0_2423:
	s_or_b64 exec, exec, s[4:5]
	v_mov_b32_e32 v6, 0
	v_cmp_ne_u32_e32 vcc, 0, v145
	v_mov_b32_e32 v5, -1
	s_and_saveexec_b64 s[4:5], vcc
	s_cbranch_execz .LBB0_2425
	v_ffbl_b32_e32 v5, v145
	v_lshlrev_b32_e32 v0, 7, v5
	v_lshl_add_u64 v[2:3], v[220:221], 0, v[0:1]
	v_lshlrev_b32_e32 v0, 13, v5
	v_lshl_add_u64 v[6:7], v[218:219], 0, v[0:1]
	s_waitcnt vmcnt(0)
	global_load_dwordx4 v[196:199], v[6:7], off
	global_load_dwordx4 v[200:203], v[2:3], off
	v_add_u32_e32 v0, -1, v145
	v_and_b32_e32 v6, v0, v145

; DI unsigned xb_ld(unsigned* p)              { return __hip_atomic_load(p, __ATOMIC_RELAXED, __HIP_MEMORY_SCOPE_AGENT); }
; DI void xcd_barrier_complete(unsigned* bar, unsigned x, unsigned& nloc, unsigned& nx) {
;     ...
;     for (;;) {
;         sum = 0u; cnt = 0u; mine = 0u;
; #pragma unroll
;         for (unsigned j = 0; j < 16; ++j) { const unsigned c = xb_ld(&bar[XB_XCNT(j)]); sum += c; cnt += (c > 0u) ? 1u : 0u; mine = (j == x) ? c : mine; }
;         if (sum == G) break;
;         __builtin_amdgcn_s_sleep(1);
;         if ((++sp & 255u) == 0u) { if (xb_ld(&bar[XB_TMO])) break; if (sp > XB_SPIN_CAP) { atomicAdd(&bar[XB_TMO], 1u); break; } }
;     }
.LBB0_2444:
	v_mov_b64_e32 v[2:3], s[4:5]
	s_waitcnt lgkmcnt(0)
	global_load_dword v0, v[2:3], off sc1
	v_mov_b64_e32 v[2:3], s[6:7]
	global_load_dword v2, v[2:3], off sc1
	v_mov_b64_e32 v[4:5], s[8:9]
	global_load_dword v3, v[4:5], off sc1
	v_mov_b64_e32 v[4:5], s[12:13]
	global_load_dword v4, v[4:5], off sc1
	s_or_b64 s[84:85], s[84:85], exec
	s_or_b64 s[54:55], s[54:55], exec
	s_waitcnt vmcnt(0) lgkmcnt(0)
	v_add_u32_e32 v6, v2, v0
	v_add_u32_e32 v6, v6, v3
	v_add_u32_e32 v8, v6, v4
	v_mov_b64_e32 v[6:7], s[14:15]
	global_load_dword v5, v[6:7], off sc1
	v_mov_b64_e32 v[6:7], s[16:17]
	global_load_dword v6, v[6:7], off sc1
	s_waitcnt vmcnt(0) lgkmcnt(0)
	v_add_u32_e32 v8, v8, v5
	v_add_u32_e32 v10, v8, v6
	v_mov_b64_e32 v[8:9], s[18:19]
	global_load_dword v7, v[8:9], off sc1
	v_mov_b64_e32 v[8:9], s[20:21]
	global_load_dword v8, v[8:9], off sc1
	s_waitcnt vmcnt(0) lgkmcnt(0)
	v_add_u32_e32 v10, v10, v7
	v_add_u32_e32 v12, v10, v8
	v_mov_b64_e32 v[10:11], s[22:23]
	global_load_dword v9, v[10:11], off sc1
	v_mov_b64_e32 v[10:11], s[24:25]
	global_load_dword v10, v[10:11], off sc1
	s_waitcnt vmcnt(0) lgkmcnt(0)
	v_add_u32_e32 v12, v12, v9
	v_add_u32_e32 v14, v12, v10
	v_mov_b64_e32 v[12:13], s[26:27]
	global_load_dword v11, v[12:13], off sc1
	v_mov_b64_e32 v[12:13], s[28:29]
	global_load_dword v12, v[12:13], off sc1
	s_waitcnt vmcnt(0) lgkmcnt(0)
	v_add_u32_e32 v14, v14, v11
	v_add_u32_e32 v16, v14, v12
	v_mov_b64_e32 v[14:15], s[30:31]
	global_load_dword v13, v[14:15], off sc1
	v_mov_b64_e32 v[14:15], s[34:35]
	global_load_dword v14, v[14:15], off sc1
	s_waitcnt vmcnt(0) lgkmcnt(0)
	v_add_u32_e32 v16, v16, v13
	v_add_u32_e32 v18, v16, v14
	v_mov_b64_e32 v[16:17], s[50:51]
	global_load_dword v15, v[16:17], off sc1
	v_mov_b64_e32 v[16:17], s[44:45]
	global_load_dword v16, v[16:17], off sc1
	s_waitcnt vmcnt(0) lgkmcnt(0)
	v_add_u32_e32 v18, v18, v15
	v_add_u32_e32 v17, v18, v16
	v_cmp_ne_u32_e32 vcc, s33, v17
	s_and_saveexec_b64 s[90:91], vcc
	s_cbranch_execz .LBB0_2443
	s_and_b32 s46, s1, 0xff
	s_mov_b64 s[60:61], -1
	s_cmp_eq_u32 s46, 0
	s_mov_b64 s[46:47], -1
	s_mov_b64 s[64:65], -1
	s_sleep 1
	s_cbranch_scc1 .LBB0_2447
	s_and_saveexec_b64 s[66:67], s[46:47]
	s_cbranch_execz .LBB0_2442
	s_branch .LBB0_2450
.LBB0_2447:
	v_mov_b64_e32 v[18:19], s[2:3]
	global_load_dword v17, v[18:19], off sc1
	s_mov_b64 s[46:47], 0
	s_waitcnt vmcnt(0) lgkmcnt(0)
	v_cmp_eq_u32_e32 vcc, 0, v17
	s_and_saveexec_b64 s[66:67], vcc
	s_cmp_lt_u32 s1, 0x40001
	s_cselect_b64 s[46:47], -1, 0
	s_xor_b64 s[64:65], exec, -1
	s_and_b64 s[46:47], s[46:47], exec
	s_or_b64 exec, exec, s[66:67]
	s_and_saveexec_b64 s[66:67], s[46:47]
	s_cbranch_execz .LBB0_2442

; #define EPI_SCHED() __builtin_amdgcn_sched_barrier(0)
; template <int STRIDE, int P0, int NP4>
; DI void rstd8(const float* parts, size_t row0, float invK, int fq, float (&rs)[2][4]) {
;     ...
;             const float* p = parts + (row0 + ai * 128 + m * 16) * STRIDE + P0;
;             if (NP4 == 1) v[ai][m] = *(const f32x4*)p;
;             else if (fq < NP4) v[ai][m] = *(const f32x4*)(p + 4 * fq);
;             else v[ai][m] = (f32x4){0.f, 0.f, 0.f, 0.f};
;         }
; #pragma unroll
;     for (int ai = 0; ai < 2; ++ai)
; #pragma unroll
;         for (int m = 0; m < 4; ++m) {
;             float t = (v[ai][m].x + v[ai][m].y) + (v[ai][m].z + v[ai][m].w);
;             if (NP4 > 1) { t += __shfl_xor(t, 16); t += __shfl_xor(t, 32); }
;             rs[ai][m] = rsqrtf(t * invK + EPS);
;         }
;     DI void operator()(const AccT& acc, const Unit& u, int wr, int wc, int fr, int fq) const {
;     ...
;         const bool do_rope = (u.pn == 2) && (wc == 0);
; #pragma unroll
;         for (int ai = 0; ai < 2; ++ai) {
;             EPI_SCHED();
;             f32x4 cs[4], sn[4];
;             if (do_rope) {
; #pragma unroll
;                 for (int m = 0; m < 4; ++m) { const int s = (int)((row0 + ai * 128 + m * 16) & 2047); cs[m] = *(const f32x4*)(rope + s * 16 + 4 * fq); sn[m] = *(const f32x4*)(rope + 32768 + s * 16 + 4 * fq); }
;             }
.LBB0_2517:
	v_pk_add_f32 v[102:103], v[166:167], v[102:103]
	v_pk_add_f32 v[98:99], v[104:105], v[98:99]
	v_xor_b32_e32 v0, 16, v207
	v_mov_b32_e32 v104, v98
	v_mov_b32_e32 v105, v102
	v_mov_b32_e32 v102, v99
	v_cmp_lt_i32_e32 vcc, v0, v222
	v_pk_add_f32 v[98:99], v[104:105], v[102:103]
	v_pk_add_f32 v[100:101], v[100:101], v[126:127]
	v_pk_add_f32 v[104:105], v[128:129], v[122:123]
	v_cndmask_b32_e32 v0, v207, v0, vcc
	v_mov_b32_e32 v122, v104
	v_mov_b32_e32 v123, v100
	v_mov_b32_e32 v100, v105
	v_lshlrev_b32_e32 v192, 2, v0
	v_pk_add_f32 v[100:101], v[122:123], v[100:101]
	ds_bpermute_b32 v103, v192, v99
	ds_bpermute_b32 v102, v192, v98
	ds_bpermute_b32 v105, v192, v101
	ds_bpermute_b32 v104, v192, v100
	v_cmp_lt_i32_e32 vcc, v223, v222
	s_cmp_lg_u32 s38, 2
	s_waitcnt lgkmcnt(0)
	v_pk_add_f32 v[170:171], v[98:99], v[102:103]
	v_pk_add_f32 v[98:99], v[124:125], v[142:143]
	v_pk_add_f32 v[180:181], v[100:101], v[104:105]
	v_pk_add_f32 v[100:101], v[144:145], v[138:139]
	v_mov_b32_e32 v103, v98
	v_mov_b32_e32 v102, v100
	v_mov_b32_e32 v98, v101
	v_pk_add_f32 v[98:99], v[102:103], v[98:99]
	v_pk_add_f32 v[102:103], v[140:141], v[158:159]
	v_pk_add_f32 v[104:105], v[160:161], v[154:155]
	v_mov_b32_e32 v123, v102
	v_mov_b32_e32 v122, v104
	v_mov_b32_e32 v102, v105
	v_pk_add_f32 v[102:103], v[122:123], v[102:103]
	ds_bpermute_b32 v101, v192, v99
	ds_bpermute_b32 v100, v192, v98
	ds_bpermute_b32 v105, v192, v103
	ds_bpermute_b32 v104, v192, v102
	v_cndmask_b32_e32 v0, v207, v223, vcc
	v_lshlrev_b32_e32 v193, 2, v0
	s_waitcnt lgkmcnt(0)
	v_pk_add_f32 v[172:173], v[98:99], v[100:101]
	ds_bpermute_b32 v185, v193, v171
	v_pk_add_f32 v[166:167], v[102:103], v[104:105]
	ds_bpermute_b32 v184, v193, v170
	ds_bpermute_b32 v183, v193, v181
	ds_bpermute_b32 v182, v193, v180
	ds_bpermute_b32 v175, v193, v173
	ds_bpermute_b32 v174, v193, v172
	ds_bpermute_b32 v169, v193, v167
	ds_bpermute_b32 v168, v193, v166
	s_cselect_b64 s[2:3], -1, 0
	s_cmp_eq_u32 s38, 2
	s_cselect_b64 s[0:1], -1, 0
	v_lshlrev_b32_e32 v194, 4, v162
	s_and_b64 s[0:1], s[26:27], s[0:1]
	v_mov_b32_e32 v154, 0
	v_cndmask_b32_e64 v0, 0, 1, s[0:1]
	v_lshlrev_b64 v[98:99], 2, v[164:165]
	v_cmp_ne_u32_e64 s[6:7], 1, v0
	s_andn2_b64 vcc, exec, s[0:1]
	v_lshl_add_u64 v[178:179], s[12:13], 0, v[98:99]
	v_lshl_add_u64 v[176:177], s[28:29], 0, v[98:99]
	v_mov_b32_e32 v155, v154
	v_mov_b32_e32 v156, v154
	v_mov_b32_e32 v157, v154
	v_mov_b32_e32 v142, v154
	v_mov_b32_e32 v143, v154
	v_mov_b32_e32 v144, v154
	v_mov_b32_e32 v145, v154
	v_mov_b32_e32 v126, v154
	v_mov_b32_e32 v127, v154
	v_mov_b32_e32 v128, v154
	v_mov_b32_e32 v129, v154
	v_mov_b32_e32 v98, v154
	v_mov_b32_e32 v99, v154
	v_mov_b32_e32 v100, v154
	v_mov_b32_e32 v101, v154
	s_cbranch_vccnz .LBB0_2519
	v_and_b32_e32 v0, 0x7cf0, v194
	v_lshlrev_b32_e32 v0, 2, v0
	v_lshl_add_u64 v[98:99], v[178:179], 0, v[0:1]
	v_lshl_add_u64 v[102:103], v[176:177], 0, v[0:1]
	global_load_dwordx4 v[154:157], v[98:99], off
	global_load_dwordx4 v[142:145], v[98:99], off offset:1024
	global_load_dwordx4 v[158:161], v[102:103], off
	global_load_dwordx4 v[138:141], v[102:103], off offset:1024
	global_load_dwordx4 v[126:129], v[98:99], off offset:2048
	s_nop 0
	global_load_dwordx4 v[98:101], v[98:99], off offset:3072
	s_nop 0
	global_load_dwordx4 v[122:125], v[102:103], off offset:2048
	s_nop 0
	global_load_dwordx4 v[102:105], v[102:103], off offset:3072
; DI u32x4 pk8(f32x4 a, f32x4 b) { u32x4 o; o.x = pk2(a.x, a.y); o.y = pk2(a.z, a.w); o.z = pk2(b.x, b.y); o.w = pk2(b.z, b.w); return o; }
;     DI void operator()(const AccT& acc, const Unit& u, int wr, int wc, int fr, int fq) const {
;     ...
; #pragma unroll
;             for (int m = 0; m < 4; ++m) {
;                 const size_t row = row0 + ai * 128 + m * 16;
;                 float sq = 0.f;
; #pragma unroll
;                 for (int bj = 0; bj < 2; ++bj) {
;                     const int col = u.pn * 256 + bj * 128 + wc * 32 + fq * 8;
;                     f32x4 a = acc[ai][bj][m][0] * rs[ai][m], b = acc[ai][bj][m][1] * rs[ai][m];
;                     if (u.pn == 2 && bj == 1) {
;                         if (wc == 0) { rope4(a, b, cs[m], sn[m]); *(u32x4*)(kr + row * 32 + fq * 8) = pk8(a, b); }
;                     } else {
;                         sq += (a.x * a.x + a.y * a.y) + (a.z * a.z + a.w * a.w) + (b.x * b.x + b.y * b.y) + (b.z * b.z + b.w * b.w);
;                         *(u32x4*)(cqkv + row * 768 + col) = pk8(a, b);
;                     }
;                 }
.LBB0_2519:
	s_waitcnt lgkmcnt(0)
	v_pk_add_f32 v[164:165], v[170:171], v[184:185]
	v_mov_b32_e32 v0, 0x358637bd
	v_pk_fma_f32 v[184:185], v[164:165], s[88:89], v[0:1] op_sel_hi:[1,0,0]
	v_lshlrev_b32_e32 v164, 3, v196
	v_mul_f32_e32 v0, 0x4b800000, v185
	v_cmp_gt_f32_e32 vcc, s42, v185
	s_lshl_b32 s0, s38, 8
	s_or_b32 s0, s0, s65
	v_cndmask_b32_e32 v0, v185, v0, vcc
	v_rsq_f32_e32 v0, v0
	s_movk_i32 s4, 0x600
	v_add_u32_e32 v170, s0, v164
	v_ashrrev_i32_e32 v171, 31, v170
	v_mul_f32_e32 v165, 0x45800000, v0
	v_cndmask_b32_e32 v196, v0, v165, vcc
	v_pk_mul_f32 v[152:153], v[152:153], v[196:197] op_sel_hi:[1,0]
	v_pk_mul_f32 v[150:151], v[150:151], v[196:197] op_sel_hi:[1,0]
	v_mul_f32_e32 v165, v153, v153
	v_mul_f32_e32 v0, v151, v151
	v_pk_mul_f32 v[146:147], v[146:147], v[196:197] op_sel_hi:[1,0]
	v_fmac_f32_e32 v0, v150, v150
	v_fmac_f32_e32 v165, v152, v152
	v_add_f32_e32 v0, v0, v165
	v_mul_f32_e32 v165, v147, v147
	v_pk_mul_f32 v[148:149], v[148:149], v[196:197] op_sel_hi:[1,0]
	v_fmac_f32_e32 v165, v146, v146
	v_cvt_pk_bf16_f32 v150, v150, v151
	v_cvt_pk_bf16_f32 v151, v152, v153
	v_cvt_pk_bf16_f32 v152, v146, v147
	v_mov_b64_e32 v[146:147], s[20:21]
	v_add_f32_e32 v0, v165, v0
	v_mul_f32_e32 v165, v149, v149
	v_mad_u64_u32 v[146:147], s[0:1], v162, s4, v[146:147]
	v_fmac_f32_e32 v165, v148, v148
	v_cvt_pk_bf16_f32 v153, v148, v149
	v_mov_b32_e32 v148, v147
	v_mad_u64_u32 v[148:149], s[0:1], v163, s4, v[148:149]
	v_mov_b32_e32 v147, v148
	v_lshl_add_u64 v[148:149], v[170:171], 1, v[146:147]
	global_store_dwordx4 v[148:149], v[150:153], off
	v_cmp_gt_f32_e64 s[8:9], s42, v184
	v_add_f32_e32 v0, v165, v0
	v_cndmask_b32_e64 v150, 0, 1, s[2:3]
	v_pk_mul_f32 v[136:137], v[136:137], v[196:197] op_sel_hi:[1,0]
	v_pk_mul_f32 v[134:135], v[134:135], v[196:197] op_sel_hi:[1,0]
	v_pk_mul_f32 v[132:133], v[132:133], v[196:197] op_sel_hi:[1,0]
	v_pk_mul_f32 v[130:131], v[130:131], v[196:197] op_sel_hi:[1,0]
	v_cmp_ne_u32_e64 s[0:1], 1, v150
	s_andn2_b64 vcc, exec, s[2:3]
	s_mov_b64 s[2:3], -1
	s_cbranch_vccnz .LBB0_2521
	v_pk_mul_f32 v[150:151], v[136:137], v[136:137]
	v_pk_mul_f32 v[152:153], v[134:135], v[134:135]
	s_mov_b64 s[2:3], 0
	v_pk_mov_b32 v[196:197], v[152:153], v[150:151] op_sel:[1,0]
	v_mov_b32_e32 v153, v151
	v_pk_add_f32 v[150:151], v[196:197], v[152:153]
	v_pk_mul_f32 v[152:153], v[132:133], v[132:133]
	v_pk_mul_f32 v[196:197], v[130:131], v[130:131]
	v_mov_b32_e32 v198, v152
	v_mov_b32_e32 v199, v196
	v_mov_b32_e32 v196, v153
	v_pk_add_f32 v[152:153], v[198:199], v[196:197]
	v_add_f32_e32 v150, v150, v151
	v_add_f32_e32 v150, v153, v150
	v_add_f32_e32 v150, v152, v150
	v_add_f32_e32 v150, v0, v150
	v_cvt_pk_bf16_f32 v196, v134, v135
	v_cvt_pk_bf16_f32 v197, v136, v137
	v_cvt_pk_bf16_f32 v198, v130, v131
	v_cvt_pk_bf16_f32 v199, v132, v133
	global_store_dwordx4 v[148:149], v[196:199], off offset:256
.LBB0_2521:
	v_cndmask_b32_e64 v148, 0, 1, s[26:27]
	v_ashrrev_i32_e32 v165, 31, v164
	s_andn2_b64 vcc, exec, s[2:3]
	v_cmp_ne_u32_e64 s[4:5], 1, v148
	s_cbranch_vccnz .LBB0_2525
	s_and_b64 vcc, exec, s[4:5]
	s_cbranch_vccnz .LBB0_2524
	s_waitcnt vmcnt(0)
	v_pk_mul_f32 v[150:151], v[134:135], v[158:159] op_sel:[1,0] op_sel_hi:[0,0]
	v_pk_fma_f32 v[152:153], v[134:135], v[154:155], v[150:151] neg_lo:[0,0,1] neg_hi:[0,0,1]
	v_pk_fma_f32 v[134:135], v[134:135], v[154:155], v[150:151] op_sel_hi:[1,0,1]
	v_pk_mul_f32 v[150:151], v[136:137], v[158:159] op_sel:[1,1] op_sel_hi:[0,1]
	v_cvt_pk_bf16_f32 v134, v152, v135
	v_pk_fma_f32 v[152:153], v[136:137], v[154:155], v[150:151] op_sel:[0,1,0] neg_lo:[0,0,1] neg_hi:[0,0,1]
	v_pk_fma_f32 v[136:137], v[136:137], v[154:155], v[150:151] op_sel:[0,1,0]
	v_lshlrev_b64 v[148:149], 6, v[162:163]
	v_cvt_pk_bf16_f32 v135, v152, v137
	v_pk_mul_f32 v[136:137], v[130:131], v[160:161] op_sel:[1,0] op_sel_hi:[0,0]
	v_pk_fma_f32 v[150:151], v[130:131], v[156:157], v[136:137] neg_lo:[0,0,1] neg_hi:[0,0,1]
	v_pk_fma_f32 v[130:131], v[130:131], v[156:157], v[136:137] op_sel_hi:[1,0,1]
	s_nop 0
	v_mov_b32_e32 v130, v161
	v_cvt_pk_bf16_f32 v136, v150, v131
	v_pk_mul_f32 v[130:131], v[132:133], v[130:131] op_sel:[1,0] op_sel_hi:[0,0]
	v_mov_b32_e32 v150, v157
	v_pk_fma_f32 v[152:153], v[132:133], v[150:151], v[130:131] op_sel_hi:[1,0,1] neg_lo:[0,0,1] neg_hi:[0,0,1]
	v_pk_fma_f32 v[130:131], v[132:133], v[150:151], v[130:131] op_sel_hi:[1,0,1]
	s_nop 0
	v_cvt_pk_bf16_f32 v137, v152, v131
	v_lshl_add_u64 v[130:131], s[22:23], 0, v[148:149]
	v_lshl_add_u64 v[130:131], v[164:165], 1, v[130:131]
	global_store_dwordx4 v[130:131], v[134:137], off

; DI u32x4 pk8(f32x4 a, f32x4 b) { u32x4 o; o.x = pk2(a.x, a.y); o.y = pk2(a.z, a.w); o.z = pk2(b.x, b.y); o.w = pk2(b.z, b.w); return o; }
;     DI void operator()(const AccT& acc, const Unit& u, int wr, int wc, int fr, int fq) const {
;     ...
;             for (int m = 0; m < 4; ++m) {
;                 const size_t row = row0 + ai * 128 + m * 16;
;                 float sq = 0.f;
; #pragma unroll
;                 for (int bj = 0; bj < 2; ++bj) {
;                     const int col = u.pn * 256 + bj * 128 + wc * 32 + fq * 8;
;                     f32x4 a = acc[ai][bj][m][0] * rs[ai][m], b = acc[ai][bj][m][1] * rs[ai][m];
;                     if (u.pn == 2 && bj == 1) {
;                         if (wc == 0) { rope4(a, b, cs[m], sn[m]); *(u32x4*)(kr + row * 32 + fq * 8) = pk8(a, b); }
;                     } else {
;                         sq += (a.x * a.x + a.y * a.y) + (a.z * a.z + a.w * a.w) + (b.x * b.x + b.y * b.y) + (b.z * b.z + b.w * b.w);
;                         *(u32x4*)(cqkv + row * 768 + col) = pk8(a, b);
;                     }
;                 }
;                 sq += __shfl_xor(sq, 16); sq += __shfl_xor(sq, 32);
;                 if (fq == 0) ssq[row * 12 + u.pn * 4 + wc] = sq;
.LBB0_2525:
	ds_bpermute_b32 v0, v192, v150
	s_lshl_b32 s92, s38, 2
	v_cmp_gt_u32_e64 s[2:3], 16, v195
	s_ashr_i32 s93, s92, 31
	s_waitcnt lgkmcnt(0)
	v_add_f32_e32 v0, v150, v0
	ds_bpermute_b32 v130, v193, v0
	s_and_saveexec_b64 s[38:39], s[2:3]
	s_cbranch_execz .LBB0_2527
	s_waitcnt lgkmcnt(0)
	v_add_f32_e32 v134, v0, v130
	v_mad_u64_u32 v[130:131], s[70:71], v162, 48, s[18:19]
	v_mov_b32_e32 v0, v131
	v_mad_u64_u32 v[132:133], s[70:71], v163, 48, v[0:1]
	v_mov_b32_e32 v131, v132
	v_lshl_add_u64 v[130:131], s[92:93], 2, v[130:131]
	s_lshl_b32 s96, s61, 2
	v_lshl_add_u64 v[130:131], v[130:131], 0, s[96:97]
	global_store_dword v[130:131], v134, off
.LBB0_2527:
	s_or_b64 exec, exec, s[38:39]
	v_mul_f32_e32 v0, 0x4b800000, v184
	v_cndmask_b32_e64 v0, v184, v0, s[8:9]
	v_rsq_f32_e32 v0, v0
	s_and_b64 vcc, exec, s[0:1]
	s_waitcnt lgkmcnt(0)
	v_mul_f32_e32 v130, 0x45800000, v0
	v_cndmask_b32_e64 v130, v0, v130, s[8:9]
	v_pk_mul_f32 v[120:121], v[120:121], v[130:131] op_sel_hi:[1,0]
	v_pk_mul_f32 v[118:119], v[118:119], v[130:131] op_sel_hi:[1,0]
	v_pk_mul_f32 v[116:117], v[116:117], v[130:131] op_sel_hi:[1,0]
	v_pk_mul_f32 v[114:115], v[114:115], v[130:131] op_sel_hi:[1,0]
	v_mul_f32_e32 v0, v119, v119
	v_mul_f32_e32 v131, v121, v121
	v_fmac_f32_e32 v0, v118, v118
	v_fmac_f32_e32 v131, v120, v120
	v_add_f32_e32 v0, v0, v131
	v_mul_f32_e32 v131, v115, v115
	v_fmac_f32_e32 v131, v114, v114
	v_add_f32_e32 v0, v131, v0
	v_mul_f32_e32 v131, v117, v117
	s_mov_b64 s[8:9], 0x6000
	v_fmac_f32_e32 v131, v116, v116
	v_cvt_pk_bf16_f32 v118, v118, v119
	v_cvt_pk_bf16_f32 v119, v120, v121
	v_cvt_pk_bf16_f32 v120, v114, v115
	v_lshl_add_u64 v[114:115], v[146:147], 0, s[8:9]
	v_add_f32_e32 v0, v131, v0
	v_cvt_pk_bf16_f32 v121, v116, v117
	v_lshl_add_u64 v[116:117], v[170:171], 1, v[114:115]
	v_pk_mul_f32 v[112:113], v[112:113], v[130:131] op_sel_hi:[1,0]
	v_pk_mul_f32 v[110:111], v[110:111], v[130:131] op_sel_hi:[1,0]
	v_pk_mul_f32 v[108:109], v[108:109], v[130:131] op_sel_hi:[1,0]
	v_pk_mul_f32 v[106:107], v[106:107], v[130:131] op_sel_hi:[1,0]
	s_mov_b64 s[8:9], -1
	global_store_dwordx4 v[116:117], v[118:121], off
	s_cbranch_vccnz .LBB0_2529
	s_nop 0
	v_pk_mul_f32 v[118:119], v[112:113], v[112:113]
	v_pk_mul_f32 v[120:121], v[110:111], v[110:111]
	s_mov_b64 s[8:9], 0
	v_pk_mov_b32 v[130:131], v[120:121], v[118:119] op_sel:[1,0]
	v_mov_b32_e32 v121, v119
	v_pk_add_f32 v[118:119], v[130:131], v[120:121]
	v_pk_mul_f32 v[120:121], v[108:109], v[108:109]
	v_pk_mul_f32 v[130:131], v[106:107], v[106:107]
	v_mov_b32_e32 v132, v120
	v_mov_b32_e32 v133, v130
	v_mov_b32_e32 v130, v121
	v_pk_add_f32 v[120:121], v[132:133], v[130:131]
	v_add_f32_e32 v118, v118, v119
	v_add_f32_e32 v118, v121, v118
	v_add_f32_e32 v118, v120, v118
	v_add_f32_e32 v118, v0, v118
	v_cvt_pk_bf16_f32 v130, v110, v111
	v_cvt_pk_bf16_f32 v131, v112, v113
	v_cvt_pk_bf16_f32 v132, v106, v107
	v_cvt_pk_bf16_f32 v133, v108, v109
	global_store_dwordx4 v[116:117], v[130:133], off offset:256
.LBB0_2529:
	v_or_b32_e32 v116, 16, v162
	s_andn2_b64 vcc, exec, s[8:9]
	v_mov_b32_e32 v117, v163
	s_cbranch_vccnz .LBB0_2533
	s_and_b64 vcc, exec, s[4:5]
	s_cbranch_vccnz .LBB0_2532
	s_waitcnt vmcnt(0)
	v_pk_mul_f32 v[120:121], v[110:111], v[138:139] op_sel:[1,0] op_sel_hi:[0,0]
	v_pk_fma_f32 v[130:131], v[110:111], v[142:143], v[120:121] neg_lo:[0,0,1] neg_hi:[0,0,1]
	v_pk_fma_f32 v[110:111], v[110:111], v[142:143], v[120:121] op_sel_hi:[1,0,1]
	v_pk_mul_f32 v[120:121], v[112:113], v[138:139] op_sel:[1,1] op_sel_hi:[0,1]
	v_cvt_pk_bf16_f32 v110, v130, v111
	v_mov_b32_e32 v130, v143
	v_pk_fma_f32 v[132:133], v[112:113], v[130:131], v[120:121] op_sel_hi:[1,0,1] neg_lo:[0,0,1] neg_hi:[0,0,1]
	v_pk_fma_f32 v[112:113], v[112:113], v[130:131], v[120:121] op_sel_hi:[1,0,1]
	v_lshlrev_b64 v[118:119], 6, v[116:117]
	v_cvt_pk_bf16_f32 v111, v132, v113
	v_pk_mul_f32 v[112:113], v[106:107], v[140:141] op_sel:[1,0] op_sel_hi:[0,0]
	v_pk_fma_f32 v[120:121], v[106:107], v[144:145], v[112:113] neg_lo:[0,0,1] neg_hi:[0,0,1]
	v_pk_fma_f32 v[106:107], v[106:107], v[144:145], v[112:113] op_sel_hi:[1,0,1]
	s_nop 0
	v_mov_b32_e32 v106, v141
	v_cvt_pk_bf16_f32 v112, v120, v107
	v_pk_mul_f32 v[106:107], v[108:109], v[106:107] op_sel:[1,0] op_sel_hi:[0,0]
	v_mov_b32_e32 v120, v145
	v_pk_fma_f32 v[130:131], v[108:109], v[120:121], v[106:107] op_sel_hi:[1,0,1] neg_lo:[0,0,1] neg_hi:[0,0,1]
	v_pk_fma_f32 v[106:107], v[108:109], v[120:121], v[106:107] op_sel_hi:[1,0,1]
	s_nop 0
	v_cvt_pk_bf16_f32 v113, v130, v107
	v_lshl_add_u64 v[106:107], s[22:23], 0, v[118:119]
	v_lshl_add_u64 v[106:107], v[164:165], 1, v[106:107]
	global_store_dwordx4 v[106:107], v[110:113], off

; DI u32x4 pk8(f32x4 a, f32x4 b) { u32x4 o; o.x = pk2(a.x, a.y); o.y = pk2(a.z, a.w); o.z = pk2(b.x, b.y); o.w = pk2(b.z, b.w); return o; }
;     DI void operator()(const AccT& acc, const Unit& u, int wr, int wc, int fr, int fq) const {
;     ...
;             for (int m = 0; m < 4; ++m) {
;                 const size_t row = row0 + ai * 128 + m * 16;
;                 float sq = 0.f;
; #pragma unroll
;                 for (int bj = 0; bj < 2; ++bj) {
;                     const int col = u.pn * 256 + bj * 128 + wc * 32 + fq * 8;
;                     f32x4 a = acc[ai][bj][m][0] * rs[ai][m], b = acc[ai][bj][m][1] * rs[ai][m];
;                     if (u.pn == 2 && bj == 1) {
;                         if (wc == 0) { rope4(a, b, cs[m], sn[m]); *(u32x4*)(kr + row * 32 + fq * 8) = pk8(a, b); }
;                     } else {
;                         sq += (a.x * a.x + a.y * a.y) + (a.z * a.z + a.w * a.w) + (b.x * b.x + b.y * b.y) + (b.z * b.z + b.w * b.w);
;                         *(u32x4*)(cqkv + row * 768 + col) = pk8(a, b);
;                     }
;                 }
;                 sq += __shfl_xor(sq, 16); sq += __shfl_xor(sq, 32);
;                 if (fq == 0) ssq[row * 12 + u.pn * 4 + wc] = sq;
.LBB0_2533:
	ds_bpermute_b32 v0, v192, v118
	s_waitcnt lgkmcnt(0)
	v_add_f32_e32 v0, v118, v0
	ds_bpermute_b32 v106, v193, v0
	s_and_saveexec_b64 s[8:9], s[2:3]
	s_cbranch_execz .LBB0_2535
	s_waitcnt lgkmcnt(0)
	v_add_f32_e32 v110, v0, v106
	v_mad_u64_u32 v[106:107], s[38:39], v116, 48, s[18:19]
	v_mov_b32_e32 v0, v107
	v_mad_u64_u32 v[108:109], s[38:39], v117, 48, v[0:1]
	v_mov_b32_e32 v107, v108
	v_lshl_add_u64 v[106:107], s[92:93], 2, v[106:107]
	s_lshl_b32 s96, s61, 2
	v_lshl_add_u64 v[106:107], v[106:107], 0, s[96:97]
	global_store_dword v[106:107], v110, off
.LBB0_2535:
	s_or_b64 exec, exec, s[8:9]
	s_waitcnt lgkmcnt(0)
	v_pk_add_f32 v[106:107], v[180:181], v[182:183]
	v_mov_b32_e32 v0, 0x358637bd
	v_pk_fma_f32 v[106:107], v[106:107], s[88:89], v[0:1] op_sel_hi:[1,0,0]
	s_mov_b64 s[38:39], 0x6000
	v_mul_f32_e32 v0, 0x4b800000, v107
	v_cmp_gt_f32_e32 vcc, s42, v107
	v_cmp_gt_f32_e64 s[8:9], s42, v106
	s_nop 0
	v_cndmask_b32_e32 v0, v107, v0, vcc
	v_rsq_f32_e32 v0, v0
	s_nop 0
	v_mul_f32_e32 v107, 0x45800000, v0
	v_cndmask_b32_e32 v108, v0, v107, vcc
	v_pk_mul_f32 v[96:97], v[96:97], v[108:109] op_sel_hi:[1,0]
	v_pk_mul_f32 v[94:95], v[94:95], v[108:109] op_sel_hi:[1,0]
	v_mul_f32_e32 v107, v97, v97
	v_mul_f32_e32 v0, v95, v95
	v_pk_mul_f32 v[90:91], v[90:91], v[108:109] op_sel_hi:[1,0]
	v_fmac_f32_e32 v0, v94, v94
	v_fmac_f32_e32 v107, v96, v96
	v_add_f32_e32 v0, v0, v107
	v_mul_f32_e32 v107, v91, v91
	v_pk_mul_f32 v[92:93], v[92:93], v[108:109] op_sel_hi:[1,0]
	v_fmac_f32_e32 v107, v90, v90
	v_add_f32_e32 v0, v107, v0
	v_mul_f32_e32 v107, v93, v93
	v_fmac_f32_e32 v107, v92, v92
	v_cvt_pk_bf16_f32 v94, v94, v95
	v_cvt_pk_bf16_f32 v95, v96, v97
	v_cvt_pk_bf16_f32 v96, v90, v91
	v_lshl_add_u64 v[90:91], v[114:115], 0, s[38:39]
	v_add_f32_e32 v0, v107, v0
	v_cvt_pk_bf16_f32 v97, v92, v93
	v_lshl_add_u64 v[92:93], v[170:171], 1, v[90:91]
	v_pk_mul_f32 v[88:89], v[88:89], v[108:109] op_sel_hi:[1,0]
	v_pk_mul_f32 v[86:87], v[86:87], v[108:109] op_sel_hi:[1,0]
	v_pk_mul_f32 v[84:85], v[84:85], v[108:109] op_sel_hi:[1,0]
	v_pk_mul_f32 v[82:83], v[82:83], v[108:109] op_sel_hi:[1,0]
	s_and_b64 vcc, exec, s[0:1]
	s_mov_b64 s[38:39], -1
	global_store_dwordx4 v[92:93], v[94:97], off
	s_cbranch_vccnz .LBB0_2537
	s_nop 0
	v_pk_mul_f32 v[94:95], v[88:89], v[88:89]
	v_pk_mul_f32 v[96:97], v[86:87], v[86:87]
	s_mov_b64 s[38:39], 0
	v_pk_mov_b32 v[108:109], v[96:97], v[94:95] op_sel:[1,0]
	v_mov_b32_e32 v97, v95
	v_pk_add_f32 v[94:95], v[108:109], v[96:97]
	v_pk_mul_f32 v[96:97], v[84:85], v[84:85]
	v_pk_mul_f32 v[108:109], v[82:83], v[82:83]
	v_mov_b32_e32 v110, v96
	v_mov_b32_e32 v111, v108
	v_mov_b32_e32 v108, v97
	v_pk_add_f32 v[96:97], v[110:111], v[108:109]
	v_add_f32_e32 v94, v94, v95
	v_add_f32_e32 v94, v97, v94
	v_add_f32_e32 v94, v96, v94
	v_add_f32_e32 v94, v0, v94
	v_cvt_pk_bf16_f32 v108, v86, v87
	v_cvt_pk_bf16_f32 v109, v88, v89
	v_cvt_pk_bf16_f32 v110, v82, v83
	v_cvt_pk_bf16_f32 v111, v84, v85
	global_store_dwordx4 v[92:93], v[108:111], off offset:256
.LBB0_2537:
	v_or_b32_e32 v92, 32, v162
	s_andn2_b64 vcc, exec, s[38:39]
	v_mov_b32_e32 v93, v163
	s_cbranch_vccnz .LBB0_2541
	s_and_b64 vcc, exec, s[4:5]
	s_cbranch_vccnz .LBB0_2540
	s_waitcnt vmcnt(0)
	v_pk_mul_f32 v[96:97], v[86:87], v[122:123] op_sel:[1,0] op_sel_hi:[0,0]
	v_pk_fma_f32 v[108:109], v[86:87], v[126:127], v[96:97] neg_lo:[0,0,1] neg_hi:[0,0,1]
	v_pk_fma_f32 v[86:87], v[86:87], v[126:127], v[96:97] op_sel_hi:[1,0,1]
	v_pk_mul_f32 v[96:97], v[88:89], v[122:123] op_sel:[1,1] op_sel_hi:[0,1]
	v_cvt_pk_bf16_f32 v86, v108, v87
	v_mov_b32_e32 v108, v127
	v_pk_fma_f32 v[110:111], v[88:89], v[108:109], v[96:97] op_sel_hi:[1,0,1] neg_lo:[0,0,1] neg_hi:[0,0,1]
	v_pk_fma_f32 v[88:89], v[88:89], v[108:109], v[96:97] op_sel_hi:[1,0,1]
	v_lshlrev_b64 v[94:95], 6, v[92:93]
	v_cvt_pk_bf16_f32 v87, v110, v89
	v_pk_mul_f32 v[88:89], v[82:83], v[124:125] op_sel:[1,0] op_sel_hi:[0,0]
	v_pk_fma_f32 v[96:97], v[82:83], v[128:129], v[88:89] neg_lo:[0,0,1] neg_hi:[0,0,1]
	v_pk_fma_f32 v[82:83], v[82:83], v[128:129], v[88:89] op_sel_hi:[1,0,1]
	s_nop 0
	v_mov_b32_e32 v82, v125
	v_cvt_pk_bf16_f32 v88, v96, v83
	v_pk_mul_f32 v[82:83], v[84:85], v[82:83] op_sel:[1,0] op_sel_hi:[0,0]
	v_mov_b32_e32 v96, v129
	v_pk_fma_f32 v[108:109], v[84:85], v[96:97], v[82:83] op_sel_hi:[1,0,1] neg_lo:[0,0,1] neg_hi:[0,0,1]
	v_pk_fma_f32 v[82:83], v[84:85], v[96:97], v[82:83] op_sel_hi:[1,0,1]
	s_nop 0
	v_cvt_pk_bf16_f32 v89, v108, v83
	v_lshl_add_u64 v[82:83], s[22:23], 0, v[94:95]
	v_lshl_add_u64 v[82:83], v[164:165], 1, v[82:83]
	global_store_dwordx4 v[82:83], v[86:89], off

; DI u32x4 pk8(f32x4 a, f32x4 b) { u32x4 o; o.x = pk2(a.x, a.y); o.y = pk2(a.z, a.w); o.z = pk2(b.x, b.y); o.w = pk2(b.z, b.w); return o; }
;     DI void operator()(const AccT& acc, const Unit& u, int wr, int wc, int fr, int fq) const {
;     ...
;             for (int m = 0; m < 4; ++m) {
;                 const size_t row = row0 + ai * 128 + m * 16;
;                 float sq = 0.f;
; #pragma unroll
;                 for (int bj = 0; bj < 2; ++bj) {
;                     const int col = u.pn * 256 + bj * 128 + wc * 32 + fq * 8;
;                     f32x4 a = acc[ai][bj][m][0] * rs[ai][m], b = acc[ai][bj][m][1] * rs[ai][m];
;                     if (u.pn == 2 && bj == 1) {
;                         if (wc == 0) { rope4(a, b, cs[m], sn[m]); *(u32x4*)(kr + row * 32 + fq * 8) = pk8(a, b); }
;                     } else {
;                         sq += (a.x * a.x + a.y * a.y) + (a.z * a.z + a.w * a.w) + (b.x * b.x + b.y * b.y) + (b.z * b.z + b.w * b.w);
;                         *(u32x4*)(cqkv + row * 768 + col) = pk8(a, b);
;                     }
;                 }
;                 sq += __shfl_xor(sq, 16); sq += __shfl_xor(sq, 32);
;                 if (fq == 0) ssq[row * 12 + u.pn * 4 + wc] = sq;
.LBB0_2541:
	ds_bpermute_b32 v0, v192, v94
	s_waitcnt lgkmcnt(0)
	v_add_f32_e32 v0, v94, v0
	ds_bpermute_b32 v82, v193, v0
	s_and_saveexec_b64 s[38:39], s[2:3]
	s_cbranch_execz .LBB0_2543
	s_waitcnt lgkmcnt(0)
	v_add_f32_e32 v86, v0, v82
	v_mad_u64_u32 v[82:83], s[70:71], v92, 48, s[18:19]
	v_mov_b32_e32 v0, v83
	v_mad_u64_u32 v[84:85], s[70:71], v93, 48, v[0:1]
	v_mov_b32_e32 v83, v84
	v_lshl_add_u64 v[82:83], s[92:93], 2, v[82:83]
	s_lshl_b32 s96, s61, 2
	v_lshl_add_u64 v[82:83], v[82:83], 0, s[96:97]
	global_store_dword v[82:83], v86, off
.LBB0_2543:
	s_or_b64 exec, exec, s[38:39]
	v_mul_f32_e32 v0, 0x4b800000, v106
	v_cndmask_b32_e64 v0, v106, v0, s[8:9]
	v_rsq_f32_e32 v0, v0
	s_and_b64 vcc, exec, s[0:1]
	s_waitcnt lgkmcnt(0)
	v_mul_f32_e32 v82, 0x45800000, v0
	v_cndmask_b32_e64 v82, v0, v82, s[8:9]
	v_pk_mul_f32 v[80:81], v[80:81], v[82:83] op_sel_hi:[1,0]
	v_pk_mul_f32 v[78:79], v[78:79], v[82:83] op_sel_hi:[1,0]
	v_pk_mul_f32 v[76:77], v[76:77], v[82:83] op_sel_hi:[1,0]
	v_pk_mul_f32 v[74:75], v[74:75], v[82:83] op_sel_hi:[1,0]
	v_mul_f32_e32 v0, v79, v79
	v_mul_f32_e32 v83, v81, v81
	v_fmac_f32_e32 v0, v78, v78
	v_fmac_f32_e32 v83, v80, v80
	v_add_f32_e32 v0, v0, v83
	v_mul_f32_e32 v83, v75, v75
	v_fmac_f32_e32 v83, v74, v74
	v_add_f32_e32 v0, v83, v0
	v_mul_f32_e32 v83, v77, v77
	s_mov_b64 s[8:9], 0x6000
	v_fmac_f32_e32 v83, v76, v76
	v_cvt_pk_bf16_f32 v78, v78, v79
	v_cvt_pk_bf16_f32 v79, v80, v81
	v_cvt_pk_bf16_f32 v80, v74, v75
	v_lshl_add_u64 v[74:75], v[90:91], 0, s[8:9]
	v_add_f32_e32 v0, v83, v0
	v_cvt_pk_bf16_f32 v81, v76, v77
	v_lshl_add_u64 v[76:77], v[170:171], 1, v[74:75]
	v_pk_mul_f32 v[72:73], v[72:73], v[82:83] op_sel_hi:[1,0]
	v_pk_mul_f32 v[70:71], v[70:71], v[82:83] op_sel_hi:[1,0]
	v_pk_mul_f32 v[68:69], v[68:69], v[82:83] op_sel_hi:[1,0]
	v_pk_mul_f32 v[66:67], v[66:67], v[82:83] op_sel_hi:[1,0]
	s_mov_b64 s[8:9], -1
	global_store_dwordx4 v[76:77], v[78:81], off
	s_cbranch_vccnz .LBB0_2545
	s_nop 0
	v_pk_mul_f32 v[78:79], v[72:73], v[72:73]
	v_pk_mul_f32 v[80:81], v[70:71], v[70:71]
	s_mov_b64 s[8:9], 0
	v_pk_mov_b32 v[82:83], v[80:81], v[78:79] op_sel:[1,0]
	v_mov_b32_e32 v81, v79
	v_pk_add_f32 v[78:79], v[82:83], v[80:81]
	v_pk_mul_f32 v[80:81], v[68:69], v[68:69]
	v_pk_mul_f32 v[82:83], v[66:67], v[66:67]
	v_mov_b32_e32 v84, v80
	v_mov_b32_e32 v85, v82
	v_mov_b32_e32 v82, v81
	v_pk_add_f32 v[80:81], v[84:85], v[82:83]
	v_add_f32_e32 v78, v78, v79
	v_add_f32_e32 v78, v81, v78
	v_add_f32_e32 v78, v80, v78
	v_add_f32_e32 v78, v0, v78
	v_cvt_pk_bf16_f32 v80, v70, v71
	v_cvt_pk_bf16_f32 v81, v72, v73
	v_cvt_pk_bf16_f32 v82, v66, v67
	v_cvt_pk_bf16_f32 v83, v68, v69
	global_store_dwordx4 v[76:77], v[80:83], off offset:256
.LBB0_2545:
	v_or_b32_e32 v76, 48, v162
	s_andn2_b64 vcc, exec, s[8:9]
	v_mov_b32_e32 v77, v163
	s_cbranch_vccnz .LBB0_2549
	s_and_b64 vcc, exec, s[4:5]
	s_cbranch_vccnz .LBB0_2548
	s_waitcnt vmcnt(0)
	v_pk_mul_f32 v[80:81], v[70:71], v[102:103] op_sel:[1,0] op_sel_hi:[0,0]
	v_pk_fma_f32 v[82:83], v[70:71], v[98:99], v[80:81] neg_lo:[0,0,1] neg_hi:[0,0,1]
	v_pk_fma_f32 v[70:71], v[70:71], v[98:99], v[80:81] op_sel_hi:[1,0,1]
	v_pk_mul_f32 v[80:81], v[72:73], v[102:103] op_sel:[1,1] op_sel_hi:[0,1]
	v_cvt_pk_bf16_f32 v70, v82, v71
	v_mov_b32_e32 v82, v99
	v_pk_fma_f32 v[84:85], v[72:73], v[82:83], v[80:81] op_sel_hi:[1,0,1] neg_lo:[0,0,1] neg_hi:[0,0,1]
	v_pk_fma_f32 v[72:73], v[72:73], v[82:83], v[80:81] op_sel_hi:[1,0,1]
	v_lshlrev_b64 v[78:79], 6, v[76:77]
	v_cvt_pk_bf16_f32 v71, v84, v73
	v_pk_mul_f32 v[72:73], v[66:67], v[104:105] op_sel:[1,0] op_sel_hi:[0,0]
	v_pk_fma_f32 v[80:81], v[66:67], v[100:101], v[72:73] neg_lo:[0,0,1] neg_hi:[0,0,1]
	v_pk_fma_f32 v[66:67], v[66:67], v[100:101], v[72:73] op_sel_hi:[1,0,1]
	s_nop 0
	v_mov_b32_e32 v66, v105
	v_cvt_pk_bf16_f32 v72, v80, v67
	v_pk_mul_f32 v[66:67], v[68:69], v[66:67] op_sel:[1,0] op_sel_hi:[0,0]
	v_mov_b32_e32 v80, v101
	v_pk_fma_f32 v[82:83], v[68:69], v[80:81], v[66:67] op_sel_hi:[1,0,1] neg_lo:[0,0,1] neg_hi:[0,0,1]
	v_pk_fma_f32 v[66:67], v[68:69], v[80:81], v[66:67] op_sel_hi:[1,0,1]
	s_nop 0
	v_cvt_pk_bf16_f32 v73, v82, v67
	v_lshl_add_u64 v[66:67], s[22:23], 0, v[78:79]
	v_lshl_add_u64 v[66:67], v[164:165], 1, v[66:67]
	global_store_dwordx4 v[66:67], v[70:73], off

; DI u32x4 pk8(f32x4 a, f32x4 b) { u32x4 o; o.x = pk2(a.x, a.y); o.y = pk2(a.z, a.w); o.z = pk2(b.x, b.y); o.w = pk2(b.z, b.w); return o; }
; #define EPI_SCHED() __builtin_amdgcn_sched_barrier(0)
;     DI void operator()(const AccT& acc, const Unit& u, int wr, int wc, int fr, int fq) const {
;     ...
;         for (int ai = 0; ai < 2; ++ai) {
;             EPI_SCHED();
;             f32x4 cs[4], sn[4];
;             if (do_rope) {
; #pragma unroll
;                 for (int m = 0; m < 4; ++m) { const int s = (int)((row0 + ai * 128 + m * 16) & 2047); cs[m] = *(const f32x4*)(rope + s * 16 + 4 * fq); sn[m] = *(const f32x4*)(rope + 32768 + s * 16 + 4 * fq); }
;             }
; #pragma unroll
;             for (int m = 0; m < 4; ++m) {
;                 const size_t row = row0 + ai * 128 + m * 16;
;                 float sq = 0.f;
; #pragma unroll
;                 for (int bj = 0; bj < 2; ++bj) {
;                     const int col = u.pn * 256 + bj * 128 + wc * 32 + fq * 8;
;                     f32x4 a = acc[ai][bj][m][0] * rs[ai][m], b = acc[ai][bj][m][1] * rs[ai][m];
;                     if (u.pn == 2 && bj == 1) {
;                         if (wc == 0) { rope4(a, b, cs[m], sn[m]); *(u32x4*)(kr + row * 32 + fq * 8) = pk8(a, b); }
;                     } else {
;                         sq += (a.x * a.x + a.y * a.y) + (a.z * a.z + a.w * a.w) + (b.x * b.x + b.y * b.y) + (b.z * b.z + b.w * b.w);
;                         *(u32x4*)(cqkv + row * 768 + col) = pk8(a, b);
;                     }
;                 }
;                 sq += __shfl_xor(sq, 16); sq += __shfl_xor(sq, 32);
;                 if (fq == 0) ssq[row * 12 + u.pn * 4 + wc] = sq;
.LBB0_2549:
	ds_bpermute_b32 v0, v192, v78
	s_waitcnt lgkmcnt(0)
	v_add_f32_e32 v0, v78, v0
	ds_bpermute_b32 v66, v193, v0
	s_and_saveexec_b64 s[8:9], s[2:3]
	s_cbranch_execz .LBB0_2551
	s_waitcnt lgkmcnt(0)
	v_add_f32_e32 v70, v0, v66
	v_mad_u64_u32 v[66:67], s[38:39], v76, 48, s[18:19]
	v_mov_b32_e32 v0, v67
	v_mad_u64_u32 v[68:69], s[38:39], v77, 48, v[0:1]
	v_mov_b32_e32 v67, v68
	v_lshl_add_u64 v[66:67], s[92:93], 2, v[66:67]
	s_lshl_b32 s96, s61, 2
	v_lshl_add_u64 v[66:67], v[66:67], 0, s[96:97]
	global_store_dword v[66:67], v70, off
.LBB0_2551:
	s_or_b64 exec, exec, s[8:9]
	s_and_b64 vcc, exec, s[6:7]
	s_cbranch_vccnz .LBB0_2553
	v_add_u32_e32 v0, 0x800, v194
	v_and_b32_e32 v0, 0x7cf0, v0
	v_lshlrev_b32_e32 v0, 2, v0
	s_waitcnt lgkmcnt(0)
	v_lshl_add_u64 v[66:67], v[178:179], 0, v[0:1]
	v_lshl_add_u64 v[68:69], v[176:177], 0, v[0:1]
	s_waitcnt vmcnt(0)
	global_load_dwordx4 v[154:157], v[66:67], off
	global_load_dwordx4 v[142:145], v[66:67], off offset:1024
	global_load_dwordx4 v[158:161], v[68:69], off
	global_load_dwordx4 v[138:141], v[68:69], off offset:1024
	global_load_dwordx4 v[126:129], v[66:67], off offset:2048
	global_load_dwordx4 v[98:101], v[66:67], off offset:3072
	global_load_dwordx4 v[122:125], v[68:69], off offset:2048
	global_load_dwordx4 v[102:105], v[68:69], off offset:3072
.LBB0_2553:
	s_waitcnt lgkmcnt(0)
	v_pk_add_f32 v[66:67], v[172:173], v[174:175]
	v_mov_b32_e32 v0, 0x358637bd
	v_pk_fma_f32 v[66:67], v[66:67], s[88:89], v[0:1] op_sel_hi:[1,0,0]
	s_mov_b64 s[8:9], 0x1e000
	v_mul_f32_e32 v0, 0x4b800000, v67
	v_cmp_gt_f32_e32 vcc, s42, v67
	v_cmp_gt_f32_e64 s[6:7], s42, v66
	s_nop 0
	v_cndmask_b32_e32 v0, v67, v0, vcc
	v_rsq_f32_e32 v0, v0
	s_nop 0
	v_mul_f32_e32 v67, 0x45800000, v0
	v_cndmask_b32_e32 v68, v0, v67, vcc
	v_pk_mul_f32 v[64:65], v[64:65], v[68:69] op_sel_hi:[1,0]
	v_pk_mul_f32 v[62:63], v[62:63], v[68:69] op_sel_hi:[1,0]
	v_mul_f32_e32 v67, v65, v65
	v_mul_f32_e32 v0, v63, v63
	v_pk_mul_f32 v[58:59], v[58:59], v[68:69] op_sel_hi:[1,0]
	v_fmac_f32_e32 v0, v62, v62
	v_fmac_f32_e32 v67, v64, v64
	v_add_f32_e32 v0, v0, v67
	v_mul_f32_e32 v67, v59, v59
	v_pk_mul_f32 v[60:61], v[60:61], v[68:69] op_sel_hi:[1,0]
	v_fmac_f32_e32 v67, v58, v58
	v_add_f32_e32 v0, v67, v0
	v_mul_f32_e32 v67, v61, v61
	v_fmac_f32_e32 v67, v60, v60
	v_cvt_pk_bf16_f32 v62, v62, v63
	v_cvt_pk_bf16_f32 v63, v64, v65
	v_cvt_pk_bf16_f32 v64, v58, v59
	v_lshl_add_u64 v[58:59], v[74:75], 0, s[8:9]
	v_add_f32_e32 v0, v67, v0
	v_cvt_pk_bf16_f32 v65, v60, v61
	v_lshl_add_u64 v[60:61], v[170:171], 1, v[58:59]
	v_pk_mul_f32 v[56:57], v[56:57], v[68:69] op_sel_hi:[1,0]
	v_pk_mul_f32 v[54:55], v[54:55], v[68:69] op_sel_hi:[1,0]
	v_pk_mul_f32 v[52:53], v[52:53], v[68:69] op_sel_hi:[1,0]
	v_pk_mul_f32 v[50:51], v[50:51], v[68:69] op_sel_hi:[1,0]
	s_and_b64 vcc, exec, s[0:1]
	s_mov_b64 s[8:9], -1
	global_store_dwordx4 v[60:61], v[62:65], off
	s_cbranch_vccnz .LBB0_2555
	s_nop 0
	v_pk_mul_f32 v[62:63], v[56:57], v[56:57]
	v_pk_mul_f32 v[64:65], v[54:55], v[54:55]
	s_mov_b64 s[8:9], 0
	v_pk_mov_b32 v[68:69], v[64:65], v[62:63] op_sel:[1,0]
	v_mov_b32_e32 v65, v63
	v_pk_add_f32 v[62:63], v[68:69], v[64:65]
	v_pk_mul_f32 v[64:65], v[52:53], v[52:53]
	v_pk_mul_f32 v[68:69], v[50:51], v[50:51]
	v_mov_b32_e32 v70, v64
	v_mov_b32_e32 v71, v68
	v_mov_b32_e32 v68, v65
	v_pk_add_f32 v[64:65], v[70:71], v[68:69]
	v_add_f32_e32 v62, v62, v63
	v_add_f32_e32 v62, v65, v62
	v_add_f32_e32 v62, v64, v62
	v_add_f32_e32 v62, v0, v62
	v_cvt_pk_bf16_f32 v68, v54, v55
	v_cvt_pk_bf16_f32 v69, v56, v57
	v_cvt_pk_bf16_f32 v70, v50, v51
	v_cvt_pk_bf16_f32 v71, v52, v53
	global_store_dwordx4 v[60:61], v[68:71], off offset:256
.LBB0_2555:
	s_andn2_b64 vcc, exec, s[8:9]
	v_lshl_add_u64 v[60:61], v[162:163], 0, s[58:59]
	s_cbranch_vccnz .LBB0_2559
	s_and_b64 vcc, exec, s[4:5]
	s_cbranch_vccnz .LBB0_2558
	s_waitcnt vmcnt(0)
	v_pk_mul_f32 v[64:65], v[54:55], v[158:159] op_sel:[1,0] op_sel_hi:[0,0]
	v_pk_fma_f32 v[68:69], v[54:55], v[154:155], v[64:65] neg_lo:[0,0,1] neg_hi:[0,0,1]
	v_pk_fma_f32 v[54:55], v[54:55], v[154:155], v[64:65] op_sel_hi:[1,0,1]
	v_pk_mul_f32 v[64:65], v[56:57], v[158:159] op_sel:[1,1] op_sel_hi:[0,1]
	v_cvt_pk_bf16_f32 v54, v68, v55
	v_mov_b32_e32 v68, v155
	v_mov_b32_e32 v70, v155
	v_pk_fma_f32 v[68:69], v[56:57], v[68:69], v[64:65] neg_lo:[0,0,1] neg_hi:[0,0,1]
	v_pk_fma_f32 v[56:57], v[56:57], v[70:71], v[64:65] op_sel_hi:[1,0,1]
	v_lshlrev_b64 v[62:63], 6, v[60:61]
	v_cvt_pk_bf16_f32 v55, v68, v57
	v_pk_mul_f32 v[56:57], v[50:51], v[160:161] op_sel:[1,0] op_sel_hi:[0,0]
	v_pk_fma_f32 v[64:65], v[50:51], v[156:157], v[56:57] neg_lo:[0,0,1] neg_hi:[0,0,1]
	v_pk_fma_f32 v[50:51], v[50:51], v[156:157], v[56:57] op_sel_hi:[1,0,1]
	v_mov_b32_e32 v68, v157
	v_mov_b32_e32 v50, v161
	v_cvt_pk_bf16_f32 v56, v64, v51
	v_pk_mul_f32 v[50:51], v[52:53], v[50:51] op_sel:[1,0] op_sel_hi:[0,0]
	v_mov_b32_e32 v64, v157
	v_pk_fma_f32 v[64:65], v[52:53], v[64:65], v[50:51] neg_lo:[0,0,1] neg_hi:[0,0,1]
	v_pk_fma_f32 v[50:51], v[52:53], v[68:69], v[50:51] op_sel_hi:[1,0,1]
	s_nop 0
	v_cvt_pk_bf16_f32 v57, v64, v51
	v_lshl_add_u64 v[50:51], s[22:23], 0, v[62:63]
	v_lshl_add_u64 v[50:51], v[164:165], 1, v[50:51]
	global_store_dwordx4 v[50:51], v[54:57], off

; DI u32x4 pk8(f32x4 a, f32x4 b) { u32x4 o; o.x = pk2(a.x, a.y); o.y = pk2(a.z, a.w); o.z = pk2(b.x, b.y); o.w = pk2(b.z, b.w); return o; }
;     DI void operator()(const AccT& acc, const Unit& u, int wr, int wc, int fr, int fq) const {
;     ...
;             for (int m = 0; m < 4; ++m) {
;                 const size_t row = row0 + ai * 128 + m * 16;
;                 float sq = 0.f;
; #pragma unroll
;                 for (int bj = 0; bj < 2; ++bj) {
;                     const int col = u.pn * 256 + bj * 128 + wc * 32 + fq * 8;
;                     f32x4 a = acc[ai][bj][m][0] * rs[ai][m], b = acc[ai][bj][m][1] * rs[ai][m];
;                     if (u.pn == 2 && bj == 1) {
;                         if (wc == 0) { rope4(a, b, cs[m], sn[m]); *(u32x4*)(kr + row * 32 + fq * 8) = pk8(a, b); }
;                     } else {
;                         sq += (a.x * a.x + a.y * a.y) + (a.z * a.z + a.w * a.w) + (b.x * b.x + b.y * b.y) + (b.z * b.z + b.w * b.w);
;                         *(u32x4*)(cqkv + row * 768 + col) = pk8(a, b);
;                     }
;                 }
;                 sq += __shfl_xor(sq, 16); sq += __shfl_xor(sq, 32);
;                 if (fq == 0) ssq[row * 12 + u.pn * 4 + wc] = sq;
.LBB0_2559:
	ds_bpermute_b32 v0, v192, v62
	s_waitcnt lgkmcnt(0)
	v_add_f32_e32 v0, v62, v0
	ds_bpermute_b32 v50, v193, v0
	s_and_saveexec_b64 s[8:9], s[2:3]
	s_cbranch_execz .LBB0_2561
	s_waitcnt lgkmcnt(0)
	v_add_f32_e32 v54, v0, v50
	v_mad_u64_u32 v[50:51], s[38:39], v60, 48, s[18:19]
	v_mov_b32_e32 v0, v51
	v_mad_u64_u32 v[52:53], s[38:39], v61, 48, v[0:1]
	v_mov_b32_e32 v51, v52
	v_lshl_add_u64 v[50:51], s[92:93], 2, v[50:51]
	s_lshl_b32 s96, s61, 2
	v_lshl_add_u64 v[50:51], v[50:51], 0, s[96:97]
	global_store_dword v[50:51], v54, off
.LBB0_2561:
	s_or_b64 exec, exec, s[8:9]
	v_mul_f32_e32 v0, 0x4b800000, v66
	v_cndmask_b32_e64 v0, v66, v0, s[6:7]
	v_rsq_f32_e32 v0, v0
	s_and_b64 vcc, exec, s[0:1]
	s_waitcnt lgkmcnt(0)
	v_mul_f32_e32 v50, 0x45800000, v0
	v_cndmask_b32_e64 v50, v0, v50, s[6:7]
	v_pk_mul_f32 v[48:49], v[48:49], v[50:51] op_sel_hi:[1,0]
	v_pk_mul_f32 v[46:47], v[46:47], v[50:51] op_sel_hi:[1,0]
	v_pk_mul_f32 v[44:45], v[44:45], v[50:51] op_sel_hi:[1,0]
	v_pk_mul_f32 v[42:43], v[42:43], v[50:51] op_sel_hi:[1,0]
	v_mul_f32_e32 v0, v47, v47
	v_mul_f32_e32 v51, v49, v49
	v_fmac_f32_e32 v0, v46, v46
	v_fmac_f32_e32 v51, v48, v48
	v_add_f32_e32 v0, v0, v51
	v_mul_f32_e32 v51, v43, v43
	v_fmac_f32_e32 v51, v42, v42
	v_add_f32_e32 v0, v51, v0
	v_mul_f32_e32 v51, v45, v45
	s_mov_b64 s[6:7], 0x6000
	v_fmac_f32_e32 v51, v44, v44
	v_cvt_pk_bf16_f32 v46, v46, v47
	v_cvt_pk_bf16_f32 v47, v48, v49
	v_cvt_pk_bf16_f32 v48, v42, v43
	v_lshl_add_u64 v[42:43], v[58:59], 0, s[6:7]
	v_add_f32_e32 v0, v51, v0
	v_cvt_pk_bf16_f32 v49, v44, v45
	v_lshl_add_u64 v[44:45], v[170:171], 1, v[42:43]
	v_pk_mul_f32 v[40:41], v[40:41], v[50:51] op_sel_hi:[1,0]
	v_pk_mul_f32 v[38:39], v[38:39], v[50:51] op_sel_hi:[1,0]
	v_pk_mul_f32 v[36:37], v[36:37], v[50:51] op_sel_hi:[1,0]
	v_pk_mul_f32 v[34:35], v[34:35], v[50:51] op_sel_hi:[1,0]
	s_mov_b64 s[6:7], -1
	global_store_dwordx4 v[44:45], v[46:49], off
	s_cbranch_vccnz .LBB0_2563
	s_nop 0
	v_pk_mul_f32 v[46:47], v[40:41], v[40:41]
	v_pk_mul_f32 v[48:49], v[38:39], v[38:39]
	s_mov_b64 s[6:7], 0
	v_pk_mov_b32 v[50:51], v[48:49], v[46:47] op_sel:[1,0]
	v_mov_b32_e32 v49, v47
	v_pk_add_f32 v[46:47], v[50:51], v[48:49]
	v_pk_mul_f32 v[48:49], v[36:37], v[36:37]
	v_pk_mul_f32 v[50:51], v[34:35], v[34:35]
	v_mov_b32_e32 v52, v48
	v_mov_b32_e32 v53, v50
	v_mov_b32_e32 v50, v49
	v_pk_add_f32 v[48:49], v[52:53], v[50:51]
	v_add_f32_e32 v46, v46, v47
	v_add_f32_e32 v46, v49, v46
	v_add_f32_e32 v46, v48, v46
	v_add_f32_e32 v46, v0, v46
	v_cvt_pk_bf16_f32 v48, v38, v39
	v_cvt_pk_bf16_f32 v49, v40, v41
	v_cvt_pk_bf16_f32 v50, v34, v35
	v_cvt_pk_bf16_f32 v51, v36, v37
	global_store_dwordx4 v[44:45], v[48:51], off offset:256
.LBB0_2563:
	s_andn2_b64 vcc, exec, s[6:7]
	s_mov_b64 s[6:7], 0x90
	v_lshl_add_u64 v[44:45], v[162:163], 0, s[6:7]
	s_cbranch_vccnz .LBB0_2567
	s_and_b64 vcc, exec, s[4:5]
	s_cbranch_vccnz .LBB0_2566
	s_waitcnt vmcnt(0)
	v_pk_mul_f32 v[48:49], v[38:39], v[138:139] op_sel:[1,0] op_sel_hi:[0,0]
	v_pk_fma_f32 v[50:51], v[38:39], v[142:143], v[48:49] neg_lo:[0,0,1] neg_hi:[0,0,1]
	v_pk_fma_f32 v[38:39], v[38:39], v[142:143], v[48:49] op_sel_hi:[1,0,1]
	v_pk_mul_f32 v[48:49], v[40:41], v[138:139] op_sel:[1,1] op_sel_hi:[0,1]
	v_cvt_pk_bf16_f32 v38, v50, v39
	v_mov_b32_e32 v50, v143
	v_pk_fma_f32 v[52:53], v[40:41], v[50:51], v[48:49] op_sel_hi:[1,0,1] neg_lo:[0,0,1] neg_hi:[0,0,1]
	v_pk_fma_f32 v[40:41], v[40:41], v[50:51], v[48:49] op_sel_hi:[1,0,1]
	v_lshlrev_b64 v[46:47], 6, v[44:45]
	v_cvt_pk_bf16_f32 v39, v52, v41
	v_pk_mul_f32 v[40:41], v[34:35], v[140:141] op_sel:[1,0] op_sel_hi:[0,0]
	v_pk_fma_f32 v[48:49], v[34:35], v[144:145], v[40:41] neg_lo:[0,0,1] neg_hi:[0,0,1]
	v_pk_fma_f32 v[34:35], v[34:35], v[144:145], v[40:41] op_sel_hi:[1,0,1]
	s_nop 0
	v_mov_b32_e32 v34, v141
	v_cvt_pk_bf16_f32 v40, v48, v35
	v_pk_mul_f32 v[34:35], v[36:37], v[34:35] op_sel:[1,0] op_sel_hi:[0,0]
	v_mov_b32_e32 v48, v145
	v_pk_fma_f32 v[50:51], v[36:37], v[48:49], v[34:35] op_sel_hi:[1,0,1] neg_lo:[0,0,1] neg_hi:[0,0,1]
	v_pk_fma_f32 v[34:35], v[36:37], v[48:49], v[34:35] op_sel_hi:[1,0,1]
	s_nop 0
	v_cvt_pk_bf16_f32 v41, v50, v35
	v_lshl_add_u64 v[34:35], s[22:23], 0, v[46:47]
	v_lshl_add_u64 v[34:35], v[164:165], 1, v[34:35]
	global_store_dwordx4 v[34:35], v[38:41], off

; DI u32x4 pk8(f32x4 a, f32x4 b) { u32x4 o; o.x = pk2(a.x, a.y); o.y = pk2(a.z, a.w); o.z = pk2(b.x, b.y); o.w = pk2(b.z, b.w); return o; }
;     DI void operator()(const AccT& acc, const Unit& u, int wr, int wc, int fr, int fq) const {
;     ...
;             for (int m = 0; m < 4; ++m) {
;                 const size_t row = row0 + ai * 128 + m * 16;
;                 float sq = 0.f;
; #pragma unroll
;                 for (int bj = 0; bj < 2; ++bj) {
;                     const int col = u.pn * 256 + bj * 128 + wc * 32 + fq * 8;
;                     f32x4 a = acc[ai][bj][m][0] * rs[ai][m], b = acc[ai][bj][m][1] * rs[ai][m];
;                     if (u.pn == 2 && bj == 1) {
;                         if (wc == 0) { rope4(a, b, cs[m], sn[m]); *(u32x4*)(kr + row * 32 + fq * 8) = pk8(a, b); }
;                     } else {
;                         sq += (a.x * a.x + a.y * a.y) + (a.z * a.z + a.w * a.w) + (b.x * b.x + b.y * b.y) + (b.z * b.z + b.w * b.w);
;                         *(u32x4*)(cqkv + row * 768 + col) = pk8(a, b);
;                     }
;                 }
;                 sq += __shfl_xor(sq, 16); sq += __shfl_xor(sq, 32);
;                 if (fq == 0) ssq[row * 12 + u.pn * 4 + wc] = sq;
.LBB0_2567:
	ds_bpermute_b32 v0, v192, v46
	s_waitcnt lgkmcnt(0)
	v_add_f32_e32 v0, v46, v0
	ds_bpermute_b32 v34, v193, v0
	s_and_saveexec_b64 s[6:7], s[2:3]
	s_cbranch_execz .LBB0_2569
	s_waitcnt lgkmcnt(0)
	v_add_f32_e32 v38, v0, v34
	v_mad_u64_u32 v[34:35], s[8:9], v44, 48, s[18:19]
	v_mov_b32_e32 v0, v35
	v_mad_u64_u32 v[36:37], s[8:9], v45, 48, v[0:1]
	v_mov_b32_e32 v35, v36
	v_lshl_add_u64 v[34:35], s[92:93], 2, v[34:35]
	s_lshl_b32 s96, s61, 2
	v_lshl_add_u64 v[34:35], v[34:35], 0, s[96:97]
	global_store_dword v[34:35], v38, off
.LBB0_2569:
	s_or_b64 exec, exec, s[6:7]
	s_waitcnt lgkmcnt(0)
	v_pk_add_f32 v[34:35], v[166:167], v[168:169]
	v_mov_b32_e32 v0, 0x358637bd
	v_pk_fma_f32 v[34:35], v[34:35], s[88:89], v[0:1] op_sel_hi:[1,0,0]
	s_mov_b64 s[8:9], 0x6000
	v_mul_f32_e32 v0, 0x4b800000, v35
	v_cmp_gt_f32_e32 vcc, s42, v35
	v_cmp_gt_f32_e64 s[6:7], s42, v34
	s_nop 0
	v_cndmask_b32_e32 v0, v35, v0, vcc
	v_rsq_f32_e32 v0, v0
	s_nop 0
	v_mul_f32_e32 v35, 0x45800000, v0
	v_cndmask_b32_e32 v36, v0, v35, vcc
	v_pk_mul_f32 v[38:39], v[28:29], v[36:37] op_sel_hi:[1,0]
	v_pk_mul_f32 v[32:33], v[32:33], v[36:37] op_sel_hi:[1,0]
	v_pk_mul_f32 v[28:29], v[30:31], v[36:37] op_sel_hi:[1,0]
	v_mul_f32_e32 v30, v33, v33
	v_mul_f32_e32 v0, v29, v29
	v_pk_mul_f32 v[26:27], v[26:27], v[36:37] op_sel_hi:[1,0]
	v_fmac_f32_e32 v0, v28, v28
	v_fmac_f32_e32 v30, v32, v32
	v_add_f32_e32 v0, v0, v30
	v_mul_f32_e32 v30, v27, v27
	v_fmac_f32_e32 v30, v26, v26
	v_add_f32_e32 v0, v30, v0
	v_mul_f32_e32 v30, v39, v39
	v_fmac_f32_e32 v30, v38, v38
	v_add_f32_e32 v0, v30, v0
	v_cvt_pk_bf16_f32 v30, v26, v27
	v_lshl_add_u64 v[26:27], v[42:43], 0, s[8:9]
	v_cvt_pk_bf16_f32 v28, v28, v29
	v_cvt_pk_bf16_f32 v29, v32, v33
	v_cvt_pk_bf16_f32 v31, v38, v39
	v_lshl_add_u64 v[26:27], v[170:171], 1, v[26:27]
	v_pk_mul_f32 v[24:25], v[24:25], v[36:37] op_sel_hi:[1,0]
	v_pk_mul_f32 v[22:23], v[22:23], v[36:37] op_sel_hi:[1,0]
	v_pk_mul_f32 v[20:21], v[20:21], v[36:37] op_sel_hi:[1,0]
	v_pk_mul_f32 v[18:19], v[18:19], v[36:37] op_sel_hi:[1,0]
	s_and_b64 vcc, exec, s[0:1]
	s_mov_b64 s[8:9], -1
	global_store_dwordx4 v[26:27], v[28:31], off
	s_cbranch_vccnz .LBB0_2571
	s_nop 0
	v_pk_mul_f32 v[28:29], v[24:25], v[24:25]
	v_pk_mul_f32 v[30:31], v[22:23], v[22:23]
	v_cvt_pk_bf16_f32 v38, v18, v19
	v_pk_mov_b32 v[32:33], v[30:31], v[28:29] op_sel:[1,0]
	v_mov_b32_e32 v31, v29
	v_pk_add_f32 v[28:29], v[32:33], v[30:31]
	v_pk_mul_f32 v[30:31], v[20:21], v[20:21]
	v_pk_mul_f32 v[32:33], v[18:19], v[18:19]
	v_mov_b32_e32 v36, v30
	v_mov_b32_e32 v37, v32
	v_mov_b32_e32 v32, v31
	v_pk_add_f32 v[30:31], v[36:37], v[32:33]
	v_add_f32_e32 v28, v28, v29
	v_add_f32_e32 v28, v31, v28
	v_add_f32_e32 v28, v30, v28
	v_add_f32_e32 v30, v0, v28
	v_cvt_pk_bf16_f32 v36, v22, v23
	v_cvt_pk_bf16_f32 v37, v24, v25
	v_cvt_pk_bf16_f32 v39, v20, v21
	s_mov_b64 s[8:9], 0
	global_store_dwordx4 v[26:27], v[36:39], off offset:256
.LBB0_2571:
	s_andn2_b64 vcc, exec, s[8:9]
	s_mov_b64 s[8:9], 0xa0
	v_lshl_add_u64 v[28:29], v[162:163], 0, s[8:9]
	s_cbranch_vccnz .LBB0_2575
	s_and_b64 vcc, exec, s[4:5]
	s_cbranch_vccnz .LBB0_2574
	s_waitcnt vmcnt(0)
	v_pk_mul_f32 v[32:33], v[22:23], v[122:123] op_sel:[1,0] op_sel_hi:[0,0]
	v_pk_fma_f32 v[36:37], v[22:23], v[126:127], v[32:33] neg_lo:[0,0,1] neg_hi:[0,0,1]
	v_pk_fma_f32 v[22:23], v[22:23], v[126:127], v[32:33] op_sel_hi:[1,0,1]
	v_pk_mul_f32 v[32:33], v[24:25], v[122:123] op_sel:[1,1] op_sel_hi:[0,1]
	v_cvt_pk_bf16_f32 v22, v36, v23
	v_mov_b32_e32 v36, v127
	v_pk_fma_f32 v[38:39], v[24:25], v[36:37], v[32:33] op_sel_hi:[1,0,1] neg_lo:[0,0,1] neg_hi:[0,0,1]
	v_pk_fma_f32 v[24:25], v[24:25], v[36:37], v[32:33] op_sel_hi:[1,0,1]
	v_lshlrev_b64 v[30:31], 6, v[28:29]
	v_cvt_pk_bf16_f32 v23, v38, v25
	v_pk_mul_f32 v[24:25], v[18:19], v[124:125] op_sel:[1,0] op_sel_hi:[0,0]
	v_pk_fma_f32 v[32:33], v[18:19], v[128:129], v[24:25] neg_lo:[0,0,1] neg_hi:[0,0,1]
	v_pk_fma_f32 v[18:19], v[18:19], v[128:129], v[24:25] op_sel_hi:[1,0,1]
	s_nop 0
	v_mov_b32_e32 v18, v125
	v_cvt_pk_bf16_f32 v24, v32, v19
	v_pk_mul_f32 v[18:19], v[20:21], v[18:19] op_sel:[1,0] op_sel_hi:[0,0]
	v_mov_b32_e32 v32, v129
	v_pk_fma_f32 v[36:37], v[20:21], v[32:33], v[18:19] op_sel_hi:[1,0,1] neg_lo:[0,0,1] neg_hi:[0,0,1]
	v_pk_fma_f32 v[18:19], v[20:21], v[32:33], v[18:19] op_sel_hi:[1,0,1]
	s_nop 0
	v_cvt_pk_bf16_f32 v25, v36, v19
	v_lshl_add_u64 v[18:19], s[22:23], 0, v[30:31]
	v_lshl_add_u64 v[18:19], v[164:165], 1, v[18:19]
	global_store_dwordx4 v[18:19], v[22:25], off

; DI u32x4 pk8(f32x4 a, f32x4 b) { u32x4 o; o.x = pk2(a.x, a.y); o.y = pk2(a.z, a.w); o.z = pk2(b.x, b.y); o.w = pk2(b.z, b.w); return o; }
;     DI void operator()(const AccT& acc, const Unit& u, int wr, int wc, int fr, int fq) const {
;     ...
;             for (int m = 0; m < 4; ++m) {
;                 const size_t row = row0 + ai * 128 + m * 16;
;                 float sq = 0.f;
; #pragma unroll
;                 for (int bj = 0; bj < 2; ++bj) {
;                     const int col = u.pn * 256 + bj * 128 + wc * 32 + fq * 8;
;                     f32x4 a = acc[ai][bj][m][0] * rs[ai][m], b = acc[ai][bj][m][1] * rs[ai][m];
;                     if (u.pn == 2 && bj == 1) {
;                         if (wc == 0) { rope4(a, b, cs[m], sn[m]); *(u32x4*)(kr + row * 32 + fq * 8) = pk8(a, b); }
;                     } else {
;                         sq += (a.x * a.x + a.y * a.y) + (a.z * a.z + a.w * a.w) + (b.x * b.x + b.y * b.y) + (b.z * b.z + b.w * b.w);
;                         *(u32x4*)(cqkv + row * 768 + col) = pk8(a, b);
;                     }
;                 }
;                 sq += __shfl_xor(sq, 16); sq += __shfl_xor(sq, 32);
;                 if (fq == 0) ssq[row * 12 + u.pn * 4 + wc] = sq;
.LBB0_2575:
	ds_bpermute_b32 v0, v192, v30
	s_waitcnt lgkmcnt(0)
	v_add_f32_e32 v0, v30, v0
	ds_bpermute_b32 v18, v193, v0
	s_and_saveexec_b64 s[8:9], s[2:3]
	s_cbranch_execz .LBB0_2577
	s_waitcnt lgkmcnt(0)
	v_add_f32_e32 v22, v0, v18
	v_mad_u64_u32 v[18:19], s[38:39], v28, 48, s[18:19]
	v_mov_b32_e32 v0, v19
	v_mad_u64_u32 v[20:21], s[38:39], v29, 48, v[0:1]
	v_mov_b32_e32 v19, v20
	v_lshl_add_u64 v[18:19], s[92:93], 2, v[18:19]
	s_lshl_b32 s96, s61, 2
	v_lshl_add_u64 v[18:19], v[18:19], 0, s[96:97]
	global_store_dword v[18:19], v22, off
.LBB0_2577:
	s_or_b64 exec, exec, s[8:9]
	v_mul_f32_e32 v0, 0x4b800000, v34
	v_cndmask_b32_e64 v0, v34, v0, s[6:7]
	v_rsq_f32_e32 v0, v0
	s_waitcnt lgkmcnt(0)
	v_mul_f32_e32 v18, 0x45800000, v0
	v_cndmask_b32_e64 v18, v0, v18, s[6:7]
	v_pk_mul_f32 v[20:21], v[12:13], v[18:19] op_sel_hi:[1,0]
	v_pk_mul_f32 v[12:13], v[10:11], v[18:19] op_sel_hi:[1,0]
	v_pk_mul_f32 v[16:17], v[16:17], v[18:19] op_sel_hi:[1,0]
	v_pk_mul_f32 v[10:11], v[14:15], v[18:19] op_sel_hi:[1,0]
	v_mul_f32_e32 v14, v17, v17
	v_mul_f32_e32 v0, v11, v11
	v_fmac_f32_e32 v0, v10, v10
	v_fmac_f32_e32 v14, v16, v16
	v_add_f32_e32 v0, v0, v14
	v_mul_f32_e32 v14, v13, v13
	v_fmac_f32_e32 v14, v12, v12
	v_add_f32_e32 v0, v14, v0
	v_mul_f32_e32 v14, v21, v21
	v_fmac_f32_e32 v14, v20, v20
	s_movk_i32 s6, 0x6000
	v_add_f32_e32 v0, v14, v0
	v_add_co_u32_e32 v14, vcc, s6, v26
	v_cvt_pk_bf16_f32 v10, v10, v11
	s_nop 0
	v_addc_co_u32_e32 v15, vcc, 0, v27, vcc
	v_cvt_pk_bf16_f32 v11, v16, v17
	v_cvt_pk_bf16_f32 v12, v12, v13
	v_cvt_pk_bf16_f32 v13, v20, v21
	v_pk_mul_f32 v[8:9], v[8:9], v[18:19] op_sel_hi:[1,0]
	v_pk_mul_f32 v[6:7], v[6:7], v[18:19] op_sel_hi:[1,0]
	v_pk_mul_f32 v[4:5], v[4:5], v[18:19] op_sel_hi:[1,0]
	v_pk_mul_f32 v[2:3], v[2:3], v[18:19] op_sel_hi:[1,0]
	s_and_b64 vcc, exec, s[0:1]
	s_mov_b64 s[0:1], -1
	global_store_dwordx4 v[14:15], v[10:13], off
	s_cbranch_vccnz .LBB0_2579
	s_nop 0
	v_pk_mul_f32 v[12:13], v[8:9], v[8:9]
	v_pk_mul_f32 v[14:15], v[6:7], v[6:7]
	s_mov_b64 s[0:1], 0x6000
	v_pk_mov_b32 v[16:17], v[14:15], v[12:13] op_sel:[1,0]
	v_mov_b32_e32 v15, v13
	v_pk_add_f32 v[12:13], v[16:17], v[14:15]
	v_pk_mul_f32 v[14:15], v[4:5], v[4:5]
	v_pk_mul_f32 v[16:17], v[2:3], v[2:3]
	v_mov_b32_e32 v18, v14
	v_mov_b32_e32 v19, v16
	v_mov_b32_e32 v16, v15
	v_pk_add_f32 v[14:15], v[18:19], v[16:17]
	v_add_f32_e32 v12, v12, v13
	v_add_f32_e32 v12, v15, v12
	v_add_f32_e32 v12, v14, v12
	v_lshl_add_u64 v[10:11], v[26:27], 0, s[0:1]
	v_add_f32_e32 v12, v0, v12
	v_cvt_pk_bf16_f32 v14, v6, v7
	v_cvt_pk_bf16_f32 v15, v8, v9
	v_cvt_pk_bf16_f32 v16, v2, v3
	v_cvt_pk_bf16_f32 v17, v4, v5
	s_mov_b64 s[0:1], 0
	global_store_dwordx4 v[10:11], v[14:17], off offset:256
.LBB0_2579:
	s_andn2_b64 vcc, exec, s[0:1]
	s_mov_b64 s[0:1], 0xb0
	v_lshl_add_u64 v[10:11], v[162:163], 0, s[0:1]
	s_cbranch_vccnz .LBB0_2583
	s_and_b64 vcc, exec, s[4:5]
	s_cbranch_vccnz .LBB0_2582
	s_waitcnt vmcnt(0)
	v_pk_mul_f32 v[14:15], v[6:7], v[102:103] op_sel:[1,0] op_sel_hi:[0,0]
	v_pk_fma_f32 v[16:17], v[6:7], v[98:99], v[14:15] neg_lo:[0,0,1] neg_hi:[0,0,1]
	v_pk_fma_f32 v[6:7], v[6:7], v[98:99], v[14:15] op_sel_hi:[1,0,1]
	v_pk_mul_f32 v[14:15], v[8:9], v[102:103] op_sel:[1,1] op_sel_hi:[0,1]
	v_cvt_pk_bf16_f32 v6, v16, v7
	v_mov_b32_e32 v16, v99
	v_pk_fma_f32 v[18:19], v[8:9], v[16:17], v[14:15] op_sel_hi:[1,0,1] neg_lo:[0,0,1] neg_hi:[0,0,1]
	v_pk_fma_f32 v[8:9], v[8:9], v[16:17], v[14:15] op_sel_hi:[1,0,1]
	v_lshlrev_b64 v[12:13], 6, v[10:11]
	v_cvt_pk_bf16_f32 v7, v18, v9
	v_pk_mul_f32 v[8:9], v[2:3], v[104:105] op_sel:[1,0] op_sel_hi:[0,0]
	v_pk_fma_f32 v[14:15], v[2:3], v[100:101], v[8:9] neg_lo:[0,0,1] neg_hi:[0,0,1]
	v_pk_fma_f32 v[2:3], v[2:3], v[100:101], v[8:9] op_sel_hi:[1,0,1]
	s_nop 0
	v_mov_b32_e32 v2, v105
	v_cvt_pk_bf16_f32 v8, v14, v3
	v_pk_mul_f32 v[2:3], v[4:5], v[2:3] op_sel:[1,0] op_sel_hi:[0,0]
	v_mov_b32_e32 v14, v101
	v_pk_fma_f32 v[16:17], v[4:5], v[14:15], v[2:3] op_sel_hi:[1,0,1] neg_lo:[0,0,1] neg_hi:[0,0,1]
	v_pk_fma_f32 v[2:3], v[4:5], v[14:15], v[2:3] op_sel_hi:[1,0,1]
	s_nop 0
	v_cvt_pk_bf16_f32 v9, v16, v3
	v_lshl_add_u64 v[2:3], s[22:23], 0, v[12:13]
	v_lshl_add_u64 v[2:3], v[164:165], 1, v[2:3]
	global_store_dwordx4 v[2:3], v[6:9], off

;     DI void operator()(const AccT& acc, const Unit& u, int wr, int wc, int fr, int fq) const {
;     ...
;                 sq += __shfl_xor(sq, 16); sq += __shfl_xor(sq, 32);
;                 if (fq == 0) ssq[row * 12 + u.pn * 4 + wc] = sq;
.LBB0_2583:
	ds_bpermute_b32 v0, v192, v12
	s_waitcnt lgkmcnt(0)
	v_add_f32_e32 v0, v12, v0
	ds_bpermute_b32 v2, v193, v0
	s_and_saveexec_b64 s[0:1], s[2:3]
	s_cbranch_execz .LBB0_2585
	s_waitcnt lgkmcnt(0)
	v_add_f32_e32 v6, v0, v2
	v_mad_u64_u32 v[2:3], s[2:3], v10, 48, s[18:19]
	v_mov_b32_e32 v0, v3
	v_mad_u64_u32 v[4:5], s[2:3], v11, 48, v[0:1]
	v_mov_b32_e32 v3, v4
	v_lshl_add_u64 v[2:3], s[92:93], 2, v[2:3]
	s_lshl_b32 s96, s61, 2
	v_lshl_add_u64 v[2:3], v[2:3], 0, s[96:97]
	global_store_dword v[2:3], v6, off

; DI unsigned xb_ld(unsigned* p)              { return __hip_atomic_load(p, __ATOMIC_RELAXED, __HIP_MEMORY_SCOPE_AGENT); }
; DI void xcd_barrier_complete(unsigned* bar, unsigned x, unsigned& nloc, unsigned& nx) {
;     ...
;     for (;;) {
;         sum = 0u; cnt = 0u; mine = 0u;
; #pragma unroll
;         for (unsigned j = 0; j < 16; ++j) { const unsigned c = xb_ld(&bar[XB_XCNT(j)]); sum += c; cnt += (c > 0u) ? 1u : 0u; mine = (j == x) ? c : mine; }
;         if (sum == G) break;
;         __builtin_amdgcn_s_sleep(1);
;         if ((++sp & 255u) == 0u) { if (xb_ld(&bar[XB_TMO])) break; if (sp > XB_SPIN_CAP) { atomicAdd(&bar[XB_TMO], 1u); break; } }
;     }
.LBB0_2595:
	v_mov_b64_e32 v[2:3], s[2:3]
	s_waitcnt lgkmcnt(0)
	global_load_dword v0, v[2:3], off sc1
	v_mov_b64_e32 v[2:3], s[4:5]
	global_load_dword v2, v[2:3], off sc1
	v_mov_b64_e32 v[4:5], s[6:7]
	global_load_dword v3, v[4:5], off sc1
	v_mov_b64_e32 v[4:5], s[8:9]
	global_load_dword v4, v[4:5], off sc1
	s_or_b64 s[54:55], s[54:55], exec
	s_or_b64 s[56:57], s[56:57], exec
	s_waitcnt vmcnt(0) lgkmcnt(0)
	v_add_u32_e32 v6, v2, v0
	v_add_u32_e32 v6, v6, v3
	v_add_u32_e32 v8, v6, v4
	v_mov_b64_e32 v[6:7], s[12:13]
	global_load_dword v5, v[6:7], off sc1
	v_mov_b64_e32 v[6:7], s[14:15]
	global_load_dword v6, v[6:7], off sc1
	s_waitcnt vmcnt(0) lgkmcnt(0)
	v_add_u32_e32 v8, v8, v5
	v_add_u32_e32 v10, v8, v6
	v_mov_b64_e32 v[8:9], s[16:17]
	global_load_dword v7, v[8:9], off sc1
	v_mov_b64_e32 v[8:9], s[18:19]
	global_load_dword v8, v[8:9], off sc1
	s_waitcnt vmcnt(0) lgkmcnt(0)
	v_add_u32_e32 v10, v10, v7
	v_add_u32_e32 v12, v10, v8
	v_mov_b64_e32 v[10:11], s[20:21]
	global_load_dword v9, v[10:11], off sc1
	v_mov_b64_e32 v[10:11], s[22:23]
	global_load_dword v10, v[10:11], off sc1
	s_waitcnt vmcnt(0) lgkmcnt(0)
	v_add_u32_e32 v12, v12, v9
	v_add_u32_e32 v14, v12, v10
	v_mov_b64_e32 v[12:13], s[24:25]
	global_load_dword v11, v[12:13], off sc1
	v_mov_b64_e32 v[12:13], s[26:27]
	global_load_dword v12, v[12:13], off sc1
	s_waitcnt vmcnt(0) lgkmcnt(0)
	v_add_u32_e32 v14, v14, v11
	v_add_u32_e32 v16, v14, v12
	v_mov_b64_e32 v[14:15], s[28:29]
	global_load_dword v13, v[14:15], off sc1
	v_mov_b64_e32 v[14:15], s[30:31]
	global_load_dword v14, v[14:15], off sc1
	s_waitcnt vmcnt(0) lgkmcnt(0)
	v_add_u32_e32 v16, v16, v13
	v_add_u32_e32 v18, v16, v14
	v_mov_b64_e32 v[16:17], s[48:49]
	global_load_dword v15, v[16:17], off sc1
	v_mov_b64_e32 v[16:17], s[50:51]
	global_load_dword v16, v[16:17], off sc1
	s_waitcnt vmcnt(0) lgkmcnt(0)
	v_add_u32_e32 v18, v18, v15
	v_add_u32_e32 v17, v18, v16
	v_cmp_ne_u32_e32 vcc, s33, v17
	s_and_saveexec_b64 s[84:85], vcc
	s_cbranch_execz .LBB0_2594
	s_and_b32 s46, s69, 0xff
	s_mov_b64 s[60:61], -1
	s_cmp_eq_u32 s46, 0
	s_mov_b64 s[64:65], -1
	s_mov_b64 s[90:91], -1
	s_sleep 1
	s_cbranch_scc1 .LBB0_2598
	s_and_saveexec_b64 s[46:47], s[64:65]
	s_cbranch_execz .LBB0_2593
	s_branch .LBB0_2601
.LBB0_2598:
	v_mov_b64_e32 v[18:19], s[0:1]
	global_load_dword v17, v[18:19], off sc1
	s_mov_b64 s[64:65], 0
	s_waitcnt vmcnt(0) lgkmcnt(0)
	v_cmp_eq_u32_e32 vcc, 0, v17
	s_and_saveexec_b64 s[46:47], vcc
	s_cmp_lt_u32 s69, 0x40001
	s_cselect_b64 s[64:65], -1, 0
	s_xor_b64 s[90:91], exec, -1
	s_and_b64 s[64:65], s[64:65], exec
	s_or_b64 exec, exec, s[46:47]
	s_and_saveexec_b64 s[46:47], s[64:65]
	s_cbranch_execz .LBB0_2593

; DI unsigned xb_ld(unsigned* p)              { return __hip_atomic_load(p, __ATOMIC_RELAXED, __HIP_MEMORY_SCOPE_AGENT); }
; DI unsigned xb_add(unsigned* p, unsigned v) { return __hip_atomic_fetch_add(p, v, __ATOMIC_RELAXED, __HIP_MEMORY_SCOPE_AGENT); }
; #define XB_SPIN(cond, bar) do { unsigned _sp = 0; while (cond) { __builtin_amdgcn_s_sleep(1); \
;     if ((++_sp & 255u) == 0u) { if (xb_ld(&(bar)[XB_TMO])) break; if (_sp > XB_SPIN_CAP) { atomicAdd(&(bar)[XB_TMO], 1u); break; } } } } while (0)
; DI void xcd_barrier(int wv, unsigned* bar, volatile LAS unsigned* st) {
;     ...
;         const unsigned old = xb_add(&bar[XB_XSUB(x)], 1u);
;         const unsigned gen = old / nloc;
;         if (old + 1u == (gen + 1u) * nloc) {
;             __builtin_amdgcn_fence(__ATOMIC_RELEASE, "agent");
;             asm volatile("s_waitcnt vmcnt(0)" ::: "memory");
;             const unsigned og = xb_add(&bar[XB_TOP], 1u);
;             const unsigned tg = og / nx;
;             if (og + 1u == (tg + 1u) * nx) xb_add(&bar[XB_TOPGEN], 1u);
;             else XB_SPIN(xb_ld(&bar[XB_TOPGEN]) == tg, bar);
;             __builtin_amdgcn_fence(__ATOMIC_ACQUIRE, "agent");
;             xb_add(&bar[XB_XGEN(x)], 1u);
;             asm volatile("s_waitcnt vmcnt(0)" ::: "memory");
;         } else {
;             XB_SPIN(xb_ld(&bar[XB_XGEN(x)]) == gen, bar);
.LBB0_2605:
	s_lshl_b32 s0, s67, 8
	s_add_u32 s0, s36, s0
	s_addc_u32 s1, s37, 0
	v_mov_b32_e32 v3, s0
	v_add_co_u32_e32 v4, vcc, 0xc1000, v3
	v_mov_b32_e32 v3, s1
	s_nop 0
	v_addc_co_u32_e32 v5, vcc, 0, v3, vcc
	v_mov_b32_e32 v3, 1
	flat_atomic_add v4, v[4:5], v3 offset:1024 sc0
	v_cvt_f32_u32_e32 v3, v2
	v_sub_u32_e32 v5, 0, v2
	s_add_u32 s25, s0, 0xc0000
	s_addc_u32 s24, s1, 0
	v_rcp_iflag_f32_e32 v3, v3
	s_nop 0
	v_mul_f32_e32 v3, 0x4f7ffffe, v3
	v_cvt_u32_f32_e32 v3, v3
	v_mul_lo_u32 v5, v5, v3
	v_mul_hi_u32 v5, v3, v5
	v_add_u32_e32 v3, v3, v5
	s_waitcnt vmcnt(0) lgkmcnt(0)
	v_mul_hi_u32 v3, v4, v3
	v_mul_lo_u32 v5, v3, v2
	v_sub_u32_e32 v5, v4, v5
	v_cmp_ge_u32_e32 vcc, v5, v2
	v_add_u32_e32 v6, 1, v3
	s_nop 0
	v_cndmask_b32_e32 v3, v3, v6, vcc
	v_sub_u32_e32 v6, v5, v2
	v_cndmask_b32_e32 v5, v5, v6, vcc
	v_cmp_ge_u32_e32 vcc, v5, v2
	v_add_u32_e32 v5, 1, v3
	v_add_u32_e32 v6, 1, v4
	v_cndmask_b32_e32 v3, v3, v5, vcc
	v_mad_u64_u32 v[4:5], s[0:1], v2, v3, v[2:3]
	v_cmp_ne_u32_e32 vcc, v6, v4
	s_and_saveexec_b64 s[0:1], vcc
	s_xor_b64 s[0:1], exec, s[0:1]
	s_cbranch_execz .LBB0_2618
	v_mov_b32_e32 v0, s25
	v_add_co_u32_e32 v4, vcc, 0x2000, v0
	v_mov_b32_e32 v0, s24
	s_nop 0
	v_addc_co_u32_e32 v5, vcc, 0, v0, vcc
	global_load_dword v0, v[4:5], off offset:1024 sc1
	s_add_u32 s4, s25, 0x2400
	s_addc_u32 s5, s24, 0
	s_waitcnt vmcnt(0) lgkmcnt(0)
	v_cmp_eq_u32_e32 vcc, v0, v3
	s_and_saveexec_b64 s[2:3], vcc
	s_cbranch_execz .LBB0_2617
	s_add_u32 s6, s36, 0xc0200
	s_addc_u32 s7, s37, 0
	s_mov_b32 s26, 1
	s_mov_b64 s[8:9], 0
	s_branch .LBB0_2609

; DI unsigned xb_ld(unsigned* p)              { return __hip_atomic_load(p, __ATOMIC_RELAXED, __HIP_MEMORY_SCOPE_AGENT); }
; #define XB_SPIN(cond, bar) do { unsigned _sp = 0; while (cond) { __builtin_amdgcn_s_sleep(1); \
;     if ((++_sp & 255u) == 0u) { if (xb_ld(&(bar)[XB_TMO])) break; if (_sp > XB_SPIN_CAP) { atomicAdd(&(bar)[XB_TMO], 1u); break; } } } } while (0)
; DI void xcd_barrier(int wv, unsigned* bar, volatile LAS unsigned* st) {
;     ...
;             XB_SPIN(xb_ld(&bar[XB_XGEN(x)]) == gen, bar);
.LBB0_2609:
	s_and_b32 s18, s26, 0xff
	s_mov_b64 s[16:17], -1
	s_cmp_lg_u32 s18, 0
	s_mov_b64 s[18:19], -1
	s_sleep 1
	s_cbranch_scc1 .LBB0_2613
	v_mov_b64_e32 v[4:5], s[6:7]
	global_load_dword v0, v[4:5], off sc1
	s_mov_b64 s[18:19], 0
	s_mov_b64 s[20:21], -1
	s_waitcnt vmcnt(0) lgkmcnt(0)
	v_cmp_eq_u32_e32 vcc, 0, v0
	s_and_saveexec_b64 s[22:23], vcc
	s_cmp_lt_u32 s26, 0x40001
	s_cselect_b64 s[18:19], -1, 0
	s_xor_b64 s[20:21], exec, -1
	s_and_b64 s[18:19], s[18:19], exec
	s_or_b64 exec, exec, s[22:23]
.LBB0_2613:
	s_andn2_b64 s[14:15], s[14:15], exec
	s_and_b64 s[20:21], s[20:21], exec
	s_or_b64 s[14:15], s[14:15], s[20:21]
	s_and_saveexec_b64 s[20:21], s[18:19]
	s_cbranch_execz .LBB0_2608
	v_mov_b64_e32 v[4:5], s[4:5]
	global_load_dword v0, v[4:5], off sc1
	s_add_i32 s26, s26, 1
	s_or_b64 s[14:15], s[14:15], exec
	s_waitcnt vmcnt(0) lgkmcnt(0)
	v_cmp_ne_u32_e32 vcc, v0, v3
	s_orn2_b64 s[16:17], vcc, exec
	s_branch .LBB0_2608

; DI unsigned xb_ld(unsigned* p)              { return __hip_atomic_load(p, __ATOMIC_RELAXED, __HIP_MEMORY_SCOPE_AGENT); }
; DI unsigned xb_add(unsigned* p, unsigned v) { return __hip_atomic_fetch_add(p, v, __ATOMIC_RELAXED, __HIP_MEMORY_SCOPE_AGENT); }
; #define XB_SPIN(cond, bar) do { unsigned _sp = 0; while (cond) { __builtin_amdgcn_s_sleep(1); \
;     if ((++_sp & 255u) == 0u) { if (xb_ld(&(bar)[XB_TMO])) break; if (_sp > XB_SPIN_CAP) { atomicAdd(&(bar)[XB_TMO], 1u); break; } } } } while (0)
; DI void xcd_barrier(int wv, unsigned* bar, volatile LAS unsigned* st) {
;     ...
;         if (old + 1u == (gen + 1u) * nloc) {
;             __builtin_amdgcn_fence(__ATOMIC_RELEASE, "agent");
;             asm volatile("s_waitcnt vmcnt(0)" ::: "memory");
;             const unsigned og = xb_add(&bar[XB_TOP], 1u);
;             const unsigned tg = og / nx;
;             if (og + 1u == (tg + 1u) * nx) xb_add(&bar[XB_TOPGEN], 1u);
;             else XB_SPIN(xb_ld(&bar[XB_TOPGEN]) == tg, bar);
.LBB0_2618:
	s_andn2_saveexec_b64 s[0:1], s[0:1]
	s_cbranch_execz .LBB0_2634
	v_mov_b32_e32 v2, s36
	v_add_co_u32_e32 v2, vcc, 0xc3000, v2
	v_mov_b32_e32 v3, s37
	buffer_wbl2 sc1
	s_waitcnt vmcnt(0)
	v_addc_co_u32_e32 v3, vcc, 0, v3, vcc
	v_mov_b32_e32 v4, 1
	flat_atomic_add v2, v[2:3], v4 offset:1024 sc0
	v_cvt_f32_u32_e32 v3, v0
	v_sub_u32_e32 v4, 0, v0
	s_mov_b64 s[4:5], -1
	v_rcp_iflag_f32_e32 v3, v3
	s_nop 0
	v_mul_f32_e32 v3, 0x4f7ffffe, v3
	v_cvt_u32_f32_e32 v3, v3
	v_mul_lo_u32 v4, v4, v3
	v_mul_hi_u32 v4, v3, v4
	v_add_u32_e32 v3, v3, v4
	s_waitcnt vmcnt(0) lgkmcnt(0)
	v_mul_hi_u32 v3, v2, v3
	v_mul_lo_u32 v4, v3, v0
	v_sub_u32_e32 v4, v2, v4
	v_cmp_ge_u32_e32 vcc, v4, v0
	v_add_u32_e32 v5, 1, v3
	s_nop 0
	v_cndmask_b32_e32 v3, v3, v5, vcc
	v_sub_u32_e32 v5, v4, v0
	v_cndmask_b32_e32 v4, v4, v5, vcc
	v_cmp_ge_u32_e32 vcc, v4, v0
	v_add_u32_e32 v4, 1, v3
	v_add_u32_e32 v5, 1, v2
	v_cndmask_b32_e32 v4, v3, v4, vcc
	v_mad_u64_u32 v[2:3], s[0:1], v0, v4, v[0:1]
	s_add_u32 s0, s36, 0xc3500
	s_addc_u32 s1, s37, 0
	v_cmp_ne_u32_e32 vcc, v5, v2
	v_mov_b64_e32 v[2:3], s[0:1]
	s_and_saveexec_b64 s[2:3], vcc
	s_cbranch_execz .LBB0_2631
	v_mov_b64_e32 v[2:3], s[0:1]
	global_load_dword v0, v[2:3], off sc1
	s_mov_b64 s[8:9], 0
	s_waitcnt vmcnt(0) lgkmcnt(0)
	v_cmp_eq_u32_e32 vcc, v0, v4
	s_and_saveexec_b64 s[6:7], vcc
	s_cbranch_execz .LBB0_2630
	s_add_u32 s4, s36, 0xc0200
	s_addc_u32 s5, s37, 0
	s_mov_b32 s22, 1
	s_branch .LBB0_2623

; DI unsigned xb_ld(unsigned* p)              { return __hip_atomic_load(p, __ATOMIC_RELAXED, __HIP_MEMORY_SCOPE_AGENT); }
; #define XB_SPIN(cond, bar) do { unsigned _sp = 0; while (cond) { __builtin_amdgcn_s_sleep(1); \
;     if ((++_sp & 255u) == 0u) { if (xb_ld(&(bar)[XB_TMO])) break; if (_sp > XB_SPIN_CAP) { atomicAdd(&(bar)[XB_TMO], 1u); break; } } } } while (0)
; DI void xcd_barrier(int wv, unsigned* bar, volatile LAS unsigned* st) {
;     ...
;             else XB_SPIN(xb_ld(&bar[XB_TOPGEN]) == tg, bar);
.LBB0_2625:
	v_mov_b64_e32 v[2:3], s[4:5]
	global_load_dword v0, v[2:3], off sc1
	s_mov_b64 s[18:19], 0
	s_mov_b64 s[16:17], -1
	s_waitcnt vmcnt(0) lgkmcnt(0)
	v_cmp_eq_u32_e32 vcc, 0, v0
	s_and_saveexec_b64 s[20:21], vcc
	s_cmp_lt_u32 s22, 0x40001
	s_cselect_b64 s[18:19], -1, 0
	s_xor_b64 s[16:17], exec, -1
	s_and_b64 s[18:19], s[18:19], exec
	s_or_b64 exec, exec, s[20:21]
	s_and_saveexec_b64 s[20:21], s[18:19]
	s_cbranch_execz .LBB0_2622
.LBB0_2628:
	v_mov_b64_e32 v[2:3], s[0:1]
	global_load_dword v0, v[2:3], off sc1
	s_add_i32 s22, s22, 1
	s_or_b64 s[16:17], s[16:17], exec
	s_waitcnt vmcnt(0) lgkmcnt(0)
	v_cmp_ne_u32_e32 vcc, v0, v4
	s_orn2_b64 s[14:15], vcc, exec
	s_branch .LBB0_2622

; DI u32x4 pk8(f32x4 a, f32x4 b) { u32x4 o; o.x = pk2(a.x, a.y); o.y = pk2(a.z, a.w); o.z = pk2(b.x, b.y); o.w = pk2(b.z, b.w); return o; }
; #define EPI_SCHED() __builtin_amdgcn_sched_barrier(0)
;     DI void operator()(const AccT& acc, const Unit& u, int wr, int wc, int fr, int fq) const {
;     ...
;             for (int ai = 0; ai < 2; ++ai) {
;                 EPI_SCHED();
;                 f32x4 cs[4], sn[4];
;                 if (do_rope) {
; #pragma unroll
;                     for (int m = 0; m < 4; ++m) { const int s = (int)((row0 + ai * 128 + m * 16) & 2047); cs[m] = *(const f32x4*)(rope + s * 16 + i0); sn[m] = *(const f32x4*)(rope + 32768 + s * 16 + i0); }
;                 }
; #pragma unroll
;                 for (int m = 0; m < 4; ++m) {
;                     const size_t row = row0 + ai * 128 + m * 16;
;                     f32x4 a = acc[ai][bj][m][0] * rs[ai][m], b = acc[ai][bj][m][1] * rs[ai][m];
;                     if (do_rope) rope4(a, b, cs[m], sn[m]);
;                     *(u32x4*)(q + row * 1536 + col) = pk8(a, b);
;                 }
.LBB0_2672:
	s_or_b64 exec, exec, s[4:5]
	v_mul_f32_e32 v0, 0x4b800000, v184
	v_cndmask_b32_e64 v0, v184, v0, s[2:3]
	v_rsq_f32_e32 v0, v0
	v_cvt_pk_bf16_f32 v185, v186, v187
	v_cvt_pk_bf16_f32 v186, v156, v157
	v_mov_b64_e32 v[156:157], s[14:15]
	v_mul_f32_e32 v154, 0x45800000, v0
	v_cvt_pk_bf16_f32 v184, v158, v159
	v_cndmask_b32_e64 v154, v0, v154, s[2:3]
	v_mad_u64_u32 v[158:159], s[2:3], v195, s77, v[156:157]
	v_mov_b32_e32 v0, v159
	v_mad_u64_u32 v[156:157], s[2:3], v194, s77, v[0:1]
	v_ashrrev_i32_e32 v165, 31, v164
	v_mov_b32_e32 v159, v156
	v_cvt_pk_bf16_f32 v187, v160, v161
	v_lshl_add_u64 v[156:157], v[164:165], 1, v[158:159]
	global_store_dwordx4 v[156:157], v[184:187], off
	v_pk_mul_f32 v[160:161], v[148:149], v[154:155] op_sel_hi:[1,0]
	v_pk_mul_f32 v[148:149], v[146:147], v[154:155] op_sel_hi:[1,0]
	v_pk_mul_f32 v[184:185], v[152:153], v[154:155] op_sel_hi:[1,0]
	v_pk_mul_f32 v[152:153], v[150:151], v[154:155] op_sel_hi:[1,0]
	s_and_saveexec_b64 s[2:3], vcc
	s_cbranch_execz .LBB0_2674
	s_waitcnt vmcnt(3)
	v_mov_b32_e32 v186, v107
	v_mov_b32_e32 v187, v111
	v_mul_f32_e32 v0, v185, v111
	v_pk_fma_f32 v[186:187], v[184:185], v[186:187], v[0:1] op_sel_hi:[1,1,0] neg_lo:[0,0,1] neg_hi:[0,0,1]
	v_mov_b32_e32 v194, v111
	v_mov_b32_e32 v195, v107
	v_mul_f32_e32 v0, v185, v107
	v_pk_fma_f32 v[194:195], v[184:185], v[194:195], v[0:1] op_sel_hi:[1,1,0]
	v_mov_b32_e32 v200, v109
	v_mov_b32_e32 v201, v113
	v_mul_f32_e32 v0, v161, v113
	v_pk_mul_f32 v[146:147], v[152:153], v[110:111] op_sel:[1,0] op_sel_hi:[0,0]
	v_pk_mul_f32 v[184:185], v[148:149], v[112:113] op_sel:[1,0] op_sel_hi:[0,0]
	v_pk_fma_f32 v[200:201], v[160:161], v[200:201], v[0:1] op_sel_hi:[1,1,0] neg_lo:[0,0,1] neg_hi:[0,0,1]
	v_mov_b32_e32 v202, v113
	v_mov_b32_e32 v203, v109
	v_mul_f32_e32 v0, v161, v109
	v_pk_mul_f32 v[150:151], v[152:153], v[106:107]
	v_pk_fma_f32 v[152:153], v[152:153], v[106:107], v[146:147] op_sel_hi:[1,0,1]
	v_pk_mul_f32 v[198:199], v[148:149], v[108:109]
	v_pk_fma_f32 v[148:149], v[148:149], v[108:109], v[184:185] op_sel_hi:[1,0,1]
	v_pk_fma_f32 v[202:203], v[160:161], v[202:203], v[0:1] op_sel_hi:[1,1,0]
	v_sub_f32_e32 v148, v198, v184
	v_sub_f32_e32 v152, v150, v146
	v_mov_b32_e32 v160, v200
	v_mov_b32_e32 v161, v202
	v_mov_b32_e32 v184, v186
	v_mov_b32_e32 v185, v194
.LBB0_2674:
	s_or_b64 exec, exec, s[2:3]
	v_pk_add_f32 v[146:147], v[180:181], v[182:183]
	s_mov_b32 s2, 0x3b2aaaab
	v_mov_b32_e32 v0, 0x358637bd
	v_pk_fma_f32 v[150:151], v[146:147], s[2:3], v[0:1] op_sel_hi:[1,0,0]
	v_cvt_pk_bf16_f32 v182, v148, v149
	v_mul_f32_e32 v0, 0x4b800000, v151
	v_cmp_gt_f32_e64 s[4:5], s42, v151
	v_cvt_pk_bf16_f32 v180, v152, v153
	v_cmp_gt_f32_e64 s[2:3], s42, v150
	v_cndmask_b32_e64 v0, v151, v0, s[4:5]
	v_rsq_f32_e32 v0, v0
	v_cvt_pk_bf16_f32 v181, v184, v185
	v_cvt_pk_bf16_f32 v183, v160, v161
	v_mul_f32_e32 v146, 0x45800000, v0
	v_cndmask_b32_e64 v146, v0, v146, s[4:5]
	s_mov_b64 s[4:5], 0xc000
	v_lshl_add_u64 v[148:149], v[158:159], 0, s[4:5]
	v_lshl_add_u64 v[152:153], v[164:165], 1, v[148:149]
	v_pk_mul_f32 v[144:145], v[144:145], v[146:147] op_sel_hi:[1,0]
	v_pk_mul_f32 v[142:143], v[142:143], v[146:147] op_sel_hi:[1,0]
	v_pk_mul_f32 v[140:141], v[140:141], v[146:147] op_sel_hi:[1,0]
	v_pk_mul_f32 v[138:139], v[138:139], v[146:147] op_sel_hi:[1,0]
	global_store_dwordx4 v[152:153], v[180:183], off
	s_and_saveexec_b64 s[4:5], vcc
	s_cbranch_execz .LBB0_2676
	s_waitcnt vmcnt(3)
	v_mov_b32_e32 v180, v99
	v_mov_b32_e32 v181, v103
	v_mul_f32_e32 v0, v145, v103
	v_pk_fma_f32 v[180:181], v[144:145], v[180:181], v[0:1] op_sel_hi:[1,1,0] neg_lo:[0,0,1] neg_hi:[0,0,1]
	v_mov_b32_e32 v182, v103
	v_mov_b32_e32 v183, v99
	v_mul_f32_e32 v0, v145, v99
	v_pk_fma_f32 v[182:183], v[144:145], v[182:183], v[0:1] op_sel_hi:[1,1,0]
	v_mov_b32_e32 v186, v101
	v_mov_b32_e32 v187, v105
	v_mul_f32_e32 v0, v141, v105
	v_pk_mul_f32 v[152:153], v[142:143], v[102:103] op_sel:[1,0] op_sel_hi:[0,0]
	v_pk_mul_f32 v[144:145], v[138:139], v[104:105] op_sel:[1,0] op_sel_hi:[0,0]
	v_pk_fma_f32 v[186:187], v[140:141], v[186:187], v[0:1] op_sel_hi:[1,1,0] neg_lo:[0,0,1] neg_hi:[0,0,1]
	v_mov_b32_e32 v194, v105
	v_mov_b32_e32 v195, v101
	v_mul_f32_e32 v0, v141, v101
	v_pk_mul_f32 v[160:161], v[142:143], v[98:99]
	v_pk_fma_f32 v[142:143], v[142:143], v[98:99], v[152:153] op_sel_hi:[1,0,1]
	v_pk_mul_f32 v[184:185], v[138:139], v[100:101]
	v_pk_fma_f32 v[138:139], v[138:139], v[100:101], v[144:145] op_sel_hi:[1,0,1]
	v_pk_fma_f32 v[194:195], v[140:141], v[194:195], v[0:1] op_sel_hi:[1,1,0]
	v_sub_f32_e32 v138, v184, v144
	v_sub_f32_e32 v142, v160, v152
	v_mov_b32_e32 v140, v186
	v_mov_b32_e32 v141, v194
	v_mov_b32_e32 v144, v180
	v_mov_b32_e32 v145, v182
; DI u32x4 pk8(f32x4 a, f32x4 b) { u32x4 o; o.x = pk2(a.x, a.y); o.y = pk2(a.z, a.w); o.z = pk2(b.x, b.y); o.w = pk2(b.z, b.w); return o; }
; #define EPI_SCHED() __builtin_amdgcn_sched_barrier(0)
;     DI void operator()(const AccT& acc, const Unit& u, int wr, int wc, int fr, int fq) const {
;     ...
;             for (int ai = 0; ai < 2; ++ai) {
;                 EPI_SCHED();
;                 f32x4 cs[4], sn[4];
;                 if (do_rope) {
; #pragma unroll
;                     for (int m = 0; m < 4; ++m) { const int s = (int)((row0 + ai * 128 + m * 16) & 2047); cs[m] = *(const f32x4*)(rope + s * 16 + i0); sn[m] = *(const f32x4*)(rope + 32768 + s * 16 + i0); }
;                 }
; #pragma unroll
;                 for (int m = 0; m < 4; ++m) {
;                     const size_t row = row0 + ai * 128 + m * 16;
;                     f32x4 a = acc[ai][bj][m][0] * rs[ai][m], b = acc[ai][bj][m][1] * rs[ai][m];
;                     if (do_rope) rope4(a, b, cs[m], sn[m]);
;                     *(u32x4*)(q + row * 1536 + col) = pk8(a, b);
;                 }
.LBB0_2676:
	s_or_b64 exec, exec, s[4:5]
	v_mul_f32_e32 v0, 0x4b800000, v150
	v_cndmask_b32_e64 v0, v150, v0, s[2:3]
	v_rsq_f32_e32 v0, v0
	v_cvt_pk_bf16_f32 v142, v142, v143
	v_cvt_pk_bf16_f32 v143, v144, v145
	v_cvt_pk_bf16_f32 v144, v138, v139
	v_mul_f32_e32 v138, 0x45800000, v0
	v_cndmask_b32_e64 v138, v0, v138, s[2:3]
	s_mov_b64 s[2:3], 0x18000
	v_cvt_pk_bf16_f32 v145, v140, v141
	v_lshl_add_u64 v[140:141], v[158:159], 0, s[2:3]
	v_lshl_add_u64 v[150:151], v[164:165], 1, v[140:141]
	v_pk_mul_f32 v[136:137], v[136:137], v[138:139] op_sel_hi:[1,0]
	v_pk_mul_f32 v[134:135], v[134:135], v[138:139] op_sel_hi:[1,0]
	v_pk_mul_f32 v[132:133], v[132:133], v[138:139] op_sel_hi:[1,0]
	v_pk_mul_f32 v[130:131], v[130:131], v[138:139] op_sel_hi:[1,0]
	global_store_dwordx4 v[150:151], v[142:145], off
	s_and_saveexec_b64 s[2:3], vcc
	s_cbranch_execz .LBB0_2678
	s_waitcnt vmcnt(3)
	v_mov_b32_e32 v150, v83
	v_mov_b32_e32 v151, v87
	v_mul_f32_e32 v0, v137, v87
	v_pk_fma_f32 v[150:151], v[136:137], v[150:151], v[0:1] op_sel_hi:[1,1,0] neg_lo:[0,0,1] neg_hi:[0,0,1]
	v_mov_b32_e32 v152, v87
	v_mov_b32_e32 v153, v83
	v_mul_f32_e32 v0, v137, v83
	v_pk_fma_f32 v[152:153], v[136:137], v[152:153], v[0:1] op_sel_hi:[1,1,0]
	v_mov_b32_e32 v180, v85
	v_mov_b32_e32 v181, v89
	v_mul_f32_e32 v0, v133, v89
	v_pk_mul_f32 v[142:143], v[134:135], v[86:87] op_sel:[1,0] op_sel_hi:[0,0]
	v_pk_mul_f32 v[136:137], v[130:131], v[88:89] op_sel:[1,0] op_sel_hi:[0,0]
	v_pk_fma_f32 v[180:181], v[132:133], v[180:181], v[0:1] op_sel_hi:[1,1,0] neg_lo:[0,0,1] neg_hi:[0,0,1]
	v_mov_b32_e32 v182, v89
	v_mov_b32_e32 v183, v85
	v_mul_f32_e32 v0, v133, v85
	v_pk_mul_f32 v[144:145], v[134:135], v[82:83]
	v_pk_fma_f32 v[134:135], v[134:135], v[82:83], v[142:143] op_sel_hi:[1,0,1]
	v_pk_mul_f32 v[160:161], v[130:131], v[84:85]
	v_pk_fma_f32 v[130:131], v[130:131], v[84:85], v[136:137] op_sel_hi:[1,0,1]
	v_pk_fma_f32 v[182:183], v[132:133], v[182:183], v[0:1] op_sel_hi:[1,1,0]
	v_sub_f32_e32 v130, v160, v136
	v_sub_f32_e32 v134, v144, v142
	v_mov_b32_e32 v132, v180
	v_mov_b32_e32 v133, v182
	v_mov_b32_e32 v136, v150
	v_mov_b32_e32 v137, v152
.LBB0_2678:
	s_or_b64 exec, exec, s[2:3]
	s_mov_b64 s[2:3], 0x24000
	v_cvt_pk_bf16_f32 v134, v134, v135
	v_cvt_pk_bf16_f32 v135, v136, v137
	v_cvt_pk_bf16_f32 v136, v130, v131
	v_lshl_add_u64 v[130:131], v[158:159], 0, s[2:3]
	v_cvt_pk_bf16_f32 v137, v132, v133
	v_lshl_add_u64 v[132:133], v[164:165], 1, v[130:131]
	global_store_dwordx4 v[132:133], v[134:137], off
	v_add_u32_e32 v0, 0x800, v196
	v_and_b32_e32 v133, 0x7cf0, v0
	s_and_saveexec_b64 s[2:3], vcc
	s_cbranch_execz .LBB0_2680
	v_lshlrev_b32_e32 v0, 2, v133
	s_waitcnt vmcnt(0)
	v_lshl_add_u64 v[82:83], v[178:179], 0, v[0:1]
	v_lshl_add_u64 v[86:87], v[176:177], 0, v[0:1]
	global_load_dwordx4 v[122:125], v[82:83], off
	global_load_dwordx4 v[106:109], v[82:83], off offset:1024
	global_load_dwordx4 v[126:129], v[86:87], off
	global_load_dwordx4 v[110:113], v[86:87], off offset:1024
	global_load_dwordx4 v[98:101], v[82:83], off offset:2048
	s_nop 0
	global_load_dwordx4 v[82:85], v[82:83], off offset:3072
	s_nop 0
	global_load_dwordx4 v[102:105], v[86:87], off offset:2048
	s_nop 0
	global_load_dwordx4 v[86:89], v[86:87], off offset:3072

; DI u32x4 pk8(f32x4 a, f32x4 b) { u32x4 o; o.x = pk2(a.x, a.y); o.y = pk2(a.z, a.w); o.z = pk2(b.x, b.y); o.w = pk2(b.z, b.w); return o; }
; #define EPI_SCHED() __builtin_amdgcn_sched_barrier(0)
;     DI void operator()(const AccT& acc, const Unit& u, int wr, int wc, int fr, int fq) const {
;     ...
;             for (int ai = 0; ai < 2; ++ai) {
;                 EPI_SCHED();
;                 f32x4 cs[4], sn[4];
;                 if (do_rope) {
; #pragma unroll
;                     for (int m = 0; m < 4; ++m) { const int s = (int)((row0 + ai * 128 + m * 16) & 2047); cs[m] = *(const f32x4*)(rope + s * 16 + i0); sn[m] = *(const f32x4*)(rope + 32768 + s * 16 + i0); }
;                 }
; #pragma unroll
;                 for (int m = 0; m < 4; ++m) {
;                     const size_t row = row0 + ai * 128 + m * 16;
;                     f32x4 a = acc[ai][bj][m][0] * rs[ai][m], b = acc[ai][bj][m][1] * rs[ai][m];
;                     if (do_rope) rope4(a, b, cs[m], sn[m]);
;                     *(u32x4*)(q + row * 1536 + col) = pk8(a, b);
;                 }
.LBB0_2682:
	s_or_b64 exec, exec, s[4:5]
	v_mul_f32_e32 v0, 0x4b800000, v134
	v_cndmask_b32_e64 v0, v134, v0, s[2:3]
	v_rsq_f32_e32 v0, v0
	v_cvt_pk_bf16_f32 v118, v118, v119
	v_cvt_pk_bf16_f32 v119, v120, v121
	v_cvt_pk_bf16_f32 v120, v114, v115
	v_mul_f32_e32 v114, 0x45800000, v0
	v_cndmask_b32_e64 v114, v0, v114, s[2:3]
	s_mov_b64 s[2:3], 0x60000
	v_cvt_pk_bf16_f32 v121, v116, v117
	v_lshl_add_u64 v[116:117], v[158:159], 0, s[2:3]
	v_lshl_add_u64 v[134:135], v[164:165], 1, v[116:117]
	global_store_dwordx4 v[134:135], v[118:121], off
	s_nop 1
	v_pk_mul_f32 v[120:121], v[96:97], v[114:115] op_sel_hi:[1,0]
	v_pk_mul_f32 v[96:97], v[94:95], v[114:115] op_sel_hi:[1,0]
	v_pk_mul_f32 v[118:119], v[92:93], v[114:115] op_sel_hi:[1,0]
	v_pk_mul_f32 v[92:93], v[90:91], v[114:115] op_sel_hi:[1,0]
	s_and_saveexec_b64 s[2:3], vcc
	s_cbranch_execz .LBB0_2684
	s_waitcnt vmcnt(3) lgkmcnt(0)
	v_mov_b32_e32 v134, v107
	v_mov_b32_e32 v135, v111
	v_mul_f32_e32 v0, v121, v111
	v_pk_fma_f32 v[134:135], v[120:121], v[134:135], v[0:1] op_sel_hi:[1,1,0] neg_lo:[0,0,1] neg_hi:[0,0,1]
	v_mov_b32_e32 v136, v111
	v_mov_b32_e32 v137, v107
	v_mul_f32_e32 v0, v121, v107
	v_pk_fma_f32 v[136:137], v[120:121], v[136:137], v[0:1] op_sel_hi:[1,1,0]
	v_mov_b32_e32 v144, v109
	v_mov_b32_e32 v145, v113
	v_mul_f32_e32 v0, v119, v113
	v_pk_mul_f32 v[90:91], v[96:97], v[110:111] op_sel:[1,0] op_sel_hi:[0,0]
	v_pk_mul_f32 v[120:121], v[92:93], v[112:113] op_sel:[1,0] op_sel_hi:[0,0]
	v_pk_fma_f32 v[144:145], v[118:119], v[144:145], v[0:1] op_sel_hi:[1,1,0] neg_lo:[0,0,1] neg_hi:[0,0,1]
	v_mov_b32_e32 v150, v113
	v_mov_b32_e32 v151, v109
	v_mul_f32_e32 v0, v119, v109
	v_pk_mul_f32 v[94:95], v[96:97], v[106:107]
	v_pk_fma_f32 v[96:97], v[96:97], v[106:107], v[90:91] op_sel_hi:[1,0,1]
	v_pk_mul_f32 v[142:143], v[92:93], v[108:109]
	v_pk_fma_f32 v[92:93], v[92:93], v[108:109], v[120:121] op_sel_hi:[1,0,1]
	v_pk_fma_f32 v[150:151], v[118:119], v[150:151], v[0:1] op_sel_hi:[1,1,0]
	v_sub_f32_e32 v92, v142, v120
	v_sub_f32_e32 v96, v94, v90
	v_mov_b32_e32 v118, v144
	v_mov_b32_e32 v119, v150
	v_mov_b32_e32 v120, v134
	v_mov_b32_e32 v121, v136
.LBB0_2684:
	s_or_b64 exec, exec, s[2:3]
	v_pk_add_f32 v[90:91], v[168:169], v[170:171]
	s_mov_b32 s2, 0x3b2aaaab
	v_mov_b32_e32 v0, 0x358637bd
	v_pk_fma_f32 v[94:95], v[90:91], s[2:3], v[0:1] op_sel_hi:[1,0,0]
	v_cvt_pk_bf16_f32 v136, v92, v93
	v_mul_f32_e32 v0, 0x4b800000, v95
	v_cmp_gt_f32_e64 s[4:5], s42, v95
	v_cvt_pk_bf16_f32 v134, v96, v97
	v_cmp_gt_f32_e64 s[2:3], s42, v94
	v_cndmask_b32_e64 v0, v95, v0, s[4:5]
	v_rsq_f32_e32 v0, v0
	v_cvt_pk_bf16_f32 v135, v120, v121
	v_cvt_pk_bf16_f32 v137, v118, v119
	v_mul_f32_e32 v90, 0x45800000, v0
	v_cndmask_b32_e64 v90, v0, v90, s[4:5]
	s_mov_b64 s[4:5], 0x6c000
	v_lshl_add_u64 v[92:93], v[158:159], 0, s[4:5]
	v_lshl_add_u64 v[96:97], v[164:165], 1, v[92:93]
	v_pk_mul_f32 v[80:81], v[80:81], v[90:91] op_sel_hi:[1,0]
	v_pk_mul_f32 v[78:79], v[78:79], v[90:91] op_sel_hi:[1,0]
	v_pk_mul_f32 v[76:77], v[76:77], v[90:91] op_sel_hi:[1,0]
	v_pk_mul_f32 v[74:75], v[74:75], v[90:91] op_sel_hi:[1,0]
	global_store_dwordx4 v[96:97], v[134:137], off
	s_and_saveexec_b64 s[4:5], vcc
	s_cbranch_execz .LBB0_2686
	s_waitcnt vmcnt(3) lgkmcnt(0)
	v_mov_b32_e32 v120, v99
	v_mov_b32_e32 v121, v103
	v_mul_f32_e32 v0, v81, v103
	v_pk_fma_f32 v[120:121], v[80:81], v[120:121], v[0:1] op_sel_hi:[1,1,0] neg_lo:[0,0,1] neg_hi:[0,0,1]
	v_mov_b32_e32 v134, v103
	v_mov_b32_e32 v135, v99
	v_mul_f32_e32 v0, v81, v99
	v_pk_fma_f32 v[134:135], v[80:81], v[134:135], v[0:1] op_sel_hi:[1,1,0]
	v_mov_b32_e32 v142, v101
	v_mov_b32_e32 v143, v105
	v_mul_f32_e32 v0, v77, v105
	v_pk_mul_f32 v[96:97], v[78:79], v[102:103] op_sel:[1,0] op_sel_hi:[0,0]
	v_pk_mul_f32 v[80:81], v[74:75], v[104:105] op_sel:[1,0] op_sel_hi:[0,0]
	v_pk_fma_f32 v[142:143], v[76:77], v[142:143], v[0:1] op_sel_hi:[1,1,0] neg_lo:[0,0,1] neg_hi:[0,0,1]
	v_mov_b32_e32 v144, v105
	v_mov_b32_e32 v145, v101
	v_mul_f32_e32 v0, v77, v101
	v_pk_mul_f32 v[118:119], v[78:79], v[98:99]
	v_pk_fma_f32 v[78:79], v[78:79], v[98:99], v[96:97] op_sel_hi:[1,0,1]
	v_pk_mul_f32 v[136:137], v[74:75], v[100:101]
	v_pk_fma_f32 v[74:75], v[74:75], v[100:101], v[80:81] op_sel_hi:[1,0,1]
	v_pk_fma_f32 v[144:145], v[76:77], v[144:145], v[0:1] op_sel_hi:[1,1,0]
	v_sub_f32_e32 v74, v136, v80
	v_sub_f32_e32 v78, v118, v96
	v_mov_b32_e32 v76, v142
	v_mov_b32_e32 v77, v144
	v_mov_b32_e32 v80, v120
	v_mov_b32_e32 v81, v134
; DI u32x4 pk8(f32x4 a, f32x4 b) { u32x4 o; o.x = pk2(a.x, a.y); o.y = pk2(a.z, a.w); o.z = pk2(b.x, b.y); o.w = pk2(b.z, b.w); return o; }
; #define EPI_SCHED() __builtin_amdgcn_sched_barrier(0)
;     DI void operator()(const AccT& acc, const Unit& u, int wr, int wc, int fr, int fq) const {
;     ...
;         for (int bj = 0; bj < 2; ++bj) {
;             const int col = u.pn * 256 + bj * 128 + wc * 32 + fq * 8;
;             const int d0 = col % 96; const bool do_rope = d0 >= 64; const int i0 = do_rope ? (d0 - 64) >> 1 : 0;
; #pragma unroll
;             for (int ai = 0; ai < 2; ++ai) {
;                 EPI_SCHED();
;                 f32x4 cs[4], sn[4];
;                 if (do_rope) {
; #pragma unroll
;                     for (int m = 0; m < 4; ++m) { const int s = (int)((row0 + ai * 128 + m * 16) & 2047); cs[m] = *(const f32x4*)(rope + s * 16 + i0); sn[m] = *(const f32x4*)(rope + 32768 + s * 16 + i0); }
;                 }
; #pragma unroll
;                 for (int m = 0; m < 4; ++m) {
;                     const size_t row = row0 + ai * 128 + m * 16;
;                     f32x4 a = acc[ai][bj][m][0] * rs[ai][m], b = acc[ai][bj][m][1] * rs[ai][m];
;                     if (do_rope) rope4(a, b, cs[m], sn[m]);
;                     *(u32x4*)(q + row * 1536 + col) = pk8(a, b);
;                 }
.LBB0_2686:
	s_or_b64 exec, exec, s[4:5]
	v_mul_f32_e32 v0, 0x4b800000, v94
	v_cndmask_b32_e64 v0, v94, v0, s[2:3]
	v_rsq_f32_e32 v0, v0
	v_cvt_pk_bf16_f32 v78, v78, v79
	v_cvt_pk_bf16_f32 v79, v80, v81
	v_cvt_pk_bf16_f32 v80, v74, v75
	v_mul_f32_e32 v74, 0x45800000, v0
	v_cndmask_b32_e64 v74, v0, v74, s[2:3]
	s_mov_b64 s[2:3], 0x78000
	v_cvt_pk_bf16_f32 v81, v76, v77
	v_lshl_add_u64 v[76:77], v[158:159], 0, s[2:3]
	v_lshl_add_u64 v[94:95], v[164:165], 1, v[76:77]
	v_pk_mul_f32 v[72:73], v[72:73], v[74:75] op_sel_hi:[1,0]
	v_pk_mul_f32 v[70:71], v[70:71], v[74:75] op_sel_hi:[1,0]
	v_pk_mul_f32 v[68:69], v[68:69], v[74:75] op_sel_hi:[1,0]
	v_pk_mul_f32 v[66:67], v[66:67], v[74:75] op_sel_hi:[1,0]
	global_store_dwordx4 v[94:95], v[78:81], off
	s_and_saveexec_b64 s[2:3], vcc
	s_cbranch_execz .LBB0_2688
	s_waitcnt vmcnt(3) lgkmcnt(0)
	v_mov_b32_e32 v94, v83
	v_mov_b32_e32 v95, v87
	v_mul_f32_e32 v0, v73, v87
	v_pk_fma_f32 v[94:95], v[72:73], v[94:95], v[0:1] op_sel_hi:[1,1,0] neg_lo:[0,0,1] neg_hi:[0,0,1]
	v_mov_b32_e32 v96, v87
	v_mov_b32_e32 v97, v83
	v_mul_f32_e32 v0, v73, v83
	v_pk_fma_f32 v[96:97], v[72:73], v[96:97], v[0:1] op_sel_hi:[1,1,0]
	v_mov_b32_e32 v120, v85
	v_mov_b32_e32 v121, v89
	v_mul_f32_e32 v0, v69, v89
	v_pk_mul_f32 v[78:79], v[70:71], v[86:87] op_sel:[1,0] op_sel_hi:[0,0]
	v_pk_mul_f32 v[72:73], v[66:67], v[88:89] op_sel:[1,0] op_sel_hi:[0,0]
	v_pk_fma_f32 v[120:121], v[68:69], v[120:121], v[0:1] op_sel_hi:[1,1,0] neg_lo:[0,0,1] neg_hi:[0,0,1]
	v_mov_b32_e32 v134, v89
	v_mov_b32_e32 v135, v85
	v_mul_f32_e32 v0, v69, v85
	v_pk_mul_f32 v[80:81], v[70:71], v[82:83]
	v_pk_fma_f32 v[70:71], v[70:71], v[82:83], v[78:79] op_sel_hi:[1,0,1]
	v_pk_mul_f32 v[118:119], v[66:67], v[84:85]
	v_pk_fma_f32 v[66:67], v[66:67], v[84:85], v[72:73] op_sel_hi:[1,0,1]
	v_pk_fma_f32 v[134:135], v[68:69], v[134:135], v[0:1] op_sel_hi:[1,1,0]
	v_sub_f32_e32 v66, v118, v72
	v_sub_f32_e32 v70, v80, v78
	v_mov_b32_e32 v68, v120
	v_mov_b32_e32 v69, v134
	v_mov_b32_e32 v72, v94
	v_mov_b32_e32 v73, v96
.LBB0_2688:
	s_or_b64 exec, exec, s[2:3]
	s_mov_b64 s[2:3], 0x84000
	v_cvt_pk_bf16_f32 v70, v70, v71
	v_cvt_pk_bf16_f32 v71, v72, v73
	v_cvt_pk_bf16_f32 v72, v66, v67
	v_lshl_add_u64 v[66:67], v[158:159], 0, s[2:3]
	v_cvt_pk_bf16_f32 v73, v68, v69
	v_lshl_add_u64 v[68:69], v[164:165], 1, v[66:67]
	global_store_dwordx4 v[68:69], v[70:73], off
	v_add_u32_e32 v68, 0x80, v164
	s_mov_b32 s2, 0x2aaaaaab
	v_mul_hi_i32 v0, v68, s2
	v_lshrrev_b32_e32 v69, 31, v0
	v_lshrrev_b32_e32 v0, 4, v0
	v_add_u32_e32 v0, v0, v69
	s_movk_i32 s2, 0x60
	v_mul_lo_u32 v0, v0, s2
	v_sub_u32_e32 v0, v68, v0
	v_subrev_u32_e32 v69, 64, v0
	v_lshrrev_b32_e32 v69, 1, v69
	v_cmp_lt_i32_e32 vcc, 63, v0
	s_nop 1
	v_cndmask_b32_e32 v0, 0, v69, vcc
	v_lshlrev_b64 v[70:71], 2, v[0:1]
	v_lshl_add_u64 v[72:73], s[6:7], 0, v[70:71]
	v_lshl_add_u64 v[70:71], s[18:19], 0, v[70:71]
	s_and_saveexec_b64 s[2:3], vcc
	s_cbranch_execz .LBB0_2690
	v_mov_b32_e32 v163, v1
	v_lshl_add_u64 v[78:79], v[72:73], 0, v[162:163]
	v_lshl_add_u64 v[80:81], v[70:71], 0, v[162:163]
	s_waitcnt vmcnt(0) lgkmcnt(0)
	global_load_dwordx4 v[122:125], v[78:79], off
	global_load_dwordx4 v[106:109], v[78:79], off offset:1024
	global_load_dwordx4 v[126:129], v[80:81], off
	global_load_dwordx4 v[110:113], v[80:81], off offset:1024
	global_load_dwordx4 v[98:101], v[78:79], off offset:2048
	global_load_dwordx4 v[82:85], v[78:79], off offset:3072
	global_load_dwordx4 v[102:105], v[80:81], off offset:2048
	global_load_dwordx4 v[86:89], v[80:81], off offset:3072

; DI u32x4 pk8(f32x4 a, f32x4 b) { u32x4 o; o.x = pk2(a.x, a.y); o.y = pk2(a.z, a.w); o.z = pk2(b.x, b.y); o.w = pk2(b.z, b.w); return o; }
; #define EPI_SCHED() __builtin_amdgcn_sched_barrier(0)
;     DI void operator()(const AccT& acc, const Unit& u, int wr, int wc, int fr, int fq) const {
;     ...
;             for (int ai = 0; ai < 2; ++ai) {
;                 EPI_SCHED();
;                 f32x4 cs[4], sn[4];
;                 if (do_rope) {
; #pragma unroll
;                     for (int m = 0; m < 4; ++m) { const int s = (int)((row0 + ai * 128 + m * 16) & 2047); cs[m] = *(const f32x4*)(rope + s * 16 + i0); sn[m] = *(const f32x4*)(rope + 32768 + s * 16 + i0); }
;                 }
; #pragma unroll
;                 for (int m = 0; m < 4; ++m) {
;                     const size_t row = row0 + ai * 128 + m * 16;
;                     f32x4 a = acc[ai][bj][m][0] * rs[ai][m], b = acc[ai][bj][m][1] * rs[ai][m];
;                     if (do_rope) rope4(a, b, cs[m], sn[m]);
;                     *(u32x4*)(q + row * 1536 + col) = pk8(a, b);
;                 }
.LBB0_2692:
	s_or_b64 exec, exec, s[2:3]
	v_mov_b32_e32 v155, v154
	v_cvt_pk_bf16_f32 v62, v62, v63
	v_cvt_pk_bf16_f32 v63, v64, v65
	v_cvt_pk_bf16_f32 v64, v58, v59
	v_mov_b32_e32 v58, v154
	v_mov_b32_e32 v59, v154
	v_cvt_pk_bf16_f32 v65, v60, v61
	v_pk_mul_f32 v[56:57], v[56:57], v[58:59]
	v_pk_mul_f32 v[54:55], v[54:55], v[154:155]
	v_pk_mul_f32 v[52:53], v[52:53], v[58:59]
	v_pk_mul_f32 v[50:51], v[50:51], v[154:155]
	global_store_dwordx4 v[156:157], v[62:65], off offset:256
	s_and_saveexec_b64 s[2:3], vcc
	s_cbranch_execz .LBB0_2694
	s_waitcnt vmcnt(3) lgkmcnt(0)
	v_mov_b32_e32 v62, v107
	v_mov_b32_e32 v63, v111
	v_mul_f32_e32 v0, v57, v111
	v_pk_fma_f32 v[62:63], v[56:57], v[62:63], v[0:1] op_sel_hi:[1,1,0] neg_lo:[0,0,1] neg_hi:[0,0,1]
	v_mov_b32_e32 v64, v111
	v_mov_b32_e32 v65, v107
	v_mul_f32_e32 v0, v57, v107
	v_pk_fma_f32 v[64:65], v[56:57], v[64:65], v[0:1] op_sel_hi:[1,1,0]
	v_mov_b32_e32 v80, v109
	v_mov_b32_e32 v81, v113
	v_mul_f32_e32 v0, v53, v113
	v_pk_mul_f32 v[58:59], v[54:55], v[110:111] op_sel:[1,0] op_sel_hi:[0,0]
	v_pk_mul_f32 v[56:57], v[50:51], v[112:113] op_sel:[1,0] op_sel_hi:[0,0]
	v_pk_fma_f32 v[80:81], v[52:53], v[80:81], v[0:1] op_sel_hi:[1,1,0] neg_lo:[0,0,1] neg_hi:[0,0,1]
	v_mov_b32_e32 v94, v113
	v_mov_b32_e32 v95, v109
	v_mul_f32_e32 v0, v53, v109
	v_pk_mul_f32 v[60:61], v[54:55], v[106:107]
	v_pk_fma_f32 v[54:55], v[54:55], v[106:107], v[58:59] op_sel_hi:[1,0,1]
	v_pk_mul_f32 v[78:79], v[50:51], v[108:109]
	v_pk_fma_f32 v[50:51], v[50:51], v[108:109], v[56:57] op_sel_hi:[1,0,1]
	v_pk_fma_f32 v[94:95], v[52:53], v[94:95], v[0:1] op_sel_hi:[1,1,0]
	v_sub_f32_e32 v50, v78, v56
	v_sub_f32_e32 v54, v60, v58
	v_mov_b32_e32 v52, v80
	v_mov_b32_e32 v53, v94
	v_mov_b32_e32 v56, v62
	v_mov_b32_e32 v57, v64
.LBB0_2694:
	s_or_b64 exec, exec, s[2:3]
	v_ashrrev_i32_e32 v69, 31, v68
	v_cvt_pk_bf16_f32 v54, v54, v55
	v_cvt_pk_bf16_f32 v55, v56, v57
	v_cvt_pk_bf16_f32 v56, v50, v51
	v_cvt_pk_bf16_f32 v57, v52, v53
	v_lshl_add_u64 v[50:51], v[68:69], 1, v[148:149]
	v_mov_b32_e32 v147, v146
	global_store_dwordx4 v[50:51], v[54:57], off
	v_mov_b32_e32 v50, v146
	v_mov_b32_e32 v51, v146
	v_pk_mul_f32 v[48:49], v[48:49], v[50:51]
	v_pk_mul_f32 v[46:47], v[46:47], v[146:147]
	v_pk_mul_f32 v[44:45], v[44:45], v[50:51]
	v_pk_mul_f32 v[42:43], v[42:43], v[146:147]
	s_and_saveexec_b64 s[2:3], vcc
	s_cbranch_execz .LBB0_2696
	s_waitcnt vmcnt(3) lgkmcnt(0)
	v_mov_b32_e32 v54, v99
	v_mov_b32_e32 v55, v103
	v_mul_f32_e32 v0, v49, v103
	v_pk_fma_f32 v[54:55], v[48:49], v[54:55], v[0:1] op_sel_hi:[1,1,0] neg_lo:[0,0,1] neg_hi:[0,0,1]
	v_mov_b32_e32 v56, v103
	v_mov_b32_e32 v57, v99
	v_mul_f32_e32 v0, v49, v99
	v_pk_fma_f32 v[56:57], v[48:49], v[56:57], v[0:1] op_sel_hi:[1,1,0]
	v_mov_b32_e32 v60, v101
	v_mov_b32_e32 v61, v105
	v_mul_f32_e32 v0, v45, v105
	v_pk_mul_f32 v[50:51], v[46:47], v[102:103] op_sel:[1,0] op_sel_hi:[0,0]
	v_pk_mul_f32 v[48:49], v[42:43], v[104:105] op_sel:[1,0] op_sel_hi:[0,0]
	v_pk_fma_f32 v[60:61], v[44:45], v[60:61], v[0:1] op_sel_hi:[1,1,0] neg_lo:[0,0,1] neg_hi:[0,0,1]
	v_mov_b32_e32 v62, v105
	v_mov_b32_e32 v63, v101
	v_mul_f32_e32 v0, v45, v101
	v_pk_mul_f32 v[52:53], v[46:47], v[98:99]
	v_pk_fma_f32 v[46:47], v[46:47], v[98:99], v[50:51] op_sel_hi:[1,0,1]
	v_pk_mul_f32 v[58:59], v[42:43], v[100:101]
	v_pk_fma_f32 v[42:43], v[42:43], v[100:101], v[48:49] op_sel_hi:[1,0,1]
	v_pk_fma_f32 v[62:63], v[44:45], v[62:63], v[0:1] op_sel_hi:[1,1,0]
	v_sub_f32_e32 v42, v58, v48
	v_sub_f32_e32 v46, v52, v50
	v_mov_b32_e32 v44, v60
	v_mov_b32_e32 v45, v62
	v_mov_b32_e32 v48, v54
	v_mov_b32_e32 v49, v56
.LBB0_2696:
	s_or_b64 exec, exec, s[2:3]
	v_cvt_pk_bf16_f32 v46, v46, v47
	v_cvt_pk_bf16_f32 v47, v48, v49
	v_cvt_pk_bf16_f32 v48, v42, v43
	v_cvt_pk_bf16_f32 v49, v44, v45
	v_lshl_add_u64 v[42:43], v[68:69], 1, v[140:141]
	v_mov_b32_e32 v139, v138
	global_store_dwordx4 v[42:43], v[46:49], off
	v_mov_b32_e32 v42, v138
	v_mov_b32_e32 v43, v138
	v_pk_mul_f32 v[40:41], v[40:41], v[42:43]
	v_pk_mul_f32 v[38:39], v[38:39], v[138:139]
	v_pk_mul_f32 v[36:37], v[36:37], v[42:43]
	v_pk_mul_f32 v[34:35], v[34:35], v[138:139]
	s_and_saveexec_b64 s[2:3], vcc
	s_cbranch_execz .LBB0_2698
	s_waitcnt vmcnt(3) lgkmcnt(0)
	v_mov_b32_e32 v46, v83
	v_mov_b32_e32 v47, v87
	v_mul_f32_e32 v0, v41, v87
	v_pk_fma_f32 v[46:47], v[40:41], v[46:47], v[0:1] op_sel_hi:[1,1,0] neg_lo:[0,0,1] neg_hi:[0,0,1]
	v_mov_b32_e32 v48, v87
	v_mov_b32_e32 v49, v83
	v_mul_f32_e32 v0, v41, v83
	v_pk_fma_f32 v[48:49], v[40:41], v[48:49], v[0:1] op_sel_hi:[1,1,0]
	v_mov_b32_e32 v52, v85
	v_mov_b32_e32 v53, v89
	v_mul_f32_e32 v0, v37, v89
	v_pk_mul_f32 v[42:43], v[38:39], v[86:87] op_sel:[1,0] op_sel_hi:[0,0]
	v_pk_mul_f32 v[40:41], v[34:35], v[88:89] op_sel:[1,0] op_sel_hi:[0,0]
	v_pk_fma_f32 v[52:53], v[36:37], v[52:53], v[0:1] op_sel_hi:[1,1,0] neg_lo:[0,0,1] neg_hi:[0,0,1]
	v_mov_b32_e32 v54, v89
	v_mov_b32_e32 v55, v85
	v_mul_f32_e32 v0, v37, v85
	v_pk_mul_f32 v[44:45], v[38:39], v[82:83]
	v_pk_fma_f32 v[38:39], v[38:39], v[82:83], v[42:43] op_sel_hi:[1,0,1]
	v_pk_mul_f32 v[50:51], v[34:35], v[84:85]
	v_pk_fma_f32 v[34:35], v[34:35], v[84:85], v[40:41] op_sel_hi:[1,0,1]
	v_pk_fma_f32 v[54:55], v[36:37], v[54:55], v[0:1] op_sel_hi:[1,1,0]
	v_sub_f32_e32 v34, v50, v40
	v_sub_f32_e32 v38, v44, v42
	v_mov_b32_e32 v36, v52
	v_mov_b32_e32 v37, v54
	v_mov_b32_e32 v40, v46
	v_mov_b32_e32 v41, v48
.LBB0_2698:
	s_or_b64 exec, exec, s[2:3]
	v_cvt_pk_bf16_f32 v38, v38, v39
	v_cvt_pk_bf16_f32 v39, v40, v41
	v_cvt_pk_bf16_f32 v40, v34, v35
	v_cvt_pk_bf16_f32 v41, v36, v37
	v_lshl_add_u64 v[34:35], v[68:69], 1, v[130:131]
	global_store_dwordx4 v[34:35], v[38:41], off
	s_and_saveexec_b64 s[2:3], vcc
	s_cbranch_execz .LBB0_2700
	v_lshlrev_b32_e32 v0, 2, v133
	v_lshl_add_u64 v[34:35], v[72:73], 0, v[0:1]
	v_lshl_add_u64 v[36:37], v[70:71], 0, v[0:1]
	s_waitcnt vmcnt(0) lgkmcnt(0)
	global_load_dwordx4 v[122:125], v[34:35], off
	global_load_dwordx4 v[106:109], v[34:35], off offset:1024
	global_load_dwordx4 v[126:129], v[36:37], off
	global_load_dwordx4 v[110:113], v[36:37], off offset:1024
	global_load_dwordx4 v[98:101], v[34:35], off offset:2048
	global_load_dwordx4 v[82:85], v[34:35], off offset:3072
	global_load_dwordx4 v[102:105], v[36:37], off offset:2048
	global_load_dwordx4 v[86:89], v[36:37], off offset:3072

; DI u32x4 pk8(f32x4 a, f32x4 b) { u32x4 o; o.x = pk2(a.x, a.y); o.y = pk2(a.z, a.w); o.z = pk2(b.x, b.y); o.w = pk2(b.z, b.w); return o; }
; #define EPI_SCHED() __builtin_amdgcn_sched_barrier(0)
; #define PG8_BAR __builtin_amdgcn_s_barrier()
; template <class Epi, class Sched>
; DI void gemm_phase(int wv, LAS unsigned char* lds, const Gemm g, const Sched& S, const Epi& E) {
;     ...
;         if (!has_next) break;
; #pragma unroll
;         for (int a = 0; a < 2; ++a)
; #pragma unroll
;             for (int b = 0; b < 2; ++b)
; #pragma unroll
;                 for (int m = 0; m < 4; ++m)
; #pragma unroll
;                     for (int n = 0; n < 2; ++n) acc[a][b][m][n] = (f32x4){0.f, 0.f, 0.f, 0.f};
;         cur = nxt; cA = nA; cB = nB; ++ui;
;         if (wr == 1) PG8_BAR;
;     DI void operator()(const AccT& acc, const Unit& u, int wr, int wc, int fr, int fq) const {
;     ...
;             for (int ai = 0; ai < 2; ++ai) {
;                 EPI_SCHED();
;                 f32x4 cs[4], sn[4];
;                 if (do_rope) {
; #pragma unroll
;                     for (int m = 0; m < 4; ++m) { const int s = (int)((row0 + ai * 128 + m * 16) & 2047); cs[m] = *(const f32x4*)(rope + s * 16 + i0); sn[m] = *(const f32x4*)(rope + 32768 + s * 16 + i0); }
;                 }
; #pragma unroll
;                 for (int m = 0; m < 4; ++m) {
;                     const size_t row = row0 + ai * 128 + m * 16;
;                     f32x4 a = acc[ai][bj][m][0] * rs[ai][m], b = acc[ai][bj][m][1] * rs[ai][m];
;                     if (do_rope) rope4(a, b, cs[m], sn[m]);
;                     *(u32x4*)(q + row * 1536 + col) = pk8(a, b);
;                 }
.LBB0_2702:
	s_or_b64 exec, exec, s[2:3]
	v_cvt_pk_bf16_f32 v30, v30, v31
	v_cvt_pk_bf16_f32 v31, v32, v33
	v_cvt_pk_bf16_f32 v32, v26, v27
	v_cvt_pk_bf16_f32 v33, v28, v29
	v_lshl_add_u64 v[26:27], v[68:69], 1, v[116:117]
	v_mov_b32_e32 v115, v114
	global_store_dwordx4 v[26:27], v[30:33], off
	v_mov_b32_e32 v26, v114
	v_mov_b32_e32 v27, v114
	v_pk_mul_f32 v[24:25], v[24:25], v[26:27]
	v_pk_mul_f32 v[22:23], v[22:23], v[114:115]
	v_pk_mul_f32 v[20:21], v[20:21], v[26:27]
	v_pk_mul_f32 v[18:19], v[18:19], v[114:115]
	s_and_saveexec_b64 s[2:3], vcc
	s_cbranch_execz .LBB0_2704
	s_waitcnt vmcnt(3) lgkmcnt(0)
	v_pk_mul_f32 v[26:27], v[22:23], v[110:111] op_sel:[1,0] op_sel_hi:[0,0]
	v_mov_b32_e32 v110, v107
	v_mul_f32_e32 v0, v25, v111
	v_pk_mul_f32 v[28:29], v[22:23], v[106:107]
	v_pk_fma_f32 v[22:23], v[22:23], v[106:107], v[26:27] op_sel_hi:[1,0,1]
	v_pk_fma_f32 v[30:31], v[24:25], v[110:111], v[0:1] op_sel_hi:[1,1,0] neg_lo:[0,0,1] neg_hi:[0,0,1]
	v_mov_b32_e32 v106, v111
	v_mul_f32_e32 v0, v25, v107
	v_pk_fma_f32 v[32:33], v[24:25], v[106:107], v[0:1] op_sel_hi:[1,1,0]
	v_pk_mul_f32 v[24:25], v[18:19], v[112:113] op_sel:[1,0] op_sel_hi:[0,0]
	v_mov_b32_e32 v112, v109
	v_mul_f32_e32 v0, v21, v113
	v_pk_mul_f32 v[34:35], v[18:19], v[108:109]
	v_pk_fma_f32 v[18:19], v[18:19], v[108:109], v[24:25] op_sel_hi:[1,0,1]
	v_pk_fma_f32 v[36:37], v[20:21], v[112:113], v[0:1] op_sel_hi:[1,1,0] neg_lo:[0,0,1] neg_hi:[0,0,1]
	v_mov_b32_e32 v108, v113
	v_mul_f32_e32 v0, v21, v109
	v_pk_fma_f32 v[38:39], v[20:21], v[108:109], v[0:1] op_sel_hi:[1,1,0]
	v_sub_f32_e32 v18, v34, v24
	v_sub_f32_e32 v22, v28, v26
	v_mov_b32_e32 v20, v36
	v_mov_b32_e32 v21, v38
	v_mov_b32_e32 v24, v30
	v_mov_b32_e32 v25, v32
.LBB0_2704:
	s_or_b64 exec, exec, s[2:3]
	v_cvt_pk_bf16_f32 v22, v22, v23
	v_cvt_pk_bf16_f32 v23, v24, v25
	v_cvt_pk_bf16_f32 v24, v18, v19
	v_cvt_pk_bf16_f32 v25, v20, v21
	v_lshl_add_u64 v[18:19], v[68:69], 1, v[92:93]
	v_mov_b32_e32 v91, v90
	global_store_dwordx4 v[18:19], v[22:25], off
	v_mov_b32_e32 v18, v90
	v_mov_b32_e32 v19, v90
	v_pk_mul_f32 v[16:17], v[16:17], v[18:19]
	v_pk_mul_f32 v[14:15], v[14:15], v[90:91]
	v_pk_mul_f32 v[12:13], v[12:13], v[18:19]
	v_pk_mul_f32 v[10:11], v[10:11], v[90:91]
	s_and_saveexec_b64 s[2:3], vcc
	s_cbranch_execz .LBB0_2706
	s_waitcnt vmcnt(3) lgkmcnt(0)
	v_pk_mul_f32 v[18:19], v[14:15], v[102:103] op_sel:[1,0] op_sel_hi:[0,0]
	v_mov_b32_e32 v102, v99
	v_mul_f32_e32 v0, v17, v103
	v_pk_mul_f32 v[20:21], v[14:15], v[98:99]
	v_pk_fma_f32 v[14:15], v[14:15], v[98:99], v[18:19] op_sel_hi:[1,0,1]
	v_pk_fma_f32 v[22:23], v[16:17], v[102:103], v[0:1] op_sel_hi:[1,1,0] neg_lo:[0,0,1] neg_hi:[0,0,1]
	v_mov_b32_e32 v98, v103
	v_mul_f32_e32 v0, v17, v99
	v_pk_fma_f32 v[24:25], v[16:17], v[98:99], v[0:1] op_sel_hi:[1,1,0]
	v_pk_mul_f32 v[16:17], v[10:11], v[104:105] op_sel:[1,0] op_sel_hi:[0,0]
	v_mov_b32_e32 v104, v101
	v_mul_f32_e32 v0, v13, v105
	v_pk_mul_f32 v[26:27], v[10:11], v[100:101]
	v_pk_fma_f32 v[10:11], v[10:11], v[100:101], v[16:17] op_sel_hi:[1,0,1]
	v_pk_fma_f32 v[28:29], v[12:13], v[104:105], v[0:1] op_sel_hi:[1,1,0] neg_lo:[0,0,1] neg_hi:[0,0,1]
	v_mov_b32_e32 v100, v105
	v_mul_f32_e32 v0, v13, v101
	v_pk_fma_f32 v[30:31], v[12:13], v[100:101], v[0:1] op_sel_hi:[1,1,0]
	v_sub_f32_e32 v10, v26, v16
	v_sub_f32_e32 v14, v20, v18
	v_mov_b32_e32 v12, v28
	v_mov_b32_e32 v13, v30
	v_mov_b32_e32 v16, v22
	v_mov_b32_e32 v17, v24
.LBB0_2706:
	s_or_b64 exec, exec, s[2:3]
	v_cvt_pk_bf16_f32 v14, v14, v15
	v_cvt_pk_bf16_f32 v15, v16, v17
	v_cvt_pk_bf16_f32 v16, v10, v11
	v_cvt_pk_bf16_f32 v17, v12, v13
	v_lshl_add_u64 v[10:11], v[68:69], 1, v[76:77]
	v_mov_b32_e32 v75, v74
	global_store_dwordx4 v[10:11], v[14:17], off
	v_mov_b32_e32 v10, v74
	v_mov_b32_e32 v11, v74
	v_pk_mul_f32 v[8:9], v[8:9], v[10:11]
	v_pk_mul_f32 v[6:7], v[6:7], v[74:75]
	v_pk_mul_f32 v[4:5], v[4:5], v[10:11]
	v_pk_mul_f32 v[2:3], v[2:3], v[74:75]
	s_and_saveexec_b64 s[2:3], vcc
	s_cbranch_execz .LBB0_2708
	s_waitcnt vmcnt(3) lgkmcnt(0)
	v_pk_mul_f32 v[10:11], v[6:7], v[86:87] op_sel:[1,0] op_sel_hi:[0,0]
	v_mov_b32_e32 v86, v83
	v_mul_f32_e32 v0, v9, v87
	v_pk_mul_f32 v[12:13], v[6:7], v[82:83]
	v_pk_fma_f32 v[6:7], v[6:7], v[82:83], v[10:11] op_sel_hi:[1,0,1]
	v_pk_fma_f32 v[14:15], v[8:9], v[86:87], v[0:1] op_sel_hi:[1,1,0] neg_lo:[0,0,1] neg_hi:[0,0,1]
	v_mov_b32_e32 v82, v87
	v_mul_f32_e32 v0, v9, v83
	v_pk_fma_f32 v[16:17], v[8:9], v[82:83], v[0:1] op_sel_hi:[1,1,0]
	v_pk_mul_f32 v[8:9], v[2:3], v[88:89] op_sel:[1,0] op_sel_hi:[0,0]
	v_mov_b32_e32 v88, v85
	v_mul_f32_e32 v0, v5, v89
	v_pk_mul_f32 v[18:19], v[2:3], v[84:85]
	v_pk_fma_f32 v[2:3], v[2:3], v[84:85], v[8:9] op_sel_hi:[1,0,1]
	v_pk_fma_f32 v[20:21], v[4:5], v[88:89], v[0:1] op_sel_hi:[1,1,0] neg_lo:[0,0,1] neg_hi:[0,0,1]
	v_mov_b32_e32 v84, v89
	v_mul_f32_e32 v0, v5, v85
	v_pk_fma_f32 v[22:23], v[4:5], v[84:85], v[0:1] op_sel_hi:[1,1,0]
	v_sub_f32_e32 v2, v18, v8
	v_sub_f32_e32 v6, v12, v10
	v_mov_b32_e32 v4, v20
	v_mov_b32_e32 v5, v22
	v_mov_b32_e32 v8, v14
	v_mov_b32_e32 v9, v16
.LBB0_2708:
	s_or_b64 exec, exec, s[2:3]
	v_cvt_pk_bf16_f32 v6, v6, v7
	v_cvt_pk_bf16_f32 v7, v8, v9
	v_cvt_pk_bf16_f32 v8, v2, v3
	v_cvt_pk_bf16_f32 v9, v4, v5
	v_lshl_add_u64 v[2:3], v[68:69], 1, v[66:67]
	s_and_b64 vcc, exec, s[0:1]
	s_mov_b64 s[0:1], -1
	global_store_dwordx4 v[2:3], v[6:9], off
	s_cbranch_vccnz .LBB0_2641
	s_andn2_b64 vcc, exec, s[8:9]
	s_cbranch_vccnz .LBB0_2640
	s_barrier
	s_branch .LBB0_2640

; DI u32x4 pk8(f32x4 a, f32x4 b) { u32x4 o; o.x = pk2(a.x, a.y); o.y = pk2(a.z, a.w); o.z = pk2(b.x, b.y); o.w = pk2(b.z, b.w); return o; }
; #define EPI_SCHED() __builtin_amdgcn_sched_barrier(0)
; template <int STRIDE, int P0, int NP4>
; DI void rstd8(const float* parts, size_t row0, float invK, int fq, float (&rs)[2][4]) {
;     f32x4 v[2][4];
; #pragma unroll
;     for (int ai = 0; ai < 2; ++ai)
; #pragma unroll
;         for (int m = 0; m < 4; ++m) {
;             const float* p = parts + (row0 + ai * 128 + m * 16) * STRIDE + P0;
;             if (NP4 == 1) v[ai][m] = *(const f32x4*)p;
;             else if (fq < NP4) v[ai][m] = *(const f32x4*)(p + 4 * fq);
;             else v[ai][m] = (f32x4){0.f, 0.f, 0.f, 0.f};
;         }
; #pragma unroll
;     for (int ai = 0; ai < 2; ++ai)
; #pragma unroll
;         for (int m = 0; m < 4; ++m) {
;             float t = (v[ai][m].x + v[ai][m].y) + (v[ai][m].z + v[ai][m].w);
;             if (NP4 > 1) { t += __shfl_xor(t, 16); t += __shfl_xor(t, 32); }
;             rs[ai][m] = rsqrtf(t * invK + EPS);
;         }
;     DI void operator()(const AccT& acc, const Unit& u, int wr, int wc, int fr, int fq) const {
;         const size_t row0 = (size_t)u.pm * 256 + wr * 64 + fr;
;         float rs[2][4]; rstd8<STRIDE, P0, NP4>(parts, row0, invK, fq, rs);
; #pragma unroll
;         for (int ai = 0; ai < 2; ++ai)
; #pragma unroll
;             for (int m = 0; m < 4; ++m) {
;                 EPI_SCHED(); const size_t row = row0 + ai * 128 + m * 16;
; #pragma unroll
;                 for (int bj = 0; bj < 2; ++bj) {
;                     const int col = u.pn * 256 + bj * 128 + wc * 32 + fq * 8;
;                     const unsigned off = ((unsigned)(row >> 11) * 32768u + (unsigned)(row & 2047)) * 64u + (unsigned)(col >> 6) * 131072u + (unsigned)(col & 63);
;                     *(u32x4*)(out + off) = pk8(acc[ai][bj][m][0] * rs[ai][m], acc[ai][bj][m][1] * rs[ai][m]);
;                 }
.LBB0_2731:
	s_mov_b32 s2, -1
	s_ashr_i32 s21, s20, 31
	v_mbcnt_lo_u32_b32 v0, s2, 0
	v_mbcnt_hi_u32_b32 v159, s2, v0
	s_lshl_b64 s[2:3], s[20:21], 8
	s_add_u32 s13, s2, s57
	v_and_b32_e32 v0, 15, v159
	v_or_b32_e32 v158, s13, v0
	s_addc_u32 s18, s3, s65
	v_mad_u64_u32 v[130:131], s[2:3], v158, 48, s[6:7]
	v_mad_i32_i24 v131, s18, 48, v131
	global_load_dwordx4 v[160:163], v[130:131], off
	global_load_dwordx4 v[164:167], v[130:131], off offset:768
	global_load_dwordx4 v[168:171], v[130:131], off offset:1536
	global_load_dwordx4 v[172:175], v[130:131], off offset:2304
	s_movk_i32 s2, 0x1000
	v_add_co_u32_e32 v132, vcc, s2, v130
	s_movk_i32 s2, 0x2000
	s_nop 0
	v_addc_co_u32_e32 v133, vcc, 0, v131, vcc
	global_load_dwordx4 v[142:145], v[132:133], off offset:2048
	global_load_dwordx4 v[138:141], v[132:133], off offset:2816
	global_load_dwordx4 v[134:137], v[132:133], off offset:3584
	v_add_co_u32_e32 v130, vcc, s2, v130
	s_mov_b32 s2, 0x358637bd
	s_nop 0
	v_addc_co_u32_e32 v131, vcc, 0, v131, vcc
	global_load_dwordx4 v[130:133], v[130:131], off offset:256
	s_waitcnt vmcnt(0) lgkmcnt(0)
	v_mov_b32_e32 v154, v161
	v_mov_b32_e32 v155, v162
	v_mov_b32_e32 v161, v163
	v_pk_add_f32 v[154:155], v[154:155], v[160:161]
	v_mov_b32_e32 v160, v165
	v_mov_b32_e32 v161, v166
	v_mov_b32_e32 v165, v167
	v_pk_add_f32 v[160:161], v[160:161], v[164:165]
	v_mov_b32_e32 v163, v154
	v_mov_b32_e32 v162, v160
	v_mov_b32_e32 v154, v161
	v_pk_add_f32 v[160:161], v[162:163], v[154:155]
	v_mov_b64_e32 v[154:155], s[2:3]
	v_pk_fma_f32 v[160:161], v[160:161], s[86:87], v[154:155] op_sel_hi:[1,0,0]
	v_mov_b32_e32 v162, v173
	v_mul_f32_e32 v146, 0x4b800000, v161
	v_cmp_gt_f32_e64 s[2:3], s42, v161
	v_cmp_gt_f32_e32 vcc, s42, v160
	v_mov_b32_e32 v163, v174
	v_cndmask_b32_e64 v146, v161, v146, s[2:3]
	v_rsq_f32_e32 v146, v146
	v_mov_b32_e32 v161, v170
	v_mov_b32_e32 v173, v175
	v_pk_add_f32 v[162:163], v[162:163], v[172:173]
	v_mul_f32_e32 v148, 0x45800000, v146
	v_cndmask_b32_e64 v150, v146, v148, s[2:3]
	v_mul_f32_e32 v146, 0x4b800000, v160
	v_cndmask_b32_e32 v146, v160, v146, vcc
	v_rsq_f32_e32 v146, v146
	v_mov_b32_e32 v160, v169
	v_mov_b32_e32 v169, v171
	v_pk_add_f32 v[160:161], v[160:161], v[168:169]
	v_mov_b32_e32 v164, v162
	v_mov_b32_e32 v165, v160
	v_mov_b32_e32 v160, v163
	v_pk_add_f32 v[160:161], v[164:165], v[160:161]
	v_mul_f32_e32 v148, 0x45800000, v146
	v_pk_fma_f32 v[160:161], v[160:161], s[86:87], v[154:155] op_sel_hi:[1,0,0]
	v_cndmask_b32_e32 v146, v146, v148, vcc
	v_mul_f32_e32 v148, 0x4b800000, v161
	v_cmp_gt_f32_e64 s[2:3], s42, v161
	v_cmp_gt_f32_e32 vcc, s42, v160
	s_nop 0
	v_cndmask_b32_e64 v148, v161, v148, s[2:3]
	v_rsq_f32_e32 v148, v148
	v_mov_b32_e32 v161, v144
	v_mov_b32_e32 v144, v139
	v_mov_b32_e32 v139, v141
	v_mul_f32_e32 v152, 0x45800000, v148
	v_cndmask_b32_e64 v152, v148, v152, s[2:3]
	v_mul_f32_e32 v148, 0x4b800000, v160
	v_cndmask_b32_e32 v148, v160, v148, vcc
	v_rsq_f32_e32 v148, v148
	s_nop 0
	v_mul_f32_e32 v160, 0x45800000, v148
	v_cndmask_b32_e32 v148, v148, v160, vcc
	v_mov_b32_e32 v160, v143
	v_mov_b32_e32 v143, v145
	v_mov_b32_e32 v145, v140
	v_pk_add_f32 v[142:143], v[160:161], v[142:143]
	v_pk_add_f32 v[138:139], v[144:145], v[138:139]
	v_mov_b32_e32 v141, v142
	v_mov_b32_e32 v140, v138
	v_mov_b32_e32 v142, v139
	v_pk_add_f32 v[138:139], v[140:141], v[142:143]
	v_mov_b32_e32 v142, v135
	v_pk_fma_f32 v[140:141], v[138:139], s[86:87], v[154:155] op_sel_hi:[1,0,0]
	v_mov_b32_e32 v143, v136
	v_mul_f32_e32 v138, 0x4b800000, v141
	v_cmp_gt_f32_e64 s[2:3], s42, v141
	v_mov_b32_e32 v135, v137
	v_mov_b32_e32 v136, v131
	v_cndmask_b32_e64 v138, v141, v138, s[2:3]
	v_rsq_f32_e32 v138, v138
	v_mov_b32_e32 v137, v132
	v_mov_b32_e32 v131, v133
	v_pk_add_f32 v[134:135], v[142:143], v[134:135]
	v_pk_add_f32 v[130:131], v[136:137], v[130:131]
	v_mov_b32_e32 v133, v134
	v_mov_b32_e32 v132, v130
	v_mov_b32_e32 v134, v131
	v_pk_add_f32 v[130:131], v[132:133], v[134:135]
	v_mul_f32_e32 v139, 0x45800000, v138
	v_pk_fma_f32 v[130:131], v[130:131], s[86:87], v[154:155] op_sel_hi:[1,0,0]
	v_cmp_gt_f32_e32 vcc, s42, v140
	v_cndmask_b32_e64 v138, v138, v139, s[2:3]
	v_mul_f32_e32 v139, 0x4b800000, v140
	v_mul_f32_e32 v132, 0x4b800000, v131
	v_cmp_gt_f32_e64 s[2:3], s42, v131
	v_cndmask_b32_e32 v139, v140, v139, vcc
	v_rsq_f32_e32 v139, v139
	v_cndmask_b32_e64 v131, v131, v132, s[2:3]
	v_rsq_f32_e32 v131, v131
	v_mov_b32_e32 v134, 0x7cf
	v_mul_f32_e32 v140, 0x45800000, v139
	v_cndmask_b32_e32 v140, v139, v140, vcc
	v_mul_f32_e32 v132, 0x45800000, v131
	v_cmp_gt_f32_e32 vcc, s42, v130
	v_cndmask_b32_e64 v132, v131, v132, s[2:3]
	v_mul_f32_e32 v131, 0x4b800000, v130
	v_cndmask_b32_e32 v130, v130, v131, vcc
	v_rsq_f32_e32 v130, v130
	s_lshl_b32 s2, s69, 8
	s_or_b32 s2, s2, s60
	v_bitop3_b32 v0, s13, v134, v0 bitop3:0xc8
	v_mul_f32_e32 v131, 0x45800000, v130
	v_cndmask_b32_e32 v130, v130, v131, vcc
	v_ashrrev_i32_e32 v131, 1, v159
	v_and_b32_e32 v131, -8, v131
	v_add_u32_e32 v131, s2, v131
	s_lshl_b32 s2, s13, 4
	v_lshlrev_b32_e32 v133, 11, v131
	s_and_b32 s2, s2, 0x3ff8000
	v_and_b32_e32 v133, 0xfffe0000, v133
	v_or_b32_e32 v0, s2, v0
	v_lshlrev_b32_e32 v136, 6, v0
	v_add_u32_e32 v0, v136, v133
	v_and_b32_e32 v131, 56, v131
	v_or_b32_e32 v0, v0, v131
	v_pk_mul_f32 v[128:129], v[128:129], v[150:151] op_sel_hi:[1,0]
	v_pk_mul_f32 v[126:127], v[126:127], v[150:151] op_sel_hi:[1,0]
	v_pk_mul_f32 v[134:135], v[124:125], v[150:151] op_sel_hi:[1,0]
	v_pk_mul_f32 v[124:125], v[122:123], v[150:151] op_sel_hi:[1,0]
	v_cvt_pk_bf16_f32 v122, v126, v127
	v_cvt_pk_bf16_f32 v123, v128, v129
	v_cvt_pk_bf16_f32 v124, v124, v125
	v_cvt_pk_bf16_f32 v125, v134, v135
; DI u32x4 pk8(f32x4 a, f32x4 b) { u32x4 o; o.x = pk2(a.x, a.y); o.y = pk2(a.z, a.w); o.z = pk2(b.x, b.y); o.w = pk2(b.z, b.w); return o; }
; #define EPI_SCHED() __builtin_amdgcn_sched_barrier(0)
;     DI void operator()(const AccT& acc, const Unit& u, int wr, int wc, int fr, int fq) const {
;     ...
;             for (int m = 0; m < 4; ++m) {
;                 EPI_SCHED(); const size_t row = row0 + ai * 128 + m * 16;
; #pragma unroll
;                 for (int bj = 0; bj < 2; ++bj) {
;                     const int col = u.pn * 256 + bj * 128 + wc * 32 + fq * 8;
;                     const unsigned off = ((unsigned)(row >> 11) * 32768u + (unsigned)(row & 2047)) * 64u + (unsigned)(col >> 6) * 131072u + (unsigned)(col & 63);
;                     *(u32x4*)(out + off) = pk8(acc[ai][bj][m][0] * rs[ai][m], acc[ai][bj][m][1] * rs[ai][m]);
;                 }
	v_lshl_add_u64 v[126:127], v[0:1], 1, s[72:73]
	global_store_dwordx4 v[126:127], v[122:125], off
	v_pk_mul_f32 v[120:121], v[120:121], v[150:151] op_sel_hi:[1,0]
	v_pk_mul_f32 v[118:119], v[118:119], v[150:151] op_sel_hi:[1,0]
	v_add_u32_e32 v124, 0x40000, v133
	v_add_u32_e32 v0, v136, v124
	v_or_b32_e32 v0, v0, v131
	v_pk_mul_f32 v[122:123], v[112:113], v[150:151] op_sel_hi:[1,0]
	v_pk_mul_f32 v[112:113], v[110:111], v[150:151] op_sel_hi:[1,0]
	v_cvt_pk_bf16_f32 v110, v118, v119
	v_cvt_pk_bf16_f32 v111, v120, v121
	v_cvt_pk_bf16_f32 v112, v112, v113
	v_cvt_pk_bf16_f32 v113, v122, v123
	v_lshl_add_u64 v[118:119], v[0:1], 1, s[72:73]
	global_store_dwordx4 v[118:119], v[110:113], off
	v_or_b32_e32 v118, 0x400, v136
	v_add_u32_e32 v0, v118, v133
	v_or_b32_e32 v0, v0, v131
	v_pk_mul_f32 v[110:111], v[116:117], v[146:147] op_sel_hi:[1,0]
	v_pk_mul_f32 v[112:113], v[114:115], v[146:147] op_sel_hi:[1,0]
	v_pk_mul_f32 v[114:115], v[108:109], v[146:147] op_sel_hi:[1,0]
	v_pk_mul_f32 v[108:109], v[106:107], v[146:147] op_sel_hi:[1,0]
	v_cvt_pk_bf16_f32 v106, v112, v113
	v_cvt_pk_bf16_f32 v107, v110, v111
	v_cvt_pk_bf16_f32 v108, v108, v109
	v_cvt_pk_bf16_f32 v109, v114, v115
	v_lshl_add_u64 v[110:111], v[0:1], 1, s[72:73]
	v_add_u32_e32 v0, v118, v124
	global_store_dwordx4 v[110:111], v[106:109], off
	v_or_b32_e32 v0, v0, v131
	v_pk_mul_f32 v[104:105], v[104:105], v[146:147] op_sel_hi:[1,0]
	v_pk_mul_f32 v[102:103], v[102:103], v[146:147] op_sel_hi:[1,0]
	v_pk_mul_f32 v[106:107], v[96:97], v[146:147] op_sel_hi:[1,0]
	v_pk_mul_f32 v[96:97], v[94:95], v[146:147] op_sel_hi:[1,0]
	v_cvt_pk_bf16_f32 v94, v102, v103
	v_cvt_pk_bf16_f32 v95, v104, v105
	v_cvt_pk_bf16_f32 v96, v96, v97
	v_cvt_pk_bf16_f32 v97, v106, v107
	v_lshl_add_u64 v[102:103], v[0:1], 1, s[72:73]
	global_store_dwordx4 v[102:103], v[94:97], off
	v_or_b32_e32 v102, 0x800, v136
	v_add_u32_e32 v0, v102, v133
	v_or_b32_e32 v0, v0, v131
	v_pk_mul_f32 v[94:95], v[100:101], v[152:153] op_sel_hi:[1,0]
	v_pk_mul_f32 v[96:97], v[98:99], v[152:153] op_sel_hi:[1,0]
	v_pk_mul_f32 v[98:99], v[92:93], v[152:153] op_sel_hi:[1,0]
	v_pk_mul_f32 v[92:93], v[90:91], v[152:153] op_sel_hi:[1,0]
	v_cvt_pk_bf16_f32 v90, v96, v97
	v_cvt_pk_bf16_f32 v91, v94, v95
	v_cvt_pk_bf16_f32 v92, v92, v93
	v_cvt_pk_bf16_f32 v93, v98, v99
	v_lshl_add_u64 v[94:95], v[0:1], 1, s[72:73]
	v_add_u32_e32 v0, v102, v124
	global_store_dwordx4 v[94:95], v[90:93], off
	v_or_b32_e32 v0, v0, v131
	v_pk_mul_f32 v[88:89], v[88:89], v[152:153] op_sel_hi:[1,0]
	v_pk_mul_f32 v[86:87], v[86:87], v[152:153] op_sel_hi:[1,0]
	v_pk_mul_f32 v[90:91], v[80:81], v[152:153] op_sel_hi:[1,0]
	v_pk_mul_f32 v[80:81], v[78:79], v[152:153] op_sel_hi:[1,0]
	v_cvt_pk_bf16_f32 v78, v86, v87
	v_cvt_pk_bf16_f32 v79, v88, v89
	v_cvt_pk_bf16_f32 v80, v80, v81
	v_cvt_pk_bf16_f32 v81, v90, v91
	v_lshl_add_u64 v[86:87], v[0:1], 1, s[72:73]
	global_store_dwordx4 v[86:87], v[78:81], off
	v_or_b32_e32 v86, 0xc00, v136
	v_add_u32_e32 v0, v86, v133
	v_or_b32_e32 v0, v0, v131
	v_pk_mul_f32 v[78:79], v[84:85], v[148:149] op_sel_hi:[1,0]
	v_pk_mul_f32 v[80:81], v[82:83], v[148:149] op_sel_hi:[1,0]
	v_pk_mul_f32 v[82:83], v[76:77], v[148:149] op_sel_hi:[1,0]
	v_pk_mul_f32 v[76:77], v[74:75], v[148:149] op_sel_hi:[1,0]
	v_cvt_pk_bf16_f32 v74, v80, v81
	v_cvt_pk_bf16_f32 v75, v78, v79
	v_cvt_pk_bf16_f32 v76, v76, v77
	v_cvt_pk_bf16_f32 v77, v82, v83
	v_lshl_add_u64 v[78:79], v[0:1], 1, s[72:73]
	v_add_u32_e32 v0, v86, v124
	global_store_dwordx4 v[78:79], v[74:77], off
	v_or_b32_e32 v0, v0, v131
	v_pk_mul_f32 v[72:73], v[72:73], v[148:149] op_sel_hi:[1,0]
	v_pk_mul_f32 v[70:71], v[70:71], v[148:149] op_sel_hi:[1,0]
	v_pk_mul_f32 v[74:75], v[68:69], v[148:149] op_sel_hi:[1,0]
	v_pk_mul_f32 v[68:69], v[66:67], v[148:149] op_sel_hi:[1,0]
	v_cvt_pk_bf16_f32 v66, v70, v71
	v_cvt_pk_bf16_f32 v67, v72, v73
	v_cvt_pk_bf16_f32 v68, v68, v69
	v_cvt_pk_bf16_f32 v69, v74, v75
	v_lshl_add_u64 v[70:71], v[0:1], 1, s[72:73]
	v_add_u32_e32 v0, 0x80, v158
	global_store_dwordx4 v[70:71], v[66:69], off
	s_mov_b32 s2, 0x3ff8000
	s_nop 0
	v_lshlrev_b32_e32 v66, 4, v0
	v_and_b32_e32 v0, 0x7cf, v0
	v_and_or_b32 v0, v66, s2, v0
	v_lshlrev_b32_e32 v68, 6, v0
	v_add_u32_e32 v0, v68, v133
	v_or_b32_e32 v0, v0, v131
	v_pk_mul_f32 v[64:65], v[64:65], v[138:139] op_sel_hi:[1,0]
; DI u32x4 pk8(f32x4 a, f32x4 b) { u32x4 o; o.x = pk2(a.x, a.y); o.y = pk2(a.z, a.w); o.z = pk2(b.x, b.y); o.w = pk2(b.z, b.w); return o; }
; #define EPI_SCHED() __builtin_amdgcn_sched_barrier(0)
;     DI void operator()(const AccT& acc, const Unit& u, int wr, int wc, int fr, int fq) const {
;     ...
;         for (int ai = 0; ai < 2; ++ai)
; #pragma unroll
;             for (int m = 0; m < 4; ++m) {
;                 EPI_SCHED(); const size_t row = row0 + ai * 128 + m * 16;
; #pragma unroll
;                 for (int bj = 0; bj < 2; ++bj) {
;                     const int col = u.pn * 256 + bj * 128 + wc * 32 + fq * 8;
;                     const unsigned off = ((unsigned)(row >> 11) * 32768u + (unsigned)(row & 2047)) * 64u + (unsigned)(col >> 6) * 131072u + (unsigned)(col & 63);
;                     *(u32x4*)(out + off) = pk8(acc[ai][bj][m][0] * rs[ai][m], acc[ai][bj][m][1] * rs[ai][m]);
;                 }
	v_pk_mul_f32 v[62:63], v[62:63], v[138:139] op_sel_hi:[1,0]
	v_pk_mul_f32 v[66:67], v[60:61], v[138:139] op_sel_hi:[1,0]
	v_pk_mul_f32 v[60:61], v[58:59], v[138:139] op_sel_hi:[1,0]
	v_cvt_pk_bf16_f32 v58, v62, v63
	v_cvt_pk_bf16_f32 v59, v64, v65
	v_cvt_pk_bf16_f32 v60, v60, v61
	v_cvt_pk_bf16_f32 v61, v66, v67
	v_lshl_add_u64 v[62:63], v[0:1], 1, s[72:73]
	v_add_u32_e32 v0, v68, v124
	global_store_dwordx4 v[62:63], v[58:61], off
	v_or_b32_e32 v0, v0, v131
	v_pk_mul_f32 v[56:57], v[56:57], v[138:139] op_sel_hi:[1,0]
	v_pk_mul_f32 v[54:55], v[54:55], v[138:139] op_sel_hi:[1,0]
	v_pk_mul_f32 v[58:59], v[48:49], v[138:139] op_sel_hi:[1,0]
	v_pk_mul_f32 v[48:49], v[46:47], v[138:139] op_sel_hi:[1,0]
	v_cvt_pk_bf16_f32 v46, v54, v55
	v_cvt_pk_bf16_f32 v47, v56, v57
	v_cvt_pk_bf16_f32 v48, v48, v49
	v_cvt_pk_bf16_f32 v49, v58, v59
	v_lshl_add_u64 v[54:55], v[0:1], 1, s[72:73]
	global_store_dwordx4 v[54:55], v[46:49], off
	v_or_b32_e32 v54, 0x400, v68
	v_add_u32_e32 v0, v54, v133
	v_or_b32_e32 v0, v0, v131
	v_pk_mul_f32 v[46:47], v[52:53], v[140:141] op_sel_hi:[1,0]
	v_pk_mul_f32 v[48:49], v[50:51], v[140:141] op_sel_hi:[1,0]
	v_pk_mul_f32 v[50:51], v[44:45], v[140:141] op_sel_hi:[1,0]
	v_pk_mul_f32 v[44:45], v[42:43], v[140:141] op_sel_hi:[1,0]
	v_cvt_pk_bf16_f32 v42, v48, v49
	v_cvt_pk_bf16_f32 v43, v46, v47
	v_cvt_pk_bf16_f32 v44, v44, v45
	v_cvt_pk_bf16_f32 v45, v50, v51
	v_lshl_add_u64 v[46:47], v[0:1], 1, s[72:73]
	v_add_u32_e32 v0, v54, v124
	global_store_dwordx4 v[46:47], v[42:45], off
	v_or_b32_e32 v0, v0, v131
	v_pk_mul_f32 v[40:41], v[40:41], v[140:141] op_sel_hi:[1,0]
	v_pk_mul_f32 v[38:39], v[38:39], v[140:141] op_sel_hi:[1,0]
	v_pk_mul_f32 v[42:43], v[32:33], v[140:141] op_sel_hi:[1,0]
	v_pk_mul_f32 v[32:33], v[30:31], v[140:141] op_sel_hi:[1,0]
	v_cvt_pk_bf16_f32 v30, v38, v39
	v_cvt_pk_bf16_f32 v31, v40, v41
	v_cvt_pk_bf16_f32 v32, v32, v33
	v_cvt_pk_bf16_f32 v33, v42, v43
	v_lshl_add_u64 v[38:39], v[0:1], 1, s[72:73]
	global_store_dwordx4 v[38:39], v[30:33], off
	v_or_b32_e32 v38, 0x800, v68
	v_add_u32_e32 v0, v38, v133
	v_or_b32_e32 v0, v0, v131
	v_pk_mul_f32 v[30:31], v[36:37], v[132:133] op_sel_hi:[1,0]
	v_pk_mul_f32 v[32:33], v[34:35], v[132:133] op_sel_hi:[1,0]
	v_pk_mul_f32 v[34:35], v[28:29], v[132:133] op_sel_hi:[1,0]
	v_pk_mul_f32 v[28:29], v[26:27], v[132:133] op_sel_hi:[1,0]
	v_cvt_pk_bf16_f32 v26, v32, v33
	v_cvt_pk_bf16_f32 v27, v30, v31
	v_cvt_pk_bf16_f32 v28, v28, v29
	v_cvt_pk_bf16_f32 v29, v34, v35
	v_lshl_add_u64 v[30:31], v[0:1], 1, s[72:73]
	v_add_u32_e32 v0, v38, v124
	global_store_dwordx4 v[30:31], v[26:29], off
	v_or_b32_e32 v0, v0, v131
	v_pk_mul_f32 v[24:25], v[24:25], v[132:133] op_sel_hi:[1,0]
	v_pk_mul_f32 v[22:23], v[22:23], v[132:133] op_sel_hi:[1,0]
	v_pk_mul_f32 v[26:27], v[16:17], v[132:133] op_sel_hi:[1,0]
	v_pk_mul_f32 v[16:17], v[14:15], v[132:133] op_sel_hi:[1,0]
	v_cvt_pk_bf16_f32 v14, v22, v23
	v_cvt_pk_bf16_f32 v15, v24, v25
	v_cvt_pk_bf16_f32 v16, v16, v17
	v_cvt_pk_bf16_f32 v17, v26, v27
	v_lshl_add_u64 v[22:23], v[0:1], 1, s[72:73]
	global_store_dwordx4 v[22:23], v[14:17], off
	v_or_b32_e32 v22, 0xc00, v68
	v_add_u32_e32 v0, v22, v133
	v_or_b32_e32 v0, v0, v131
	v_pk_mul_f32 v[14:15], v[20:21], v[130:131] op_sel_hi:[1,0]
	v_pk_mul_f32 v[16:17], v[18:19], v[130:131] op_sel_hi:[1,0]
	v_pk_mul_f32 v[18:19], v[12:13], v[130:131] op_sel_hi:[1,0]
	v_pk_mul_f32 v[12:13], v[10:11], v[130:131] op_sel_hi:[1,0]
	v_cvt_pk_bf16_f32 v10, v16, v17
	v_cvt_pk_bf16_f32 v11, v14, v15
	v_cvt_pk_bf16_f32 v12, v12, v13
	v_cvt_pk_bf16_f32 v13, v18, v19
	v_lshl_add_u64 v[14:15], v[0:1], 1, s[72:73]
	v_add_u32_e32 v0, v22, v124
	global_store_dwordx4 v[14:15], v[10:13], off
	v_or_b32_e32 v0, v0, v131
	v_pk_mul_f32 v[8:9], v[8:9], v[130:131] op_sel_hi:[1,0]
	v_pk_mul_f32 v[6:7], v[6:7], v[130:131] op_sel_hi:[1,0]
	v_pk_mul_f32 v[10:11], v[4:5], v[130:131] op_sel_hi:[1,0]
	v_pk_mul_f32 v[4:5], v[2:3], v[130:131] op_sel_hi:[1,0]
	v_cvt_pk_bf16_f32 v2, v6, v7
	v_cvt_pk_bf16_f32 v3, v8, v9
	v_cvt_pk_bf16_f32 v4, v4, v5
	v_cvt_pk_bf16_f32 v5, v10, v11
	v_lshl_add_u64 v[6:7], v[0:1], 1, s[72:73]
	s_and_b64 vcc, exec, s[0:1]
	s_mov_b64 s[0:1], -1
	global_store_dwordx4 v[6:7], v[2:5], off
	s_cbranch_vccnz .LBB0_2718
	s_andn2_b64 vcc, exec, s[4:5]
	s_cbranch_vccnz .LBB0_2717
	s_barrier
	s_branch .LBB0_2717

; #define EPI_SCHED() __builtin_amdgcn_sched_barrier(0)
;     DI void operator()(const AccT& acc, const Unit& u, int wr, int wc, int fr, int fq) const {
; #pragma unroll
;         for (int bj = 0; bj < 2; ++bj) {
;             EPI_SCHED();
;             const size_t col = (size_t)u.pn * 256 + bj * 128 + wc * 32 + fq * 8;
;             f32x4 c0, c1;
;             if (NP4 == 1) {
;                 f32x4 v[8];
; #pragma unroll
;                 for (int e = 0; e < 8; ++e) v[e] = *(const f32x4*)(parts + (col + e) * STRIDE + P0);
; #pragma unroll
;                 for (int e = 0; e < 4; ++e) { c0[e] = rsqrtf(((v[e].x + v[e].y) + (v[e].z + v[e].w)) * invK + EPS); c1[e] = rsqrtf(((v[4 + e].x + v[4 + e].y) + (v[4 + e].z + v[4 + e].w)) * invK + EPS); }
.LBB0_2756:
	s_mov_b32 s2, -1
	s_ashr_i32 s25, s24, 31
	v_mbcnt_lo_u32_b32 v0, s2, 0
	v_mbcnt_hi_u32_b32 v0, s2, v0
	s_lshl_b64 s[2:3], s[24:25], 8
	v_ashrrev_i32_e32 v130, 1, v0
	v_and_b32_e32 v130, -8, v130
	v_ashrrev_i32_e32 v131, 31, v130
	s_or_b64 s[2:3], s[2:3], s[96:97]
	s_ashr_i32 s23, s22, 31
	v_lshl_add_u64 v[152:153], s[2:3], 0, v[130:131]
	s_lshl_b64 s[2:3], s[22:23], 8
	s_add_u32 s2, s2, s65
	s_addc_u32 s3, s3, s69
	v_and_or_b32 v146, v0, 15, s2
	v_mov_b32_e32 v147, s3
	v_mad_u64_u32 v[150:151], s[2:3], v152, 48, s[6:7]
	v_mad_i32_i24 v151, v153, 48, v151
	global_load_dwordx4 v[154:157], v[150:151], off
	global_load_dwordx4 v[164:167], v[150:151], off offset:48
	global_load_dwordx4 v[138:141], v[150:151], off offset:96
	global_load_dwordx4 v[142:145], v[150:151], off offset:144
	global_load_dwordx4 v[168:171], v[150:151], off offset:192
	global_load_dwordx4 v[172:175], v[150:151], off offset:240
	global_load_dwordx4 v[134:137], v[150:151], off offset:288
	global_load_dwordx4 v[130:133], v[150:151], off offset:336
	s_mov_b32 s2, 0x358637bd
	s_waitcnt vmcnt(0) lgkmcnt(0)
	v_mov_b32_e32 v148, v154
	v_mov_b32_e32 v149, v164
	v_mov_b32_e32 v164, v155
	v_mov_b32_e32 v154, v156
	v_mov_b32_e32 v155, v166
	v_mov_b32_e32 v166, v157
	v_pk_add_f32 v[148:149], v[148:149], v[164:165]
	v_pk_add_f32 v[154:155], v[154:155], v[166:167]
	v_mov_b32_e32 v164, v170
	v_pk_add_f32 v[154:155], v[148:149], v[154:155]
	v_mov_b64_e32 v[148:149], s[2:3]
	v_pk_fma_f32 v[154:155], v[154:155], s[86:87], v[148:149] op_sel_hi:[1,0,0]
	v_mov_b32_e32 v165, v174
	v_mul_f32_e32 v0, 0x4b800000, v154
	v_cmp_gt_f32_e64 s[2:3], s42, v154
	v_cmp_gt_f32_e32 vcc, s42, v155
	v_mov_b32_e32 v174, v171
	v_cndmask_b32_e64 v0, v154, v0, s[2:3]
	v_rsq_f32_e32 v154, v0
	v_mul_f32_e32 v0, 0x4b800000, v155
	v_cndmask_b32_e32 v0, v155, v0, vcc
	v_rsq_f32_e32 v155, v0
	v_pk_add_f32 v[164:165], v[164:165], v[174:175]
	v_pk_mul_f32 v[156:157], v[154:155], s[52:53] op_sel_hi:[1,0]
	s_nop 0
	v_cndmask_b32_e32 v155, v155, v157, vcc
	v_cndmask_b32_e64 v154, v154, v156, s[2:3]
	v_mov_b32_e32 v156, v168
	v_mov_b32_e32 v157, v172
	v_mov_b32_e32 v172, v169
	v_pk_add_f32 v[156:157], v[156:157], v[172:173]
	v_pk_mul_f32 v[126:127], v[126:127], v[154:155]
	v_pk_add_f32 v[156:157], v[156:157], v[164:165]
	v_pk_mul_f32 v[118:119], v[118:119], v[154:155]
	v_pk_fma_f32 v[156:157], v[156:157], s[86:87], v[148:149] op_sel_hi:[1,0,0]
	v_pk_mul_f32 v[110:111], v[110:111], v[154:155]
	v_mul_f32_e32 v0, 0x4b800000, v156
	v_cmp_gt_f32_e64 s[2:3], s42, v156
	v_cmp_gt_f32_e32 vcc, s42, v157
	v_pk_mul_f32 v[102:103], v[102:103], v[154:155]
	v_cndmask_b32_e64 v0, v156, v0, s[2:3]
	v_rsq_f32_e32 v156, v0
	v_mul_f32_e32 v0, 0x4b800000, v157
	v_cndmask_b32_e32 v0, v157, v0, vcc
	v_rsq_f32_e32 v157, v0
	v_cvt_pk_bf16_f32 v102, v102, v103
	v_pk_mul_f32 v[94:95], v[94:95], v[154:155]
	v_pk_mul_f32 v[86:87], v[86:87], v[154:155]
	v_pk_mul_f32 v[164:165], v[156:157], s[52:53] op_sel_hi:[1,0]
	v_pk_mul_f32 v[78:79], v[78:79], v[154:155]
	v_cndmask_b32_e32 v157, v157, v165, vcc
	v_cndmask_b32_e64 v156, v156, v164, s[2:3]
	v_mov_b32_e32 v164, v138
	v_mov_b32_e32 v165, v142
	v_mov_b32_e32 v142, v139
	v_pk_add_f32 v[138:139], v[164:165], v[142:143]
	v_mov_b32_e32 v142, v140
	v_mov_b32_e32 v143, v144
	v_mov_b32_e32 v144, v141
	v_pk_add_f32 v[140:141], v[142:143], v[144:145]
	v_pk_mul_f32 v[122:123], v[122:123], v[156:157]
	v_pk_add_f32 v[138:139], v[138:139], v[140:141]
	v_pk_mul_f32 v[114:115], v[114:115], v[156:157]
	v_pk_fma_f32 v[138:139], v[138:139], s[86:87], v[148:149] op_sel_hi:[1,0,0]
	v_pk_mul_f32 v[106:107], v[106:107], v[156:157]
	v_mul_f32_e32 v0, 0x4b800000, v138
	v_cmp_gt_f32_e64 s[2:3], s42, v138
	v_cmp_gt_f32_e32 vcc, s42, v139
	v_pk_mul_f32 v[98:99], v[98:99], v[156:157]
	v_cndmask_b32_e64 v0, v138, v0, s[2:3]
	v_rsq_f32_e32 v138, v0
	v_mul_f32_e32 v0, 0x4b800000, v139
	v_cndmask_b32_e32 v0, v139, v0, vcc
	v_rsq_f32_e32 v139, v0
	v_pk_mul_f32 v[82:83], v[82:83], v[156:157]
	v_pk_mul_f32 v[74:75], v[74:75], v[156:157]
	v_pk_mul_f32 v[70:71], v[70:71], v[154:155]
	v_pk_mul_f32 v[140:141], v[138:139], s[52:53] op_sel_hi:[1,0]
	s_nop 0
	v_cndmask_b32_e32 v139, v139, v141, vcc
	v_cndmask_b32_e64 v138, v138, v140, s[2:3]
	v_mov_b32_e32 v140, v134
	v_mov_b32_e32 v141, v130
	v_mov_b32_e32 v130, v135
	v_mov_b32_e32 v134, v136
	v_mov_b32_e32 v135, v132
	v_mov_b32_e32 v132, v137
	v_pk_add_f32 v[130:131], v[140:141], v[130:131]
	v_pk_add_f32 v[132:133], v[134:135], v[132:133]
	v_pk_mul_f32 v[128:129], v[128:129], v[138:139]
	v_pk_add_f32 v[130:131], v[130:131], v[132:133]
	v_and_b32_e32 v136, 0x7f8, v152
	v_pk_fma_f32 v[130:131], v[130:131], s[86:87], v[148:149] op_sel_hi:[1,0,0]
	v_pk_mul_f32 v[120:121], v[120:121], v[138:139]
	v_mul_f32_e32 v0, 0x4b800000, v130
	v_cmp_gt_f32_e64 s[2:3], s42, v130
	v_cmp_gt_f32_e32 vcc, s42, v131
	v_pk_mul_f32 v[112:113], v[112:113], v[138:139]
	v_cndmask_b32_e64 v0, v130, v0, s[2:3]
	v_rsq_f32_e32 v130, v0
	v_mul_f32_e32 v0, 0x4b800000, v131
	v_cndmask_b32_e32 v0, v131, v0, vcc
	v_rsq_f32_e32 v131, v0
	v_pk_mul_f32 v[104:105], v[104:105], v[138:139]
	v_pk_mul_f32 v[96:97], v[96:97], v[138:139]
	v_cvt_pk_bf16_f32 v103, v104, v105
	v_pk_mul_f32 v[132:133], v[130:131], s[52:53] op_sel_hi:[1,0]
	v_cvt_pk_bf16_f32 v104, v98, v99
	v_cndmask_b32_e32 v131, v131, v133, vcc
	v_cndmask_b32_e64 v130, v130, v132, s[2:3]
	v_pk_mul_f32 v[132:133], v[124:125], v[130:131]
	v_cvt_pk_bf16_f32 v124, v126, v127
	v_cvt_pk_bf16_f32 v126, v122, v123
	v_lshrrev_b64 v[122:123], 1, v[152:153]
	v_cvt_pk_bf16_f32 v125, v128, v129
	v_and_b32_e32 v129, 0x7fffffff, v123
	v_and_b32_e32 v128, 0xfffffc00, v122
; DI u32x4 pk8(f32x4 a, f32x4 b) { u32x4 o; o.x = pk2(a.x, a.y); o.y = pk2(a.z, a.w); o.z = pk2(b.x, b.y); o.w = pk2(b.z, b.w); return o; }
;     DI void operator()(const AccT& acc, const Unit& u, int wr, int wc, int fr, int fq) const {
;     ...
;             const size_t col = (size_t)u.pn * 256 + bj * 128 + wc * 32 + fq * 8;
;             f32x4 c0, c1;
;             if (NP4 == 1) {
;                 f32x4 v[8];
; #pragma unroll
;                 for (int e = 0; e < 8; ++e) v[e] = *(const f32x4*)(parts + (col + e) * STRIDE + P0);
; #pragma unroll
;                 for (int e = 0; e < 4; ++e) { c0[e] = rsqrtf(((v[e].x + v[e].y) + (v[e].z + v[e].w)) * invK + EPS); c1[e] = rsqrtf(((v[4 + e].x + v[4 + e].y) + (v[4 + e].z + v[4 + e].w)) * invK + EPS); }
;     ...
; #pragma unroll
;             for (int ai = 0; ai < 2; ++ai)
; #pragma unroll
;                 for (int m = 0; m < 4; ++m) {
;                     const size_t row = (size_t)u.pm * 256 + ai * 128 + wr * 64 + m * 16 + fr;
;                     *(u32x4*)(out + ((col >> 11) * nrows + row) * VPITCH + (col & 2047)) = pk8(acc[ai][bj][m][0] * c0, acc[ai][bj][m][1] * c1);
;                 }
	v_cvt_pk_bf16_f32 v127, v132, v133
	v_lshl_add_u64 v[132:133], v[128:129], 0, v[146:147]
	v_mov_b64_e32 v[122:123], s[8:9]
	v_mad_u64_u32 v[134:135], s[2:3], v132, s43, v[122:123]
	v_mov_b32_e32 v0, v135
	v_mad_u64_u32 v[132:133], s[2:3], v133, s43, v[0:1]
	v_mov_b32_e32 v135, v132
	v_lshlrev_b32_e32 v0, 1, v136
	v_lshl_add_u64 v[132:133], v[134:135], 0, v[0:1]
	global_store_dwordx4 v[132:133], v[124:127], off
	v_pk_mul_f32 v[100:101], v[100:101], v[130:131]
	v_pk_mul_f32 v[88:89], v[88:89], v[138:139]
	v_pk_mul_f32 v[124:125], v[116:117], v[130:131]
	v_cvt_pk_bf16_f32 v116, v118, v119
	v_cvt_pk_bf16_f32 v118, v114, v115
	v_or_b32_e32 v114, 16, v146
	v_mov_b32_e32 v115, v147
	v_cvt_pk_bf16_f32 v117, v120, v121
	v_lshl_add_u64 v[120:121], v[128:129], 0, v[114:115]
	v_cvt_pk_bf16_f32 v119, v124, v125
	v_mad_u64_u32 v[124:125], s[2:3], v120, s43, v[122:123]
	v_mov_b32_e32 v120, v125
	v_mad_u64_u32 v[120:121], s[2:3], v121, s43, v[120:121]
	v_mov_b32_e32 v125, v120
	v_lshl_add_u64 v[120:121], v[124:125], 0, v[0:1]
	global_store_dwordx4 v[120:121], v[116:119], off
	v_cvt_pk_bf16_f32 v105, v100, v101
	v_or_b32_e32 v100, 48, v146
	v_pk_mul_f32 v[116:117], v[108:109], v[130:131]
	v_cvt_pk_bf16_f32 v108, v110, v111
	v_cvt_pk_bf16_f32 v110, v106, v107
	v_or_b32_e32 v106, 32, v146
	v_mov_b32_e32 v107, v147
	v_cvt_pk_bf16_f32 v109, v112, v113
	v_lshl_add_u64 v[112:113], v[128:129], 0, v[106:107]
	v_cvt_pk_bf16_f32 v111, v116, v117
	v_mad_u64_u32 v[116:117], s[2:3], v112, s43, v[122:123]
	v_mov_b32_e32 v112, v117
	v_mad_u64_u32 v[112:113], s[2:3], v113, s43, v[112:113]
	v_mov_b32_e32 v117, v112
	v_mov_b32_e32 v101, v147
	v_lshl_add_u64 v[112:113], v[116:117], 0, v[0:1]
	v_lshl_add_u64 v[98:99], v[128:129], 0, v[100:101]
	global_store_dwordx4 v[112:113], v[108:111], off
	v_pk_mul_f32 v[80:81], v[80:81], v[138:139]
	v_pk_mul_f32 v[72:73], v[72:73], v[138:139]
	v_mad_u64_u32 v[108:109], s[2:3], v98, s43, v[122:123]
	v_mov_b32_e32 v98, v109
	v_mad_u64_u32 v[98:99], s[2:3], v99, s43, v[98:99]
	v_mov_b32_e32 v109, v98
	v_lshl_add_u64 v[98:99], v[108:109], 0, v[0:1]
	global_store_dwordx4 v[98:99], v[102:105], off
	v_lshl_add_u64 v[98:99], v[146:147], 0, s[58:59]
	s_nop 0
	v_pk_mul_f32 v[102:103], v[92:93], v[130:131]
	v_pk_mul_f32 v[92:93], v[90:91], v[156:157]
	v_cvt_pk_bf16_f32 v90, v94, v95
	v_lshl_add_u64 v[94:95], v[128:129], 0, v[98:99]
	v_cvt_pk_bf16_f32 v91, v96, v97
	v_mad_u64_u32 v[96:97], s[2:3], v94, s43, v[122:123]
	v_mov_b32_e32 v94, v97
	v_mad_u64_u32 v[94:95], s[2:3], v95, s43, v[94:95]
	v_mov_b32_e32 v97, v94
	v_cvt_pk_bf16_f32 v92, v92, v93
	v_cvt_pk_bf16_f32 v93, v102, v103
	v_lshl_add_u64 v[94:95], v[96:97], 0, v[0:1]
	s_mov_b64 s[2:3], 0x90
	global_store_dwordx4 v[94:95], v[90:93], off
	s_nop 1
	v_pk_mul_f32 v[90:91], v[84:85], v[130:131]
	v_cvt_pk_bf16_f32 v84, v86, v87
	v_cvt_pk_bf16_f32 v86, v82, v83
	v_lshl_add_u64 v[82:83], v[146:147], 0, s[2:3]
	v_cvt_pk_bf16_f32 v85, v88, v89
	v_lshl_add_u64 v[88:89], v[128:129], 0, v[82:83]
	v_cvt_pk_bf16_f32 v87, v90, v91
	v_mad_u64_u32 v[90:91], s[2:3], v88, s43, v[122:123]
	v_mov_b32_e32 v88, v91
	v_mad_u64_u32 v[88:89], s[2:3], v89, s43, v[88:89]
	v_mov_b32_e32 v91, v88
	v_lshl_add_u64 v[88:89], v[90:91], 0, v[0:1]
	s_mov_b64 s[2:3], 0xa0
	global_store_dwordx4 v[88:89], v[84:87], off
	s_nop 1
	v_pk_mul_f32 v[84:85], v[76:77], v[130:131]
	v_cvt_pk_bf16_f32 v76, v78, v79
	v_cvt_pk_bf16_f32 v78, v74, v75
	v_lshl_add_u64 v[74:75], v[146:147], 0, s[2:3]
	v_cvt_pk_bf16_f32 v77, v80, v81
	v_lshl_add_u64 v[80:81], v[128:129], 0, v[74:75]
	v_cvt_pk_bf16_f32 v79, v84, v85
	v_mad_u64_u32 v[84:85], s[2:3], v80, s43, v[122:123]
	v_mov_b32_e32 v80, v85
	v_mad_u64_u32 v[80:81], s[2:3], v81, s43, v[80:81]
	v_mov_b32_e32 v85, v80
	v_lshl_add_u64 v[80:81], v[84:85], 0, v[0:1]
	global_store_dwordx4 v[80:81], v[76:79], off
	s_mov_b64 s[2:3], 0xb0
	s_nop 0
	v_pk_mul_f32 v[76:77], v[68:69], v[130:131]
	v_pk_mul_f32 v[68:69], v[66:67], v[156:157]
	v_cvt_pk_bf16_f32 v66, v70, v71
	v_cvt_pk_bf16_f32 v68, v68, v69
	v_cvt_pk_bf16_f32 v69, v76, v77
	v_lshl_add_u64 v[76:77], v[146:147], 0, s[2:3]
	v_lshl_add_u64 v[70:71], v[128:129], 0, v[76:77]
	v_cvt_pk_bf16_f32 v67, v72, v73
	v_mad_u64_u32 v[72:73], s[2:3], v70, s43, v[122:123]
	v_mov_b32_e32 v70, v73
	v_mad_u64_u32 v[70:71], s[2:3], v71, s43, v[70:71]
	v_mov_b32_e32 v73, v70
	v_lshl_add_u64 v[70:71], v[72:73], 0, v[0:1]
	global_store_dwordx4 v[70:71], v[66:69], off
	v_lshl_add_u64 v[80:81], v[152:153], 0, s[58:59]
	s_nop 0
	v_mad_u64_u32 v[66:67], s[2:3], v80, 48, s[6:7]
	v_mad_i32_i24 v67, v81, 48, v67
	global_load_dwordx4 v[84:87], v[66:67], off
	s_movk_i32 s2, 0x1000
	v_add_co_u32_e32 v66, vcc, s2, v150
	s_waitcnt vmcnt(0) lgkmcnt(0)
	v_mov_b32_e32 v78, v84
	v_addc_co_u32_e32 v67, vcc, 0, v151, vcc
	global_load_dwordx4 v[88:91], v[66:67], off offset:2096
	global_load_dwordx4 v[92:95], v[66:67], off offset:2144
	global_load_dwordx4 v[102:105], v[66:67], off offset:2192
	global_load_dwordx4 v[108:111], v[66:67], off offset:2240
	global_load_dwordx4 v[116:119], v[66:67], off offset:2288
	global_load_dwordx4 v[70:73], v[66:67], off offset:2336
	s_nop 0
	global_load_dwordx4 v[66:69], v[66:67], off offset:2384
	v_mov_b32_e32 v84, v86
	s_waitcnt vmcnt(0) lgkmcnt(0)
;     DI void operator()(const AccT& acc, const Unit& u, int wr, int wc, int fr, int fq) const {
;     ...
;             if (NP4 == 1) {
;                 f32x4 v[8];
; #pragma unroll
;                 for (int e = 0; e < 8; ++e) v[e] = *(const f32x4*)(parts + (col + e) * STRIDE + P0);
; #pragma unroll
;                 for (int e = 0; e < 4; ++e) { c0[e] = rsqrtf(((v[e].x + v[e].y) + (v[e].z + v[e].w)) * invK + EPS); c1[e] = rsqrtf(((v[4 + e].x + v[4 + e].y) + (v[4 + e].z + v[4 + e].w)) * invK + EPS); }
	v_mov_b32_e32 v79, v88
	v_mov_b32_e32 v88, v85
	v_mov_b32_e32 v85, v90
	v_mov_b32_e32 v90, v87
	v_pk_add_f32 v[78:79], v[78:79], v[88:89]
	v_pk_add_f32 v[84:85], v[84:85], v[90:91]
	v_mov_b32_e32 v86, v110
	v_pk_add_f32 v[78:79], v[78:79], v[84:85]
	v_mov_b32_e32 v87, v118
	v_pk_fma_f32 v[78:79], v[78:79], s[86:87], v[148:149] op_sel_hi:[1,0,0]
	v_mov_b32_e32 v118, v111
	v_mul_f32_e32 v0, 0x4b800000, v78
	v_cmp_gt_f32_e64 s[2:3], s42, v78
	v_cmp_gt_f32_e32 vcc, s42, v79
	v_pk_add_f32 v[86:87], v[86:87], v[118:119]
	v_cndmask_b32_e64 v0, v78, v0, s[2:3]
	v_rsq_f32_e32 v78, v0
	v_mul_f32_e32 v0, 0x4b800000, v79
	v_cndmask_b32_e32 v0, v79, v0, vcc
	v_rsq_f32_e32 v79, v0
	v_mov_b32_e32 v88, v94
	v_mov_b32_e32 v89, v104
	v_mov_b32_e32 v104, v95
	v_pk_mul_f32 v[84:85], v[78:79], s[52:53] op_sel_hi:[1,0]
	v_pk_add_f32 v[88:89], v[88:89], v[104:105]
	v_cndmask_b32_e32 v79, v79, v85, vcc
	v_cndmask_b32_e64 v78, v78, v84, s[2:3]
	v_mov_b32_e32 v84, v108
	v_mov_b32_e32 v85, v116
	v_mov_b32_e32 v116, v109
	v_pk_add_f32 v[84:85], v[84:85], v[116:117]
	v_pk_mul_f32 v[62:63], v[62:63], v[78:79]
	v_pk_add_f32 v[84:85], v[84:85], v[86:87]
	v_pk_mul_f32 v[54:55], v[54:55], v[78:79]
	v_pk_fma_f32 v[84:85], v[84:85], s[86:87], v[148:149] op_sel_hi:[1,0,0]
	v_pk_mul_f32 v[46:47], v[46:47], v[78:79]
	v_mul_f32_e32 v0, 0x4b800000, v84
	v_cmp_gt_f32_e64 s[2:3], s42, v84
	v_cmp_gt_f32_e32 vcc, s42, v85
	v_pk_mul_f32 v[38:39], v[38:39], v[78:79]
	v_cndmask_b32_e64 v0, v84, v0, s[2:3]
	v_rsq_f32_e32 v84, v0
	v_mul_f32_e32 v0, 0x4b800000, v85
	v_cndmask_b32_e32 v0, v85, v0, vcc
	v_rsq_f32_e32 v85, v0
	v_pk_mul_f32 v[30:31], v[30:31], v[78:79]
	v_pk_mul_f32 v[22:23], v[22:23], v[78:79]
	v_pk_mul_f32 v[14:15], v[14:15], v[78:79]
	v_pk_mul_f32 v[86:87], v[84:85], s[52:53] op_sel_hi:[1,0]
	v_pk_mul_f32 v[6:7], v[6:7], v[78:79]
	v_cndmask_b32_e32 v85, v85, v87, vcc
	v_cndmask_b32_e64 v84, v84, v86, s[2:3]
	v_mov_b32_e32 v86, v92
	v_mov_b32_e32 v87, v102
	v_mov_b32_e32 v102, v93
	v_pk_add_f32 v[86:87], v[86:87], v[102:103]
	s_nop 0
	v_pk_add_f32 v[86:87], v[86:87], v[88:89]
	s_nop 0
	v_pk_fma_f32 v[86:87], v[86:87], s[86:87], v[148:149] op_sel_hi:[1,0,0]
	s_nop 0
	v_mul_f32_e32 v0, 0x4b800000, v86
	v_cmp_gt_f32_e64 s[2:3], s42, v86
	v_cmp_gt_f32_e32 vcc, s42, v87
	s_nop 0
	v_cndmask_b32_e64 v0, v86, v0, s[2:3]
	v_rsq_f32_e32 v86, v0
	v_mul_f32_e32 v0, 0x4b800000, v87
	v_cndmask_b32_e32 v0, v87, v0, vcc
	v_rsq_f32_e32 v87, v0
	s_nop 0
	v_pk_mul_f32 v[88:89], v[86:87], s[52:53] op_sel_hi:[1,0]
	s_nop 0
	v_cndmask_b32_e32 v87, v87, v89, vcc
	v_cndmask_b32_e64 v86, v86, v88, s[2:3]
	v_mov_b32_e32 v88, v70
	v_mov_b32_e32 v89, v66
	v_mov_b32_e32 v66, v71
	v_mov_b32_e32 v70, v72
	v_mov_b32_e32 v71, v68
	v_mov_b32_e32 v68, v73
	v_pk_add_f32 v[66:67], v[88:89], v[66:67]
	v_pk_add_f32 v[68:69], v[70:71], v[68:69]
	v_pk_mul_f32 v[64:65], v[64:65], v[86:87]
	v_pk_add_f32 v[66:67], v[66:67], v[68:69]
	v_and_b32_e32 v70, 0x7f8, v80
	v_pk_fma_f32 v[66:67], v[66:67], s[86:87], v[148:149] op_sel_hi:[1,0,0]
	v_pk_mul_f32 v[56:57], v[56:57], v[86:87]
	v_mul_f32_e32 v0, 0x4b800000, v66
	v_cmp_gt_f32_e64 s[2:3], s42, v66
	v_cmp_gt_f32_e32 vcc, s42, v67
	v_pk_mul_f32 v[48:49], v[48:49], v[86:87]
	v_cndmask_b32_e64 v0, v66, v0, s[2:3]
	v_rsq_f32_e32 v66, v0
	v_mul_f32_e32 v0, 0x4b800000, v67
	v_cndmask_b32_e32 v0, v67, v0, vcc
	v_rsq_f32_e32 v67, v0
	v_pk_mul_f32 v[40:41], v[40:41], v[86:87]
	v_pk_mul_f32 v[32:33], v[32:33], v[86:87]
	v_pk_mul_f32 v[24:25], v[24:25], v[86:87]
	v_pk_mul_f32 v[68:69], v[66:67], s[52:53] op_sel_hi:[1,0]
	v_pk_mul_f32 v[16:17], v[16:17], v[86:87]
	v_cndmask_b32_e32 v67, v67, v69, vcc
	v_cndmask_b32_e64 v66, v66, v68, s[2:3]
	v_pk_mul_f32 v[68:69], v[60:61], v[66:67]
	v_pk_mul_f32 v[60:61], v[58:59], v[84:85]
	v_cvt_pk_bf16_f32 v58, v62, v63
	v_lshrrev_b64 v[62:63], 1, v[80:81]
	v_and_b32_e32 v63, 0x7fffffff, v63
	v_and_b32_e32 v62, 0xfffffc00, v62
	v_cvt_pk_bf16_f32 v59, v64, v65
	v_lshl_add_u64 v[64:65], v[62:63], 0, v[146:147]
	v_cvt_pk_bf16_f32 v60, v60, v61
	v_cvt_pk_bf16_f32 v61, v68, v69
; DI u32x4 pk8(f32x4 a, f32x4 b) { u32x4 o; o.x = pk2(a.x, a.y); o.y = pk2(a.z, a.w); o.z = pk2(b.x, b.y); o.w = pk2(b.z, b.w); return o; }
;     DI void operator()(const AccT& acc, const Unit& u, int wr, int wc, int fr, int fq) const {
;     ...
; #pragma unroll
;             for (int ai = 0; ai < 2; ++ai)
; #pragma unroll
;                 for (int m = 0; m < 4; ++m) {
;                     const size_t row = (size_t)u.pm * 256 + ai * 128 + wr * 64 + m * 16 + fr;
;                     *(u32x4*)(out + ((col >> 11) * nrows + row) * VPITCH + (col & 2047)) = pk8(acc[ai][bj][m][0] * c0, acc[ai][bj][m][1] * c1);
;                 }
	v_mad_u64_u32 v[68:69], s[2:3], v64, s43, v[122:123]
	v_mov_b32_e32 v0, v69
	v_mad_u64_u32 v[64:65], s[2:3], v65, s43, v[0:1]
	v_mov_b32_e32 v69, v64
	v_lshlrev_b32_e32 v0, 1, v70
	v_lshl_add_u64 v[64:65], v[68:69], 0, v[0:1]
	global_store_dwordx4 v[64:65], v[58:61], off
	v_pk_mul_f32 v[8:9], v[8:9], v[86:87]
	s_and_b64 vcc, exec, s[0:1]
	v_pk_mul_f32 v[58:59], v[52:53], v[66:67]
	v_pk_mul_f32 v[52:53], v[50:51], v[84:85]
	v_cvt_pk_bf16_f32 v50, v54, v55
	v_lshl_add_u64 v[54:55], v[62:63], 0, v[114:115]
	v_cvt_pk_bf16_f32 v51, v56, v57
	v_mad_u64_u32 v[56:57], s[2:3], v54, s43, v[122:123]
	v_mov_b32_e32 v54, v57
	v_mad_u64_u32 v[54:55], s[2:3], v55, s43, v[54:55]
	v_mov_b32_e32 v57, v54
	v_cvt_pk_bf16_f32 v52, v52, v53
	v_cvt_pk_bf16_f32 v53, v58, v59
	v_lshl_add_u64 v[54:55], v[56:57], 0, v[0:1]
	global_store_dwordx4 v[54:55], v[50:53], off
	s_nop 1
	v_pk_mul_f32 v[50:51], v[44:45], v[66:67]
	v_pk_mul_f32 v[44:45], v[42:43], v[84:85]
	v_cvt_pk_bf16_f32 v42, v46, v47
	v_lshl_add_u64 v[46:47], v[62:63], 0, v[106:107]
	v_cvt_pk_bf16_f32 v43, v48, v49
	v_mad_u64_u32 v[48:49], s[2:3], v46, s43, v[122:123]
	v_mov_b32_e32 v46, v49
	v_mad_u64_u32 v[46:47], s[2:3], v47, s43, v[46:47]
	v_mov_b32_e32 v49, v46
	v_cvt_pk_bf16_f32 v44, v44, v45
	v_cvt_pk_bf16_f32 v45, v50, v51
	v_lshl_add_u64 v[46:47], v[48:49], 0, v[0:1]
	global_store_dwordx4 v[46:47], v[42:45], off
	s_nop 1
	v_pk_mul_f32 v[42:43], v[36:37], v[66:67]
	v_pk_mul_f32 v[36:37], v[34:35], v[84:85]
	v_cvt_pk_bf16_f32 v34, v38, v39
	v_lshl_add_u64 v[38:39], v[62:63], 0, v[100:101]
	v_cvt_pk_bf16_f32 v35, v40, v41
	v_mad_u64_u32 v[40:41], s[2:3], v38, s43, v[122:123]
	v_mov_b32_e32 v38, v41
	v_mad_u64_u32 v[38:39], s[2:3], v39, s43, v[38:39]
	v_mov_b32_e32 v41, v38
	v_cvt_pk_bf16_f32 v36, v36, v37
	v_cvt_pk_bf16_f32 v37, v42, v43
	v_lshl_add_u64 v[38:39], v[40:41], 0, v[0:1]
	global_store_dwordx4 v[38:39], v[34:37], off
	s_nop 1
	v_pk_mul_f32 v[34:35], v[28:29], v[66:67]
	v_pk_mul_f32 v[28:29], v[26:27], v[84:85]
	v_cvt_pk_bf16_f32 v26, v30, v31
	v_lshl_add_u64 v[30:31], v[62:63], 0, v[98:99]
	v_cvt_pk_bf16_f32 v27, v32, v33
	v_mad_u64_u32 v[32:33], s[2:3], v30, s43, v[122:123]
	v_mov_b32_e32 v30, v33
	v_mad_u64_u32 v[30:31], s[2:3], v31, s43, v[30:31]
	v_mov_b32_e32 v33, v30
	v_cvt_pk_bf16_f32 v28, v28, v29
	v_cvt_pk_bf16_f32 v29, v34, v35
	v_lshl_add_u64 v[30:31], v[32:33], 0, v[0:1]
	global_store_dwordx4 v[30:31], v[26:29], off
	s_nop 1
	v_pk_mul_f32 v[26:27], v[20:21], v[66:67]
	v_pk_mul_f32 v[20:21], v[18:19], v[84:85]
	v_cvt_pk_bf16_f32 v18, v22, v23
	v_lshl_add_u64 v[22:23], v[62:63], 0, v[82:83]
	v_cvt_pk_bf16_f32 v19, v24, v25
	v_mad_u64_u32 v[24:25], s[2:3], v22, s43, v[122:123]
	v_mov_b32_e32 v22, v25
	v_mad_u64_u32 v[22:23], s[2:3], v23, s43, v[22:23]
	v_mov_b32_e32 v25, v22
	v_cvt_pk_bf16_f32 v20, v20, v21
	v_cvt_pk_bf16_f32 v21, v26, v27
	v_lshl_add_u64 v[22:23], v[24:25], 0, v[0:1]
	global_store_dwordx4 v[22:23], v[18:21], off
	s_nop 1
	v_pk_mul_f32 v[18:19], v[12:13], v[66:67]
	v_pk_mul_f32 v[12:13], v[10:11], v[84:85]
	v_cvt_pk_bf16_f32 v10, v14, v15
	v_lshl_add_u64 v[14:15], v[62:63], 0, v[74:75]
	v_cvt_pk_bf16_f32 v11, v16, v17
	v_mad_u64_u32 v[16:17], s[2:3], v14, s43, v[122:123]
	v_mov_b32_e32 v14, v17
	v_mad_u64_u32 v[14:15], s[2:3], v15, s43, v[14:15]
	v_mov_b32_e32 v17, v14
	v_cvt_pk_bf16_f32 v12, v12, v13
	v_cvt_pk_bf16_f32 v13, v18, v19
	v_lshl_add_u64 v[14:15], v[16:17], 0, v[0:1]
	global_store_dwordx4 v[14:15], v[10:13], off
	s_nop 1
	v_pk_mul_f32 v[10:11], v[4:5], v[66:67]
	v_pk_mul_f32 v[4:5], v[2:3], v[84:85]
	v_cvt_pk_bf16_f32 v2, v6, v7
	v_lshl_add_u64 v[6:7], v[62:63], 0, v[76:77]
	v_cvt_pk_bf16_f32 v3, v8, v9
	v_mad_u64_u32 v[8:9], s[2:3], v6, s43, v[122:123]
	v_mov_b32_e32 v6, v9
	v_mad_u64_u32 v[6:7], s[2:3], v7, s43, v[6:7]
	v_mov_b32_e32 v9, v6
	v_cvt_pk_bf16_f32 v4, v4, v5
	v_cvt_pk_bf16_f32 v5, v10, v11
	v_lshl_add_u64 v[6:7], v[8:9], 0, v[0:1]
	s_mov_b64 s[2:3], -1
	global_store_dwordx4 v[6:7], v[2:5], off
	s_cbranch_vccnz .LBB0_2743
	s_andn2_b64 vcc, exec, s[4:5]
	s_cbranch_vccnz .LBB0_2742
	s_barrier
	s_branch .LBB0_2742

; DI int opaque_tid(int wv) { unsigned ones = ~0u; asm volatile("" : "+s"(ones)); int t = wv * 64 + (int)__builtin_amdgcn_mbcnt_hi(ones, __builtin_amdgcn_mbcnt_lo(ones, 0u)); asm volatile("" : "+v"(t)); return t; }
; DI float frcp(float x) { return __builtin_amdgcn_rcpf(x); }
; DI f32x16 zero16() { f32x16 z; for (int i = 0; i < 16; ++i) z[i] = 0.f; return z; }
; DI void mla_qblock(int wv, int w, LAS unsigned char* lds, const bf16_t* Q, const bf16_t* KN, const bf16_t* KR, const bf16_t* VT, bf16_t* O, size_t tok0, int h, int qb) {
;     ...
;     const int tid = opaque_tid(wv), lane = tid & 63, r = lane & 31, hh = lane >> 5;
;     const int R0 = 512 * qb + 64 * w, tq0 = R0 + r, tq1 = tq0 + 32;
;     bf16x8 q0[6], q1[6];
; #pragma unroll
;     for (int ks = 0; ks < 6; ++ks) { q0[ks] = *(const bf16x8*)(Q + (tok0 + tq0) * 1536 + h * 96 + 16 * ks + 8 * hh); q1[ks] = *(const bf16x8*)(Q + (tok0 + tq1) * 1536 + h * 96 + 16 * ks + 8 * hh); }
;     float m0 = 0.f, l0 = 0.f, m1 = 0.f, l1 = 0.f; f32x16 o0[2] = {zero16(), zero16()}, o1[2] = {zero16(), zero16()};
;     const int nt = 8 * qb + 8, nfull = 8 * qb;
;     u32x4 rk, rr, rv;
;     const bf16_t* gk = KN + ((tok0 >> 11) * 16 + h) * (size_t)(2048 * 64) + (size_t)tid * 8;
;     const bf16_t* gr = KR + tok0 * 32 + (size_t)tid * 8;
;     const bf16_t* gv = VT + ((tok0 >> 11) * 1024 + h * 64 + (tid >> 3)) * (size_t)VPITCH + (tid & 7) * 8;
;     const bool lo256 = tid < 256;
;     ...
;     store_ot(o0, frcp(l0), O + (tok0 + tq0) * 1024 + h * 64, hh);
;     store_ot(o1, frcp(l1), O + (tok0 + tq1) * 1024 + h * 64, hh);
.LBB0_2813:
	v_rcp_f32_e32 v68, v200
	v_lshlrev_b64 v[2:3], 11, v[182:183]
	v_lshl_add_u64 v[2:3], s[8:9], 0, v[2:3]
	s_lshl_b32 s96, s44, 1
	v_mul_f32_e32 v4, v68, v4
	v_mul_f32_e32 v5, v68, v5
	v_lshl_add_u64 v[2:3], v[2:3], 0, s[96:97]
	v_lshlrev_b32_e32 v0, 1, v164
	v_cvt_pk_bf16_f32 v4, v4, v5
	v_mul_f32_e32 v5, v68, v6
	v_mul_f32_e32 v6, v68, v7
	v_lshl_add_u64 v[2:3], v[2:3], 0, v[0:1]
	v_cvt_pk_bf16_f32 v5, v5, v6
	global_store_dwordx2 v[2:3], v[4:5], off
	v_mul_f32_e32 v4, v68, v8
	v_mul_f32_e32 v5, v68, v9
	v_cvt_pk_bf16_f32 v4, v4, v5
	v_mul_f32_e32 v5, v68, v10
	v_mul_f32_e32 v6, v68, v11
	v_cvt_pk_bf16_f32 v5, v5, v6
	global_store_dwordx2 v[2:3], v[4:5], off offset:16
	v_mul_f32_e32 v4, v68, v12
	v_mul_f32_e32 v5, v68, v13
	v_cvt_pk_bf16_f32 v4, v4, v5
	v_mul_f32_e32 v5, v68, v14
	v_mul_f32_e32 v6, v68, v15
	v_cvt_pk_bf16_f32 v5, v5, v6
	global_store_dwordx2 v[2:3], v[4:5], off offset:32
	v_mul_f32_e32 v4, v68, v16
	v_mul_f32_e32 v5, v68, v17
	v_cvt_pk_bf16_f32 v4, v4, v5
	v_mul_f32_e32 v5, v68, v18
	v_mul_f32_e32 v6, v68, v19
	v_cvt_pk_bf16_f32 v5, v5, v6
	global_store_dwordx2 v[2:3], v[4:5], off offset:48
	v_mul_f32_e32 v4, v68, v20
	v_mul_f32_e32 v5, v68, v21
	v_cvt_pk_bf16_f32 v4, v4, v5
	v_mul_f32_e32 v5, v68, v22
	v_mul_f32_e32 v6, v68, v23
	v_cvt_pk_bf16_f32 v5, v5, v6
	global_store_dwordx2 v[2:3], v[4:5], off offset:64
	v_mul_f32_e32 v4, v68, v24
	v_mul_f32_e32 v5, v68, v25
	v_cvt_pk_bf16_f32 v4, v4, v5
	v_mul_f32_e32 v5, v68, v26
	v_mul_f32_e32 v6, v68, v27
	v_cvt_pk_bf16_f32 v5, v5, v6
	global_store_dwordx2 v[2:3], v[4:5], off offset:80
	v_mul_f32_e32 v4, v68, v28
	v_mul_f32_e32 v5, v68, v29
	v_cvt_pk_bf16_f32 v4, v4, v5
	v_mul_f32_e32 v5, v68, v30
	v_mul_f32_e32 v6, v68, v31
	v_cvt_pk_bf16_f32 v5, v5, v6
	global_store_dwordx2 v[2:3], v[4:5], off offset:96
	v_mul_f32_e32 v4, v68, v32
	v_mul_f32_e32 v5, v68, v33
	v_cvt_pk_bf16_f32 v4, v4, v5
	v_mul_f32_e32 v5, v68, v34
	v_mul_f32_e32 v6, v68, v35
	v_cvt_pk_bf16_f32 v5, v5, v6
	v_rcp_f32_e32 v6, v196
	global_store_dwordx2 v[2:3], v[4:5], off offset:112
	v_lshlrev_b64 v[2:3], 11, v[176:177]
	v_lshl_add_u64 v[2:3], s[8:9], 0, v[2:3]
	v_lshl_add_u64 v[2:3], v[2:3], 0, s[96:97]
	v_lshl_add_u64 v[2:3], v[2:3], 0, v[0:1]
	v_mul_f32_e32 v0, v6, v52
	v_mul_f32_e32 v4, v6, v53
	v_cvt_pk_bf16_f32 v4, v0, v4
	v_mul_f32_e32 v0, v6, v54
	v_mul_f32_e32 v5, v6, v55
	v_cvt_pk_bf16_f32 v5, v0, v5
	global_store_dwordx2 v[2:3], v[4:5], off
	v_mul_f32_e32 v0, v6, v56
	v_mul_f32_e32 v4, v6, v57
	v_cvt_pk_bf16_f32 v4, v0, v4
	v_mul_f32_e32 v0, v6, v58
	v_mul_f32_e32 v5, v6, v59
	v_cvt_pk_bf16_f32 v5, v0, v5
	global_store_dwordx2 v[2:3], v[4:5], off offset:16
	v_mul_f32_e32 v0, v6, v60
	v_mul_f32_e32 v4, v6, v61
	v_cvt_pk_bf16_f32 v4, v0, v4
	v_mul_f32_e32 v0, v6, v62
	v_mul_f32_e32 v5, v6, v63
	v_cvt_pk_bf16_f32 v5, v0, v5
	global_store_dwordx2 v[2:3], v[4:5], off offset:32
	v_mul_f32_e32 v0, v6, v64
	v_mul_f32_e32 v4, v6, v65
	v_cvt_pk_bf16_f32 v4, v0, v4
	v_mul_f32_e32 v0, v6, v66
	v_mul_f32_e32 v5, v6, v67
	v_cvt_pk_bf16_f32 v5, v0, v5
	global_store_dwordx2 v[2:3], v[4:5], off offset:48
	v_mul_f32_e32 v0, v6, v36
	v_mul_f32_e32 v4, v6, v37
	v_cvt_pk_bf16_f32 v4, v0, v4
	v_mul_f32_e32 v0, v6, v38
	v_mul_f32_e32 v5, v6, v39
	v_cvt_pk_bf16_f32 v5, v0, v5
	global_store_dwordx2 v[2:3], v[4:5], off offset:64
	v_mul_f32_e32 v0, v6, v40
	v_mul_f32_e32 v4, v6, v41
	v_cvt_pk_bf16_f32 v4, v0, v4
	v_mul_f32_e32 v0, v6, v42
	v_mul_f32_e32 v5, v6, v43
	v_cvt_pk_bf16_f32 v5, v0, v5
	global_store_dwordx2 v[2:3], v[4:5], off offset:80
	v_mul_f32_e32 v0, v6, v44
	v_mul_f32_e32 v4, v6, v45
	v_cvt_pk_bf16_f32 v4, v0, v4
	v_mul_f32_e32 v0, v6, v46
	v_mul_f32_e32 v5, v6, v47
	v_cvt_pk_bf16_f32 v5, v0, v5
	global_store_dwordx2 v[2:3], v[4:5], off offset:96
	v_mul_f32_e32 v0, v6, v48
	v_mul_f32_e32 v4, v6, v49
	v_cvt_pk_bf16_f32 v4, v0, v4
	v_mul_f32_e32 v0, v6, v50
	v_mul_f32_e32 v5, v6, v51
	s_add_i32 s39, s39, 1
	v_cvt_pk_bf16_f32 v5, v0, v5
	s_cmp_eq_u32 s39, 4
	global_store_dwordx2 v[2:3], v[4:5], off offset:112
	s_cbranch_scc1 .LBB0_2811
.LBB0_2814:
	s_mov_b32 s0, -1
	s_bitcmp0_b32 s39, 0
	s_cselect_b32 s4, s95, s89
	v_mbcnt_lo_u32_b32 v0, s0, 0
	v_mbcnt_hi_u32_b32 v0, s0, v0
	v_add_u32_e32 v10, s11, v0
	s_lshl_b32 s45, s4, 9
	s_add_i32 s45, s45, s34
	v_and_b32_e32 v194, 31, v10
	v_or_b32_e32 v178, s45, v194
	v_or_b32_e32 v180, 32, v178
	v_ashrrev_i32_e32 v179, 31, v178
	s_or_b32 s5, s39, s36
	v_lshl_add_u64 v[182:183], s[16:17], 0, v[178:179]
	s_waitcnt lgkmcnt(0)
	v_mov_b64_e32 v[2:3], s[12:13]
	v_ashrrev_i32_e32 v181, 31, v180
	v_mad_u64_u32 v[4:5], s[0:1], v182, s77, v[2:3]
	s_mul_i32 s96, s5, 0x60
	v_lshl_add_u64 v[176:177], s[16:17], 0, v[180:181]
	s_waitcnt vmcnt(0)
	v_bfe_u32 v202, v10, 5, 1
	v_mad_i32_i24 v5, v183, s77, v5
	s_lshl_b64 s[0:1], s[96:97], 1
	v_mad_u64_u32 v[2:3], s[2:3], v176, s77, v[2:3]
	v_lshl_add_u64 v[4:5], v[4:5], 0, s[0:1]
	v_lshlrev_b32_e32 v184, 4, v202
	v_mov_b32_e32 v185, v1
	v_mad_i32_i24 v3, v177, s77, v3
	v_lshl_add_u64 v[4:5], v[4:5], 0, v[184:185]
	v_lshl_add_u64 v[2:3], v[2:3], 0, s[0:1]
	v_lshl_add_u64 v[2:3], v[2:3], 0, v[184:185]
	global_load_dwordx4 v[100:103], v[4:5], off
	global_load_dwordx4 v[104:107], v[4:5], off offset:32
	global_load_dwordx4 v[108:111], v[2:3], off
	global_load_dwordx4 v[112:115], v[2:3], off offset:32
	global_load_dwordx4 v[116:119], v[4:5], off offset:64
	global_load_dwordx4 v[120:123], v[4:5], off offset:96
	global_load_dwordx4 v[124:127], v[2:3], off offset:64
	global_load_dwordx4 v[128:131], v[2:3], off offset:96
	global_load_dwordx4 v[132:135], v[4:5], off offset:128
	global_load_dwordx4 v[136:139], v[4:5], off offset:160
	global_load_dwordx4 v[140:143], v[2:3], off offset:128
	global_load_dwordx4 v[144:147], v[2:3], off offset:160
	s_lshl_b32 s0, s5, 18
	s_add_u32 s0, s37, s0
	v_ashrrev_i32_e32 v11, 31, v10
	s_addc_u32 s1, s38, 0
	v_lshlrev_b64 v[6:7], 4, v[10:11]
	v_lshl_add_u64 v[186:187], s[0:1], 0, v[6:7]
	global_load_dwordx4 v[2:5], v[186:187], off
	s_movk_i32 s0, 0x100
	v_lshl_add_u64 v[188:189], s[18:19], 0, v[6:7]
	v_cmp_gt_i32_e64 s[0:1], s0, v10
	s_and_saveexec_b64 s[2:3], s[0:1]
	s_cbranch_execz .LBB0_2816
	global_load_dwordx4 v[160:163], v[188:189], off
; #define LAS __attribute__((address_space(3)))
; #define MLA_GLOAD(t) do { const size_t ko = (size_t)(64 * (t)); rk = *(const u32x4*)(gk + ko * 64); if (lo256) rr = *(const u32x4*)(gr + ko * 32); rv = *(const u32x4*)(gv + ko); } while (0)
; #define MLA_LSTORE(buf) do { LAS unsigned char* kb_ = lds + (buf) * TILE; *(LAS u32x4*)(kb_ + (tid >> 3) * KS + (tid & 7) * 16) = rk; \
;         if (lo256) *(LAS u32x4*)(kb_ + (tid >> 2) * KS + 128 + (tid & 3) * 16) = rr; lds_store16_as2x8(kb_ + VOFF + (tid >> 3) * VS + (tid & 7) * 16, rv); } while (0)
; DI void mla_qblock(int wv, int w, LAS unsigned char* lds, const bf16_t* Q, const bf16_t* KN, const bf16_t* KR, const bf16_t* VT, bf16_t* O, size_t tok0, int h, int qb) {
;     ...
;     const bf16_t* gk = KN + ((tok0 >> 11) * 16 + h) * (size_t)(2048 * 64) + (size_t)tid * 8;
;     const bf16_t* gr = KR + tok0 * 32 + (size_t)tid * 8;
;     const bf16_t* gv = VT + ((tok0 >> 11) * 1024 + h * 64 + (tid >> 3)) * (size_t)VPITCH + (tid & 7) * 8;
;     const bool lo256 = tid < 256;
;     ...
;     MLA_GLOAD(0); MLA_LSTORE(0); if (nt > 1) MLA_GLOAD(1); __syncthreads();
;     ...
;     int bi = 0;
;     for (int t = 0; t < nfull; ++t) {
;         const int bn = bi == 2 ? 0 : bi + 1;
;         MLA_LSTORE(bn);
;         if (t + 2 < nt) MLA_GLOAD(t + 2);
;         const LAS unsigned char* kb = lds + bi * TILE;
.LBB0_2816:
	s_or_b64 exec, exec, s[2:3]
	s_lshl_b32 s44, s5, 6
	s_add_u32 s2, s20, s44
	v_ashrrev_i32_e32 v12, 3, v10
	s_addc_u32 s3, s21, 0
	v_ashrrev_i32_e32 v13, 31, v12
	v_lshl_add_u64 v[6:7], s[2:3], 0, v[12:13]
	v_mov_b64_e32 v[8:9], s[14:15]
	v_mad_u64_u32 v[8:9], s[2:3], v6, s43, v[8:9]
	v_mov_b32_e32 v0, v9
	v_mad_u64_u32 v[6:7], s[2:3], v7, s43, v[0:1]
	v_lshlrev_b32_e32 v11, 4, v10
	v_mov_b32_e32 v9, v6
	v_and_b32_e32 v190, 0x70, v11
	v_mov_b32_e32 v191, v1
	v_lshl_add_u64 v[192:193], v[8:9], 0, v[190:191]
	global_load_dwordx4 v[6:9], v[192:193], off
	v_mul_lo_u32 v179, v12, s80
	v_add_u32_e32 v0, 0, v179
	v_add_u32_e32 v13, v0, v190
	s_waitcnt vmcnt(0)
	ds_write_b128 v13, v[2:5]
	v_lshrrev_b32_e32 v2, 2, v10
	v_mul_lo_u32 v181, v2, s80
	v_and_b32_e32 v185, 48, v11
	s_and_saveexec_b64 s[2:3], s[0:1]
	s_cbranch_execz .LBB0_2818
	v_add3_u32 v2, 0, v181, v185
	s_waitcnt lgkmcnt(0)
	ds_write_b128 v2, v[160:163] offset:128
.LBB0_2818:
	s_or_b64 exec, exec, s[2:3]
	s_movk_i32 s2, 0xffb8
	v_mad_u64_u32 v[2:3], s[2:3], v12, s2, v[0:1]
	v_add3_u32 v0, v2, v190, s81
	v_add_co_u32_e32 v2, vcc, 0x2000, v186
	s_waitcnt lgkmcnt(0)
	ds_write2_b64 v0, v[6:7], v[8:9] offset1:1
	v_addc_co_u32_e32 v3, vcc, 0, v187, vcc
	global_load_dwordx4 v[164:167], v[2:3], off
	s_and_saveexec_b64 s[2:3], s[0:1]
	s_cbranch_execz .LBB0_2820
	v_add_co_u32_e32 v2, vcc, 0x1000, v188
	s_nop 1
	v_addc_co_u32_e32 v3, vcc, 0, v189, vcc
	global_load_dwordx4 v[160:163], v[2:3], off
.LBB0_2820:
	s_or_b64 exec, exec, s[2:3]
	global_load_dwordx4 v[168:171], v[192:193], off offset:128
	s_lshl_b32 s46, s4, 3
	v_lshlrev_b32_e32 v191, 3, v202
	v_mul_lo_u32 v195, v12, s94
	s_cmp_lg_u32 s4, 0
	v_cmp_eq_u32_e64 s[2:3], 0, v202
	v_mul_u32_u24_e32 v203, 0x88, v194
	v_mad_u32_u24 v204, v194, s94, v208
	s_waitcnt lgkmcnt(0)
	s_barrier
	s_cbranch_scc0 .LBB0_2878
	v_cmp_lt_i32_e32 vcc, v223, v222
	v_mov_b32_e32 v14, v1
	v_mov_b32_e32 v15, v1
	v_cndmask_b32_e32 v0, v207, v223, vcc
	v_lshlrev_b32_e32 v205, 2, v0
	v_mov_b32_e32 v0, v1
	v_mov_b32_e32 v2, v1
	v_mov_b32_e32 v3, v1
	v_mov_b32_e32 v4, v1
	v_mov_b32_e32 v5, v1
	v_mov_b32_e32 v6, v1
	v_mov_b32_e32 v7, v1
	v_mov_b32_e32 v8, v1
	v_mov_b32_e32 v9, v1
	v_mov_b32_e32 v10, v1
	v_mov_b32_e32 v11, v1
	v_mov_b32_e32 v12, v1
	v_mov_b32_e32 v13, v1
	v_mov_b32_e32 v196, 0
	s_waitcnt vmcnt(0)
	v_mov_b64_e32 v[152:153], v[164:165]
	v_mov_b64_e32 v[148:149], v[160:161]
	v_mov_b64_e32 v[156:157], v[168:169]
	v_mov_b64_e32 v[66:67], v[14:15]
	v_mov_b64_e32 v[50:51], v[14:15]
	s_mov_b32 s22, 0
	v_cndmask_b32_e64 v172, 0, v232, s[2:3]
	v_cndmask_b32_e64 v173, 0, v228, s[2:3]
	v_mov_b32_e32 v174, v1
	v_mov_b32_e32 v175, v1
	v_mul_u32_u24_e32 v197, 0x88, v194
	v_mad_u32_u24 v198, v194, s94, v208
	v_mov_b64_e32 v[154:155], v[166:167]
	v_mov_b64_e32 v[150:151], v[162:163]
	v_mov_b64_e32 v[158:159], v[170:171]
	s_mov_b32 s47, 0
	v_mov_b64_e32 v[64:65], v[12:13]
	v_mov_b64_e32 v[62:63], v[10:11]
	v_mov_b64_e32 v[60:61], v[8:9]
	v_mov_b64_e32 v[58:59], v[6:7]
	v_mov_b64_e32 v[56:57], v[4:5]
	v_mov_b64_e32 v[54:55], v[2:3]
	v_mov_b64_e32 v[52:53], v[0:1]
	v_mov_b64_e32 v[48:49], v[12:13]
	v_mov_b64_e32 v[46:47], v[10:11]
	v_mov_b64_e32 v[44:45], v[8:9]
	v_mov_b64_e32 v[42:43], v[6:7]
	v_mov_b64_e32 v[40:41], v[4:5]
	v_mov_b64_e32 v[38:39], v[2:3]
	v_mov_b64_e32 v[36:37], v[0:1]
	v_mov_b32_e32 v201, 0
	v_mov_b32_e32 v200, 0
	v_mov_b32_e32 v199, 0
	v_mov_b32_e32 v4, 0
	v_mov_b32_e32 v5, v196
	v_mov_b32_e32 v6, v196
	v_mov_b32_e32 v7, v196
	v_mov_b32_e32 v8, v196
	v_mov_b32_e32 v9, v196
	v_mov_b32_e32 v10, v196
	v_mov_b32_e32 v11, v196
	v_mov_b32_e32 v12, v196
	v_mov_b32_e32 v13, v196
	v_mov_b32_e32 v14, v196
	v_mov_b32_e32 v15, v196
	v_mov_b32_e32 v16, v196
	v_mov_b32_e32 v17, v196
	v_mov_b32_e32 v18, v196
	v_mov_b32_e32 v19, v196
	v_mov_b32_e32 v20, v196
	v_mov_b32_e32 v21, v196
	v_mov_b32_e32 v22, v196
	v_mov_b32_e32 v23, v196
	v_mov_b32_e32 v24, v196
	v_mov_b32_e32 v25, v196
	v_mov_b32_e32 v26, v196
	v_mov_b32_e32 v27, v196
	v_mov_b32_e32 v28, v196
	v_mov_b32_e32 v29, v196
	v_mov_b32_e32 v30, v196
	v_mov_b32_e32 v31, v196
	v_mov_b32_e32 v32, v196
	v_mov_b32_e32 v33, v196
	v_mov_b32_e32 v34, v196
	v_mov_b32_e32 v35, v196
.LBB0_2822:
	s_add_i32 s4, s22, 1
	s_cmp_lg_u32 s22, 2
	s_cselect_b32 s50, s4, 0
	s_mul_i32 s4, s50, 0x5600
	s_add_i32 s6, s4, 0
	v_add3_u32 v0, s6, v179, v190
	s_waitcnt vmcnt(0)
	ds_write_b128 v0, v[152:155]
	s_and_saveexec_b64 s[4:5], s[0:1]
	v_add3_u32 v0, s6, v181, v185
	ds_write_b128 v0, v[148:151] offset:128
	s_or_b64 exec, exec, s[4:5]
	s_lshl_b32 s4, s47, 6
	s_add_i32 s96, s4, 0x80
	v_add_u32_e32 v0, s6, v195
	s_lshl_b64 s[6:7], s[96:97], 7
	v_lshl_add_u64 v[2:3], v[186:187], 0, s[6:7]
	global_load_dwordx4 v[152:155], v[2:3], off
	v_add3_u32 v0, v0, v190, s81
	ds_write2_b64 v0, v[156:157], v[158:159] offset1:1
	s_and_saveexec_b64 s[6:7], s[0:1]
	s_cbranch_execz .LBB0_2826
	s_lshl_b64 s[24:25], s[96:97], 6
	v_lshl_add_u64 v[2:3], v[188:189], 0, s[24:25]
	global_load_dwordx4 v[148:151], v[2:3], off
.LBB0_2826:
	s_or_b64 exec, exec, s[6:7]
	s_mov_b32 s5, s97
	v_lshl_add_u64 v[2:3], s[4:5], 1, v[192:193]
	global_load_dwordx4 v[156:159], v[2:3], off offset:256
	s_mul_i32 s4, s22, 0x5600
	s_add_i32 s4, s4, 0
	v_add_u32_e32 v206, s4, v184
	v_add3_u32 v210, s4, v191, v197
	s_mov_b32 s48, 0
	s_mov_b64 s[22:23], -1
	s_branch .LBB0_2828

; #define MLA_GLOAD(t) do { const size_t ko = (size_t)(64 * (t)); rk = *(const u32x4*)(gk + ko * 64); if (lo256) rr = *(const u32x4*)(gr + ko * 32); rv = *(const u32x4*)(gv + ko); } while (0)
; #define MLA_LSTORE(buf) do { LAS unsigned char* kb_ = lds + (buf) * TILE; *(LAS u32x4*)(kb_ + (tid >> 3) * KS + (tid & 7) * 16) = rk; \
;         if (lo256) *(LAS u32x4*)(kb_ + (tid >> 2) * KS + 128 + (tid & 3) * 16) = rr; lds_store16_as2x8(kb_ + VOFF + (tid >> 3) * VS + (tid & 7) * 16, rv); } while (0)
; DI void mla_qblock(int wv, int w, LAS unsigned char* lds, const bf16_t* Q, const bf16_t* KN, const bf16_t* KR, const bf16_t* VT, bf16_t* O, size_t tok0, int h, int qb) {
;     ...
;     for (int t = nfull; t < nt; ++t) {
;         const int bn = bi == 2 ? 0 : bi + 1;
;         if (t + 1 < nt) MLA_LSTORE(bn);
;         if (t + 2 < nt) MLA_GLOAD(t + 2);
;         const int k0 = 64 * t;
;         if (k0 <= R0 + 63) {
.LBB0_2855:
	s_lshl_b32 s96, s4, 6
	s_lshl_b64 s[4:5], s[96:97], 7
	v_lshl_add_u64 v[2:3], v[186:187], 0, s[4:5]
	global_load_dwordx4 v[152:155], v[2:3], off
	s_and_saveexec_b64 s[4:5], s[0:1]
	s_cbranch_execz .LBB0_2857
	s_lshl_b64 s[6:7], s[96:97], 6
	v_lshl_add_u64 v[2:3], v[188:189], 0, s[6:7]
	s_waitcnt vmcnt(0)
	global_load_dwordx4 v[148:151], v[2:3], off
.LBB0_2857:
	s_or_b64 exec, exec, s[4:5]
	s_lshl_b32 s96, s96, 1
	v_lshl_add_u64 v[2:3], v[192:193], 0, s[96:97]
	s_waitcnt vmcnt(0)
	global_load_dwordx4 v[156:159], v[2:3], off
	s_lshl_b32 s4, s46, 6
	s_cmp_gt_i32 s4, s45
	s_cbranch_scc1 .LBB0_2876

; DI unsigned xb_ld(unsigned* p)              { return __hip_atomic_load(p, __ATOMIC_RELAXED, __HIP_MEMORY_SCOPE_AGENT); }
; DI void xcd_barrier_complete(unsigned* bar, unsigned x, unsigned& nloc, unsigned& nx) {
;     ...
;     for (;;) {
;         sum = 0u; cnt = 0u; mine = 0u;
; #pragma unroll
;         for (unsigned j = 0; j < 16; ++j) { const unsigned c = xb_ld(&bar[XB_XCNT(j)]); sum += c; cnt += (c > 0u) ? 1u : 0u; mine = (j == x) ? c : mine; }
;         if (sum == G) break;
;         __builtin_amdgcn_s_sleep(1);
;         if ((++sp & 255u) == 0u) { if (xb_ld(&bar[XB_TMO])) break; if (sp > XB_SPIN_CAP) { atomicAdd(&bar[XB_TMO], 1u); break; } }
;     }
;     nloc = mine > 0u ? mine : 1u; nx = cnt > 0u ? cnt : 1u;
.LBB0_2885:
	v_mov_b64_e32 v[2:3], s[2:3]
	s_waitcnt lgkmcnt(0)
	global_load_dword v0, v[2:3], off sc1
	v_mov_b64_e32 v[2:3], s[4:5]
	global_load_dword v2, v[2:3], off sc1
	v_mov_b64_e32 v[4:5], s[6:7]
	global_load_dword v3, v[4:5], off sc1
	v_mov_b64_e32 v[4:5], s[8:9]
	global_load_dword v4, v[4:5], off sc1
	s_or_b64 s[54:55], s[54:55], exec
	s_or_b64 s[56:57], s[56:57], exec
	s_waitcnt vmcnt(0) lgkmcnt(0)
	v_add_u32_e32 v6, v2, v0
	v_add_u32_e32 v6, v6, v3
	v_add_u32_e32 v8, v6, v4
	v_mov_b64_e32 v[6:7], s[12:13]
	global_load_dword v5, v[6:7], off sc1
	v_mov_b64_e32 v[6:7], s[14:15]
	global_load_dword v6, v[6:7], off sc1
	s_waitcnt vmcnt(0) lgkmcnt(0)
	v_add_u32_e32 v8, v8, v5
	v_add_u32_e32 v10, v8, v6
	v_mov_b64_e32 v[8:9], s[16:17]
	global_load_dword v7, v[8:9], off sc1
	v_mov_b64_e32 v[8:9], s[18:19]
	global_load_dword v8, v[8:9], off sc1
	s_waitcnt vmcnt(0) lgkmcnt(0)
	v_add_u32_e32 v10, v10, v7
	v_add_u32_e32 v12, v10, v8
	v_mov_b64_e32 v[10:11], s[20:21]
	global_load_dword v9, v[10:11], off sc1
	v_mov_b64_e32 v[10:11], s[22:23]
	global_load_dword v10, v[10:11], off sc1
	s_waitcnt vmcnt(0) lgkmcnt(0)
	v_add_u32_e32 v12, v12, v9
	v_add_u32_e32 v14, v12, v10
	v_mov_b64_e32 v[12:13], s[24:25]
	global_load_dword v11, v[12:13], off sc1
	v_mov_b64_e32 v[12:13], s[26:27]
	global_load_dword v12, v[12:13], off sc1
	s_waitcnt vmcnt(0) lgkmcnt(0)
	v_add_u32_e32 v14, v14, v11
	v_add_u32_e32 v16, v14, v12
	v_mov_b64_e32 v[14:15], s[28:29]
	global_load_dword v13, v[14:15], off sc1
	v_mov_b64_e32 v[14:15], s[30:31]
	global_load_dword v14, v[14:15], off sc1
	s_waitcnt vmcnt(0) lgkmcnt(0)
	v_add_u32_e32 v16, v16, v13
	v_add_u32_e32 v18, v16, v14
	v_mov_b64_e32 v[16:17], s[48:49]
	global_load_dword v15, v[16:17], off sc1
	v_mov_b64_e32 v[16:17], s[50:51]
	global_load_dword v16, v[16:17], off sc1
	s_waitcnt vmcnt(0) lgkmcnt(0)
	v_add_u32_e32 v18, v18, v15
	v_add_u32_e32 v17, v18, v16
	v_cmp_ne_u32_e32 vcc, s33, v17
	s_and_saveexec_b64 s[84:85], vcc
	s_cbranch_execz .LBB0_2884
	s_and_b32 s46, s67, 0xff
	s_mov_b64 s[60:61], -1
	s_cmp_eq_u32 s46, 0
	s_mov_b64 s[64:65], -1
	s_mov_b64 s[90:91], -1
	s_sleep 1
	s_cbranch_scc1 .LBB0_2888
	s_and_saveexec_b64 s[46:47], s[64:65]
	s_cbranch_execz .LBB0_2883
	s_branch .LBB0_2891
.LBB0_2888:
	v_mov_b64_e32 v[18:19], s[0:1]
	global_load_dword v17, v[18:19], off sc1
	s_mov_b64 s[64:65], 0
	s_waitcnt vmcnt(0) lgkmcnt(0)
	v_cmp_eq_u32_e32 vcc, 0, v17
	s_and_saveexec_b64 s[46:47], vcc
	s_cmp_lt_u32 s67, 0x40001
	s_cselect_b64 s[64:65], -1, 0
	s_xor_b64 s[90:91], exec, -1
	s_and_b64 s[64:65], s[64:65], exec
	s_or_b64 exec, exec, s[46:47]
	s_and_saveexec_b64 s[46:47], s[64:65]
	s_cbranch_execz .LBB0_2883

; DI unsigned xb_ld(unsigned* p)              { return __hip_atomic_load(p, __ATOMIC_RELAXED, __HIP_MEMORY_SCOPE_AGENT); }
; DI unsigned xb_add(unsigned* p, unsigned v) { return __hip_atomic_fetch_add(p, v, __ATOMIC_RELAXED, __HIP_MEMORY_SCOPE_AGENT); }
; #define XB_SPIN(cond, bar) do { unsigned _sp = 0; while (cond) { __builtin_amdgcn_s_sleep(1); \
;     if ((++_sp & 255u) == 0u) { if (xb_ld(&(bar)[XB_TMO])) break; if (_sp > XB_SPIN_CAP) { atomicAdd(&(bar)[XB_TMO], 1u); break; } } } } while (0)
; DI void xcd_barrier(int wv, unsigned* bar, volatile LAS unsigned* st) {
;     ...
;         const unsigned old = xb_add(&bar[XB_XSUB(x)], 1u);
;         const unsigned gen = old / nloc;
;         if (old + 1u == (gen + 1u) * nloc) {
;             __builtin_amdgcn_fence(__ATOMIC_RELEASE, "agent");
;             asm volatile("s_waitcnt vmcnt(0)" ::: "memory");
;             const unsigned og = xb_add(&bar[XB_TOP], 1u);
;             const unsigned tg = og / nx;
;             if (og + 1u == (tg + 1u) * nx) xb_add(&bar[XB_TOPGEN], 1u);
;             else XB_SPIN(xb_ld(&bar[XB_TOPGEN]) == tg, bar);
;             __builtin_amdgcn_fence(__ATOMIC_ACQUIRE, "agent");
;             xb_add(&bar[XB_XGEN(x)], 1u);
;             asm volatile("s_waitcnt vmcnt(0)" ::: "memory");
;         } else {
;             XB_SPIN(xb_ld(&bar[XB_XGEN(x)]) == gen, bar);
.LBB0_2895:
	s_lshl_b32 s0, s66, 8
	s_add_u32 s0, s36, s0
	s_addc_u32 s1, s37, 0
	v_mov_b32_e32 v3, s0
	v_add_co_u32_e32 v4, vcc, 0xc1000, v3
	v_mov_b32_e32 v3, s1
	s_nop 0
	v_addc_co_u32_e32 v5, vcc, 0, v3, vcc
	v_mov_b32_e32 v3, 1
	flat_atomic_add v4, v[4:5], v3 offset:1024 sc0
	v_cvt_f32_u32_e32 v3, v2
	v_sub_u32_e32 v5, 0, v2
	s_add_u32 s25, s0, 0xc0000
	s_addc_u32 s24, s1, 0
	v_rcp_iflag_f32_e32 v3, v3
	s_nop 0
	v_mul_f32_e32 v3, 0x4f7ffffe, v3
	v_cvt_u32_f32_e32 v3, v3
	v_mul_lo_u32 v5, v5, v3
	v_mul_hi_u32 v5, v3, v5
	v_add_u32_e32 v3, v3, v5
	s_waitcnt vmcnt(0) lgkmcnt(0)
	v_mul_hi_u32 v3, v4, v3
	v_mul_lo_u32 v5, v3, v2
	v_sub_u32_e32 v5, v4, v5
	v_cmp_ge_u32_e32 vcc, v5, v2
	v_add_u32_e32 v6, 1, v3
	s_nop 0
	v_cndmask_b32_e32 v3, v3, v6, vcc
	v_sub_u32_e32 v6, v5, v2
	v_cndmask_b32_e32 v5, v5, v6, vcc
	v_cmp_ge_u32_e32 vcc, v5, v2
	v_add_u32_e32 v5, 1, v3
	v_add_u32_e32 v6, 1, v4
	v_cndmask_b32_e32 v3, v3, v5, vcc
	v_mad_u64_u32 v[4:5], s[0:1], v2, v3, v[2:3]
	v_cmp_ne_u32_e32 vcc, v6, v4
	s_and_saveexec_b64 s[0:1], vcc
	s_xor_b64 s[0:1], exec, s[0:1]
	s_cbranch_execz .LBB0_2908
	v_mov_b32_e32 v0, s25
	v_add_co_u32_e32 v4, vcc, 0x2000, v0
	v_mov_b32_e32 v0, s24
	s_nop 0
	v_addc_co_u32_e32 v5, vcc, 0, v0, vcc
	global_load_dword v0, v[4:5], off offset:1024 sc1
	s_add_u32 s4, s25, 0x2400
	s_addc_u32 s5, s24, 0
	s_waitcnt vmcnt(0) lgkmcnt(0)
	v_cmp_eq_u32_e32 vcc, v0, v3
	s_and_saveexec_b64 s[2:3], vcc
	s_cbranch_execz .LBB0_2907
	s_add_u32 s6, s36, 0xc0200
	s_addc_u32 s7, s37, 0
	s_mov_b32 s26, 1
	s_mov_b64 s[8:9], 0
	s_branch .LBB0_2899

; DI u32x4 pk8(f32x4 a, f32x4 b) { u32x4 o; o.x = pk2(a.x, a.y); o.y = pk2(a.z, a.w); o.z = pk2(b.x, b.y); o.w = pk2(b.z, b.w); return o; }
; #define EPI_SCHED() __builtin_amdgcn_sched_barrier(0)
;     DI void operator()(const AccT& acc, const Unit& u, int wr, int wc, int fr, int fq) const {
;         const size_t row0 = (size_t)u.pm * 256 + wr * 64 + fr;
;         const int col0 = u.pn * 256 + wc * 32 + fq * 8;
; #pragma unroll
;         for (int ai = 0; ai < 2; ++ai) {
;             EPI_SCHED();
;             u32x4 hv[4][2];
; #pragma unroll
;             for (int m = 0; m < 4; ++m)
; #pragma unroll
;                 for (int bj = 0; bj < 2; ++bj) hv[m][bj] = *(const u32x4*)(hb + (row0 + ai * 128 + m * 16) * D + col0 + bj * 128);
; #pragma unroll
;             for (int m = 0; m < 4; ++m) {
;                 const size_t row = row0 + ai * 128 + m * 16;
;                 float sq = 0.f;
; #pragma unroll
;                 for (int bj = 0; bj < 2; ++bj) {
;                     const u32x4 w = hv[m][bj];
;                     f32x4 a, b;
;                     a.x = __uint_as_float(w.x << 16); a.y = __uint_as_float(w.x & 0xffff0000u); a.z = __uint_as_float(w.y << 16); a.w = __uint_as_float(w.y & 0xffff0000u);
;                     b.x = __uint_as_float(w.z << 16); b.y = __uint_as_float(w.z & 0xffff0000u); b.z = __uint_as_float(w.w << 16); b.w = __uint_as_float(w.w & 0xffff0000u);
;                     a += acc[ai][bj][m][0] * alpha; b += acc[ai][bj][m][1] * alpha;
;                     sq += (a.x * a.x + a.y * a.y) + (a.z * a.z + a.w * a.w) + (b.x * b.x + b.y * b.y) + (b.z * b.z + b.w * b.w);
;                     *(u32x4*)(hb + row * D + col0 + bj * 128) = pk8(a, b);
;                 }
;                 sq += __shfl_xor(sq, 16); sq += __shfl_xor(sq, 32);
;                 if (fq == 0) ss[row * 16 + u.pn * 4 + wc] = sq;
;             }
.LBB0_2953:
	s_mov_b32 s23, -1
	s_nop 0
	v_mbcnt_lo_u32_b32 v130, s23, 0
	v_mbcnt_hi_u32_b32 v130, s23, v130
	s_ashr_i32 s23, s22, 31
	s_lshl_b64 s[22:23], s[22:23], 8
	s_add_u32 s22, s22, s49
	s_addc_u32 s23, s23, s56
	v_and_or_b32 v156, v130, 15, s22
	s_lshl_b32 s22, s64, 8
	v_ashrrev_i32_e32 v131, 1, v130
	s_or_b32 s22, s22, s50
	v_and_b32_e32 v131, -8, v131
	v_add_u32_e32 v154, s22, v131
	v_xor_b32_e32 v131, 16, v207
	v_cmp_lt_i32_e32 vcc, v131, v222
	s_lshl_b32 s22, s64, 2
	v_mov_b32_e32 v157, s23
	v_cndmask_b32_e32 v131, v207, v131, vcc
	v_cmp_lt_i32_e32 vcc, v223, v222
	v_lshlrev_b32_e32 v178, 2, v131
	v_ashrrev_i32_e32 v155, 31, v154
	v_cndmask_b32_e32 v131, v207, v223, vcc
	v_lshlrev_b32_e32 v177, 2, v131
	v_cmp_gt_u32_e32 vcc, 16, v130
	s_ashr_i32 s23, s22, 31
	v_lshlrev_b64 v[188:189], 1, v[154:155]
	v_lshl_add_u64 v[158:159], s[8:9], 0, v[188:189]
	v_lshlrev_b64 v[190:191], 11, v[156:157]
	v_lshl_add_u64 v[130:131], v[158:159], 0, v[190:191]
	global_load_dwordx4 v[180:183], v[130:131], off
	global_load_dwordx4 v[184:187], v[130:131], off offset:256
	v_or_b32_e32 v168, 16, v156
	v_mov_b32_e32 v169, v157
	v_lshlrev_b64 v[170:171], 11, v[168:169]
	v_or_b32_e32 v164, 32, v156
	v_mov_b32_e32 v165, v157
	v_lshl_add_u64 v[130:131], v[158:159], 0, v[170:171]
	v_lshlrev_b64 v[166:167], 11, v[164:165]
	v_or_b32_e32 v160, 48, v156
	v_mov_b32_e32 v161, v157
	global_load_dwordx4 v[150:153], v[130:131], off
	global_load_dwordx4 v[146:149], v[130:131], off offset:256
	v_lshl_add_u64 v[130:131], v[158:159], 0, v[166:167]
	v_lshlrev_b64 v[162:163], 11, v[160:161]
	global_load_dwordx4 v[142:145], v[130:131], off
	global_load_dwordx4 v[138:141], v[130:131], off offset:256
	v_lshl_add_u64 v[130:131], v[158:159], 0, v[162:163]
	global_load_dwordx4 v[134:137], v[130:131], off
	s_nop 0
	global_load_dwordx4 v[130:133], v[130:131], off offset:256
	s_waitcnt vmcnt(0) lgkmcnt(0)
	v_lshlrev_b32_e32 v192, 16, v180
	v_and_b32_e32 v193, 0xffff0000, v180
	v_lshlrev_b32_e32 v180, 16, v181
	v_and_b32_e32 v181, 0xffff0000, v181
	v_lshlrev_b32_e32 v194, 16, v182
	v_and_b32_e32 v195, 0xffff0000, v182
	v_lshlrev_b32_e32 v182, 16, v183
	v_and_b32_e32 v183, 0xffff0000, v183
	v_pk_fma_f32 v[128:129], s[14:15], v[128:129], v[180:181]
	v_pk_fma_f32 v[126:127], s[4:5], v[126:127], v[192:193]
	v_pk_fma_f32 v[180:181], s[14:15], v[124:125], v[182:183]
	v_mul_f32_e32 v124, v127, v127
	v_mul_f32_e32 v125, v129, v129
	v_pk_fma_f32 v[122:123], s[4:5], v[122:123], v[194:195]
	v_fmac_f32_e32 v124, v126, v126
	v_fmac_f32_e32 v125, v128, v128
	v_add_f32_e32 v124, v124, v125
	v_mul_f32_e32 v125, v123, v123
	v_fmac_f32_e32 v125, v122, v122
	v_add_f32_e32 v124, v125, v124
	v_mul_f32_e32 v125, v181, v181
	v_fmac_f32_e32 v125, v180, v180
	v_add_f32_e32 v179, v125, v124
	v_cvt_pk_bf16_f32 v124, v126, v127
	v_cvt_pk_bf16_f32 v126, v122, v123
	v_lshl_add_u64 v[122:123], s[8:9], 0, v[190:191]
	v_cvt_pk_bf16_f32 v125, v128, v129
	v_cvt_pk_bf16_f32 v127, v180, v181
	v_lshl_add_u64 v[122:123], v[122:123], 0, v[188:189]
	global_store_dwordx4 v[122:123], v[124:127], off
	v_lshlrev_b32_e32 v128, 16, v186
	v_and_b32_e32 v129, 0xffff0000, v186
	v_lshlrev_b32_e32 v124, 16, v184
	v_and_b32_e32 v125, 0xffff0000, v184
	v_lshlrev_b32_e32 v126, 16, v185
	v_and_b32_e32 v127, 0xffff0000, v185
	v_lshlrev_b32_e32 v180, 16, v187
	v_and_b32_e32 v181, 0xffff0000, v187
	v_pk_fma_f32 v[120:121], s[14:15], v[120:121], v[126:127]
	v_pk_fma_f32 v[118:119], s[4:5], v[118:119], v[124:125]
	v_pk_fma_f32 v[124:125], s[14:15], v[116:117], v[180:181]
	v_pk_fma_f32 v[116:117], s[4:5], v[114:115], v[128:129]
	v_mul_f32_e32 v114, v119, v119
	v_mul_f32_e32 v115, v121, v121
	v_fmac_f32_e32 v114, v118, v118
	v_fmac_f32_e32 v115, v120, v120
	v_add_f32_e32 v114, v114, v115
	v_mul_f32_e32 v115, v117, v117
	v_fmac_f32_e32 v115, v116, v116
	v_add_f32_e32 v114, v115, v114
	v_mul_f32_e32 v115, v125, v125
	v_fmac_f32_e32 v115, v124, v124
	v_add_f32_e32 v114, v115, v114
	v_add_f32_e32 v126, v179, v114
	v_cvt_pk_bf16_f32 v114, v118, v119
	v_cvt_pk_bf16_f32 v115, v120, v121
	v_cvt_pk_bf16_f32 v116, v116, v117
	v_cvt_pk_bf16_f32 v117, v124, v125
	global_store_dwordx4 v[122:123], v[114:117], off offset:256
	ds_bpermute_b32 v114, v178, v126
	s_waitcnt lgkmcnt(0)
	v_add_f32_e32 v114, v126, v114
	ds_bpermute_b32 v115, v177, v114
	s_and_saveexec_b64 s[24:25], vcc
	s_cbranch_execz .LBB0_2955
	v_lshlrev_b64 v[116:117], 6, v[156:157]
	v_lshl_add_u64 v[116:117], s[12:13], 0, v[116:117]
	v_lshl_add_u64 v[116:117], s[22:23], 2, v[116:117]
	s_lshl_b32 s96, s47, 2
	v_lshl_add_u64 v[116:117], v[116:117], 0, s[96:97]
	s_waitcnt lgkmcnt(0)
	v_add_f32_e32 v114, v114, v115
	global_store_dword v[116:117], v114, off
; DI u32x4 pk8(f32x4 a, f32x4 b) { u32x4 o; o.x = pk2(a.x, a.y); o.y = pk2(a.z, a.w); o.z = pk2(b.x, b.y); o.w = pk2(b.z, b.w); return o; }
;     DI void operator()(const AccT& acc, const Unit& u, int wr, int wc, int fr, int fq) const {
;     ...
;                 for (int bj = 0; bj < 2; ++bj) hv[m][bj] = *(const u32x4*)(hb + (row0 + ai * 128 + m * 16) * D + col0 + bj * 128);
; #pragma unroll
;             for (int m = 0; m < 4; ++m) {
;                 const size_t row = row0 + ai * 128 + m * 16;
;                 float sq = 0.f;
; #pragma unroll
;                 for (int bj = 0; bj < 2; ++bj) {
;                     const u32x4 w = hv[m][bj];
;                     f32x4 a, b;
;                     a.x = __uint_as_float(w.x << 16); a.y = __uint_as_float(w.x & 0xffff0000u); a.z = __uint_as_float(w.y << 16); a.w = __uint_as_float(w.y & 0xffff0000u);
;                     b.x = __uint_as_float(w.z << 16); b.y = __uint_as_float(w.z & 0xffff0000u); b.z = __uint_as_float(w.w << 16); b.w = __uint_as_float(w.w & 0xffff0000u);
;                     a += acc[ai][bj][m][0] * alpha; b += acc[ai][bj][m][1] * alpha;
;                     sq += (a.x * a.x + a.y * a.y) + (a.z * a.z + a.w * a.w) + (b.x * b.x + b.y * b.y) + (b.z * b.z + b.w * b.w);
;                     *(u32x4*)(hb + row * D + col0 + bj * 128) = pk8(a, b);
;                 }
;                 sq += __shfl_xor(sq, 16); sq += __shfl_xor(sq, 32);
;                 if (fq == 0) ss[row * 16 + u.pn * 4 + wc] = sq;
;             }
.LBB0_2955:
	s_or_b64 exec, exec, s[24:25]
	v_lshlrev_b32_e32 v114, 16, v150
	s_waitcnt lgkmcnt(0)
	v_and_b32_e32 v115, 0xffff0000, v150
	v_lshlrev_b32_e32 v116, 16, v151
	v_and_b32_e32 v117, 0xffff0000, v151
	v_lshlrev_b32_e32 v118, 16, v152
	v_and_b32_e32 v119, 0xffff0000, v152
	v_lshlrev_b32_e32 v120, 16, v153
	v_and_b32_e32 v121, 0xffff0000, v153
	v_pk_fma_f32 v[112:113], s[14:15], v[112:113], v[116:117]
	v_pk_fma_f32 v[110:111], s[4:5], v[110:111], v[114:115]
	v_pk_fma_f32 v[114:115], s[14:15], v[108:109], v[120:121]
	v_pk_fma_f32 v[108:109], s[4:5], v[106:107], v[118:119]
	v_mul_f32_e32 v106, v111, v111
	v_mul_f32_e32 v107, v113, v113
	v_fmac_f32_e32 v106, v110, v110
	v_fmac_f32_e32 v107, v112, v112
	v_add_f32_e32 v106, v106, v107
	v_mul_f32_e32 v107, v109, v109
	v_fmac_f32_e32 v107, v108, v108
	v_add_f32_e32 v106, v107, v106
	v_mul_f32_e32 v107, v115, v115
	v_fmac_f32_e32 v107, v114, v114
	v_add_f32_e32 v118, v107, v106
	v_cvt_pk_bf16_f32 v106, v110, v111
	v_cvt_pk_bf16_f32 v107, v112, v113
	v_lshlrev_b32_e32 v110, 16, v146
	v_and_b32_e32 v111, 0xffff0000, v146
	v_lshlrev_b32_e32 v112, 16, v147
	v_and_b32_e32 v113, 0xffff0000, v147
	v_cvt_pk_bf16_f32 v108, v108, v109
	v_cvt_pk_bf16_f32 v109, v114, v115
	v_lshlrev_b32_e32 v114, 16, v148
	v_and_b32_e32 v115, 0xffff0000, v148
	v_pk_fma_f32 v[104:105], s[14:15], v[104:105], v[112:113]
	v_pk_fma_f32 v[102:103], s[4:5], v[102:103], v[110:111]
	v_pk_fma_f32 v[112:113], s[4:5], v[98:99], v[114:115]
	v_mul_f32_e32 v98, v103, v103
	v_mul_f32_e32 v99, v105, v105
	v_fmac_f32_e32 v98, v102, v102
	v_fmac_f32_e32 v99, v104, v104
	v_lshlrev_b32_e32 v116, 16, v149
	v_and_b32_e32 v117, 0xffff0000, v149
	v_add_f32_e32 v98, v98, v99
	v_mul_f32_e32 v99, v113, v113
	v_pk_fma_f32 v[110:111], s[14:15], v[100:101], v[116:117]
	v_fmac_f32_e32 v99, v112, v112
	v_add_f32_e32 v98, v99, v98
	v_mul_f32_e32 v99, v111, v111
	v_fmac_f32_e32 v99, v110, v110
	v_add_f32_e32 v98, v99, v98
	v_add_f32_e32 v101, v118, v98
	ds_bpermute_b32 v116, v178, v101
	v_lshl_add_u64 v[98:99], s[8:9], 0, v[170:171]
	v_lshl_add_u64 v[114:115], v[154:155], 1, v[98:99]
	v_cvt_pk_bf16_f32 v100, v102, v103
	v_cvt_pk_bf16_f32 v102, v112, v113
	s_waitcnt lgkmcnt(0)
	v_add_f32_e32 v98, v101, v116
	ds_bpermute_b32 v99, v177, v98
	v_cvt_pk_bf16_f32 v101, v104, v105
	v_cvt_pk_bf16_f32 v103, v110, v111
	global_store_dwordx4 v[114:115], v[106:109], off
	global_store_dwordx4 v[114:115], v[100:103], off offset:256
	s_and_saveexec_b64 s[24:25], vcc
	s_cbranch_execz .LBB0_2957
	v_lshlrev_b64 v[100:101], 6, v[168:169]
	v_lshl_add_u64 v[100:101], s[12:13], 0, v[100:101]
	v_lshl_add_u64 v[100:101], s[22:23], 2, v[100:101]
	s_lshl_b32 s96, s47, 2
	v_lshl_add_u64 v[100:101], v[100:101], 0, s[96:97]
	s_waitcnt lgkmcnt(0)
	v_add_f32_e32 v98, v98, v99
	global_store_dword v[100:101], v98, off
.LBB0_2957:
	s_or_b64 exec, exec, s[24:25]
	v_lshlrev_b32_e32 v98, 16, v142
	s_waitcnt lgkmcnt(0)
	v_and_b32_e32 v99, 0xffff0000, v142
	v_lshlrev_b32_e32 v100, 16, v143
	v_and_b32_e32 v101, 0xffff0000, v143
	v_lshlrev_b32_e32 v102, 16, v144
	v_and_b32_e32 v103, 0xffff0000, v144
	v_lshlrev_b32_e32 v104, 16, v145
	v_and_b32_e32 v105, 0xffff0000, v145
	v_pk_fma_f32 v[96:97], s[14:15], v[96:97], v[100:101]
	v_pk_fma_f32 v[94:95], s[4:5], v[94:95], v[98:99]
	v_pk_fma_f32 v[98:99], s[14:15], v[92:93], v[104:105]
	v_pk_fma_f32 v[92:93], s[4:5], v[90:91], v[102:103]
	v_mul_f32_e32 v90, v95, v95
	v_mul_f32_e32 v91, v97, v97
	v_fmac_f32_e32 v90, v94, v94
	v_fmac_f32_e32 v91, v96, v96
	v_add_f32_e32 v90, v90, v91
	v_mul_f32_e32 v91, v93, v93
	v_fmac_f32_e32 v91, v92, v92
	v_add_f32_e32 v90, v91, v90
	v_mul_f32_e32 v91, v99, v99
	v_fmac_f32_e32 v91, v98, v98
	v_add_f32_e32 v102, v91, v90
	v_cvt_pk_bf16_f32 v90, v94, v95
	v_cvt_pk_bf16_f32 v91, v96, v97
	v_lshlrev_b32_e32 v94, 16, v138
	v_and_b32_e32 v95, 0xffff0000, v138
	v_lshlrev_b32_e32 v96, 16, v139
	v_and_b32_e32 v97, 0xffff0000, v139
	v_cvt_pk_bf16_f32 v92, v92, v93
	v_cvt_pk_bf16_f32 v93, v98, v99
	v_lshlrev_b32_e32 v98, 16, v140
	v_and_b32_e32 v99, 0xffff0000, v140
	v_pk_fma_f32 v[88:89], s[14:15], v[88:89], v[96:97]
	v_pk_fma_f32 v[86:87], s[4:5], v[86:87], v[94:95]
	v_pk_fma_f32 v[96:97], s[4:5], v[82:83], v[98:99]
	v_mul_f32_e32 v82, v87, v87
	v_mul_f32_e32 v83, v89, v89
	v_fmac_f32_e32 v82, v86, v86
	v_fmac_f32_e32 v83, v88, v88
	v_lshlrev_b32_e32 v100, 16, v141
	v_and_b32_e32 v101, 0xffff0000, v141
	v_add_f32_e32 v82, v82, v83
	v_mul_f32_e32 v83, v97, v97
	v_pk_fma_f32 v[94:95], s[14:15], v[84:85], v[100:101]
	v_fmac_f32_e32 v83, v96, v96
	v_add_f32_e32 v82, v83, v82
	v_mul_f32_e32 v83, v95, v95
	v_fmac_f32_e32 v83, v94, v94
	v_add_f32_e32 v82, v83, v82
	v_add_f32_e32 v85, v102, v82
	ds_bpermute_b32 v100, v178, v85
	v_lshl_add_u64 v[82:83], s[8:9], 0, v[166:167]
	v_lshl_add_u64 v[98:99], v[154:155], 1, v[82:83]
	v_cvt_pk_bf16_f32 v84, v86, v87
	v_cvt_pk_bf16_f32 v86, v96, v97
	s_waitcnt lgkmcnt(0)
	v_add_f32_e32 v82, v85, v100
	ds_bpermute_b32 v83, v177, v82
	v_cvt_pk_bf16_f32 v85, v88, v89
	v_cvt_pk_bf16_f32 v87, v94, v95
	global_store_dwordx4 v[98:99], v[90:93], off
	global_store_dwordx4 v[98:99], v[84:87], off offset:256
	s_and_saveexec_b64 s[24:25], vcc
	s_cbranch_execz .LBB0_2959
	v_lshlrev_b64 v[84:85], 6, v[164:165]
	v_lshl_add_u64 v[84:85], s[12:13], 0, v[84:85]
	v_lshl_add_u64 v[84:85], s[22:23], 2, v[84:85]
	s_lshl_b32 s96, s47, 2
	v_lshl_add_u64 v[84:85], v[84:85], 0, s[96:97]
	s_waitcnt lgkmcnt(0)
	v_add_f32_e32 v82, v82, v83
	global_store_dword v[84:85], v82, off
; DI u32x4 pk8(f32x4 a, f32x4 b) { u32x4 o; o.x = pk2(a.x, a.y); o.y = pk2(a.z, a.w); o.z = pk2(b.x, b.y); o.w = pk2(b.z, b.w); return o; }
;     DI void operator()(const AccT& acc, const Unit& u, int wr, int wc, int fr, int fq) const {
;     ...
;                 for (int bj = 0; bj < 2; ++bj) hv[m][bj] = *(const u32x4*)(hb + (row0 + ai * 128 + m * 16) * D + col0 + bj * 128);
; #pragma unroll
;             for (int m = 0; m < 4; ++m) {
;                 const size_t row = row0 + ai * 128 + m * 16;
;                 float sq = 0.f;
; #pragma unroll
;                 for (int bj = 0; bj < 2; ++bj) {
;                     const u32x4 w = hv[m][bj];
;                     f32x4 a, b;
;                     a.x = __uint_as_float(w.x << 16); a.y = __uint_as_float(w.x & 0xffff0000u); a.z = __uint_as_float(w.y << 16); a.w = __uint_as_float(w.y & 0xffff0000u);
;                     b.x = __uint_as_float(w.z << 16); b.y = __uint_as_float(w.z & 0xffff0000u); b.z = __uint_as_float(w.w << 16); b.w = __uint_as_float(w.w & 0xffff0000u);
;                     a += acc[ai][bj][m][0] * alpha; b += acc[ai][bj][m][1] * alpha;
;                     sq += (a.x * a.x + a.y * a.y) + (a.z * a.z + a.w * a.w) + (b.x * b.x + b.y * b.y) + (b.z * b.z + b.w * b.w);
;                     *(u32x4*)(hb + row * D + col0 + bj * 128) = pk8(a, b);
;                 }
;                 sq += __shfl_xor(sq, 16); sq += __shfl_xor(sq, 32);
;                 if (fq == 0) ss[row * 16 + u.pn * 4 + wc] = sq;
;             }
.LBB0_2959:
	s_or_b64 exec, exec, s[24:25]
	v_lshlrev_b32_e32 v82, 16, v134
	s_waitcnt lgkmcnt(0)
	v_and_b32_e32 v83, 0xffff0000, v134
	v_lshlrev_b32_e32 v84, 16, v135
	v_and_b32_e32 v85, 0xffff0000, v135
	v_lshlrev_b32_e32 v86, 16, v136
	v_and_b32_e32 v87, 0xffff0000, v136
	v_lshlrev_b32_e32 v88, 16, v137
	v_and_b32_e32 v89, 0xffff0000, v137
	v_pk_fma_f32 v[80:81], s[14:15], v[80:81], v[84:85]
	v_pk_fma_f32 v[78:79], s[4:5], v[78:79], v[82:83]
	v_pk_fma_f32 v[82:83], s[14:15], v[76:77], v[88:89]
	v_pk_fma_f32 v[76:77], s[4:5], v[74:75], v[86:87]
	v_mul_f32_e32 v74, v79, v79
	v_mul_f32_e32 v75, v81, v81
	v_fmac_f32_e32 v74, v78, v78
	v_fmac_f32_e32 v75, v80, v80
	v_add_f32_e32 v74, v74, v75
	v_mul_f32_e32 v75, v77, v77
	v_fmac_f32_e32 v75, v76, v76
	v_add_f32_e32 v74, v75, v74
	v_mul_f32_e32 v75, v83, v83
	v_fmac_f32_e32 v75, v82, v82
	v_add_f32_e32 v86, v75, v74
	v_cvt_pk_bf16_f32 v74, v78, v79
	v_cvt_pk_bf16_f32 v75, v80, v81
	v_lshlrev_b32_e32 v78, 16, v130
	v_and_b32_e32 v79, 0xffff0000, v130
	v_lshlrev_b32_e32 v80, 16, v131
	v_and_b32_e32 v81, 0xffff0000, v131
	v_cvt_pk_bf16_f32 v76, v76, v77
	v_cvt_pk_bf16_f32 v77, v82, v83
	v_lshlrev_b32_e32 v82, 16, v132
	v_and_b32_e32 v83, 0xffff0000, v132
	v_pk_fma_f32 v[72:73], s[14:15], v[72:73], v[80:81]
	v_pk_fma_f32 v[70:71], s[4:5], v[70:71], v[78:79]
	v_pk_fma_f32 v[80:81], s[4:5], v[66:67], v[82:83]
	v_mul_f32_e32 v66, v71, v71
	v_mul_f32_e32 v67, v73, v73
	v_fmac_f32_e32 v66, v70, v70
	v_fmac_f32_e32 v67, v72, v72
	v_lshlrev_b32_e32 v84, 16, v133
	v_and_b32_e32 v85, 0xffff0000, v133
	v_add_f32_e32 v66, v66, v67
	v_mul_f32_e32 v67, v81, v81
	v_pk_fma_f32 v[78:79], s[14:15], v[68:69], v[84:85]
	v_fmac_f32_e32 v67, v80, v80
	v_add_f32_e32 v66, v67, v66
	v_mul_f32_e32 v67, v79, v79
	v_fmac_f32_e32 v67, v78, v78
	v_add_f32_e32 v66, v67, v66
	v_add_f32_e32 v69, v86, v66
	ds_bpermute_b32 v84, v178, v69
	v_lshl_add_u64 v[66:67], s[8:9], 0, v[162:163]
	v_lshl_add_u64 v[82:83], v[154:155], 1, v[66:67]
	v_cvt_pk_bf16_f32 v68, v70, v71
	v_cvt_pk_bf16_f32 v70, v80, v81
	s_waitcnt lgkmcnt(0)
	v_add_f32_e32 v66, v69, v84
	ds_bpermute_b32 v67, v177, v66
	v_cvt_pk_bf16_f32 v69, v72, v73
	v_cvt_pk_bf16_f32 v71, v78, v79
	global_store_dwordx4 v[82:83], v[74:77], off
	global_store_dwordx4 v[82:83], v[68:71], off offset:256
	s_and_saveexec_b64 s[24:25], vcc
	s_cbranch_execz .LBB0_2961
	v_lshlrev_b64 v[68:69], 6, v[160:161]
	v_lshl_add_u64 v[68:69], s[12:13], 0, v[68:69]
	v_lshl_add_u64 v[68:69], s[22:23], 2, v[68:69]
	s_lshl_b32 s96, s47, 2
	v_lshl_add_u64 v[68:69], v[68:69], 0, s[96:97]
	s_waitcnt lgkmcnt(0)
	v_add_f32_e32 v66, v66, v67
	global_store_dword v[68:69], v66, off
.LBB0_2961:
	s_or_b64 exec, exec, s[24:25]
	v_lshl_add_u64 v[102:103], v[156:157], 0, s[58:59]
	v_lshlrev_b64 v[112:113], 11, v[102:103]
	s_waitcnt lgkmcnt(0)
	v_lshl_add_u64 v[66:67], v[158:159], 0, v[112:113]
	global_load_dwordx4 v[104:107], v[66:67], off
	global_load_dwordx4 v[108:111], v[66:67], off offset:256
	s_mov_b64 s[24:25], 0x90
	v_lshl_add_u64 v[98:99], v[156:157], 0, s[24:25]
	s_mov_b64 s[24:25], 0xa0
	v_lshlrev_b64 v[100:101], 11, v[98:99]
	v_lshl_add_u64 v[94:95], v[156:157], 0, s[24:25]
	s_mov_b64 s[24:25], 0xb0
	v_lshl_add_u64 v[66:67], v[158:159], 0, v[100:101]
	v_lshlrev_b64 v[96:97], 11, v[94:95]
	v_lshl_add_u64 v[90:91], v[156:157], 0, s[24:25]
	global_load_dwordx4 v[86:89], v[66:67], off
	global_load_dwordx4 v[82:85], v[66:67], off offset:256
	v_lshl_add_u64 v[66:67], v[158:159], 0, v[96:97]
	v_lshlrev_b64 v[92:93], 11, v[90:91]
	global_load_dwordx4 v[78:81], v[66:67], off
	global_load_dwordx4 v[74:77], v[66:67], off offset:256
	v_lshl_add_u64 v[66:67], v[158:159], 0, v[92:93]
	global_load_dwordx4 v[70:73], v[66:67], off
	s_nop 0
	global_load_dwordx4 v[66:69], v[66:67], off offset:256
	s_waitcnt vmcnt(0) lgkmcnt(0)
	v_lshlrev_b32_e32 v114, 16, v104
	v_and_b32_e32 v115, 0xffff0000, v104
	v_lshlrev_b32_e32 v104, 16, v105
	v_and_b32_e32 v105, 0xffff0000, v105
	v_lshlrev_b32_e32 v116, 16, v106
	v_and_b32_e32 v117, 0xffff0000, v106
	v_lshlrev_b32_e32 v106, 16, v107
	v_and_b32_e32 v107, 0xffff0000, v107
	v_pk_fma_f32 v[64:65], s[14:15], v[64:65], v[104:105]
	v_pk_fma_f32 v[62:63], s[4:5], v[62:63], v[114:115]
	v_pk_fma_f32 v[104:105], s[14:15], v[60:61], v[106:107]
	v_mul_f32_e32 v60, v63, v63
	v_mul_f32_e32 v61, v65, v65
	v_pk_fma_f32 v[58:59], s[4:5], v[58:59], v[116:117]
	v_fmac_f32_e32 v60, v62, v62
	v_fmac_f32_e32 v61, v64, v64
	v_add_f32_e32 v60, v60, v61
	v_mul_f32_e32 v61, v59, v59
	v_fmac_f32_e32 v61, v58, v58
	v_add_f32_e32 v60, v61, v60
	v_mul_f32_e32 v61, v105, v105
	v_fmac_f32_e32 v61, v104, v104
	v_add_f32_e32 v106, v61, v60
	v_cvt_pk_bf16_f32 v60, v62, v63
	v_cvt_pk_bf16_f32 v62, v58, v59
	v_lshl_add_u64 v[58:59], s[8:9], 0, v[112:113]
	v_cvt_pk_bf16_f32 v61, v64, v65
	v_cvt_pk_bf16_f32 v63, v104, v105
	v_lshl_add_u64 v[58:59], v[154:155], 1, v[58:59]
	global_store_dwordx4 v[58:59], v[60:63], off
	v_lshlrev_b32_e32 v64, 16, v110
	v_and_b32_e32 v65, 0xffff0000, v110
	v_lshlrev_b32_e32 v60, 16, v108
	v_and_b32_e32 v61, 0xffff0000, v108
	v_lshlrev_b32_e32 v62, 16, v109
	v_and_b32_e32 v63, 0xffff0000, v109
	v_lshlrev_b32_e32 v104, 16, v111
	v_and_b32_e32 v105, 0xffff0000, v111
	v_pk_fma_f32 v[56:57], s[14:15], v[56:57], v[62:63]
	v_pk_fma_f32 v[54:55], s[4:5], v[54:55], v[60:61]
	v_pk_fma_f32 v[60:61], s[14:15], v[52:53], v[104:105]
	v_pk_fma_f32 v[52:53], s[4:5], v[50:51], v[64:65]
	v_mul_f32_e32 v50, v55, v55
	v_mul_f32_e32 v51, v57, v57
	v_fmac_f32_e32 v50, v54, v54
	v_fmac_f32_e32 v51, v56, v56
	v_add_f32_e32 v50, v50, v51
	v_mul_f32_e32 v51, v53, v53
	v_fmac_f32_e32 v51, v52, v52
	v_add_f32_e32 v50, v51, v50
	v_mul_f32_e32 v51, v61, v61
	v_fmac_f32_e32 v51, v60, v60
	v_add_f32_e32 v50, v51, v50
	v_add_f32_e32 v62, v106, v50
	v_cvt_pk_bf16_f32 v50, v54, v55
	v_cvt_pk_bf16_f32 v51, v56, v57
	v_cvt_pk_bf16_f32 v52, v52, v53
	v_cvt_pk_bf16_f32 v53, v60, v61
	global_store_dwordx4 v[58:59], v[50:53], off offset:256
	ds_bpermute_b32 v50, v178, v62
	s_waitcnt lgkmcnt(0)
	v_add_f32_e32 v50, v62, v50
	ds_bpermute_b32 v51, v177, v50
	s_and_saveexec_b64 s[24:25], vcc
	s_cbranch_execz .LBB0_2963
	v_lshlrev_b64 v[52:53], 6, v[102:103]
	v_lshl_add_u64 v[52:53], s[12:13], 0, v[52:53]
	v_lshl_add_u64 v[52:53], s[22:23], 2, v[52:53]
	s_lshl_b32 s96, s47, 2
	v_lshl_add_u64 v[52:53], v[52:53], 0, s[96:97]
	s_waitcnt lgkmcnt(0)
	v_add_f32_e32 v50, v50, v51
	global_store_dword v[52:53], v50, off
; DI u32x4 pk8(f32x4 a, f32x4 b) { u32x4 o; o.x = pk2(a.x, a.y); o.y = pk2(a.z, a.w); o.z = pk2(b.x, b.y); o.w = pk2(b.z, b.w); return o; }
;     DI void operator()(const AccT& acc, const Unit& u, int wr, int wc, int fr, int fq) const {
;     ...
;                 for (int bj = 0; bj < 2; ++bj) hv[m][bj] = *(const u32x4*)(hb + (row0 + ai * 128 + m * 16) * D + col0 + bj * 128);
; #pragma unroll
;             for (int m = 0; m < 4; ++m) {
;                 const size_t row = row0 + ai * 128 + m * 16;
;                 float sq = 0.f;
; #pragma unroll
;                 for (int bj = 0; bj < 2; ++bj) {
;                     const u32x4 w = hv[m][bj];
;                     f32x4 a, b;
;                     a.x = __uint_as_float(w.x << 16); a.y = __uint_as_float(w.x & 0xffff0000u); a.z = __uint_as_float(w.y << 16); a.w = __uint_as_float(w.y & 0xffff0000u);
;                     b.x = __uint_as_float(w.z << 16); b.y = __uint_as_float(w.z & 0xffff0000u); b.z = __uint_as_float(w.w << 16); b.w = __uint_as_float(w.w & 0xffff0000u);
;                     a += acc[ai][bj][m][0] * alpha; b += acc[ai][bj][m][1] * alpha;
;                     sq += (a.x * a.x + a.y * a.y) + (a.z * a.z + a.w * a.w) + (b.x * b.x + b.y * b.y) + (b.z * b.z + b.w * b.w);
;                     *(u32x4*)(hb + row * D + col0 + bj * 128) = pk8(a, b);
;                 }
;                 sq += __shfl_xor(sq, 16); sq += __shfl_xor(sq, 32);
;                 if (fq == 0) ss[row * 16 + u.pn * 4 + wc] = sq;
;             }
.LBB0_2963:
	s_or_b64 exec, exec, s[24:25]
	v_lshlrev_b32_e32 v50, 16, v86
	s_waitcnt lgkmcnt(0)
	v_and_b32_e32 v51, 0xffff0000, v86
	v_lshlrev_b32_e32 v52, 16, v87
	v_and_b32_e32 v53, 0xffff0000, v87
	v_lshlrev_b32_e32 v54, 16, v88
	v_and_b32_e32 v55, 0xffff0000, v88
	v_lshlrev_b32_e32 v56, 16, v89
	v_and_b32_e32 v57, 0xffff0000, v89
	v_pk_fma_f32 v[48:49], s[14:15], v[48:49], v[52:53]
	v_pk_fma_f32 v[46:47], s[4:5], v[46:47], v[50:51]
	v_pk_fma_f32 v[50:51], s[14:15], v[44:45], v[56:57]
	v_pk_fma_f32 v[44:45], s[4:5], v[42:43], v[54:55]
	v_mul_f32_e32 v42, v47, v47
	v_mul_f32_e32 v43, v49, v49
	v_fmac_f32_e32 v42, v46, v46
	v_fmac_f32_e32 v43, v48, v48
	v_add_f32_e32 v42, v42, v43
	v_mul_f32_e32 v43, v45, v45
	v_fmac_f32_e32 v43, v44, v44
	v_add_f32_e32 v42, v43, v42
	v_mul_f32_e32 v43, v51, v51
	v_fmac_f32_e32 v43, v50, v50
	v_add_f32_e32 v54, v43, v42
	v_cvt_pk_bf16_f32 v42, v46, v47
	v_cvt_pk_bf16_f32 v43, v48, v49
	v_lshlrev_b32_e32 v46, 16, v82
	v_and_b32_e32 v47, 0xffff0000, v82
	v_lshlrev_b32_e32 v48, 16, v83
	v_and_b32_e32 v49, 0xffff0000, v83
	v_cvt_pk_bf16_f32 v44, v44, v45
	v_cvt_pk_bf16_f32 v45, v50, v51
	v_lshlrev_b32_e32 v50, 16, v84
	v_and_b32_e32 v51, 0xffff0000, v84
	v_pk_fma_f32 v[40:41], s[14:15], v[40:41], v[48:49]
	v_pk_fma_f32 v[38:39], s[4:5], v[38:39], v[46:47]
	v_pk_fma_f32 v[48:49], s[4:5], v[34:35], v[50:51]
	v_mul_f32_e32 v34, v39, v39
	v_mul_f32_e32 v35, v41, v41
	v_fmac_f32_e32 v34, v38, v38
	v_fmac_f32_e32 v35, v40, v40
	v_lshlrev_b32_e32 v52, 16, v85
	v_and_b32_e32 v53, 0xffff0000, v85
	v_add_f32_e32 v34, v34, v35
	v_mul_f32_e32 v35, v49, v49
	v_pk_fma_f32 v[46:47], s[14:15], v[36:37], v[52:53]
	v_fmac_f32_e32 v35, v48, v48
	v_add_f32_e32 v34, v35, v34
	v_mul_f32_e32 v35, v47, v47
	v_fmac_f32_e32 v35, v46, v46
	v_add_f32_e32 v34, v35, v34
	v_add_f32_e32 v37, v54, v34
	ds_bpermute_b32 v52, v178, v37
	v_lshl_add_u64 v[34:35], s[8:9], 0, v[100:101]
	v_lshl_add_u64 v[50:51], v[154:155], 1, v[34:35]
	v_cvt_pk_bf16_f32 v36, v38, v39
	v_cvt_pk_bf16_f32 v38, v48, v49
	s_waitcnt lgkmcnt(0)
	v_add_f32_e32 v34, v37, v52
	ds_bpermute_b32 v35, v177, v34
	v_cvt_pk_bf16_f32 v37, v40, v41
	v_cvt_pk_bf16_f32 v39, v46, v47
	global_store_dwordx4 v[50:51], v[42:45], off
	global_store_dwordx4 v[50:51], v[36:39], off offset:256
	s_and_saveexec_b64 s[24:25], vcc
	s_cbranch_execz .LBB0_2965
	v_lshlrev_b64 v[36:37], 6, v[98:99]
	v_lshl_add_u64 v[36:37], s[12:13], 0, v[36:37]
	v_lshl_add_u64 v[36:37], s[22:23], 2, v[36:37]
	s_lshl_b32 s96, s47, 2
	v_lshl_add_u64 v[36:37], v[36:37], 0, s[96:97]
	s_waitcnt lgkmcnt(0)
	v_add_f32_e32 v34, v34, v35
	global_store_dword v[36:37], v34, off
; DI u32x4 pk8(f32x4 a, f32x4 b) { u32x4 o; o.x = pk2(a.x, a.y); o.y = pk2(a.z, a.w); o.z = pk2(b.x, b.y); o.w = pk2(b.z, b.w); return o; }
;     DI void operator()(const AccT& acc, const Unit& u, int wr, int wc, int fr, int fq) const {
;     ...
;                 for (int bj = 0; bj < 2; ++bj) hv[m][bj] = *(const u32x4*)(hb + (row0 + ai * 128 + m * 16) * D + col0 + bj * 128);
; #pragma unroll
;             for (int m = 0; m < 4; ++m) {
;                 const size_t row = row0 + ai * 128 + m * 16;
;                 float sq = 0.f;
; #pragma unroll
;                 for (int bj = 0; bj < 2; ++bj) {
;                     const u32x4 w = hv[m][bj];
;                     f32x4 a, b;
;                     a.x = __uint_as_float(w.x << 16); a.y = __uint_as_float(w.x & 0xffff0000u); a.z = __uint_as_float(w.y << 16); a.w = __uint_as_float(w.y & 0xffff0000u);
;                     b.x = __uint_as_float(w.z << 16); b.y = __uint_as_float(w.z & 0xffff0000u); b.z = __uint_as_float(w.w << 16); b.w = __uint_as_float(w.w & 0xffff0000u);
;                     a += acc[ai][bj][m][0] * alpha; b += acc[ai][bj][m][1] * alpha;
;                     sq += (a.x * a.x + a.y * a.y) + (a.z * a.z + a.w * a.w) + (b.x * b.x + b.y * b.y) + (b.z * b.z + b.w * b.w);
;                     *(u32x4*)(hb + row * D + col0 + bj * 128) = pk8(a, b);
;                 }
;                 sq += __shfl_xor(sq, 16); sq += __shfl_xor(sq, 32);
;                 if (fq == 0) ss[row * 16 + u.pn * 4 + wc] = sq;
;             }
.LBB0_2965:
	s_or_b64 exec, exec, s[24:25]
	v_lshlrev_b32_e32 v34, 16, v78
	s_waitcnt lgkmcnt(0)
	v_and_b32_e32 v35, 0xffff0000, v78
	v_lshlrev_b32_e32 v36, 16, v79
	v_and_b32_e32 v37, 0xffff0000, v79
	v_lshlrev_b32_e32 v38, 16, v80
	v_and_b32_e32 v39, 0xffff0000, v80
	v_lshlrev_b32_e32 v40, 16, v81
	v_and_b32_e32 v41, 0xffff0000, v81
	v_pk_fma_f32 v[32:33], s[14:15], v[32:33], v[36:37]
	v_pk_fma_f32 v[30:31], s[4:5], v[30:31], v[34:35]
	v_pk_fma_f32 v[34:35], s[14:15], v[28:29], v[40:41]
	v_pk_fma_f32 v[28:29], s[4:5], v[26:27], v[38:39]
	v_mul_f32_e32 v26, v31, v31
	v_mul_f32_e32 v27, v33, v33
	v_fmac_f32_e32 v26, v30, v30
	v_fmac_f32_e32 v27, v32, v32
	v_add_f32_e32 v26, v26, v27
	v_mul_f32_e32 v27, v29, v29
	v_fmac_f32_e32 v27, v28, v28
	v_add_f32_e32 v26, v27, v26
	v_mul_f32_e32 v27, v35, v35
	v_fmac_f32_e32 v27, v34, v34
	v_add_f32_e32 v38, v27, v26
	v_cvt_pk_bf16_f32 v26, v30, v31
	v_cvt_pk_bf16_f32 v27, v32, v33
	v_lshlrev_b32_e32 v30, 16, v74
	v_and_b32_e32 v31, 0xffff0000, v74
	v_lshlrev_b32_e32 v32, 16, v75
	v_and_b32_e32 v33, 0xffff0000, v75
	v_cvt_pk_bf16_f32 v28, v28, v29
	v_cvt_pk_bf16_f32 v29, v34, v35
	v_lshlrev_b32_e32 v34, 16, v76
	v_and_b32_e32 v35, 0xffff0000, v76
	v_pk_fma_f32 v[24:25], s[14:15], v[24:25], v[32:33]
	v_pk_fma_f32 v[22:23], s[4:5], v[22:23], v[30:31]
	v_pk_fma_f32 v[32:33], s[4:5], v[18:19], v[34:35]
	v_mul_f32_e32 v18, v23, v23
	v_mul_f32_e32 v19, v25, v25
	v_fmac_f32_e32 v18, v22, v22
	v_fmac_f32_e32 v19, v24, v24
	v_lshlrev_b32_e32 v36, 16, v77
	v_and_b32_e32 v37, 0xffff0000, v77
	v_add_f32_e32 v18, v18, v19
	v_mul_f32_e32 v19, v33, v33
	v_pk_fma_f32 v[30:31], s[14:15], v[20:21], v[36:37]
	v_fmac_f32_e32 v19, v32, v32
	v_add_f32_e32 v18, v19, v18
	v_mul_f32_e32 v19, v31, v31
	v_fmac_f32_e32 v19, v30, v30
	v_add_f32_e32 v18, v19, v18
	v_add_f32_e32 v21, v38, v18
	ds_bpermute_b32 v36, v178, v21
	v_lshl_add_u64 v[18:19], s[8:9], 0, v[96:97]
	v_lshl_add_u64 v[34:35], v[154:155], 1, v[18:19]
	v_cvt_pk_bf16_f32 v20, v22, v23
	v_cvt_pk_bf16_f32 v22, v32, v33
	s_waitcnt lgkmcnt(0)
	v_add_f32_e32 v18, v21, v36
	ds_bpermute_b32 v19, v177, v18
	v_cvt_pk_bf16_f32 v21, v24, v25
	v_cvt_pk_bf16_f32 v23, v30, v31
	global_store_dwordx4 v[34:35], v[26:29], off
	global_store_dwordx4 v[34:35], v[20:23], off offset:256
	s_and_saveexec_b64 s[24:25], vcc
	s_cbranch_execz .LBB0_2967
	v_lshlrev_b64 v[20:21], 6, v[94:95]
	v_lshl_add_u64 v[20:21], s[12:13], 0, v[20:21]
	v_lshl_add_u64 v[20:21], s[22:23], 2, v[20:21]
	s_lshl_b32 s96, s47, 2
	v_lshl_add_u64 v[20:21], v[20:21], 0, s[96:97]
	s_waitcnt lgkmcnt(0)
	v_add_f32_e32 v18, v18, v19
	global_store_dword v[20:21], v18, off
.LBB0_2967:
	s_or_b64 exec, exec, s[24:25]
	v_lshlrev_b32_e32 v18, 16, v70
	s_waitcnt lgkmcnt(0)
	v_and_b32_e32 v19, 0xffff0000, v70
	v_lshlrev_b32_e32 v20, 16, v71
	v_and_b32_e32 v21, 0xffff0000, v71
	v_lshlrev_b32_e32 v22, 16, v72
	v_and_b32_e32 v23, 0xffff0000, v72
	v_lshlrev_b32_e32 v24, 16, v73
	v_and_b32_e32 v25, 0xffff0000, v73
	v_pk_fma_f32 v[16:17], s[14:15], v[16:17], v[20:21]
	v_pk_fma_f32 v[14:15], s[4:5], v[14:15], v[18:19]
	v_pk_fma_f32 v[18:19], s[14:15], v[12:13], v[24:25]
	v_pk_fma_f32 v[12:13], s[4:5], v[10:11], v[22:23]
	v_mul_f32_e32 v10, v15, v15
	v_mul_f32_e32 v11, v17, v17
	v_fmac_f32_e32 v10, v14, v14
	v_fmac_f32_e32 v11, v16, v16
	v_add_f32_e32 v10, v10, v11
	v_mul_f32_e32 v11, v13, v13
	v_fmac_f32_e32 v11, v12, v12
	v_add_f32_e32 v10, v11, v10
	v_mul_f32_e32 v11, v19, v19
	v_fmac_f32_e32 v11, v18, v18
	v_add_f32_e32 v22, v11, v10
	v_cvt_pk_bf16_f32 v10, v14, v15
	v_cvt_pk_bf16_f32 v11, v16, v17
	v_lshlrev_b32_e32 v14, 16, v66
	v_and_b32_e32 v15, 0xffff0000, v66
	v_lshlrev_b32_e32 v16, 16, v67
	v_and_b32_e32 v17, 0xffff0000, v67
	v_cvt_pk_bf16_f32 v12, v12, v13
	v_cvt_pk_bf16_f32 v13, v18, v19
	v_lshlrev_b32_e32 v18, 16, v68
	v_and_b32_e32 v19, 0xffff0000, v68
	v_pk_fma_f32 v[8:9], s[14:15], v[8:9], v[16:17]
	v_pk_fma_f32 v[6:7], s[4:5], v[6:7], v[14:15]
	v_pk_fma_f32 v[16:17], s[4:5], v[2:3], v[18:19]
	v_mul_f32_e32 v2, v7, v7
	v_mul_f32_e32 v3, v9, v9
	v_fmac_f32_e32 v2, v6, v6
	v_fmac_f32_e32 v3, v8, v8
	v_lshlrev_b32_e32 v20, 16, v69
	v_and_b32_e32 v21, 0xffff0000, v69
	v_add_f32_e32 v2, v2, v3
	v_mul_f32_e32 v3, v17, v17
	v_pk_fma_f32 v[14:15], s[14:15], v[4:5], v[20:21]
	v_fmac_f32_e32 v3, v16, v16
	v_add_f32_e32 v2, v3, v2
	v_mul_f32_e32 v3, v15, v15
	v_fmac_f32_e32 v3, v14, v14
	v_add_f32_e32 v2, v3, v2
	v_add_f32_e32 v5, v22, v2
	ds_bpermute_b32 v20, v178, v5
	v_lshl_add_u64 v[2:3], s[8:9], 0, v[92:93]
	v_lshl_add_u64 v[18:19], v[154:155], 1, v[2:3]
	v_cvt_pk_bf16_f32 v4, v6, v7
	v_cvt_pk_bf16_f32 v6, v16, v17
	s_waitcnt lgkmcnt(0)
	v_add_f32_e32 v2, v5, v20
	ds_bpermute_b32 v3, v177, v2
	v_cvt_pk_bf16_f32 v5, v8, v9
	v_cvt_pk_bf16_f32 v7, v14, v15
	global_store_dwordx4 v[18:19], v[10:13], off
	global_store_dwordx4 v[18:19], v[4:7], off offset:256
	s_and_saveexec_b64 s[24:25], vcc
	s_cbranch_execz .LBB0_2969
	v_lshlrev_b64 v[4:5], 6, v[90:91]
	v_lshl_add_u64 v[4:5], s[12:13], 0, v[4:5]
	v_lshl_add_u64 v[4:5], s[22:23], 2, v[4:5]
	s_lshl_b32 s96, s47, 2
	v_lshl_add_u64 v[4:5], v[4:5], 0, s[96:97]
	s_waitcnt lgkmcnt(0)
	v_add_f32_e32 v2, v2, v3
	global_store_dword v[4:5], v2, off

; DI unsigned xb_ld(unsigned* p)              { return __hip_atomic_load(p, __ATOMIC_RELAXED, __HIP_MEMORY_SCOPE_AGENT); }
; DI void xcd_barrier_complete(unsigned* bar, unsigned x, unsigned& nloc, unsigned& nx) {
;     ...
;     for (;;) {
;         sum = 0u; cnt = 0u; mine = 0u;
; #pragma unroll
;         for (unsigned j = 0; j < 16; ++j) { const unsigned c = xb_ld(&bar[XB_XCNT(j)]); sum += c; cnt += (c > 0u) ? 1u : 0u; mine = (j == x) ? c : mine; }
;         if (sum == G) break;
;         __builtin_amdgcn_s_sleep(1);
;         if ((++sp & 255u) == 0u) { if (xb_ld(&bar[XB_TMO])) break; if (sp > XB_SPIN_CAP) { atomicAdd(&bar[XB_TMO], 1u); break; } }
;     }
;     nloc = mine > 0u ? mine : 1u; nx = cnt > 0u ? cnt : 1u;
.LBB0_2979:
	v_mov_b64_e32 v[2:3], s[2:3]
	s_waitcnt lgkmcnt(0)
	global_load_dword v0, v[2:3], off sc1
	v_mov_b64_e32 v[2:3], s[4:5]
	global_load_dword v2, v[2:3], off sc1
	v_mov_b64_e32 v[4:5], s[6:7]
	global_load_dword v3, v[4:5], off sc1
	v_mov_b64_e32 v[4:5], s[8:9]
	global_load_dword v4, v[4:5], off sc1
	s_or_b64 s[54:55], s[54:55], exec
	s_or_b64 s[50:51], s[50:51], exec
	s_waitcnt vmcnt(0) lgkmcnt(0)
	v_add_u32_e32 v6, v2, v0
	v_add_u32_e32 v6, v6, v3
	v_add_u32_e32 v8, v6, v4
	v_mov_b64_e32 v[6:7], s[12:13]
	global_load_dword v5, v[6:7], off sc1
	v_mov_b64_e32 v[6:7], s[14:15]
	global_load_dword v6, v[6:7], off sc1
	s_waitcnt vmcnt(0) lgkmcnt(0)
	v_add_u32_e32 v8, v8, v5
	v_add_u32_e32 v10, v8, v6
	v_mov_b64_e32 v[8:9], s[16:17]
	global_load_dword v7, v[8:9], off sc1
	v_mov_b64_e32 v[8:9], s[18:19]
	global_load_dword v8, v[8:9], off sc1
	s_waitcnt vmcnt(0) lgkmcnt(0)
	v_add_u32_e32 v10, v10, v7
	v_add_u32_e32 v12, v10, v8
	v_mov_b64_e32 v[10:11], s[20:21]
	global_load_dword v9, v[10:11], off sc1
	v_mov_b64_e32 v[10:11], s[22:23]
	global_load_dword v10, v[10:11], off sc1
	s_waitcnt vmcnt(0) lgkmcnt(0)
	v_add_u32_e32 v12, v12, v9
	v_add_u32_e32 v14, v12, v10
	v_mov_b64_e32 v[12:13], s[24:25]
	global_load_dword v11, v[12:13], off sc1
	v_mov_b64_e32 v[12:13], s[26:27]
	global_load_dword v12, v[12:13], off sc1
	s_waitcnt vmcnt(0) lgkmcnt(0)
	v_add_u32_e32 v14, v14, v11
	v_add_u32_e32 v16, v14, v12
	v_mov_b64_e32 v[14:15], s[28:29]
	global_load_dword v13, v[14:15], off sc1
	v_mov_b64_e32 v[14:15], s[30:31]
	global_load_dword v14, v[14:15], off sc1
	s_waitcnt vmcnt(0) lgkmcnt(0)
	v_add_u32_e32 v16, v16, v13
	v_add_u32_e32 v18, v16, v14
	v_mov_b64_e32 v[16:17], s[46:47]
	global_load_dword v15, v[16:17], off sc1
	v_mov_b64_e32 v[16:17], s[44:45]
	global_load_dword v16, v[16:17], off sc1
	s_waitcnt vmcnt(0) lgkmcnt(0)
	v_add_u32_e32 v18, v18, v15
	v_add_u32_e32 v17, v18, v16
	v_cmp_ne_u32_e32 vcc, s33, v17
	s_and_saveexec_b64 s[56:57], vcc
	s_cbranch_execz .LBB0_2978
	s_and_b32 s64, s91, 0xff
	s_mov_b64 s[60:61], -1
	s_cmp_eq_u32 s64, 0
	s_mov_b64 s[84:85], -1
	s_mov_b64 s[64:65], -1
	s_sleep 1
	s_cbranch_scc1 .LBB0_2982
	s_and_saveexec_b64 s[66:67], s[84:85]
	s_cbranch_execz .LBB0_2977
	s_branch .LBB0_2985
.LBB0_2982:
	v_mov_b64_e32 v[18:19], s[0:1]
	global_load_dword v17, v[18:19], off sc1
	s_mov_b64 s[84:85], 0
	s_waitcnt vmcnt(0) lgkmcnt(0)
	v_cmp_eq_u32_e32 vcc, 0, v17
	s_and_saveexec_b64 s[66:67], vcc
	s_cmp_lt_u32 s91, 0x40001
	s_cselect_b64 s[70:71], -1, 0
	s_xor_b64 s[64:65], exec, -1
	s_and_b64 s[84:85], s[70:71], exec
	s_or_b64 exec, exec, s[66:67]
	s_and_saveexec_b64 s[66:67], s[84:85]
	s_cbranch_execz .LBB0_2977

; DI unsigned xb_ld(unsigned* p)              { return __hip_atomic_load(p, __ATOMIC_RELAXED, __HIP_MEMORY_SCOPE_AGENT); }
; DI unsigned xb_add(unsigned* p, unsigned v) { return __hip_atomic_fetch_add(p, v, __ATOMIC_RELAXED, __HIP_MEMORY_SCOPE_AGENT); }
; #define XB_SPIN(cond, bar) do { unsigned _sp = 0; while (cond) { __builtin_amdgcn_s_sleep(1); \
;     if ((++_sp & 255u) == 0u) { if (xb_ld(&(bar)[XB_TMO])) break; if (_sp > XB_SPIN_CAP) { atomicAdd(&(bar)[XB_TMO], 1u); break; } } } } while (0)
; DI void xcd_barrier(int wv, unsigned* bar, volatile LAS unsigned* st) {
;     ...
;         const unsigned old = xb_add(&bar[XB_XSUB(x)], 1u);
;         const unsigned gen = old / nloc;
;         if (old + 1u == (gen + 1u) * nloc) {
;             __builtin_amdgcn_fence(__ATOMIC_RELEASE, "agent");
;             asm volatile("s_waitcnt vmcnt(0)" ::: "memory");
;             const unsigned og = xb_add(&bar[XB_TOP], 1u);
;             const unsigned tg = og / nx;
;             if (og + 1u == (tg + 1u) * nx) xb_add(&bar[XB_TOPGEN], 1u);
;             else XB_SPIN(xb_ld(&bar[XB_TOPGEN]) == tg, bar);
;             __builtin_amdgcn_fence(__ATOMIC_ACQUIRE, "agent");
;             xb_add(&bar[XB_XGEN(x)], 1u);
;             asm volatile("s_waitcnt vmcnt(0)" ::: "memory");
;         } else {
;             XB_SPIN(xb_ld(&bar[XB_XGEN(x)]) == gen, bar);
.LBB0_2989:
	s_lshl_b32 s0, s90, 8
	s_add_u32 s0, s36, s0
	s_addc_u32 s1, s37, 0
	v_mov_b32_e32 v3, s0
	v_add_co_u32_e32 v4, vcc, 0xc1000, v3
	v_mov_b32_e32 v3, s1
	s_nop 0
	v_addc_co_u32_e32 v5, vcc, 0, v3, vcc
	v_mov_b32_e32 v3, 1
	flat_atomic_add v4, v[4:5], v3 offset:1024 sc0
	v_cvt_f32_u32_e32 v3, v2
	v_sub_u32_e32 v5, 0, v2
	s_add_u32 s25, s0, 0xc0000
	s_addc_u32 s24, s1, 0
	v_rcp_iflag_f32_e32 v3, v3
	s_nop 0
	v_mul_f32_e32 v3, 0x4f7ffffe, v3
	v_cvt_u32_f32_e32 v3, v3
	v_mul_lo_u32 v5, v5, v3
	v_mul_hi_u32 v5, v3, v5
	v_add_u32_e32 v3, v3, v5
	s_waitcnt vmcnt(0) lgkmcnt(0)
	v_mul_hi_u32 v3, v4, v3
	v_mul_lo_u32 v5, v3, v2
	v_sub_u32_e32 v5, v4, v5
	v_cmp_ge_u32_e32 vcc, v5, v2
	v_add_u32_e32 v6, 1, v3
	s_nop 0
	v_cndmask_b32_e32 v3, v3, v6, vcc
	v_sub_u32_e32 v6, v5, v2
	v_cndmask_b32_e32 v5, v5, v6, vcc
	v_cmp_ge_u32_e32 vcc, v5, v2
	v_add_u32_e32 v5, 1, v3
	v_add_u32_e32 v6, 1, v4
	v_cndmask_b32_e32 v3, v3, v5, vcc
	v_mad_u64_u32 v[4:5], s[0:1], v2, v3, v[2:3]
	v_cmp_ne_u32_e32 vcc, v6, v4
	s_and_saveexec_b64 s[0:1], vcc
	s_xor_b64 s[0:1], exec, s[0:1]
	s_cbranch_execz .LBB0_3002
	v_mov_b32_e32 v0, s25
	v_add_co_u32_e32 v4, vcc, 0x2000, v0
	v_mov_b32_e32 v0, s24
	s_nop 0
	v_addc_co_u32_e32 v5, vcc, 0, v0, vcc
	global_load_dword v0, v[4:5], off offset:1024 sc1
	s_add_u32 s4, s25, 0x2400
	s_addc_u32 s5, s24, 0
	s_waitcnt vmcnt(0) lgkmcnt(0)
	v_cmp_eq_u32_e32 vcc, v0, v3
	s_and_saveexec_b64 s[2:3], vcc
	s_cbranch_execz .LBB0_3001
	s_add_u32 s6, s36, 0xc0200
	s_addc_u32 s7, s37, 0
	s_mov_b32 s26, 1
	s_mov_b64 s[8:9], 0
	s_branch .LBB0_2993

; DI unsigned xb_ld(unsigned* p)              { return __hip_atomic_load(p, __ATOMIC_RELAXED, __HIP_MEMORY_SCOPE_AGENT); }
; DI void xcd_barrier_complete(unsigned* bar, unsigned x, unsigned& nloc, unsigned& nx) {
;     ...
;     for (;;) {
;         sum = 0u; cnt = 0u; mine = 0u;
; #pragma unroll
;         for (unsigned j = 0; j < 16; ++j) { const unsigned c = xb_ld(&bar[XB_XCNT(j)]); sum += c; cnt += (c > 0u) ? 1u : 0u; mine = (j == x) ? c : mine; }
;         if (sum == G) break;
;         __builtin_amdgcn_s_sleep(1);
;         if ((++sp & 255u) == 0u) { if (xb_ld(&bar[XB_TMO])) break; if (sp > XB_SPIN_CAP) { atomicAdd(&bar[XB_TMO], 1u); break; } }
;     }
;     nloc = mine > 0u ? mine : 1u; nx = cnt > 0u ? cnt : 1u;
.LBB0_3027:
	global_load_dword v47, v[0:1], off sc1
	global_load_dword v32, v[2:3], off sc1
	global_load_dword v33, v[4:5], off sc1
	global_load_dword v34, v[6:7], off sc1
	global_load_dword v35, v[8:9], off sc1
	global_load_dword v36, v[10:11], off sc1
	global_load_dword v37, v[12:13], off sc1
	global_load_dword v38, v[14:15], off sc1
	global_load_dword v39, v[16:17], off sc1
	global_load_dword v40, v[18:19], off sc1
	global_load_dword v41, v[20:21], off sc1
	global_load_dword v42, v[22:23], off sc1
	global_load_dword v43, v[24:25], off sc1
	global_load_dword v44, v[26:27], off sc1
	global_load_dword v45, v[28:29], off sc1
	global_load_dword v46, v[30:31], off sc1
	s_or_b64 s[8:9], s[8:9], exec
	s_or_b64 s[6:7], s[6:7], exec
	s_waitcnt vmcnt(0) lgkmcnt(0)
	v_add_u32_e32 v48, v32, v47
	v_add_u32_e32 v48, v48, v33
	v_add_u32_e32 v48, v48, v34
	v_add_u32_e32 v48, v48, v35
	v_add_u32_e32 v48, v48, v36
	v_add_u32_e32 v48, v48, v37
	v_add_u32_e32 v48, v48, v38
	v_add_u32_e32 v48, v48, v39
	v_add_u32_e32 v48, v48, v40
	v_add_u32_e32 v48, v48, v41
	v_add_u32_e32 v48, v48, v42
	v_add_u32_e32 v48, v48, v43
	v_add_u32_e32 v48, v48, v44
	v_add_u32_e32 v48, v48, v45
	v_add_u32_e32 v48, v48, v46
	v_cmp_ne_u32_e32 vcc, s33, v48
	s_and_saveexec_b64 s[10:11], vcc
	s_cbranch_execz .LBB0_3026
	s_and_b32 s14, s20, 0xff
	s_mov_b64 s[12:13], -1
	s_cmp_eq_u32 s14, 0
	s_mov_b64 s[16:17], -1
	s_mov_b64 s[14:15], -1
	s_sleep 1
	s_cbranch_scc1 .LBB0_3030
	s_and_saveexec_b64 s[18:19], s[16:17]
	s_cbranch_execz .LBB0_3025
	s_branch .LBB0_3033
.LBB0_3030:
	v_mov_b64_e32 v[48:49], s[0:1]
	global_load_dword v48, v[48:49], off sc1
	s_mov_b64 s[16:17], 0
	s_waitcnt vmcnt(0) lgkmcnt(0)
	v_cmp_eq_u32_e32 vcc, 0, v48
	s_and_saveexec_b64 s[18:19], vcc
	s_cmp_lt_u32 s20, 0x40001
	s_cselect_b64 s[16:17], -1, 0
	s_xor_b64 s[14:15], exec, -1
	s_and_b64 s[16:17], s[16:17], exec
	s_or_b64 exec, exec, s[18:19]
	s_and_saveexec_b64 s[18:19], s[16:17]
	s_cbranch_execz .LBB0_3025

; DI unsigned xb_ld(unsigned* p)              { return __hip_atomic_load(p, __ATOMIC_RELAXED, __HIP_MEMORY_SCOPE_AGENT); }
; DI unsigned xb_add(unsigned* p, unsigned v) { return __hip_atomic_fetch_add(p, v, __ATOMIC_RELAXED, __HIP_MEMORY_SCOPE_AGENT); }
; #define XB_SPIN(cond, bar) do { unsigned _sp = 0; while (cond) { __builtin_amdgcn_s_sleep(1); \
;     if ((++_sp & 255u) == 0u) { if (xb_ld(&(bar)[XB_TMO])) break; if (_sp > XB_SPIN_CAP) { atomicAdd(&(bar)[XB_TMO], 1u); break; } } } } while (0)
; DI void xcd_barrier(int wv, unsigned* bar, volatile LAS unsigned* st) {
;     ...
;         const unsigned old = xb_add(&bar[XB_XSUB(x)], 1u);
;         const unsigned gen = old / nloc;
;         if (old + 1u == (gen + 1u) * nloc) {
;             __builtin_amdgcn_fence(__ATOMIC_RELEASE, "agent");
;             asm volatile("s_waitcnt vmcnt(0)" ::: "memory");
;             const unsigned og = xb_add(&bar[XB_TOP], 1u);
;             const unsigned tg = og / nx;
;             if (og + 1u == (tg + 1u) * nx) xb_add(&bar[XB_TOPGEN], 1u);
;             else XB_SPIN(xb_ld(&bar[XB_TOPGEN]) == tg, bar);
;             __builtin_amdgcn_fence(__ATOMIC_ACQUIRE, "agent");
;             xb_add(&bar[XB_XGEN(x)], 1u);
;             asm volatile("s_waitcnt vmcnt(0)" ::: "memory");
;         } else {
;             XB_SPIN(xb_ld(&bar[XB_XGEN(x)]) == gen, bar);
.LBB0_3037:
	s_lshl_b32 s0, s34, 8
	s_add_u32 s0, s74, s0
	s_addc_u32 s1, s75, 0
	v_mov_b32_e32 v1, s0
	v_add_co_u32_e32 v4, vcc, 0xc1000, v1
	v_mov_b32_e32 v1, s1
	s_nop 0
	v_addc_co_u32_e32 v5, vcc, 0, v1, vcc
	v_mov_b32_e32 v1, 1
	flat_atomic_add v1, v[4:5], v1 offset:1024 sc0
	v_cvt_f32_u32_e32 v3, v2
	v_sub_u32_e32 v4, 0, v2
	s_add_u32 s23, s0, 0xc0000
	s_addc_u32 s22, s1, 0
	v_rcp_iflag_f32_e32 v3, v3
	s_nop 0
	v_mul_f32_e32 v3, 0x4f7ffffe, v3
	v_cvt_u32_f32_e32 v3, v3
	v_mul_lo_u32 v4, v4, v3
	v_mul_hi_u32 v4, v3, v4
	v_add_u32_e32 v3, v3, v4
	s_waitcnt vmcnt(0) lgkmcnt(0)
	v_mul_hi_u32 v3, v1, v3
	v_mul_lo_u32 v5, v3, v2
	v_add_u32_e32 v4, 1, v1
	v_sub_u32_e32 v1, v1, v5
	v_add_u32_e32 v6, 1, v3
	v_cmp_ge_u32_e32 vcc, v1, v2
	v_sub_u32_e32 v5, v1, v2
	s_nop 0
	v_cndmask_b32_e32 v3, v3, v6, vcc
	v_cndmask_b32_e32 v1, v1, v5, vcc
	v_add_u32_e32 v5, 1, v3
	v_cmp_ge_u32_e32 vcc, v1, v2
	s_nop 1
	v_cndmask_b32_e32 v1, v3, v5, vcc
	v_mad_u64_u32 v[2:3], s[0:1], v2, v1, v[2:3]
	v_cmp_ne_u32_e32 vcc, v4, v2
	s_and_saveexec_b64 s[0:1], vcc
	s_xor_b64 s[0:1], exec, s[0:1]
	s_cbranch_execz .LBB0_3050
	v_mov_b32_e32 v0, s23
	v_add_co_u32_e32 v2, vcc, 0x2000, v0
	v_mov_b32_e32 v0, s22
	s_nop 0
	v_addc_co_u32_e32 v3, vcc, 0, v0, vcc
	global_load_dword v0, v[2:3], off offset:1024 sc1
	s_add_u32 s6, s23, 0x2400
	s_addc_u32 s7, s22, 0
	s_waitcnt vmcnt(0) lgkmcnt(0)
	v_cmp_eq_u32_e32 vcc, v0, v1
	s_and_saveexec_b64 s[2:3], vcc
	s_cbranch_execz .LBB0_3049
	s_add_u32 s4, s74, 0xc0200
	s_addc_u32 s5, s75, 0
	s_mov_b32 s24, 1
	s_mov_b64 s[8:9], 0
	s_branch .LBB0_3041

; DI unsigned xb_ld(unsigned* p)              { return __hip_atomic_load(p, __ATOMIC_RELAXED, __HIP_MEMORY_SCOPE_AGENT); }
; #define XB_SPIN(cond, bar) do { unsigned _sp = 0; while (cond) { __builtin_amdgcn_s_sleep(1); \
;     if ((++_sp & 255u) == 0u) { if (xb_ld(&(bar)[XB_TMO])) break; if (_sp > XB_SPIN_CAP) { atomicAdd(&(bar)[XB_TMO], 1u); break; } } } } while (0)
; DI void xcd_barrier(int wv, unsigned* bar, volatile LAS unsigned* st) {
;     ...
;             XB_SPIN(xb_ld(&bar[XB_XGEN(x)]) == gen, bar);
.LBB0_3041:
	s_and_b32 s16, s24, 0xff
	s_mov_b64 s[14:15], -1
	s_cmp_lg_u32 s16, 0
	s_mov_b64 s[16:17], -1
	s_sleep 1
	s_cbranch_scc1 .LBB0_3045
	v_mov_b64_e32 v[2:3], s[4:5]
	global_load_dword v0, v[2:3], off sc1
	s_mov_b64 s[16:17], 0
	s_mov_b64 s[18:19], -1
	s_waitcnt vmcnt(0) lgkmcnt(0)
	v_cmp_eq_u32_e32 vcc, 0, v0
	s_and_saveexec_b64 s[20:21], vcc
	s_cmp_lt_u32 s24, 0x40001
	s_cselect_b64 s[16:17], -1, 0
	s_xor_b64 s[18:19], exec, -1
	s_and_b64 s[16:17], s[16:17], exec
	s_or_b64 exec, exec, s[20:21]
.LBB0_3045:
	s_andn2_b64 s[12:13], s[12:13], exec
	s_and_b64 s[18:19], s[18:19], exec
	s_or_b64 s[12:13], s[12:13], s[18:19]
	s_and_saveexec_b64 s[18:19], s[16:17]
	s_cbranch_execz .LBB0_3040
	v_mov_b64_e32 v[2:3], s[6:7]
	global_load_dword v0, v[2:3], off sc1
	s_add_i32 s24, s24, 1
	s_or_b64 s[12:13], s[12:13], exec
	s_waitcnt vmcnt(0) lgkmcnt(0)
	v_cmp_ne_u32_e32 vcc, v0, v1
	s_orn2_b64 s[14:15], vcc, exec
	s_branch .LBB0_3040

; DI unsigned xb_ld(unsigned* p)              { return __hip_atomic_load(p, __ATOMIC_RELAXED, __HIP_MEMORY_SCOPE_AGENT); }
; DI unsigned xb_add(unsigned* p, unsigned v) { return __hip_atomic_fetch_add(p, v, __ATOMIC_RELAXED, __HIP_MEMORY_SCOPE_AGENT); }
; #define XB_SPIN(cond, bar) do { unsigned _sp = 0; while (cond) { __builtin_amdgcn_s_sleep(1); \
;     if ((++_sp & 255u) == 0u) { if (xb_ld(&(bar)[XB_TMO])) break; if (_sp > XB_SPIN_CAP) { atomicAdd(&(bar)[XB_TMO], 1u); break; } } } } while (0)
; DI void xcd_barrier(int wv, unsigned* bar, volatile LAS unsigned* st) {
;     ...
;         if (old + 1u == (gen + 1u) * nloc) {
;             __builtin_amdgcn_fence(__ATOMIC_RELEASE, "agent");
;             asm volatile("s_waitcnt vmcnt(0)" ::: "memory");
;             const unsigned og = xb_add(&bar[XB_TOP], 1u);
;             const unsigned tg = og / nx;
;             if (og + 1u == (tg + 1u) * nx) xb_add(&bar[XB_TOPGEN], 1u);
;             else XB_SPIN(xb_ld(&bar[XB_TOPGEN]) == tg, bar);
.LBB0_3050:
	s_andn2_saveexec_b64 s[0:1], s[0:1]
	s_cbranch_execz .LBB0_3066
	v_mov_b32_e32 v1, s74
	v_add_co_u32_e32 v2, vcc, 0xc3000, v1
	v_mov_b32_e32 v1, s75
	buffer_wbl2 sc1
	s_waitcnt vmcnt(0)
	v_addc_co_u32_e32 v3, vcc, 0, v1, vcc
	v_mov_b32_e32 v1, 1
	flat_atomic_add v1, v[2:3], v1 offset:1024 sc0
	v_cvt_f32_u32_e32 v2, v0
	v_sub_u32_e32 v3, 0, v0
	s_add_u32 s0, s74, 0xc3500
	s_addc_u32 s1, s75, 0
	v_rcp_iflag_f32_e32 v2, v2
	s_mov_b64 s[4:5], -1
	v_mul_f32_e32 v2, 0x4f7ffffe, v2
	v_cvt_u32_f32_e32 v2, v2
	v_mul_lo_u32 v3, v3, v2
	v_mul_hi_u32 v3, v2, v3
	v_add_u32_e32 v2, v2, v3
	s_waitcnt vmcnt(0) lgkmcnt(0)
	v_mul_hi_u32 v2, v1, v2
	v_mul_lo_u32 v4, v2, v0
	v_add_u32_e32 v3, 1, v1
	v_sub_u32_e32 v1, v1, v4
	v_add_u32_e32 v5, 1, v2
	v_cmp_ge_u32_e32 vcc, v1, v0
	v_sub_u32_e32 v4, v1, v0
	s_nop 0
	v_cndmask_b32_e32 v2, v2, v5, vcc
	v_cndmask_b32_e32 v1, v1, v4, vcc
	v_add_u32_e32 v4, 1, v2
	v_cmp_ge_u32_e32 vcc, v1, v0
	s_nop 1
	v_cndmask_b32_e32 v2, v2, v4, vcc
	v_mad_u64_u32 v[0:1], s[2:3], v0, v2, v[0:1]
	v_cmp_ne_u32_e32 vcc, v3, v0
	v_mov_b64_e32 v[0:1], s[0:1]
	s_and_saveexec_b64 s[2:3], vcc
	s_cbranch_execz .LBB0_3063
	v_mov_b64_e32 v[0:1], s[0:1]
	global_load_dword v0, v[0:1], off sc1
	s_mov_b64 s[8:9], 0
	s_waitcnt vmcnt(0) lgkmcnt(0)
	v_cmp_eq_u32_e32 vcc, v0, v2
	s_and_saveexec_b64 s[6:7], vcc
	s_cbranch_execz .LBB0_3062
	s_add_u32 s4, s74, 0xc0200
	s_addc_u32 s5, s75, 0
	s_mov_b32 s20, 1
	s_branch .LBB0_3055

; DI unsigned xb_ld(unsigned* p)              { return __hip_atomic_load(p, __ATOMIC_RELAXED, __HIP_MEMORY_SCOPE_AGENT); }
; #define XB_SPIN(cond, bar) do { unsigned _sp = 0; while (cond) { __builtin_amdgcn_s_sleep(1); \
;     if ((++_sp & 255u) == 0u) { if (xb_ld(&(bar)[XB_TMO])) break; if (_sp > XB_SPIN_CAP) { atomicAdd(&(bar)[XB_TMO], 1u); break; } } } } while (0)
; DI void xcd_barrier(int wv, unsigned* bar, volatile LAS unsigned* st) {
;     ...
;             else XB_SPIN(xb_ld(&bar[XB_TOPGEN]) == tg, bar);
.LBB0_3057:
	v_mov_b64_e32 v[0:1], s[4:5]
	global_load_dword v0, v[0:1], off sc1
	s_mov_b64 s[14:15], 0
	s_mov_b64 s[12:13], -1
	s_waitcnt vmcnt(0) lgkmcnt(0)
	v_cmp_eq_u32_e32 vcc, 0, v0
	s_and_saveexec_b64 s[16:17], vcc
	s_cmp_lt_u32 s20, 0x40001
	s_cselect_b64 s[14:15], -1, 0
	s_xor_b64 s[12:13], exec, -1
	s_and_b64 s[14:15], s[14:15], exec
	s_or_b64 exec, exec, s[16:17]
	s_mov_b64 s[16:17], -1
	s_and_saveexec_b64 s[18:19], s[14:15]
	s_cbranch_execz .LBB0_3054
.LBB0_3060:
	v_mov_b64_e32 v[0:1], s[0:1]
	global_load_dword v0, v[0:1], off sc1
	s_add_i32 s20, s20, 1
	s_or_b64 s[12:13], s[12:13], exec
	s_waitcnt vmcnt(0) lgkmcnt(0)
	v_cmp_ne_u32_e32 vcc, v0, v2
	s_orn2_b64 s[16:17], vcc, exec
	s_branch .LBB0_3054
